# baseline (speedup 1.0000x reference)
; __device__ __forceinline__ int opaque_tid() { int t = threadIdx.x; asm volatile("" : "+v"(t)); return t; }
; template <int AMODE>
; __device__ __forceinline__ void gemm_kloop(f32x4 (&acc)[4][4], const u16* __restrict__ A, int lda,
;                                            const u16* __restrict__ Bt, int ldb, int K, char* smem,
;                                            const float* __restrict__ ssq_rows) {
;     const int tid = opaque_tid(), lane = tid & 63, wid = tid >> 6, wr = wid >> 1, wc = wid & 1;
;     const int r = lane & 15, g4 = lane >> 4;
;     char* As = smem; char* Bs = smem + 32768;
;     const int grow = wid * 8 + (lane >> 3);
;     const int gch = ((lane & 7) ^ ((lane >> 3) & 7)) * 8;
;     const u16* Ag = A + (size_t)grow * lda + gch;
;     const u16* Bg = Bt + (size_t)grow * ldb + gch;
;     const int lrow = tid >> 3, lkc = tid & 7;
;     const u16* Ap = A + (size_t)lrow * lda + lkc * 8;
;     const int lds_w = lrow * 128 + ((lkc ^ (lrow & 7)) << 4);
;     uint4 ra[4];
;     float rs[4];
;     const int nk = K >> 6;
;     ...
;     GLOAD(0, 0);
;     LSTORE(0);
;     asm volatile("s_waitcnt vmcnt(0)" ::: "memory");
;     __syncthreads();
;     for (int kt = 0; kt < nk; ++kt) {
; __device__ void phaseA_tile(const Params& p, int l, int mt, int nt, char* smem) {
;     ...
; #pragma unroll
;     for (int i = 0; i < 4; ++i)
; #pragma unroll
;         for (int j = 0; j < 4; ++j) acc[i][j] = (f32x4){0.f, 0.f, 0.f, 0.f};
;     const int m0 = mt * 128, n0 = nt * 128;
;     gemm_kloop<0>(acc, p.xb + (size_t)m0 * 1024, 1024, p.wt_in + ((size_t)l * NIN + n0) * 1024, 1024, 1024, smem, nullptr);
.LBB0_151:
	s_lshl_b32 s54, s52, 7
	s_ashr_i32 s55, s54, 31
	v_readlane_b32 s4, v214, 34
	s_lshl_b32 s56, s53, 7
	s_lshl_b64 s[0:1], s[54:55], 11
	v_readlane_b32 s10, v214, 40
	v_readlane_b32 s5, v214, 35
	v_readlane_b32 s11, v214, 41
	v_readlane_b32 s16, v214, 46
	v_readlane_b32 s17, v214, 47
	v_readlane_b32 s18, v214, 48
	v_readlane_b32 s19, v214, 49
	s_add_u32 s4, s10, s0
	v_readlane_b32 s6, v214, 36
	s_addc_u32 s5, s11, s1
	s_mov_b64 s[98:99], s[4:5]
	s_ashr_i32 s57, s56, 31
	s_mul_i32 s2, s48, 0x3080
	v_readlane_b32 s16, v214, 0
	v_mov_b32_e32 v70, v141
	v_readlane_b32 s7, v214, 37
	s_add_u32 s6, s2, s56
	v_readlane_b32 s17, v214, 1
	v_readlane_b32 s18, v214, 2
	v_readlane_b32 s19, v214, 3
	v_readlane_b32 s20, v214, 4
	v_readlane_b32 s21, v214, 5
	v_readlane_b32 s22, v214, 6
	v_readlane_b32 s23, v214, 7
	v_readlane_b32 s24, v214, 8
	v_readlane_b32 s25, v214, 9
	v_mov_b32_e32 v10, v141
	s_addc_u32 s7, 0, s57
	v_readlane_b32 s26, v214, 10
	v_readlane_b32 s27, v214, 11
	v_readlane_b32 s28, v214, 12
	v_readlane_b32 s29, v214, 13
	v_readlane_b32 s30, v214, 14
	v_readlane_b32 s31, v214, 15
	s_mov_b64 s[16:17], s[24:25]
	s_lshl_b64 s[6:7], s[6:7], 11
	v_ashrrev_i32_e32 v8, 6, v10
	v_bfe_u32 v0, v10, 3, 3
	s_mov_b64 s[22:23], s[30:31]
	v_lshl_or_b32 v2, v8, 3, v0
	s_add_u32 s6, s22, s6
	v_ashrrev_i32_e32 v3, 31, v2
	v_lshlrev_b32_e32 v71, 10, v8
	s_addc_u32 s7, s23, s7
	s_mov_b64 s[100:101], s[6:7]
	v_bitop3_b32 v0, v0, v10, 7 bitop3:0x78
	v_lshlrev_b64 v[2:3], 11, v[2:3]
	v_add_u32_e32 v8, 0x8000, v71
	v_lshlrev_b32_e32 v0, 4, v0
	v_lshl_add_u64 v[6:7], s[6:7], 0, v[2:3]
	v_readfirstlane_b32 s2, v8
	v_lshl_add_u64 v[4:5], s[4:5], 0, v[2:3]
	v_lshl_add_u64 v[6:7], v[6:7], 0, v[0:1]
	s_mov_b32 m0, s2
	v_readfirstlane_b32 s2, v71
	v_add_u32_e32 v12, 0x9000, v71
	v_lshl_add_u64 v[4:5], v[4:5], 0, v[0:1]
	global_load_lds_dwordx4 v[6:7], off
	s_mov_b32 m0, s2
	s_mov_b64 s[4:5], 0x10000
	v_readfirstlane_b32 s2, v12
	v_add_u32_e32 v12, 0x1000, v71
	global_load_lds_dwordx4 v[4:5], off
	v_lshl_add_u64 v[8:9], v[6:7], 0, s[4:5]
	s_mov_b32 m0, s2
	v_readfirstlane_b32 s2, v12
	v_add_u32_e32 v12, 0xa000, v71
	global_load_lds_dwordx4 v[8:9], off
	v_lshl_add_u64 v[8:9], v[4:5], 0, s[4:5]
	s_mov_b32 m0, s2
	s_mov_b64 s[4:5], 0x20000
	v_readfirstlane_b32 s2, v12
	v_add_u32_e32 v12, 0x2000, v71
	global_load_lds_dwordx4 v[8:9], off
	v_lshl_add_u64 v[8:9], v[6:7], 0, s[4:5]
	s_mov_b32 m0, s2
	v_readfirstlane_b32 s2, v12
	global_load_lds_dwordx4 v[8:9], off
	v_lshl_add_u64 v[8:9], v[4:5], 0, s[4:5]
	s_mov_b32 m0, s2
	s_mov_b64 s[4:5], 0x30000
	global_load_lds_dwordx4 v[8:9], off
	v_add_u32_e32 v8, 0xb000, v71
	v_lshl_add_u64 v[6:7], v[6:7], 0, s[4:5]
	v_readfirstlane_b32 s2, v8
	s_mov_b32 m0, s2
	v_lshl_add_u64 v[4:5], v[4:5], 0, s[4:5]
	global_load_lds_dwordx4 v[6:7], off
	v_add_u32_e32 v6, 0x3000, v71
	v_and_b32_e32 v11, 7, v10
	v_readfirstlane_b32 s2, v6
	s_mov_b32 m0, s2
	v_lshrrev_b32_e32 v6, 1, v10
	global_load_lds_dwordx4 v[4:5], off
	v_and_b32_e32 v5, 15, v10
	s_mov_b32 s2, 0x1ffffc0
	v_and_or_b32 v5, v6, s2, v5
	v_bfe_u32 v4, v10, 4, 2
	v_lshlrev_b32_e32 v73, 7, v5
	v_lshlrev_b32_e32 v5, 7, v10
	v_and_b32_e32 v72, 0x2780, v5
	v_bitop3_b32 v5, v4, v10, 7 bitop3:0x78
	v_bitop3_b32 v4, v4, v11, 4 bitop3:0x36
	s_lshl_b64 s[4:5], s[56:57], 11
	v_lshlrev_b32_e32 v76, 4, v5
	v_lshlrev_b32_e32 v74, 4, v4
	v_lshl_add_u64 v[4:5], s[4:5], 0, v[2:3]
	v_lshl_add_u64 v[2:3], s[0:1], 0, v[2:3]
	s_waitcnt vmcnt(0)
	v_or_b32_e32 v2, v2, v0
	v_or_b32_e32 v4, v4, v0
	v_lshl_add_u64 v[68:69], s[10:11], 0, v[2:3]
	v_mov_b32_e32 v2, 0
	v_mov_b32_e32 v75, v70
	v_lshl_add_u64 v[66:67], s[44:45], 0, v[4:5]
	s_mov_b64 s[0:1], 0
	s_mov_b32 s2, 0
	v_mov_b32_e32 v3, v2
	v_mov_b32_e32 v4, v2
	v_mov_b32_e32 v5, v2
	v_mov_b32_e32 v6, v2
	v_mov_b32_e32 v7, v2
	v_mov_b32_e32 v8, v2
	v_mov_b32_e32 v9, v2
	v_mov_b32_e32 v10, v2
	v_mov_b32_e32 v11, v2
	v_mov_b32_e32 v12, v2
	v_mov_b32_e32 v13, v2
	v_mov_b32_e32 v14, v2
	v_mov_b32_e32 v15, v2
	v_mov_b32_e32 v16, v2
	v_mov_b32_e32 v17, v2
	v_mov_b32_e32 v18, v2
	v_mov_b32_e32 v19, v2
	v_mov_b32_e32 v20, v2
	v_mov_b32_e32 v21, v2
	v_mov_b32_e32 v22, v2
	v_mov_b32_e32 v23, v2
	v_mov_b32_e32 v24, v2
	v_mov_b32_e32 v25, v2
	v_mov_b32_e32 v26, v2
	v_mov_b32_e32 v27, v2
	v_mov_b32_e32 v28, v2
	v_mov_b32_e32 v29, v2
	v_mov_b32_e32 v30, v2
	v_mov_b32_e32 v31, v2
	v_mov_b32_e32 v32, v2
	v_mov_b32_e32 v33, v2
	v_mov_b32_e32 v34, v2
	v_mov_b32_e32 v35, v2
	v_mov_b32_e32 v36, v2
	v_mov_b32_e32 v37, v2
	v_mov_b32_e32 v38, v2
	v_mov_b32_e32 v39, v2
	v_mov_b32_e32 v40, v2
	v_mov_b32_e32 v41, v2
	v_mov_b32_e32 v42, v2
	v_mov_b32_e32 v43, v2
	v_mov_b32_e32 v44, v2
	v_mov_b32_e32 v45, v2
	v_mov_b32_e32 v46, v2
	v_mov_b32_e32 v47, v2
	v_mov_b32_e32 v48, v2
	v_mov_b32_e32 v49, v2
	v_mov_b32_e32 v50, v2
	v_mov_b32_e32 v51, v2
	v_mov_b32_e32 v52, v2
	v_mov_b32_e32 v53, v2
	v_mov_b32_e32 v54, v2
	v_mov_b32_e32 v55, v2
	v_mov_b32_e32 v56, v2
	v_mov_b32_e32 v57, v2
	v_mov_b32_e32 v58, v2
	v_mov_b32_e32 v59, v2
	v_mov_b32_e32 v60, v2
	v_mov_b32_e32 v61, v2
	v_mov_b32_e32 v62, v2
	v_mov_b32_e32 v63, v2
	v_mov_b32_e32 v64, v2
	v_mov_b32_e32 v65, v2
	v_readlane_b32 s8, v214, 38
	v_readlane_b32 s9, v214, 39
	v_readlane_b32 s12, v214, 42
	v_readlane_b32 s13, v214, 43
	v_readlane_b32 s14, v214, 44
	v_readlane_b32 s15, v214, 45
	s_mov_b64 s[18:19], s[26:27]
	s_mov_b64 s[20:21], s[28:29]
	s_waitcnt vmcnt(0) lgkmcnt(0)
	s_barrier
	v_lshrrev_b32_e32 v220, 6, v70
	v_bfe_u32 v221, v70, 3, 3
	v_lshl_or_b32 v216, v220, 3, v221
	v_and_b32_e32 v220, 7, v70
	v_xor_b32_e32 v220, v220, v221
	v_lshlrev_b32_e32 v220, 4, v220
	v_lshl_or_b32 v216, v216, 11, v220
	v_add_u32_e32 v217, 0x10000, v216
	v_add_u32_e32 v218, 0x20000, v216
	v_add_u32_e32 v219, 0x30000, v216
	v_readfirstlane_b32 s5, v71
	s_mov_b32 s0, 0
	s_mov_b32 s2, 0
	v_add_u32_e32 v0, s2, v73
	v_or_b32_e32 v77, s2, v72
	v_add_u32_e32 v90, v0, v76
	v_add_u32_e32 v102, v77, v76
	v_add_u32_e32 v0, v0, v74
	s_xor_b32 s4, s2, 0x4000
	s_add_u32 s4, s4, s5
	s_add_u32 s100, s100, 0x80
	s_addc_u32 s101, s101, 0
	s_add_u32 s98, s98, 0x80
	s_addc_u32 s99, s99, 0
; #define MFMA(a, b, c) __builtin_amdgcn_mfma_f32_16x16x32_bf16((a), (b), (c), 0, 0, 0)
; template <int AMODE>
; __device__ __forceinline__ void gemm_kloop(f32x4 (&acc)[4][4], const u16* __restrict__ A, int lda,
;                                            const u16* __restrict__ Bt, int ldb, int K, char* smem,
;                                            const float* __restrict__ ssq_rows) {
;     ...
;     for (int kt = 0; kt < nk; ++kt) {
;         const int buf = kt & 1;
;         if (kt + 1 < nk) GLOAD(kt + 1, buf ^ 1);
;         const char* ab = As + buf * 16384 + (wr * 64 + r) * 128;
;         const char* bb = Bs + buf * 16384 + (wc * 64 + r) * 128;
;         bf16x8 af[2][4], bfr[2][4];
; #pragma unroll
;         for (int ks = 0; ks < 2; ++ks) {
;             const int co = ((ks * 4 + g4) ^ (r & 7)) << 4;
; #pragma unroll
;             for (int i = 0; i < 4; ++i) af[ks][i] = ld_frag(ab + i * 2048 + co);
; #pragma unroll
;             for (int j = 0; j < 4; ++j) bfr[ks][j] = ld_frag(bb + j * 2048 + co);
;         }
;         __builtin_amdgcn_sched_barrier(0);
;         __builtin_amdgcn_s_setprio(1);
; #pragma unroll
;         for (int ks = 0; ks < 2; ++ks)
; #pragma unroll
;             for (int i = 0; i < 4; ++i)
; #pragma unroll
;                 for (int j = 0; j < 4; ++j) acc[i][j] = MFMA(bfr[ks][j], af[ks][i], acc[i][j]);
;         __builtin_amdgcn_s_setprio(0);
;         __builtin_amdgcn_sched_barrier(0);
;         if (kt + 1 < nk) LSTORE(buf ^ 1);
;         asm volatile("s_waitcnt vmcnt(0)" ::: "memory");
;         __syncthreads();
;     }
.LBB0_152:
	s_setprio 1
	s_add_u32 m0, s4, 0x8000
	ds_read_b128 v[78:81], v90
	global_load_lds_dwordx4 v216, s[100:101]
	ds_read_b128 v[82:85], v90 offset:2048
	s_add_u32 m0, s4, 0x0
	ds_read_b128 v[86:89], v90 offset:4096
	global_load_lds_dwordx4 v216, s[98:99]
	ds_read_b128 v[90:93], v90 offset:6144
	s_add_u32 m0, s4, 0x9000
	ds_read_b128 v[94:97], v102 offset:32768
	global_load_lds_dwordx4 v217, s[100:101]
	ds_read_b128 v[98:101], v102 offset:34816
	s_add_u32 m0, s4, 0x1000
	ds_read_b128 v[110:113], v102 offset:36864
	global_load_lds_dwordx4 v217, s[98:99]
	ds_read_b128 v[114:117], v102 offset:38912
	s_add_u32 m0, s4, 0xa000
	ds_read_b128 v[118:121], v0
	global_load_lds_dwordx4 v218, s[100:101]
	ds_read_b128 v[122:125], v0 offset:2048
	s_add_u32 m0, s4, 0x2000
	ds_read_b128 v[126:129], v0 offset:4096
	global_load_lds_dwordx4 v218, s[98:99]
	ds_read_b128 v[130:133], v0 offset:6144
	s_add_u32 m0, s4, 0xb000
	v_add_u32_e32 v0, v77, v74
	global_load_lds_dwordx4 v219, s[100:101]
	ds_read_b128 v[134:137], v0 offset:32768
	s_add_u32 m0, s4, 0x3000
	ds_read_b128 v[142:145], v0 offset:34816
	global_load_lds_dwordx4 v219, s[98:99]
	ds_read_b128 v[146:149], v0 offset:36864
	ds_read_b128 v[150:153], v0 offset:38912
	s_setprio 0
	s_waitcnt lgkmcnt(11)
	v_mfma_f32_16x16x32_bf16 v[62:65], v[94:97], v[78:81], v[62:65]
	s_waitcnt lgkmcnt(10)
	v_mfma_f32_16x16x32_bf16 v[58:61], v[98:101], v[78:81], v[58:61]
	s_waitcnt lgkmcnt(9)
	v_mfma_f32_16x16x32_bf16 v[54:57], v[110:113], v[78:81], v[54:57]
	s_waitcnt lgkmcnt(8)
	v_mfma_f32_16x16x32_bf16 v[50:53], v[114:117], v[78:81], v[50:53]
	v_mfma_f32_16x16x32_bf16 v[46:49], v[94:97], v[82:85], v[46:49]
	v_mfma_f32_16x16x32_bf16 v[42:45], v[98:101], v[82:85], v[42:45]
	v_mfma_f32_16x16x32_bf16 v[38:41], v[110:113], v[82:85], v[38:41]
	v_mfma_f32_16x16x32_bf16 v[34:37], v[114:117], v[82:85], v[34:37]
	v_mfma_f32_16x16x32_bf16 v[30:33], v[94:97], v[86:89], v[30:33]
	v_mfma_f32_16x16x32_bf16 v[26:29], v[98:101], v[86:89], v[26:29]
	v_mfma_f32_16x16x32_bf16 v[22:25], v[110:113], v[86:89], v[22:25]
	v_mfma_f32_16x16x32_bf16 v[18:21], v[114:117], v[86:89], v[18:21]
	v_mfma_f32_16x16x32_bf16 v[14:17], v[94:97], v[90:93], v[14:17]
	v_mfma_f32_16x16x32_bf16 v[10:13], v[98:101], v[90:93], v[10:13]
	v_mfma_f32_16x16x32_bf16 v[6:9], v[110:113], v[90:93], v[6:9]
	v_mfma_f32_16x16x32_bf16 v[2:5], v[114:117], v[90:93], v[2:5]
	s_waitcnt lgkmcnt(3)
	v_mfma_f32_16x16x32_bf16 v[62:65], v[134:137], v[118:121], v[62:65]
	s_waitcnt lgkmcnt(2)
	v_mfma_f32_16x16x32_bf16 v[58:61], v[142:145], v[118:121], v[58:61]
	s_waitcnt lgkmcnt(1)
	v_mfma_f32_16x16x32_bf16 v[54:57], v[146:149], v[118:121], v[54:57]
	s_waitcnt lgkmcnt(0)
	v_mfma_f32_16x16x32_bf16 v[50:53], v[150:153], v[118:121], v[50:53]
	v_mfma_f32_16x16x32_bf16 v[46:49], v[134:137], v[122:125], v[46:49]
	v_mfma_f32_16x16x32_bf16 v[42:45], v[142:145], v[122:125], v[42:45]
	v_mfma_f32_16x16x32_bf16 v[38:41], v[146:149], v[122:125], v[38:41]
	v_mfma_f32_16x16x32_bf16 v[34:37], v[150:153], v[122:125], v[34:37]
	v_mfma_f32_16x16x32_bf16 v[30:33], v[134:137], v[126:129], v[30:33]
	v_mfma_f32_16x16x32_bf16 v[26:29], v[142:145], v[126:129], v[26:29]
	v_mfma_f32_16x16x32_bf16 v[22:25], v[146:149], v[126:129], v[22:25]
	v_mfma_f32_16x16x32_bf16 v[18:21], v[150:153], v[126:129], v[18:21]
	v_mfma_f32_16x16x32_bf16 v[14:17], v[134:137], v[130:133], v[14:17]
	v_mfma_f32_16x16x32_bf16 v[10:13], v[142:145], v[130:133], v[10:13]
	v_mfma_f32_16x16x32_bf16 v[6:9], v[146:149], v[130:133], v[6:9]
	v_mfma_f32_16x16x32_bf16 v[2:5], v[150:153], v[130:133], v[2:5]
	s_nop 0
	s_xor_b32 s2, s2, 0x4000
	s_add_i32 s0, s0, 1
	v_add_u32_e32 v0, s2, v73
	v_or_b32_e32 v77, s2, v72
	v_add_u32_e32 v90, v0, v76
	v_add_u32_e32 v102, v77, v76
	v_add_u32_e32 v0, v0, v74
	s_xor_b32 s4, s2, 0x4000
	s_add_u32 s4, s4, s5
	s_add_u32 s100, s100, 0x80
	s_addc_u32 s101, s101, 0
	s_add_u32 s98, s98, 0x80
	s_addc_u32 s99, s99, 0
	s_cmp_eq_u32 s0, 15
	s_waitcnt vmcnt(0)
	s_barrier
	s_cbranch_scc0 .LBB0_152
	v_add_u32_e32 v0, v73, v76
	ds_read_b128 v[66:69], v0 offset:16384
	ds_read_b128 v[78:81], v0 offset:18432
	ds_read_b128 v[82:85], v0 offset:20480
	ds_read_b128 v[86:89], v0 offset:22528
	v_add_u32_e32 v0, v72, v76
	ds_read_b128 v[90:93], v0 offset:49152
	ds_read_b128 v[98:101], v0 offset:51200
	ds_read_b128 v[110:113], v0 offset:53248
	ds_read_b128 v[114:117], v0 offset:55296
	v_add_u32_e32 v0, v73, v74
	ds_read_b128 v[118:121], v0 offset:16384
	ds_read_b128 v[122:125], v0 offset:18432
	ds_read_b128 v[126:129], v0 offset:20480
	ds_read_b128 v[130:133], v0 offset:22528
	v_add_u32_e32 v0, v72, v74
	ds_read_b128 v[134:137], v0 offset:49152
	ds_read_b128 v[142:145], v0 offset:51200
	ds_read_b128 v[146:149], v0 offset:53248
	ds_read_b128 v[150:153], v0 offset:55296
	v_ashrrev_i32_e32 v96, 7, v70
	v_and_b32_e32 v72, 15, v70
	v_bfe_u32 v74, v70, 6, 1
	v_bfe_u32 v73, v70, 4, 2
	s_setprio 1
	s_waitcnt lgkmcnt(11)
	v_mfma_f32_16x16x32_bf16 v[62:65], v[90:93], v[66:69], v[62:65]
	s_waitcnt lgkmcnt(10)
	v_mfma_f32_16x16x32_bf16 v[58:61], v[98:101], v[66:69], v[58:61]
	s_waitcnt lgkmcnt(9)
	v_mfma_f32_16x16x32_bf16 v[54:57], v[110:113], v[66:69], v[54:57]
	s_waitcnt lgkmcnt(8)
	v_mfma_f32_16x16x32_bf16 v[50:53], v[114:117], v[66:69], v[50:53]
	v_mfma_f32_16x16x32_bf16 v[46:49], v[90:93], v[78:81], v[46:49]
	v_mfma_f32_16x16x32_bf16 v[42:45], v[98:101], v[78:81], v[42:45]
	v_mfma_f32_16x16x32_bf16 v[38:41], v[110:113], v[78:81], v[38:41]
	v_mfma_f32_16x16x32_bf16 v[34:37], v[114:117], v[78:81], v[34:37]
	v_mfma_f32_16x16x32_bf16 v[30:33], v[90:93], v[82:85], v[30:33]
	v_mfma_f32_16x16x32_bf16 v[26:29], v[98:101], v[82:85], v[26:29]
	v_mfma_f32_16x16x32_bf16 v[22:25], v[110:113], v[82:85], v[22:25]
	v_mfma_f32_16x16x32_bf16 v[18:21], v[114:117], v[82:85], v[18:21]
	v_mfma_f32_16x16x32_bf16 v[14:17], v[90:93], v[86:89], v[14:17]
	v_mfma_f32_16x16x32_bf16 v[10:13], v[98:101], v[86:89], v[10:13]
	v_mfma_f32_16x16x32_bf16 v[6:9], v[110:113], v[86:89], v[6:9]
	v_mfma_f32_16x16x32_bf16 v[2:5], v[114:117], v[86:89], v[2:5]
	s_waitcnt lgkmcnt(3)
; __device__ __forceinline__ float softplusf(float x) { return fmaxf(x, 0.f) + log1pf(__expf(-fabsf(x))); }
; #define MFMA(a, b, c) __builtin_amdgcn_mfma_f32_16x16x32_bf16((a), (b), (c), 0, 0, 0)
; template <int AMODE>
; __device__ __forceinline__ void gemm_kloop(f32x4 (&acc)[4][4], const u16* __restrict__ A, int lda,
;                                            const u16* __restrict__ Bt, int ldb, int K, char* smem,
;                                            const float* __restrict__ ssq_rows) {
;     ...
;         for (int ks = 0; ks < 2; ++ks)
; #pragma unroll
;             for (int i = 0; i < 4; ++i)
; #pragma unroll
;                 for (int j = 0; j < 4; ++j) acc[i][j] = MFMA(bfr[ks][j], af[ks][i], acc[i][j]);
;         __builtin_amdgcn_s_setprio(0);
;         __builtin_amdgcn_sched_barrier(0);
;         if (kt + 1 < nk) LSTORE(buf ^ 1);
;         asm volatile("s_waitcnt vmcnt(0)" ::: "memory");
;         __syncthreads();
; __device__ void phaseA_tile(const Params& p, int l, int mt, int nt, char* smem) {
;     ...
;         float* lf_s = (float*)smem;
;         if (wc == 0) {
; #pragma unroll
;             for (int i = 0; i < 4; ++i) {
;                 const int rl = wr * 64 + i * 16 + r;
;                 const int row = m0 + rl;
; #pragma unroll
;                 for (int j = 0; j < 2; ++j) {
;                     const int c = j * 16 + g4 * 4;
;                     const float4 db = *(const float4*)(p.dt_bias + l * 32 + c);
;                     const f32x4 v = acc[i][j];
;                     *(float4*)(p.dtb + (size_t)row * 32 + c) =
;                         make_float4(softplusf(v[0] + db.x), softplusf(v[1] + db.y), softplusf(v[2] + db.z), softplusf(v[3] + db.w));
	v_mfma_f32_16x16x32_bf16 v[62:65], v[134:137], v[118:121], v[62:65]
	s_waitcnt lgkmcnt(2)
	v_mfma_f32_16x16x32_bf16 v[58:61], v[142:145], v[118:121], v[58:61]
	s_waitcnt lgkmcnt(1)
	v_mfma_f32_16x16x32_bf16 v[54:57], v[146:149], v[118:121], v[54:57]
	s_waitcnt lgkmcnt(0)
	v_mfma_f32_16x16x32_bf16 v[50:53], v[150:153], v[118:121], v[50:53]
	v_mfma_f32_16x16x32_bf16 v[46:49], v[134:137], v[122:125], v[46:49]
	v_mfma_f32_16x16x32_bf16 v[42:45], v[142:145], v[122:125], v[42:45]
	v_mfma_f32_16x16x32_bf16 v[38:41], v[146:149], v[122:125], v[38:41]
	v_mfma_f32_16x16x32_bf16 v[34:37], v[150:153], v[122:125], v[34:37]
	v_mfma_f32_16x16x32_bf16 v[30:33], v[134:137], v[126:129], v[30:33]
	v_mfma_f32_16x16x32_bf16 v[26:29], v[142:145], v[126:129], v[26:29]
	v_mfma_f32_16x16x32_bf16 v[22:25], v[146:149], v[126:129], v[22:25]
	v_mfma_f32_16x16x32_bf16 v[18:21], v[150:153], v[126:129], v[18:21]
	v_mfma_f32_16x16x32_bf16 v[14:17], v[134:137], v[130:133], v[14:17]
	v_mfma_f32_16x16x32_bf16 v[10:13], v[142:145], v[130:133], v[10:13]
	v_mfma_f32_16x16x32_bf16 v[6:9], v[146:149], v[130:133], v[6:9]
	v_mfma_f32_16x16x32_bf16 v[2:5], v[150:153], v[130:133], v[2:5]
	s_setprio 0
	s_waitcnt vmcnt(0)
	s_cmpk_eq_i32 s52, 0x100
	s_cselect_b64 s[60:61], -1, 0
	s_cmpk_lg_i32 s52, 0x100
	s_cselect_b64 s[24:25], -1, 0
	s_cmpk_gt_i32 s53, 0x5f
	s_mov_b64 s[0:1], -1
	s_barrier
	s_cbranch_scc0 .LBB0_182
	v_cmp_eq_u32_e32 vcc, 0, v74
	s_and_saveexec_b64 s[4:5], vcc
	s_cbranch_execz .LBB0_156
	v_lshlrev_b32_e32 v0, 4, v73
	global_load_dwordx4 v[66:69], v0, s[74:75]
	s_mov_b32 s2, 0xbfb8aa3b
	s_mov_b32 s26, 0x3f2aaaab
	s_mov_b32 s0, 0x3ecc95a3
	s_mov_b32 s28, 0x3e9b6dac
	s_mov_b32 s30, 0x3f2aaada
	v_lshl_or_b32 v71, v96, 6, v72
	v_add_u32_e32 v76, s54, v71
	v_ashrrev_i32_e32 v77, 31, v76
	v_readlane_b32 s8, v213, 4
	v_lshlrev_b64 v[80:81], 7, v[76:77]
	v_readlane_b32 s10, v213, 6
	v_readlane_b32 s11, v213, 7
	v_readlane_b32 s12, v213, 8
	v_readlane_b32 s13, v213, 9
	s_mov_b32 s12, 0x3f317218
	v_readlane_b32 s14, v213, 10
	v_readlane_b32 s15, v213, 11
	s_mov_b32 s14, 0xb102e308
	s_mov_b32 s8, 0x7f800000
	v_readlane_b32 s9, v213, 5
	s_mov_b32 s9, 0x33800000
	v_readlane_b32 s16, v213, 12
	v_readlane_b32 s17, v213, 13
	v_readlane_b32 s18, v213, 14
	v_readlane_b32 s19, v213, 15
	v_readlane_b32 s20, v213, 16
	v_readlane_b32 s21, v213, 17
	v_readlane_b32 s22, v213, 18
	v_readlane_b32 s23, v213, 19
	s_waitcnt vmcnt(0)
	v_add_f32_e32 v66, v62, v66
	v_max_f32_e32 v78, 0, v66
	v_mul_f32_e64 v66, |v66|, s2
	v_exp_f32_e32 v97, v66
	v_add_f32_e32 v67, v63, v67
	v_add_f32_e32 v68, v64, v68
	v_add_f32_e32 v69, v65, v69
	v_add_f32_e32 v66, 1.0, v97
	v_add_f32_e32 v79, -1.0, v66
	v_sub_f32_e32 v82, v79, v66
	v_add_f32_e32 v82, 1.0, v82
	v_sub_f32_e32 v79, v97, v79
	v_add_f32_e32 v79, v79, v82
	v_frexp_mant_f32_e32 v82, v66
	v_cmp_gt_f32_e32 vcc, s26, v82
	v_cvt_f64_f32_e32 v[82:83], v66
	v_frexp_exp_i32_f64_e32 v82, v[82:83]
	v_subbrev_co_u32_e32 v88, vcc, 0, v82, vcc
	v_sub_u32_e32 v82, 0, v88
	v_ldexp_f32 v66, v66, v82
	v_ldexp_f32 v82, v79, v82
	v_max_f32_e32 v79, 0, v67
	v_mul_f32_e64 v67, |v67|, s2
	v_exp_f32_e32 v98, v67
	s_nop 0
	v_add_f32_e32 v67, 1.0, v98
	v_add_f32_e32 v83, -1.0, v67
	v_sub_f32_e32 v84, v83, v67
	v_add_f32_e32 v84, 1.0, v84
	v_sub_f32_e32 v83, v98, v83
	v_add_f32_e32 v83, v83, v84
	v_frexp_mant_f32_e32 v84, v67
	v_cmp_gt_f32_e32 vcc, s26, v84
	v_cvt_f64_f32_e32 v[84:85], v67
	v_frexp_exp_i32_f64_e32 v84, v[84:85]
	v_subbrev_co_u32_e32 v99, vcc, 0, v84, vcc
	v_sub_u32_e32 v84, 0, v99
	v_ldexp_f32 v67, v67, v84
	v_ldexp_f32 v83, v83, v84
	v_pk_add_f32 v[84:85], v[66:67], 1.0 op_sel_hi:[1,0]
	v_pk_add_f32 v[94:95], v[66:67], -1.0 op_sel_hi:[1,0]
	v_pk_add_f32 v[86:87], v[84:85], -1.0 op_sel_hi:[1,0]
	v_pk_add_f32 v[100:101], v[94:95], 1.0 op_sel_hi:[1,0]
	v_pk_add_f32 v[86:87], v[66:67], v[86:87] neg_lo:[0,1] neg_hi:[0,1]
	v_pk_add_f32 v[66:67], v[66:67], v[100:101] neg_lo:[0,1] neg_hi:[0,1]
	v_pk_add_f32 v[86:87], v[82:83], v[86:87]
	v_pk_add_f32 v[66:67], v[82:83], v[66:67]
	v_pk_add_f32 v[90:91], v[84:85], v[86:87]
	v_pk_add_f32 v[82:83], v[94:95], v[66:67]
	v_rcp_f32_e32 v92, v90
	v_rcp_f32_e32 v93, v91
	v_pk_add_f32 v[84:85], v[90:91], v[84:85] neg_lo:[0,1] neg_hi:[0,1]
	v_pk_add_f32 v[94:95], v[82:83], v[94:95] neg_lo:[0,1] neg_hi:[0,1]
	v_pk_add_f32 v[84:85], v[86:87], v[84:85] neg_lo:[0,1] neg_hi:[0,1]
	v_pk_mul_f32 v[86:87], v[82:83], v[92:93]
	v_pk_add_f32 v[66:67], v[66:67], v[94:95] neg_lo:[0,1] neg_hi:[0,1]
	v_pk_mul_f32 v[94:95], v[90:91], v[86:87]
	s_nop 0
	v_pk_fma_f32 v[100:101], v[86:87], v[90:91], v[94:95] neg_lo:[0,0,1] neg_hi:[0,0,1]
	s_nop 0
	v_pk_fma_f32 v[100:101], v[86:87], v[84:85], v[100:101]
	s_nop 0
	v_pk_add_f32 v[102:103], v[94:95], v[100:101]
	s_nop 0
	v_pk_add_f32 v[110:111], v[82:83], v[102:103] neg_lo:[0,1] neg_hi:[0,1]
	v_pk_add_f32 v[94:95], v[102:103], v[94:95] neg_lo:[0,1] neg_hi:[0,1]
	v_pk_add_f32 v[82:83], v[82:83], v[110:111] neg_lo:[0,1] neg_hi:[0,1]
	s_nop 0
	v_pk_add_f32 v[82:83], v[82:83], v[102:103] neg_lo:[0,1] neg_hi:[0,1]
	s_nop 0
	v_pk_add_f32 v[66:67], v[66:67], v[82:83]
	v_pk_add_f32 v[82:83], v[94:95], v[100:101] neg_lo:[0,1] neg_hi:[0,1]
	s_nop 0
	v_pk_add_f32 v[66:67], v[82:83], v[66:67]
	s_nop 0
	v_pk_add_f32 v[82:83], v[110:111], v[66:67]
	s_nop 0
	v_pk_mul_f32 v[94:95], v[92:93], v[82:83]
	s_nop 0
	v_pk_mul_f32 v[100:101], v[90:91], v[94:95]
	s_nop 0
	v_pk_fma_f32 v[90:91], v[94:95], v[90:91], v[100:101] neg_lo:[0,0,1] neg_hi:[0,0,1]
	s_nop 0
	v_pk_fma_f32 v[84:85], v[94:95], v[84:85], v[90:91]
	v_pk_add_f32 v[90:91], v[110:111], v[82:83] neg_lo:[0,1] neg_hi:[0,1]
	s_nop 0
	v_pk_add_f32 v[66:67], v[66:67], v[90:91]
; __device__ __forceinline__ float softplusf(float x) { return fmaxf(x, 0.f) + log1pf(__expf(-fabsf(x))); }
; __device__ void phaseA_tile(const Params& p, int l, int mt, int nt, char* smem) {
;     ...
; #pragma unroll
;                 for (int j = 0; j < 2; ++j) {
;                     const int c = j * 16 + g4 * 4;
;                     const float4 db = *(const float4*)(p.dt_bias + l * 32 + c);
;                     const f32x4 v = acc[i][j];
;                     *(float4*)(p.dtb + (size_t)row * 32 + c) =
;                         make_float4(softplusf(v[0] + db.x), softplusf(v[1] + db.y), softplusf(v[2] + db.z), softplusf(v[3] + db.w));
	v_pk_add_f32 v[90:91], v[100:101], v[84:85]
	s_nop 0
	v_pk_add_f32 v[102:103], v[82:83], v[90:91] neg_lo:[0,1] neg_hi:[0,1]
	v_pk_add_f32 v[100:101], v[90:91], v[100:101] neg_lo:[0,1] neg_hi:[0,1]
	v_pk_add_f32 v[82:83], v[82:83], v[102:103] neg_lo:[0,1] neg_hi:[0,1]
	s_nop 0
	v_pk_add_f32 v[82:83], v[82:83], v[90:91] neg_lo:[0,1] neg_hi:[0,1]
	s_nop 0
	v_pk_add_f32 v[66:67], v[66:67], v[82:83]
	v_pk_add_f32 v[82:83], v[100:101], v[84:85] neg_lo:[0,1] neg_hi:[0,1]
	s_nop 0
	v_pk_add_f32 v[66:67], v[82:83], v[66:67]
	v_pk_add_f32 v[82:83], v[86:87], v[94:95]
	v_pk_add_f32 v[66:67], v[102:103], v[66:67]
	v_pk_add_f32 v[84:85], v[82:83], v[86:87] neg_lo:[0,1] neg_hi:[0,1]
	v_pk_mul_f32 v[66:67], v[92:93], v[66:67]
	v_pk_add_f32 v[84:85], v[94:95], v[84:85] neg_lo:[0,1] neg_hi:[0,1]
	s_nop 0
	v_pk_add_f32 v[66:67], v[84:85], v[66:67]
	s_nop 0
	v_pk_add_f32 v[86:87], v[82:83], v[66:67]
	s_nop 0
	v_pk_add_f32 v[82:83], v[86:87], v[82:83] neg_lo:[0,1] neg_hi:[0,1]
	v_pk_mul_f32 v[92:93], v[86:87], v[86:87]
	v_pk_add_f32 v[82:83], v[66:67], v[82:83] neg_lo:[0,1] neg_hi:[0,1]
	v_mov_b64_e32 v[66:67], s[0:1]
	v_pk_fma_f32 v[90:91], v[92:93], s[28:29], v[66:67] op_sel_hi:[1,0,0]
	v_ldexp_f32 v84, v86, 1
	v_pk_fma_f32 v[90:91], v[92:93], v[90:91], s[30:31] op_sel_hi:[1,1,0]
	v_pk_mul_f32 v[92:93], v[86:87], v[92:93]
	v_max_f32_e32 v86, 0, v68
	v_mul_f32_e64 v68, |v68|, s2
	v_exp_f32_e32 v100, v68
	v_ldexp_f32 v89, v83, 1
	v_ldexp_f32 v85, v87, 1
	v_pk_mul_f32 v[90:91], v[92:93], v[90:91]
	v_add_f32_e32 v68, 1.0, v100
	v_add_f32_e32 v83, -1.0, v68
	v_sub_f32_e32 v87, v83, v68
	v_add_f32_e32 v87, 1.0, v87
	v_sub_f32_e32 v83, v100, v83
	v_add_f32_e32 v83, v83, v87
	v_frexp_mant_f32_e32 v87, v68
	v_cvt_f64_f32_e32 v[94:95], v68
	v_cmp_gt_f32_e32 vcc, s26, v87
	v_frexp_exp_i32_f64_e32 v87, v[94:95]
	v_pk_add_f32 v[92:93], v[84:85], v[90:91]
	v_subbrev_co_u32_e32 v102, vcc, 0, v87, vcc
	v_sub_u32_e32 v87, 0, v102
	v_ldexp_f32 v94, v68, v87
	v_ldexp_f32 v68, v83, v87
	v_max_f32_e32 v87, 0, v69
	v_mul_f32_e64 v69, |v69|, s2
	v_exp_f32_e32 v101, v69
	v_pk_add_f32 v[84:85], v[92:93], v[84:85] neg_lo:[0,1] neg_hi:[0,1]
	v_ldexp_f32 v82, v82, 1
	v_pk_add_f32 v[84:85], v[90:91], v[84:85] neg_lo:[0,1] neg_hi:[0,1]
	v_add_f32_e32 v69, 1.0, v101
	v_add_f32_e32 v83, -1.0, v69
	v_sub_f32_e32 v95, v83, v69
	v_add_f32_e32 v95, 1.0, v95
	v_sub_f32_e32 v83, v101, v83
	v_add_f32_e32 v83, v83, v95
	v_frexp_mant_f32_e32 v95, v69
	v_cvt_f64_f32_e32 v[110:111], v69
	v_cmp_gt_f32_e32 vcc, s26, v95
	v_frexp_exp_i32_f64_e32 v95, v[110:111]
	v_mov_b32_e32 v91, v85
	v_subbrev_co_u32_e32 v132, vcc, 0, v95, vcc
	v_sub_u32_e32 v103, 0, v132
	v_ldexp_f32 v95, v69, v103
	v_pk_add_f32 v[110:111], v[94:95], 1.0 op_sel_hi:[1,0]
	v_ldexp_f32 v69, v83, v103
	v_pk_add_f32 v[112:113], v[110:111], -1.0 op_sel_hi:[1,0]
	v_pk_add_f32 v[118:119], v[94:95], -1.0 op_sel_hi:[1,0]
	v_pk_add_f32 v[112:113], v[94:95], v[112:113] neg_lo:[0,1] neg_hi:[0,1]
	v_pk_add_f32 v[120:121], v[118:119], 1.0 op_sel_hi:[1,0]
	v_pk_add_f32 v[112:113], v[68:69], v[112:113]
	v_pk_add_f32 v[94:95], v[94:95], v[120:121] neg_lo:[0,1] neg_hi:[0,1]
	v_pk_add_f32 v[114:115], v[110:111], v[112:113]
	v_pk_add_f32 v[68:69], v[68:69], v[94:95]
	v_rcp_f32_e32 v116, v114
	v_rcp_f32_e32 v117, v115
	v_pk_add_f32 v[94:95], v[118:119], v[68:69]
	v_pk_add_f32 v[110:111], v[114:115], v[110:111] neg_lo:[0,1] neg_hi:[0,1]
	v_pk_add_f32 v[118:119], v[94:95], v[118:119] neg_lo:[0,1] neg_hi:[0,1]
	v_pk_add_f32 v[110:111], v[112:113], v[110:111] neg_lo:[0,1] neg_hi:[0,1]
	v_pk_mul_f32 v[112:113], v[94:95], v[116:117]
	v_pk_add_f32 v[68:69], v[68:69], v[118:119] neg_lo:[0,1] neg_hi:[0,1]
	v_pk_mul_f32 v[118:119], v[114:115], v[112:113]
	v_mov_b32_e32 v83, v89
	v_pk_fma_f32 v[120:121], v[112:113], v[114:115], v[118:119] neg_lo:[0,0,1] neg_hi:[0,0,1]
	v_mov_b32_e32 v128, v92
	v_pk_fma_f32 v[120:121], v[112:113], v[110:111], v[120:121]
	v_cmp_neq_f32_e32 vcc, s8, v97
	v_pk_add_f32 v[122:123], v[118:119], v[120:121]
	v_cmp_lt_f32_e64 s[0:1], |v98|, s9
	v_pk_add_f32 v[124:125], v[94:95], v[122:123] neg_lo:[0,1] neg_hi:[0,1]
	v_pk_add_f32 v[118:119], v[122:123], v[118:119] neg_lo:[0,1] neg_hi:[0,1]
	v_pk_add_f32 v[94:95], v[94:95], v[124:125] neg_lo:[0,1] neg_hi:[0,1]
	s_nop 0
	v_pk_add_f32 v[94:95], v[94:95], v[122:123] neg_lo:[0,1] neg_hi:[0,1]
	s_nop 0
	v_pk_add_f32 v[68:69], v[68:69], v[94:95]
	v_pk_add_f32 v[94:95], v[118:119], v[120:121] neg_lo:[0,1] neg_hi:[0,1]
	s_nop 0
	v_pk_add_f32 v[68:69], v[94:95], v[68:69]
	s_nop 0
	v_pk_add_f32 v[94:95], v[124:125], v[68:69]
	s_nop 0
	v_pk_mul_f32 v[118:119], v[116:117], v[94:95]
	s_nop 0
	v_pk_mul_f32 v[120:121], v[114:115], v[118:119]
	s_nop 0
	v_pk_fma_f32 v[114:115], v[118:119], v[114:115], v[120:121] neg_lo:[0,0,1] neg_hi:[0,0,1]
	s_nop 0
	v_pk_fma_f32 v[110:111], v[118:119], v[110:111], v[114:115]
	v_pk_add_f32 v[114:115], v[124:125], v[94:95] neg_lo:[0,1] neg_hi:[0,1]
	s_nop 0
	v_pk_add_f32 v[68:69], v[68:69], v[114:115]
	v_pk_add_f32 v[114:115], v[120:121], v[110:111]
	s_nop 0
	v_pk_add_f32 v[122:123], v[94:95], v[114:115] neg_lo:[0,1] neg_hi:[0,1]
	v_pk_add_f32 v[120:121], v[114:115], v[120:121] neg_lo:[0,1] neg_hi:[0,1]
	v_pk_add_f32 v[94:95], v[94:95], v[122:123] neg_lo:[0,1] neg_hi:[0,1]
	s_nop 0
	v_pk_add_f32 v[94:95], v[94:95], v[114:115] neg_lo:[0,1] neg_hi:[0,1]
	s_nop 0
	v_pk_add_f32 v[68:69], v[68:69], v[94:95]
	v_pk_add_f32 v[94:95], v[120:121], v[110:111] neg_lo:[0,1] neg_hi:[0,1]
	s_nop 0
	v_pk_add_f32 v[68:69], v[94:95], v[68:69]
	v_pk_add_f32 v[94:95], v[112:113], v[118:119]
	v_pk_add_f32 v[68:69], v[122:123], v[68:69]
	v_pk_add_f32 v[110:111], v[94:95], v[112:113] neg_lo:[0,1] neg_hi:[0,1]
; __device__ __forceinline__ float softplusf(float x) { return fmaxf(x, 0.f) + log1pf(__expf(-fabsf(x))); }
; __device__ void phaseA_tile(const Params& p, int l, int mt, int nt, char* smem) {
;     ...
;                 for (int j = 0; j < 2; ++j) {
;                     const int c = j * 16 + g4 * 4;
;                     const float4 db = *(const float4*)(p.dt_bias + l * 32 + c);
;                     const f32x4 v = acc[i][j];
;                     *(float4*)(p.dtb + (size_t)row * 32 + c) =
;                         make_float4(softplusf(v[0] + db.x), softplusf(v[1] + db.y), softplusf(v[2] + db.z), softplusf(v[3] + db.w));
	v_pk_mul_f32 v[68:69], v[116:117], v[68:69]
	v_pk_add_f32 v[110:111], v[118:119], v[110:111] neg_lo:[0,1] neg_hi:[0,1]
	s_nop 0
	v_pk_add_f32 v[68:69], v[110:111], v[68:69]
	s_nop 0
	v_pk_add_f32 v[110:111], v[94:95], v[68:69]
	s_nop 0
	v_pk_add_f32 v[94:95], v[110:111], v[94:95] neg_lo:[0,1] neg_hi:[0,1]
	v_pk_mul_f32 v[114:115], v[110:111], v[110:111]
	v_pk_add_f32 v[68:69], v[68:69], v[94:95] neg_lo:[0,1] neg_hi:[0,1]
	v_pk_fma_f32 v[116:117], v[114:115], s[28:29], v[66:67] op_sel_hi:[1,0,0]
	v_ldexp_f32 v112, v68, 1
	v_ldexp_f32 v103, v69, 1
	v_lshl_add_u64 v[68:69], s[10:11], 0, v[80:81]
	v_cvt_f32_i32_e32 v81, v99
	v_cvt_f32_i32_e32 v80, v88
	v_ldexp_f32 v94, v110, 1
	v_pk_fma_f32 v[116:117], v[114:115], v[116:117], s[30:31] op_sel_hi:[1,1,0]
	v_ldexp_f32 v95, v111, 1
	v_pk_mul_f32 v[110:111], v[110:111], v[114:115]
	v_pk_mul_f32 v[114:115], v[80:81], s[12:13] op_sel_hi:[1,0]
	v_mov_b32_e32 v113, v103
	v_pk_fma_f32 v[118:119], v[80:81], s[12:13], v[114:115] op_sel_hi:[1,0,1] neg_lo:[0,0,1] neg_hi:[0,0,1]
	v_mov_b32_e32 v90, v114
	v_pk_fma_f32 v[80:81], v[80:81], s[14:15], v[118:119] op_sel_hi:[1,0,1]
	v_mov_b32_e32 v125, v115
	v_mov_b32_e32 v88, v80
	v_pk_add_f32 v[90:91], v[90:91], v[88:89]
	v_pk_add_f32 v[88:89], v[82:83], v[84:85]
	v_mov_b32_e32 v85, v93
	v_mov_b32_e32 v83, v89
	v_pk_add_f32 v[118:119], v[114:115], v[80:81]
	v_pk_add_f32 v[82:83], v[82:83], v[84:85]
	v_pk_add_f32 v[84:85], v[92:93], v[88:89]
	v_mov_b32_e32 v129, v119
	v_pk_add_f32 v[120:121], v[118:119], v[84:85]
	v_mov_b32_e32 v126, v84
	v_mov_b32_e32 v127, v121
	v_pk_add_f32 v[126:127], v[126:127], v[128:129] neg_lo:[0,1] neg_hi:[0,1]
	v_mov_b32_e32 v122, v120
	v_mov_b32_e32 v123, v119
	v_mov_b32_e32 v124, v118
	v_mov_b32_e32 v128, v118
	v_mov_b32_e32 v129, v121
	v_mov_b32_e32 v115, v127
	v_pk_add_f32 v[122:123], v[122:123], v[124:125] neg_lo:[0,1] neg_hi:[0,1]
	v_mov_b32_e32 v124, v84
	v_mov_b32_e32 v125, v81
	v_pk_add_f32 v[114:115], v[128:129], v[114:115] neg_lo:[0,1] neg_hi:[0,1]
	v_pk_add_f32 v[124:125], v[124:125], v[122:123] neg_lo:[0,1] neg_hi:[0,1]
	v_mov_b32_e32 v128, v114
	v_mov_b32_e32 v129, v123
	v_mov_b32_e32 v130, v120
	v_mov_b32_e32 v131, v85
	v_mov_b32_e32 v123, v93
	v_pk_add_f32 v[128:129], v[80:81], v[128:129] neg_lo:[0,1] neg_hi:[0,1]
	v_pk_add_f32 v[122:123], v[130:131], v[122:123] neg_lo:[0,1] neg_hi:[0,1]
	v_mov_b32_e32 v81, v119
	v_pk_add_f32 v[84:85], v[84:85], v[92:93] neg_lo:[0,1] neg_hi:[0,1]
	v_pk_add_f32 v[90:91], v[90:91], v[122:123] neg_lo:[0,1] neg_hi:[0,1]
	v_pk_add_f32 v[80:81], v[80:81], v[114:115] neg_lo:[0,1] neg_hi:[0,1]
	v_pk_add_f32 v[82:83], v[82:83], v[126:127] neg_lo:[0,1] neg_hi:[0,1]
	v_pk_add_f32 v[84:85], v[88:89], v[84:85] neg_lo:[0,1] neg_hi:[0,1]
	v_pk_add_f32 v[88:89], v[82:83], v[80:81]
	v_mov_b32_e32 v81, v125
	v_mov_b32_e32 v83, v91
	v_pk_add_f32 v[92:93], v[124:125], v[90:91]
	v_pk_add_f32 v[82:83], v[80:81], v[82:83]
	v_mov_b32_e32 v90, v88
	v_pk_add_f32 v[82:83], v[82:83], v[128:129] neg_lo:[0,1] neg_hi:[0,1]
	v_mov_b32_e32 v91, v93
	v_pk_add_f32 v[90:91], v[90:91], v[82:83] neg_lo:[0,1] neg_hi:[0,1]
	v_pk_add_f32 v[82:83], v[84:85], v[82:83] neg_lo:[0,1] neg_hi:[0,1]
	v_pk_add_f32 v[80:81], v[80:81], v[90:91] neg_lo:[0,1] neg_hi:[0,1]
	v_lshl_add_u64 v[68:69], v[68:69], 0, v[0:1]
	v_pk_add_f32 v[80:81], v[82:83], v[80:81]
	v_pk_add_f32 v[82:83], v[92:93], v[88:89]
	s_nop 0
	v_pk_add_f32 v[84:85], v[120:121], v[82:83]
	s_nop 0
	v_pk_add_f32 v[88:89], v[84:85], v[120:121] neg_lo:[0,1] neg_hi:[0,1]
	s_nop 0
	v_pk_add_f32 v[82:83], v[82:83], v[88:89] neg_lo:[0,1] neg_hi:[0,1]
	s_nop 0
	v_pk_add_f32 v[80:81], v[80:81], v[82:83]
	s_nop 0
	v_pk_add_f32 v[80:81], v[84:85], v[80:81]
	v_pk_mul_f32 v[84:85], v[110:111], v[116:117]
	v_cndmask_b32_e32 v80, v160, v80, vcc
	v_cmp_neq_f32_e32 vcc, s8, v98
	v_pk_add_f32 v[88:89], v[94:95], v[84:85]
	s_nop 0
	v_cndmask_b32_e32 v81, v160, v81, vcc
	v_cmp_ngt_f32_e32 vcc, -1.0, v98
	v_pk_add_f32 v[92:93], v[88:89], v[94:95] neg_lo:[0,1] neg_hi:[0,1]
	v_mov_b32_e32 v116, v88
	v_cndmask_b32_e32 v81, v161, v81, vcc
	v_cmp_ngt_f32_e32 vcc, -1.0, v97
	v_pk_add_f32 v[84:85], v[84:85], v[92:93] neg_lo:[0,1] neg_hi:[0,1]
	s_nop 0
	v_cndmask_b32_e32 v80, v161, v80, vcc
	v_cmp_neq_f32_e32 vcc, -1.0, v97
	v_pk_add_f32 v[94:95], v[112:113], v[84:85]
	v_mov_b32_e32 v93, v85
	v_cndmask_b32_e32 v80, v162, v80, vcc
	v_cmp_neq_f32_e32 vcc, -1.0, v98
	v_mov_b32_e32 v113, v95
	v_mov_b32_e32 v85, v89
	v_cndmask_b32_e32 v81, v162, v81, vcc
	v_cmp_lt_f32_e64 vcc, |v97|, s9
	v_cndmask_b32_e64 v81, v81, v98, s[0:1]
	v_pk_add_f32 v[98:99], v[88:89], v[94:95]
	v_cndmask_b32_e32 v80, v80, v97, vcc
	v_pk_add_f32 v[78:79], v[78:79], v[80:81]
	v_cvt_f32_i32_e32 v81, v132
	v_cvt_f32_i32_e32 v80, v102
	v_mov_b32_e32 v114, v98
	v_pk_add_f32 v[84:85], v[112:113], v[84:85]
	v_mov_b32_e32 v119, v99
	v_pk_mul_f32 v[82:83], v[80:81], s[12:13] op_sel_hi:[1,0]
	v_cmp_neq_f32_e32 vcc, s8, v100
	v_pk_fma_f32 v[90:91], v[80:81], s[12:13], v[82:83] op_sel_hi:[1,0,1] neg_lo:[0,0,1] neg_hi:[0,0,1]
	v_mov_b32_e32 v92, v82
	v_pk_fma_f32 v[80:81], v[80:81], s[14:15], v[90:91] op_sel_hi:[1,0,1]
	v_mov_b32_e32 v113, v83
	v_pk_add_f32 v[90:91], v[82:83], v[80:81]
	v_mov_b32_e32 v102, v80
	v_pk_add_f32 v[92:93], v[92:93], v[102:103]
	v_pk_add_f32 v[102:103], v[90:91], v[98:99]
	v_mov_b32_e32 v117, v91
	v_mov_b32_e32 v115, v103
	v_pk_add_f32 v[114:115], v[114:115], v[116:117] neg_lo:[0,1] neg_hi:[0,1]
	v_mov_b32_e32 v110, v102
	v_mov_b32_e32 v111, v91
	v_mov_b32_e32 v112, v90
	v_mov_b32_e32 v116, v90
	v_mov_b32_e32 v117, v103
	v_mov_b32_e32 v83, v115
	v_pk_add_f32 v[110:111], v[110:111], v[112:113] neg_lo:[0,1] neg_hi:[0,1]
; __device__ __forceinline__ float softplusf(float x) { return fmaxf(x, 0.f) + log1pf(__expf(-fabsf(x))); }
; __device__ void phaseA_tile(const Params& p, int l, int mt, int nt, char* smem) {
;     ...
;                 for (int j = 0; j < 2; ++j) {
;                     const int c = j * 16 + g4 * 4;
;                     const float4 db = *(const float4*)(p.dt_bias + l * 32 + c);
;                     const f32x4 v = acc[i][j];
;                     *(float4*)(p.dtb + (size_t)row * 32 + c) =
;                         make_float4(softplusf(v[0] + db.x), softplusf(v[1] + db.y), softplusf(v[2] + db.z), softplusf(v[3] + db.w));
	v_mov_b32_e32 v112, v98
	v_mov_b32_e32 v113, v81
	v_pk_add_f32 v[82:83], v[116:117], v[82:83] neg_lo:[0,1] neg_hi:[0,1]
	v_pk_add_f32 v[112:113], v[112:113], v[110:111] neg_lo:[0,1] neg_hi:[0,1]
	v_mov_b32_e32 v116, v82
	v_mov_b32_e32 v117, v111
	v_mov_b32_e32 v118, v102
	v_mov_b32_e32 v111, v89
	v_pk_add_f32 v[116:117], v[80:81], v[116:117] neg_lo:[0,1] neg_hi:[0,1]
	v_pk_add_f32 v[110:111], v[118:119], v[110:111] neg_lo:[0,1] neg_hi:[0,1]
	v_mov_b32_e32 v81, v91
	v_pk_add_f32 v[92:93], v[92:93], v[110:111] neg_lo:[0,1] neg_hi:[0,1]
	v_pk_add_f32 v[80:81], v[80:81], v[82:83] neg_lo:[0,1] neg_hi:[0,1]
	v_pk_add_f32 v[82:83], v[84:85], v[114:115] neg_lo:[0,1] neg_hi:[0,1]
	v_pk_add_f32 v[90:91], v[112:113], v[92:93]
	v_pk_add_f32 v[84:85], v[82:83], v[80:81]
	v_mov_b32_e32 v81, v113
	v_mov_b32_e32 v83, v93
	v_pk_add_f32 v[82:83], v[80:81], v[82:83]
	v_pk_add_f32 v[88:89], v[98:99], v[88:89] neg_lo:[0,1] neg_hi:[0,1]
	v_pk_add_f32 v[82:83], v[82:83], v[116:117] neg_lo:[0,1] neg_hi:[0,1]
	v_mov_b32_e32 v92, v84
	v_mov_b32_e32 v93, v91
	v_pk_add_f32 v[88:89], v[94:95], v[88:89] neg_lo:[0,1] neg_hi:[0,1]
	v_pk_add_f32 v[92:93], v[92:93], v[82:83] neg_lo:[0,1] neg_hi:[0,1]
	v_pk_add_f32 v[82:83], v[88:89], v[82:83] neg_lo:[0,1] neg_hi:[0,1]
	v_pk_add_f32 v[80:81], v[80:81], v[92:93] neg_lo:[0,1] neg_hi:[0,1]
	v_cmp_lt_f32_e64 s[0:1], |v101|, s9
	v_pk_add_f32 v[80:81], v[82:83], v[80:81]
	v_pk_add_f32 v[82:83], v[90:91], v[84:85]
	s_nop 0
	v_pk_add_f32 v[84:85], v[102:103], v[82:83]
	s_nop 0
	v_pk_add_f32 v[88:89], v[84:85], v[102:103] neg_lo:[0,1] neg_hi:[0,1]
	s_nop 0
	v_pk_add_f32 v[82:83], v[82:83], v[88:89] neg_lo:[0,1] neg_hi:[0,1]
	s_nop 0
	v_pk_add_f32 v[80:81], v[80:81], v[82:83]
	s_nop 0
	v_pk_add_f32 v[80:81], v[84:85], v[80:81]
	s_nop 0
	v_cndmask_b32_e32 v80, v160, v80, vcc
	v_cmp_neq_f32_e32 vcc, s8, v101
	s_nop 1
	v_cndmask_b32_e32 v81, v160, v81, vcc
	v_cmp_ngt_f32_e32 vcc, -1.0, v101
	s_nop 1
	v_cndmask_b32_e32 v81, v161, v81, vcc
	v_cmp_ngt_f32_e32 vcc, -1.0, v100
	s_nop 1
	v_cndmask_b32_e32 v80, v161, v80, vcc
	v_cmp_neq_f32_e32 vcc, -1.0, v100
	s_nop 1
	v_cndmask_b32_e32 v80, v162, v80, vcc
	v_cmp_neq_f32_e32 vcc, -1.0, v101
	s_nop 1
	v_cndmask_b32_e32 v81, v162, v81, vcc
	v_cmp_lt_f32_e64 vcc, |v100|, s9
	v_cndmask_b32_e64 v81, v81, v101, s[0:1]
	s_nop 0
	v_cndmask_b32_e32 v80, v80, v100, vcc
	v_pk_add_f32 v[80:81], v[86:87], v[80:81]
	global_store_dwordx4 v[68:69], v[78:81], off
	global_load_dwordx4 v[78:81], v0, s[74:75] offset:64
	s_waitcnt vmcnt(0)
	v_add_f32_e32 v82, v58, v78
	v_max_f32_e32 v78, 0, v82
	v_mul_f32_e64 v82, |v82|, s2
	v_exp_f32_e32 v97, v82
	s_nop 0
	v_add_f32_e32 v84, 1.0, v97
	v_add_f32_e32 v82, -1.0, v84
	v_sub_f32_e32 v83, v82, v84
	v_add_f32_e32 v83, 1.0, v83
	v_sub_f32_e32 v82, v97, v82
	v_add_f32_e32 v85, v82, v83
	v_frexp_mant_f32_e32 v82, v84
	v_cmp_gt_f32_e32 vcc, s26, v82
	v_cvt_f64_f32_e32 v[82:83], v84
	v_frexp_exp_i32_f64_e32 v82, v[82:83]
	v_subbrev_co_u32_e32 v120, vcc, 0, v82, vcc
	v_sub_u32_e32 v83, 0, v120
	v_ldexp_f32 v82, v84, v83
	v_ldexp_f32 v84, v85, v83
	v_add_f32_e32 v83, v59, v79
	v_max_f32_e32 v79, 0, v83
	v_mul_f32_e64 v83, |v83|, s2
	v_exp_f32_e32 v128, v83
	s_nop 0
	v_add_f32_e32 v83, 1.0, v128
	v_add_f32_e32 v85, -1.0, v83
	v_sub_f32_e32 v86, v85, v83
	v_add_f32_e32 v86, 1.0, v86
	v_sub_f32_e32 v85, v128, v85
	v_add_f32_e32 v85, v85, v86
	v_frexp_mant_f32_e32 v86, v83
	v_cmp_gt_f32_e32 vcc, s26, v86
	v_cvt_f64_f32_e32 v[86:87], v83
	v_frexp_exp_i32_f64_e32 v86, v[86:87]
	v_subbrev_co_u32_e32 v121, vcc, 0, v86, vcc
	v_sub_u32_e32 v86, 0, v121
	v_ldexp_f32 v83, v83, v86
	v_ldexp_f32 v85, v85, v86
	v_pk_add_f32 v[86:87], v[82:83], 1.0 op_sel_hi:[1,0]
	v_pk_add_f32 v[94:95], v[82:83], -1.0 op_sel_hi:[1,0]
	v_pk_add_f32 v[88:89], v[86:87], -1.0 op_sel_hi:[1,0]
	v_pk_add_f32 v[98:99], v[94:95], 1.0 op_sel_hi:[1,0]
	v_pk_add_f32 v[88:89], v[82:83], v[88:89] neg_lo:[0,1] neg_hi:[0,1]
	v_pk_add_f32 v[82:83], v[82:83], v[98:99] neg_lo:[0,1] neg_hi:[0,1]
	v_pk_add_f32 v[88:89], v[84:85], v[88:89]
	v_pk_add_f32 v[82:83], v[84:85], v[82:83]
	v_pk_add_f32 v[90:91], v[86:87], v[88:89]
	v_pk_add_f32 v[84:85], v[94:95], v[82:83]
	v_rcp_f32_e32 v92, v90
	v_rcp_f32_e32 v93, v91
	v_pk_add_f32 v[86:87], v[90:91], v[86:87] neg_lo:[0,1] neg_hi:[0,1]
	v_pk_add_f32 v[94:95], v[84:85], v[94:95] neg_lo:[0,1] neg_hi:[0,1]
	v_pk_add_f32 v[86:87], v[88:89], v[86:87] neg_lo:[0,1] neg_hi:[0,1]
	v_pk_mul_f32 v[88:89], v[84:85], v[92:93]
	v_pk_add_f32 v[82:83], v[82:83], v[94:95] neg_lo:[0,1] neg_hi:[0,1]
	v_pk_mul_f32 v[94:95], v[90:91], v[88:89]
	v_cmp_lt_f32_e64 s[0:1], |v128|, s9
	v_pk_fma_f32 v[98:99], v[88:89], v[90:91], v[94:95] neg_lo:[0,0,1] neg_hi:[0,0,1]
	s_nop 0
	v_pk_fma_f32 v[98:99], v[88:89], v[86:87], v[98:99]
	s_nop 0
	v_pk_add_f32 v[100:101], v[94:95], v[98:99]
	s_nop 0
	v_pk_add_f32 v[102:103], v[84:85], v[100:101] neg_lo:[0,1] neg_hi:[0,1]
	v_pk_add_f32 v[94:95], v[100:101], v[94:95] neg_lo:[0,1] neg_hi:[0,1]
	v_pk_add_f32 v[84:85], v[84:85], v[102:103] neg_lo:[0,1] neg_hi:[0,1]
	s_nop 0
	v_pk_add_f32 v[84:85], v[84:85], v[100:101] neg_lo:[0,1] neg_hi:[0,1]
	s_nop 0
	v_pk_add_f32 v[82:83], v[82:83], v[84:85]
	v_pk_add_f32 v[84:85], v[94:95], v[98:99] neg_lo:[0,1] neg_hi:[0,1]
	s_nop 0
	v_pk_add_f32 v[82:83], v[84:85], v[82:83]
	s_nop 0
	v_pk_add_f32 v[84:85], v[102:103], v[82:83]
	s_nop 0
	v_pk_mul_f32 v[94:95], v[92:93], v[84:85]
	s_nop 0
	v_pk_mul_f32 v[98:99], v[90:91], v[94:95]
	s_nop 0
	v_pk_fma_f32 v[90:91], v[94:95], v[90:91], v[98:99] neg_lo:[0,0,1] neg_hi:[0,0,1]
	s_nop 0
	v_pk_fma_f32 v[86:87], v[94:95], v[86:87], v[90:91]
	v_pk_add_f32 v[90:91], v[102:103], v[84:85] neg_lo:[0,1] neg_hi:[0,1]
; __device__ __forceinline__ float softplusf(float x) { return fmaxf(x, 0.f) + log1pf(__expf(-fabsf(x))); }
; __device__ void phaseA_tile(const Params& p, int l, int mt, int nt, char* smem) {
;     ...
;                 for (int j = 0; j < 2; ++j) {
;                     const int c = j * 16 + g4 * 4;
;                     const float4 db = *(const float4*)(p.dt_bias + l * 32 + c);
;                     const f32x4 v = acc[i][j];
;                     *(float4*)(p.dtb + (size_t)row * 32 + c) =
;                         make_float4(softplusf(v[0] + db.x), softplusf(v[1] + db.y), softplusf(v[2] + db.z), softplusf(v[3] + db.w));
	s_nop 0
	v_pk_add_f32 v[82:83], v[82:83], v[90:91]
	v_pk_add_f32 v[90:91], v[98:99], v[86:87]
	s_nop 0
	v_pk_add_f32 v[100:101], v[84:85], v[90:91] neg_lo:[0,1] neg_hi:[0,1]
	v_pk_add_f32 v[98:99], v[90:91], v[98:99] neg_lo:[0,1] neg_hi:[0,1]
	v_pk_add_f32 v[84:85], v[84:85], v[100:101] neg_lo:[0,1] neg_hi:[0,1]
	s_nop 0
	v_pk_add_f32 v[84:85], v[84:85], v[90:91] neg_lo:[0,1] neg_hi:[0,1]
	s_nop 0
	v_pk_add_f32 v[82:83], v[82:83], v[84:85]
	v_pk_add_f32 v[84:85], v[98:99], v[86:87] neg_lo:[0,1] neg_hi:[0,1]
	s_nop 0
	v_pk_add_f32 v[82:83], v[84:85], v[82:83]
	v_pk_add_f32 v[84:85], v[88:89], v[94:95]
	v_pk_add_f32 v[82:83], v[100:101], v[82:83]
	v_pk_add_f32 v[86:87], v[84:85], v[88:89] neg_lo:[0,1] neg_hi:[0,1]
	v_pk_mul_f32 v[82:83], v[92:93], v[82:83]
	v_pk_add_f32 v[86:87], v[94:95], v[86:87] neg_lo:[0,1] neg_hi:[0,1]
	s_nop 0
	v_pk_add_f32 v[82:83], v[86:87], v[82:83]
	s_nop 0
	v_pk_add_f32 v[86:87], v[84:85], v[82:83]
	s_nop 0
	v_pk_add_f32 v[84:85], v[86:87], v[84:85] neg_lo:[0,1] neg_hi:[0,1]
	v_pk_mul_f32 v[88:89], v[86:87], v[86:87]
	v_pk_add_f32 v[82:83], v[82:83], v[84:85] neg_lo:[0,1] neg_hi:[0,1]
	v_pk_fma_f32 v[90:91], v[88:89], s[28:29], v[66:67] op_sel_hi:[1,0,0]
	v_ldexp_f32 v93, v83, 1
	v_add_f32_e32 v83, v60, v80
	v_max_f32_e32 v80, 0, v83
	v_mul_f32_e64 v83, |v83|, s2
	v_exp_f32_e32 v129, v83
	v_ldexp_f32 v84, v86, 1
	v_pk_fma_f32 v[90:91], v[88:89], v[90:91], s[30:31] op_sel_hi:[1,1,0]
	v_ldexp_f32 v85, v87, 1
	v_add_f32_e32 v83, 1.0, v129
	v_pk_mul_f32 v[86:87], v[86:87], v[88:89]
	v_add_f32_e32 v88, -1.0, v83
	v_sub_f32_e32 v89, v88, v83
	v_add_f32_e32 v89, 1.0, v89
	v_sub_f32_e32 v88, v129, v88
	v_add_f32_e32 v92, v88, v89
	v_frexp_mant_f32_e32 v88, v83
	v_cmp_gt_f32_e32 vcc, s26, v88
	v_cvt_f64_f32_e32 v[88:89], v83
	v_frexp_exp_i32_f64_e32 v88, v[88:89]
	v_subbrev_co_u32_e32 v130, vcc, 0, v88, vcc
	v_sub_u32_e32 v89, 0, v130
	v_ldexp_f32 v88, v83, v89
	v_add_f32_e32 v83, v61, v81
	v_max_f32_e32 v81, 0, v83
	v_mul_f32_e64 v83, |v83|, s2
	v_exp_f32_e32 v131, v83
	v_ldexp_f32 v94, v92, v89
	v_pk_mul_f32 v[86:87], v[86:87], v[90:91]
	v_ldexp_f32 v82, v82, 1
	v_add_f32_e32 v83, 1.0, v131
	v_add_f32_e32 v89, -1.0, v83
	v_sub_f32_e32 v92, v89, v83
	v_add_f32_e32 v92, 1.0, v92
	v_sub_f32_e32 v89, v131, v89
	v_add_f32_e32 v92, v89, v92
	v_frexp_mant_f32_e32 v89, v83
	v_cvt_f64_f32_e32 v[98:99], v83
	v_cmp_gt_f32_e32 vcc, s26, v89
	v_frexp_exp_i32_f64_e32 v89, v[98:99]
	v_pk_add_f32 v[90:91], v[84:85], v[86:87]
	v_subbrev_co_u32_e32 v132, vcc, 0, v89, vcc
	v_sub_u32_e32 v95, 0, v132
	v_ldexp_f32 v89, v83, v95
	v_pk_add_f32 v[98:99], v[88:89], 1.0 op_sel_hi:[1,0]
	v_ldexp_f32 v95, v92, v95
	v_pk_add_f32 v[100:101], v[98:99], -1.0 op_sel_hi:[1,0]
	v_pk_add_f32 v[112:113], v[88:89], -1.0 op_sel_hi:[1,0]
	v_pk_add_f32 v[100:101], v[88:89], v[100:101] neg_lo:[0,1] neg_hi:[0,1]
	v_pk_add_f32 v[114:115], v[112:113], 1.0 op_sel_hi:[1,0]
	v_pk_add_f32 v[100:101], v[94:95], v[100:101]
	v_pk_add_f32 v[88:89], v[88:89], v[114:115] neg_lo:[0,1] neg_hi:[0,1]
	v_pk_add_f32 v[102:103], v[98:99], v[100:101]
	v_pk_add_f32 v[88:89], v[94:95], v[88:89]
	v_rcp_f32_e32 v110, v102
	v_rcp_f32_e32 v111, v103
	v_pk_add_f32 v[94:95], v[112:113], v[88:89]
	v_pk_add_f32 v[98:99], v[102:103], v[98:99] neg_lo:[0,1] neg_hi:[0,1]
	v_pk_add_f32 v[112:113], v[94:95], v[112:113] neg_lo:[0,1] neg_hi:[0,1]
	v_pk_add_f32 v[98:99], v[100:101], v[98:99] neg_lo:[0,1] neg_hi:[0,1]
	v_pk_mul_f32 v[100:101], v[94:95], v[110:111]
	v_pk_add_f32 v[88:89], v[88:89], v[112:113] neg_lo:[0,1] neg_hi:[0,1]
	v_pk_mul_f32 v[112:113], v[102:103], v[100:101]
	v_pk_add_f32 v[84:85], v[90:91], v[84:85] neg_lo:[0,1] neg_hi:[0,1]
	v_pk_fma_f32 v[114:115], v[100:101], v[102:103], v[112:113] neg_lo:[0,0,1] neg_hi:[0,0,1]
	v_pk_add_f32 v[84:85], v[86:87], v[84:85] neg_lo:[0,1] neg_hi:[0,1]
	v_pk_fma_f32 v[114:115], v[100:101], v[98:99], v[114:115]
	v_mov_b32_e32 v87, v85
	v_pk_add_f32 v[116:117], v[112:113], v[114:115]
	v_mov_b32_e32 v83, v93
	v_pk_add_f32 v[118:119], v[94:95], v[116:117] neg_lo:[0,1] neg_hi:[0,1]
	v_pk_add_f32 v[112:113], v[116:117], v[112:113] neg_lo:[0,1] neg_hi:[0,1]
	v_pk_add_f32 v[94:95], v[94:95], v[118:119] neg_lo:[0,1] neg_hi:[0,1]
	v_mov_b32_e32 v124, v90
	v_pk_add_f32 v[94:95], v[94:95], v[116:117] neg_lo:[0,1] neg_hi:[0,1]
	v_cmp_neq_f32_e32 vcc, s8, v97
	v_pk_add_f32 v[88:89], v[88:89], v[94:95]
	v_pk_add_f32 v[94:95], v[112:113], v[114:115] neg_lo:[0,1] neg_hi:[0,1]
	s_nop 0
	v_pk_add_f32 v[88:89], v[94:95], v[88:89]
	s_nop 0
	v_pk_add_f32 v[94:95], v[118:119], v[88:89]
	s_nop 0
	v_pk_mul_f32 v[112:113], v[110:111], v[94:95]
	s_nop 0
	v_pk_mul_f32 v[114:115], v[102:103], v[112:113]
	s_nop 0
	v_pk_fma_f32 v[102:103], v[112:113], v[102:103], v[114:115] neg_lo:[0,0,1] neg_hi:[0,0,1]
	s_nop 0
	v_pk_fma_f32 v[98:99], v[112:113], v[98:99], v[102:103]
	v_pk_add_f32 v[102:103], v[118:119], v[94:95] neg_lo:[0,1] neg_hi:[0,1]
	s_nop 0
	v_pk_add_f32 v[88:89], v[88:89], v[102:103]
	v_pk_add_f32 v[102:103], v[114:115], v[98:99]
	s_nop 0
	v_pk_add_f32 v[116:117], v[94:95], v[102:103] neg_lo:[0,1] neg_hi:[0,1]
	v_pk_add_f32 v[114:115], v[102:103], v[114:115] neg_lo:[0,1] neg_hi:[0,1]
	v_pk_add_f32 v[94:95], v[94:95], v[116:117] neg_lo:[0,1] neg_hi:[0,1]
	s_nop 0
	v_pk_add_f32 v[94:95], v[94:95], v[102:103] neg_lo:[0,1] neg_hi:[0,1]
	s_nop 0
	v_pk_add_f32 v[88:89], v[88:89], v[94:95]
	v_pk_add_f32 v[94:95], v[114:115], v[98:99] neg_lo:[0,1] neg_hi:[0,1]
	s_nop 0
	v_pk_add_f32 v[88:89], v[94:95], v[88:89]
	v_pk_add_f32 v[94:95], v[100:101], v[112:113]
	v_pk_add_f32 v[88:89], v[116:117], v[88:89]
	v_pk_add_f32 v[98:99], v[94:95], v[100:101] neg_lo:[0,1] neg_hi:[0,1]
; __device__ __forceinline__ float softplusf(float x) { return fmaxf(x, 0.f) + log1pf(__expf(-fabsf(x))); }
; __device__ void phaseA_tile(const Params& p, int l, int mt, int nt, char* smem) {
;     ...
;                 for (int j = 0; j < 2; ++j) {
;                     const int c = j * 16 + g4 * 4;
;                     const float4 db = *(const float4*)(p.dt_bias + l * 32 + c);
;                     const f32x4 v = acc[i][j];
;                     *(float4*)(p.dtb + (size_t)row * 32 + c) =
;                         make_float4(softplusf(v[0] + db.x), softplusf(v[1] + db.y), softplusf(v[2] + db.z), softplusf(v[3] + db.w));
	v_pk_mul_f32 v[88:89], v[110:111], v[88:89]
	v_pk_add_f32 v[98:99], v[112:113], v[98:99] neg_lo:[0,1] neg_hi:[0,1]
	s_nop 0
	v_pk_add_f32 v[88:89], v[98:99], v[88:89]
	s_nop 0
	v_pk_add_f32 v[98:99], v[94:95], v[88:89]
	s_nop 0
	v_pk_mul_f32 v[100:101], v[98:99], v[98:99]
	v_pk_add_f32 v[94:95], v[98:99], v[94:95] neg_lo:[0,1] neg_hi:[0,1]
	v_pk_fma_f32 v[102:103], v[100:101], s[28:29], v[66:67] op_sel_hi:[1,0,0]
	v_pk_add_f32 v[88:89], v[88:89], v[94:95] neg_lo:[0,1] neg_hi:[0,1]
	v_ldexp_f32 v94, v98, 1
	v_pk_fma_f32 v[102:103], v[100:101], v[102:103], s[30:31] op_sel_hi:[1,1,0]
	v_ldexp_f32 v95, v99, 1
	v_pk_mul_f32 v[98:99], v[98:99], v[100:101]
	v_cvt_f32_i32_e32 v101, v121
	v_cvt_f32_i32_e32 v100, v120
	v_ldexp_f32 v111, v89, 1
	v_ldexp_f32 v88, v88, 1
	v_mov_b32_e32 v89, v111
	v_pk_mul_f32 v[112:113], v[100:101], s[12:13] op_sel_hi:[1,0]
	s_nop 0
	v_pk_fma_f32 v[114:115], v[100:101], s[12:13], v[112:113] op_sel_hi:[1,0,1] neg_lo:[0,0,1] neg_hi:[0,0,1]
	v_mov_b32_e32 v86, v112
	v_pk_fma_f32 v[100:101], v[100:101], s[14:15], v[114:115] op_sel_hi:[1,0,1]
	v_mov_b32_e32 v121, v113
	v_mov_b32_e32 v92, v100
	v_pk_add_f32 v[86:87], v[86:87], v[92:93]
	v_pk_add_f32 v[92:93], v[82:83], v[84:85]
	v_mov_b32_e32 v85, v91
	v_mov_b32_e32 v83, v93
	v_pk_add_f32 v[114:115], v[112:113], v[100:101]
	v_pk_add_f32 v[82:83], v[82:83], v[84:85]
	v_pk_add_f32 v[84:85], v[90:91], v[92:93]
	v_mov_b32_e32 v125, v115
	v_pk_add_f32 v[116:117], v[114:115], v[84:85]
	v_mov_b32_e32 v122, v84
	v_mov_b32_e32 v123, v117
	v_pk_add_f32 v[122:123], v[122:123], v[124:125] neg_lo:[0,1] neg_hi:[0,1]
	v_mov_b32_e32 v118, v116
	v_mov_b32_e32 v119, v115
	v_mov_b32_e32 v120, v114
	v_mov_b32_e32 v124, v114
	v_mov_b32_e32 v125, v117
	v_mov_b32_e32 v113, v123
	v_pk_add_f32 v[118:119], v[118:119], v[120:121] neg_lo:[0,1] neg_hi:[0,1]
	v_mov_b32_e32 v120, v84
	v_mov_b32_e32 v121, v101
	v_pk_add_f32 v[112:113], v[124:125], v[112:113] neg_lo:[0,1] neg_hi:[0,1]
	v_pk_add_f32 v[120:121], v[120:121], v[118:119] neg_lo:[0,1] neg_hi:[0,1]
	v_mov_b32_e32 v124, v112
	v_mov_b32_e32 v125, v119
	v_mov_b32_e32 v126, v116
	v_mov_b32_e32 v127, v85
	v_mov_b32_e32 v119, v91
	v_pk_add_f32 v[124:125], v[100:101], v[124:125] neg_lo:[0,1] neg_hi:[0,1]
	v_pk_add_f32 v[118:119], v[126:127], v[118:119] neg_lo:[0,1] neg_hi:[0,1]
	v_mov_b32_e32 v101, v115
	v_pk_add_f32 v[84:85], v[84:85], v[90:91] neg_lo:[0,1] neg_hi:[0,1]
	v_pk_add_f32 v[86:87], v[86:87], v[118:119] neg_lo:[0,1] neg_hi:[0,1]
	v_pk_add_f32 v[90:91], v[100:101], v[112:113] neg_lo:[0,1] neg_hi:[0,1]
	v_pk_add_f32 v[82:83], v[82:83], v[122:123] neg_lo:[0,1] neg_hi:[0,1]
	v_pk_add_f32 v[84:85], v[92:93], v[84:85] neg_lo:[0,1] neg_hi:[0,1]
	v_pk_add_f32 v[92:93], v[82:83], v[90:91]
	v_mov_b32_e32 v91, v121
	v_mov_b32_e32 v83, v87
	v_pk_add_f32 v[100:101], v[120:121], v[86:87]
	v_pk_add_f32 v[82:83], v[90:91], v[82:83]
	v_mov_b32_e32 v86, v92
	v_pk_add_f32 v[82:83], v[82:83], v[124:125] neg_lo:[0,1] neg_hi:[0,1]
	v_mov_b32_e32 v87, v101
	v_pk_add_f32 v[86:87], v[86:87], v[82:83] neg_lo:[0,1] neg_hi:[0,1]
	v_pk_add_f32 v[82:83], v[84:85], v[82:83] neg_lo:[0,1] neg_hi:[0,1]
	v_pk_add_f32 v[86:87], v[90:91], v[86:87] neg_lo:[0,1] neg_hi:[0,1]
	v_pk_add_f32 v[84:85], v[100:101], v[92:93]
	v_pk_add_f32 v[82:83], v[82:83], v[86:87]
	v_pk_add_f32 v[86:87], v[116:117], v[84:85]
	s_nop 0
	v_pk_add_f32 v[90:91], v[86:87], v[116:117] neg_lo:[0,1] neg_hi:[0,1]
	s_nop 0
	v_pk_add_f32 v[84:85], v[84:85], v[90:91] neg_lo:[0,1] neg_hi:[0,1]
	s_nop 0
	v_pk_add_f32 v[82:83], v[82:83], v[84:85]
	s_nop 0
	v_pk_add_f32 v[82:83], v[86:87], v[82:83]
	v_pk_mul_f32 v[86:87], v[98:99], v[102:103]
	v_cndmask_b32_e32 v82, v160, v82, vcc
	v_cmp_neq_f32_e32 vcc, s8, v128
	v_pk_add_f32 v[90:91], v[94:95], v[86:87]
	s_nop 0
	v_cndmask_b32_e32 v83, v160, v83, vcc
	v_cmp_ngt_f32_e32 vcc, -1.0, v128
	v_pk_add_f32 v[94:95], v[90:91], v[94:95] neg_lo:[0,1] neg_hi:[0,1]
	v_mov_b32_e32 v114, v90
	v_cndmask_b32_e32 v83, v161, v83, vcc
	v_cmp_ngt_f32_e32 vcc, -1.0, v97
	v_pk_add_f32 v[86:87], v[86:87], v[94:95] neg_lo:[0,1] neg_hi:[0,1]
	s_nop 0
	v_cndmask_b32_e32 v82, v161, v82, vcc
	v_cmp_neq_f32_e32 vcc, -1.0, v97
	v_pk_add_f32 v[98:99], v[88:89], v[86:87]
	v_mov_b32_e32 v95, v87
	v_cndmask_b32_e32 v82, v162, v82, vcc
	v_cmp_neq_f32_e32 vcc, -1.0, v128
	v_mov_b32_e32 v89, v99
	v_mov_b32_e32 v87, v91
	v_cndmask_b32_e32 v83, v162, v83, vcc
	v_cmp_lt_f32_e64 vcc, |v97|, s9
	v_cndmask_b32_e64 v83, v83, v128, s[0:1]
	v_pk_add_f32 v[86:87], v[88:89], v[86:87]
	v_cndmask_b32_e32 v82, v82, v97, vcc
	v_pk_add_f32 v[78:79], v[78:79], v[82:83]
	v_cvt_f32_i32_e32 v83, v132
	v_cvt_f32_i32_e32 v82, v130
	v_pk_add_f32 v[88:89], v[90:91], v[98:99]
	v_cmp_neq_f32_e32 vcc, s8, v129
	v_mov_b32_e32 v112, v88
	v_pk_mul_f32 v[84:85], v[82:83], s[12:13] op_sel_hi:[1,0]
	v_mov_b32_e32 v117, v89
	v_pk_fma_f32 v[92:93], v[82:83], s[12:13], v[84:85] op_sel_hi:[1,0,1] neg_lo:[0,0,1] neg_hi:[0,0,1]
	v_mov_b32_e32 v94, v84
	v_pk_fma_f32 v[82:83], v[82:83], s[14:15], v[92:93] op_sel_hi:[1,0,1]
	v_cmp_lt_f32_e64 s[0:1], |v131|, s9
	v_pk_add_f32 v[92:93], v[84:85], v[82:83]
	v_mov_b32_e32 v110, v82
	v_pk_add_f32 v[100:101], v[92:93], v[88:89]
	v_mov_b32_e32 v115, v93
	v_mov_b32_e32 v113, v101
	v_pk_add_f32 v[112:113], v[112:113], v[114:115] neg_lo:[0,1] neg_hi:[0,1]
	v_pk_add_f32 v[94:95], v[94:95], v[110:111]
	v_mov_b32_e32 v102, v100
	v_mov_b32_e32 v103, v93
	v_mov_b32_e32 v110, v92
	v_mov_b32_e32 v111, v85
	v_mov_b32_e32 v114, v92
	v_mov_b32_e32 v115, v101
	v_mov_b32_e32 v85, v113
	v_pk_add_f32 v[102:103], v[102:103], v[110:111] neg_lo:[0,1] neg_hi:[0,1]
	v_mov_b32_e32 v110, v88
	v_mov_b32_e32 v111, v83
; __device__ __forceinline__ float softplusf(float x) { return fmaxf(x, 0.f) + log1pf(__expf(-fabsf(x))); }
; __device__ __forceinline__ float logsigf(float x) { return fminf(x, 0.f) - log1pf(__expf(-fabsf(x))); }
; __device__ void phaseA_tile(const Params& p, int l, int mt, int nt, char* smem) {
;     ...
;                 for (int j = 0; j < 2; ++j) {
;                     const int c = j * 16 + g4 * 4;
;                     const float4 db = *(const float4*)(p.dt_bias + l * 32 + c);
;                     const f32x4 v = acc[i][j];
;                     *(float4*)(p.dtb + (size_t)row * 32 + c) =
;                         make_float4(softplusf(v[0] + db.x), softplusf(v[1] + db.y), softplusf(v[2] + db.z), softplusf(v[3] + db.w));
;                 }
;                 {
;                     const int c = g4 * 4;
;                     const float4 fb = *(const float4*)(p.b_f + l * 16 + c);
;                     const f32x4 v = acc[i][2];
;                     float4 lf = make_float4(logsigf(v[0] + fb.x), logsigf(v[1] + fb.y), logsigf(v[2] + fb.z), logsigf(v[3] + fb.w));
	v_pk_add_f32 v[84:85], v[114:115], v[84:85] neg_lo:[0,1] neg_hi:[0,1]
	v_pk_add_f32 v[110:111], v[110:111], v[102:103] neg_lo:[0,1] neg_hi:[0,1]
	v_mov_b32_e32 v114, v84
	v_mov_b32_e32 v115, v103
	v_mov_b32_e32 v116, v100
	v_mov_b32_e32 v103, v91
	v_pk_add_f32 v[114:115], v[82:83], v[114:115] neg_lo:[0,1] neg_hi:[0,1]
	v_pk_add_f32 v[102:103], v[116:117], v[102:103] neg_lo:[0,1] neg_hi:[0,1]
	v_mov_b32_e32 v83, v93
	v_pk_add_f32 v[88:89], v[88:89], v[90:91] neg_lo:[0,1] neg_hi:[0,1]
	v_pk_add_f32 v[90:91], v[94:95], v[102:103] neg_lo:[0,1] neg_hi:[0,1]
	v_pk_add_f32 v[82:83], v[82:83], v[84:85] neg_lo:[0,1] neg_hi:[0,1]
	v_pk_add_f32 v[84:85], v[86:87], v[112:113] neg_lo:[0,1] neg_hi:[0,1]
	v_pk_add_f32 v[92:93], v[110:111], v[90:91]
	v_pk_add_f32 v[86:87], v[84:85], v[82:83]
	v_mov_b32_e32 v83, v111
	v_mov_b32_e32 v85, v91
	v_pk_add_f32 v[84:85], v[82:83], v[84:85]
	v_mov_b32_e32 v90, v86
	v_pk_add_f32 v[84:85], v[84:85], v[114:115] neg_lo:[0,1] neg_hi:[0,1]
	v_mov_b32_e32 v91, v93
	v_pk_add_f32 v[88:89], v[98:99], v[88:89] neg_lo:[0,1] neg_hi:[0,1]
	v_pk_add_f32 v[90:91], v[90:91], v[84:85] neg_lo:[0,1] neg_hi:[0,1]
	v_pk_add_f32 v[84:85], v[88:89], v[84:85] neg_lo:[0,1] neg_hi:[0,1]
	v_pk_add_f32 v[82:83], v[82:83], v[90:91] neg_lo:[0,1] neg_hi:[0,1]
	s_nop 0
	v_pk_add_f32 v[82:83], v[84:85], v[82:83]
	v_pk_add_f32 v[84:85], v[92:93], v[86:87]
	s_nop 0
	v_pk_add_f32 v[86:87], v[100:101], v[84:85]
	s_nop 0
	v_pk_add_f32 v[88:89], v[86:87], v[100:101] neg_lo:[0,1] neg_hi:[0,1]
	s_nop 0
	v_pk_add_f32 v[84:85], v[84:85], v[88:89] neg_lo:[0,1] neg_hi:[0,1]
	s_nop 0
	v_pk_add_f32 v[82:83], v[82:83], v[84:85]
	s_nop 0
	v_pk_add_f32 v[82:83], v[86:87], v[82:83]
	s_nop 0
	v_cndmask_b32_e32 v82, v160, v82, vcc
	v_cmp_neq_f32_e32 vcc, s8, v131
	s_nop 1
	v_cndmask_b32_e32 v83, v160, v83, vcc
	v_cmp_ngt_f32_e32 vcc, -1.0, v131
	s_nop 1
	v_cndmask_b32_e32 v83, v161, v83, vcc
	v_cmp_ngt_f32_e32 vcc, -1.0, v129
	s_nop 1
	v_cndmask_b32_e32 v82, v161, v82, vcc
	v_cmp_neq_f32_e32 vcc, -1.0, v129
	s_nop 1
	v_cndmask_b32_e32 v82, v162, v82, vcc
	v_cmp_neq_f32_e32 vcc, -1.0, v131
	s_nop 1
	v_cndmask_b32_e32 v83, v162, v83, vcc
	v_cmp_lt_f32_e64 vcc, |v129|, s9
	v_cndmask_b32_e64 v83, v83, v131, s[0:1]
	s_and_b64 s[0:1], s[60:61], exec
	v_cndmask_b32_e32 v82, v82, v129, vcc
	v_pk_add_f32 v[80:81], v[80:81], v[82:83]
	global_store_dwordx4 v[68:69], v[78:81], off offset:64
	global_load_dwordx4 v[78:81], v0, s[78:79]
	s_cselect_b32 s7, s46, s42
	s_cselect_b32 s6, s43, s59
	s_waitcnt vmcnt(0)
	v_add_f32_e32 v69, v54, v78
	v_min_f32_e32 v68, 0, v69
	v_mul_f32_e64 v69, |v69|, s2
	v_exp_f32_e32 v97, v69
	v_add_f32_e32 v79, v55, v79
	v_add_f32_e32 v81, v57, v81
	v_add_f32_e32 v69, 1.0, v97
	v_add_f32_e32 v78, -1.0, v69
	v_sub_f32_e32 v82, v78, v69
	v_add_f32_e32 v82, 1.0, v82
	v_sub_f32_e32 v78, v97, v78
	v_add_f32_e32 v84, v78, v82
	v_frexp_mant_f32_e32 v78, v69
	v_cvt_f64_f32_e32 v[82:83], v69
	v_cmp_gt_f32_e32 vcc, s26, v78
	v_frexp_exp_i32_f64_e32 v78, v[82:83]
	s_nop 0
	v_subbrev_co_u32_e32 v118, vcc, 0, v78, vcc
	v_sub_u32_e32 v82, 0, v118
	v_ldexp_f32 v78, v69, v82
	v_min_f32_e32 v69, 0, v79
	v_mul_f32_e64 v79, |v79|, s2
	v_exp_f32_e32 v126, v79
	v_ldexp_f32 v82, v84, v82
	v_add_f32_e32 v79, 1.0, v126
	v_add_f32_e32 v83, -1.0, v79
	v_sub_f32_e32 v84, v83, v79
	v_add_f32_e32 v84, 1.0, v84
	v_sub_f32_e32 v83, v126, v83
	v_add_f32_e32 v83, v83, v84
	v_frexp_mant_f32_e32 v84, v79
	v_cmp_gt_f32_e32 vcc, s26, v84
	v_cvt_f64_f32_e32 v[84:85], v79
	v_frexp_exp_i32_f64_e32 v84, v[84:85]
	v_subbrev_co_u32_e32 v119, vcc, 0, v84, vcc
	v_sub_u32_e32 v84, 0, v119
	v_ldexp_f32 v79, v79, v84
	v_ldexp_f32 v83, v83, v84
	v_pk_add_f32 v[84:85], v[78:79], 1.0 op_sel_hi:[1,0]
	v_pk_add_f32 v[92:93], v[78:79], -1.0 op_sel_hi:[1,0]
	v_pk_add_f32 v[86:87], v[84:85], -1.0 op_sel_hi:[1,0]
	v_pk_add_f32 v[94:95], v[92:93], 1.0 op_sel_hi:[1,0]
	v_pk_add_f32 v[86:87], v[78:79], v[86:87] neg_lo:[0,1] neg_hi:[0,1]
	v_pk_add_f32 v[78:79], v[78:79], v[94:95] neg_lo:[0,1] neg_hi:[0,1]
	v_pk_add_f32 v[86:87], v[82:83], v[86:87]
	v_pk_add_f32 v[78:79], v[82:83], v[78:79]
	v_pk_add_f32 v[88:89], v[84:85], v[86:87]
	v_pk_add_f32 v[82:83], v[92:93], v[78:79]
	v_rcp_f32_e32 v90, v88
	v_rcp_f32_e32 v91, v89
	v_pk_add_f32 v[84:85], v[88:89], v[84:85] neg_lo:[0,1] neg_hi:[0,1]
	v_pk_add_f32 v[92:93], v[82:83], v[92:93] neg_lo:[0,1] neg_hi:[0,1]
	v_pk_add_f32 v[84:85], v[86:87], v[84:85] neg_lo:[0,1] neg_hi:[0,1]
	v_pk_mul_f32 v[86:87], v[82:83], v[90:91]
	v_pk_add_f32 v[78:79], v[78:79], v[92:93] neg_lo:[0,1] neg_hi:[0,1]
	v_pk_mul_f32 v[92:93], v[88:89], v[86:87]
	v_cmp_lt_f32_e64 s[0:1], |v126|, s9
	v_pk_fma_f32 v[94:95], v[86:87], v[88:89], v[92:93] neg_lo:[0,0,1] neg_hi:[0,0,1]
	s_nop 0
	v_pk_fma_f32 v[94:95], v[86:87], v[84:85], v[94:95]
	s_nop 0
	v_pk_add_f32 v[98:99], v[92:93], v[94:95]
	s_nop 0
	v_pk_add_f32 v[100:101], v[82:83], v[98:99] neg_lo:[0,1] neg_hi:[0,1]
	v_pk_add_f32 v[92:93], v[98:99], v[92:93] neg_lo:[0,1] neg_hi:[0,1]
	v_pk_add_f32 v[82:83], v[82:83], v[100:101] neg_lo:[0,1] neg_hi:[0,1]
	s_nop 0
	v_pk_add_f32 v[82:83], v[82:83], v[98:99] neg_lo:[0,1] neg_hi:[0,1]
	s_nop 0
	v_pk_add_f32 v[78:79], v[78:79], v[82:83]
	v_pk_add_f32 v[82:83], v[92:93], v[94:95] neg_lo:[0,1] neg_hi:[0,1]
	s_nop 0
	v_pk_add_f32 v[78:79], v[82:83], v[78:79]
	s_nop 0
	v_pk_add_f32 v[82:83], v[100:101], v[78:79]
	s_nop 0
	v_pk_mul_f32 v[92:93], v[90:91], v[82:83]
	s_nop 0
	v_pk_mul_f32 v[94:95], v[88:89], v[92:93]
	s_nop 0
	v_pk_fma_f32 v[88:89], v[92:93], v[88:89], v[94:95] neg_lo:[0,0,1] neg_hi:[0,0,1]
	s_nop 0
	v_pk_fma_f32 v[84:85], v[92:93], v[84:85], v[88:89]
; __device__ __forceinline__ float logsigf(float x) { return fminf(x, 0.f) - log1pf(__expf(-fabsf(x))); }
; __device__ void phaseA_tile(const Params& p, int l, int mt, int nt, char* smem) {
;     ...
;                 {
;                     const int c = g4 * 4;
;                     const float4 fb = *(const float4*)(p.b_f + l * 16 + c);
;                     const f32x4 v = acc[i][2];
;                     float4 lf = make_float4(logsigf(v[0] + fb.x), logsigf(v[1] + fb.y), logsigf(v[2] + fb.z), logsigf(v[3] + fb.w));
	v_pk_add_f32 v[88:89], v[100:101], v[82:83] neg_lo:[0,1] neg_hi:[0,1]
	s_nop 0
	v_pk_add_f32 v[78:79], v[78:79], v[88:89]
	v_pk_add_f32 v[88:89], v[94:95], v[84:85]
	s_nop 0
	v_pk_add_f32 v[98:99], v[82:83], v[88:89] neg_lo:[0,1] neg_hi:[0,1]
	v_pk_add_f32 v[94:95], v[88:89], v[94:95] neg_lo:[0,1] neg_hi:[0,1]
	v_pk_add_f32 v[82:83], v[82:83], v[98:99] neg_lo:[0,1] neg_hi:[0,1]
	s_nop 0
	v_pk_add_f32 v[82:83], v[82:83], v[88:89] neg_lo:[0,1] neg_hi:[0,1]
	s_nop 0
	v_pk_add_f32 v[78:79], v[78:79], v[82:83]
	v_pk_add_f32 v[82:83], v[94:95], v[84:85] neg_lo:[0,1] neg_hi:[0,1]
	s_nop 0
	v_pk_add_f32 v[78:79], v[82:83], v[78:79]
	v_pk_add_f32 v[82:83], v[86:87], v[92:93]
	v_pk_add_f32 v[78:79], v[98:99], v[78:79]
	v_pk_add_f32 v[84:85], v[82:83], v[86:87] neg_lo:[0,1] neg_hi:[0,1]
	v_pk_mul_f32 v[78:79], v[90:91], v[78:79]
	v_pk_add_f32 v[84:85], v[92:93], v[84:85] neg_lo:[0,1] neg_hi:[0,1]
	s_nop 0
	v_pk_add_f32 v[78:79], v[84:85], v[78:79]
	s_nop 0
	v_pk_add_f32 v[84:85], v[82:83], v[78:79]
	s_nop 0
	v_pk_add_f32 v[82:83], v[84:85], v[82:83] neg_lo:[0,1] neg_hi:[0,1]
	v_pk_mul_f32 v[88:89], v[84:85], v[84:85]
	v_pk_add_f32 v[78:79], v[78:79], v[82:83] neg_lo:[0,1] neg_hi:[0,1]
	v_pk_fma_f32 v[90:91], v[88:89], s[28:29], v[66:67] op_sel_hi:[1,0,0]
	v_ldexp_f32 v93, v79, 1
	v_add_f32_e32 v79, v56, v80
	v_ldexp_f32 v86, v78, 1
	v_min_f32_e32 v78, 0, v79
	v_mul_f32_e64 v79, |v79|, s2
	v_exp_f32_e32 v127, v79
	v_ldexp_f32 v82, v84, 1
	v_pk_fma_f32 v[90:91], v[88:89], v[90:91], s[30:31] op_sel_hi:[1,1,0]
	v_ldexp_f32 v83, v85, 1
	v_add_f32_e32 v79, 1.0, v127
	v_add_f32_e32 v80, -1.0, v79
	v_sub_f32_e32 v87, v80, v79
	v_add_f32_e32 v87, 1.0, v87
	v_sub_f32_e32 v80, v127, v80
	v_pk_mul_f32 v[84:85], v[84:85], v[88:89]
	v_add_f32_e32 v87, v80, v87
	v_frexp_mant_f32_e32 v80, v79
	v_cvt_f64_f32_e32 v[88:89], v79
	v_cmp_gt_f32_e32 vcc, s26, v80
	v_frexp_exp_i32_f64_e32 v80, v[88:89]
	v_pk_mul_f32 v[84:85], v[84:85], v[90:91]
	v_subbrev_co_u32_e32 v128, vcc, 0, v80, vcc
	v_sub_u32_e32 v88, 0, v128
	v_ldexp_f32 v80, v79, v88
	v_min_f32_e32 v79, 0, v81
	v_mul_f32_e64 v81, |v81|, s2
	v_exp_f32_e32 v129, v81
	v_ldexp_f32 v88, v87, v88
	v_pk_add_f32 v[90:91], v[82:83], v[84:85]
	v_add_f32_e32 v81, 1.0, v129
	v_add_f32_e32 v87, -1.0, v81
	v_sub_f32_e32 v89, v87, v81
	v_add_f32_e32 v89, 1.0, v89
	v_sub_f32_e32 v87, v129, v87
	v_add_f32_e32 v87, v87, v89
	v_frexp_mant_f32_e32 v89, v81
	v_cvt_f64_f32_e32 v[94:95], v81
	v_cmp_gt_f32_e32 vcc, s26, v89
	v_frexp_exp_i32_f64_e32 v89, v[94:95]
	v_pk_add_f32 v[82:83], v[90:91], v[82:83] neg_lo:[0,1] neg_hi:[0,1]
	v_subbrev_co_u32_e32 v130, vcc, 0, v89, vcc
	v_sub_u32_e32 v89, 0, v130
	v_ldexp_f32 v81, v81, v89
	v_pk_add_f32 v[94:95], v[80:81], 1.0 op_sel_hi:[1,0]
	v_ldexp_f32 v89, v87, v89
	v_pk_add_f32 v[98:99], v[94:95], -1.0 op_sel_hi:[1,0]
	v_pk_add_f32 v[110:111], v[80:81], -1.0 op_sel_hi:[1,0]
	v_pk_add_f32 v[98:99], v[80:81], v[98:99] neg_lo:[0,1] neg_hi:[0,1]
	v_pk_add_f32 v[112:113], v[110:111], 1.0 op_sel_hi:[1,0]
	v_pk_add_f32 v[98:99], v[88:89], v[98:99]
	v_pk_add_f32 v[80:81], v[80:81], v[112:113] neg_lo:[0,1] neg_hi:[0,1]
	v_pk_add_f32 v[100:101], v[94:95], v[98:99]
	v_pk_add_f32 v[80:81], v[88:89], v[80:81]
	v_rcp_f32_e32 v102, v100
	v_rcp_f32_e32 v103, v101
	v_pk_add_f32 v[88:89], v[110:111], v[80:81]
	v_pk_add_f32 v[94:95], v[100:101], v[94:95] neg_lo:[0,1] neg_hi:[0,1]
	v_pk_add_f32 v[110:111], v[88:89], v[110:111] neg_lo:[0,1] neg_hi:[0,1]
	v_pk_add_f32 v[94:95], v[98:99], v[94:95] neg_lo:[0,1] neg_hi:[0,1]
	v_pk_mul_f32 v[98:99], v[88:89], v[102:103]
	v_pk_add_f32 v[80:81], v[80:81], v[110:111] neg_lo:[0,1] neg_hi:[0,1]
	v_pk_mul_f32 v[110:111], v[100:101], v[98:99]
	v_pk_add_f32 v[82:83], v[84:85], v[82:83] neg_lo:[0,1] neg_hi:[0,1]
	v_pk_fma_f32 v[112:113], v[98:99], v[100:101], v[110:111] neg_lo:[0,0,1] neg_hi:[0,0,1]
	v_mov_b32_e32 v85, v83
	v_pk_fma_f32 v[112:113], v[98:99], v[94:95], v[112:113]
	v_mov_b32_e32 v87, v93
	v_pk_add_f32 v[114:115], v[110:111], v[112:113]
	v_mov_b32_e32 v122, v90
	v_pk_add_f32 v[116:117], v[88:89], v[114:115] neg_lo:[0,1] neg_hi:[0,1]
	v_pk_add_f32 v[110:111], v[114:115], v[110:111] neg_lo:[0,1] neg_hi:[0,1]
	v_pk_add_f32 v[88:89], v[88:89], v[116:117] neg_lo:[0,1] neg_hi:[0,1]
	v_cmp_neq_f32_e32 vcc, s8, v97
	v_pk_add_f32 v[88:89], v[88:89], v[114:115] neg_lo:[0,1] neg_hi:[0,1]
	s_nop 0
	v_pk_add_f32 v[80:81], v[80:81], v[88:89]
	v_pk_add_f32 v[88:89], v[110:111], v[112:113] neg_lo:[0,1] neg_hi:[0,1]
	s_nop 0
	v_pk_add_f32 v[80:81], v[88:89], v[80:81]
	s_nop 0
	v_pk_add_f32 v[88:89], v[116:117], v[80:81]
	s_nop 0
	v_pk_mul_f32 v[110:111], v[102:103], v[88:89]
	s_nop 0
	v_pk_mul_f32 v[112:113], v[100:101], v[110:111]
	s_nop 0
	v_pk_fma_f32 v[100:101], v[110:111], v[100:101], v[112:113] neg_lo:[0,0,1] neg_hi:[0,0,1]
	s_nop 0
	v_pk_fma_f32 v[94:95], v[110:111], v[94:95], v[100:101]
	v_pk_add_f32 v[100:101], v[116:117], v[88:89] neg_lo:[0,1] neg_hi:[0,1]
	s_nop 0
	v_pk_add_f32 v[80:81], v[80:81], v[100:101]
	v_pk_add_f32 v[100:101], v[112:113], v[94:95]
	s_nop 0
	v_pk_add_f32 v[114:115], v[88:89], v[100:101] neg_lo:[0,1] neg_hi:[0,1]
	v_pk_add_f32 v[112:113], v[100:101], v[112:113] neg_lo:[0,1] neg_hi:[0,1]
	v_pk_add_f32 v[88:89], v[88:89], v[114:115] neg_lo:[0,1] neg_hi:[0,1]
	s_nop 0
	v_pk_add_f32 v[88:89], v[88:89], v[100:101] neg_lo:[0,1] neg_hi:[0,1]
	s_nop 0
	v_pk_add_f32 v[80:81], v[80:81], v[88:89]
	v_pk_add_f32 v[88:89], v[112:113], v[94:95] neg_lo:[0,1] neg_hi:[0,1]
	s_nop 0
	v_pk_add_f32 v[80:81], v[88:89], v[80:81]
	v_pk_add_f32 v[88:89], v[98:99], v[110:111]
	v_pk_add_f32 v[80:81], v[114:115], v[80:81]
	v_pk_add_f32 v[94:95], v[88:89], v[98:99] neg_lo:[0,1] neg_hi:[0,1]
; __device__ __forceinline__ float logsigf(float x) { return fminf(x, 0.f) - log1pf(__expf(-fabsf(x))); }
; __device__ void phaseA_tile(const Params& p, int l, int mt, int nt, char* smem) {
;     ...
;                 {
;                     const int c = g4 * 4;
;                     const float4 fb = *(const float4*)(p.b_f + l * 16 + c);
;                     const f32x4 v = acc[i][2];
;                     float4 lf = make_float4(logsigf(v[0] + fb.x), logsigf(v[1] + fb.y), logsigf(v[2] + fb.z), logsigf(v[3] + fb.w));
;                     float* o = samp ? (p.out + O_LFS + ((size_t)l * TSM + (row - TP)) * 16 + c)
;                                     : (p.out + O_LFP + ((size_t)l * TP + row) * 16 + c);
	v_pk_mul_f32 v[80:81], v[102:103], v[80:81]
	v_pk_add_f32 v[94:95], v[110:111], v[94:95] neg_lo:[0,1] neg_hi:[0,1]
	s_nop 0
	v_pk_add_f32 v[80:81], v[94:95], v[80:81]
	s_nop 0
	v_pk_add_f32 v[94:95], v[88:89], v[80:81]
	s_nop 0
	v_pk_add_f32 v[88:89], v[94:95], v[88:89] neg_lo:[0,1] neg_hi:[0,1]
	v_pk_mul_f32 v[100:101], v[94:95], v[94:95]
	v_pk_add_f32 v[80:81], v[80:81], v[88:89] neg_lo:[0,1] neg_hi:[0,1]
	v_pk_fma_f32 v[102:103], v[100:101], s[28:29], v[66:67] op_sel_hi:[1,0,0]
	v_ldexp_f32 v98, v80, 1
	v_add_u32_e32 v80, 0xffff8000, v76
	v_ldexp_f32 v111, v81, 1
	v_ashrrev_i32_e32 v81, 31, v80
	v_cndmask_b32_e64 v77, v77, v81, s[60:61]
	v_cndmask_b32_e64 v76, v76, v80, s[60:61]
	v_cvt_f32_i32_e32 v81, v119
	v_cvt_f32_i32_e32 v80, v118
	v_ldexp_f32 v88, v94, 1
	v_pk_fma_f32 v[102:103], v[100:101], v[102:103], s[30:31] op_sel_hi:[1,1,0]
	v_ldexp_f32 v89, v95, 1
	v_pk_mul_f32 v[94:95], v[94:95], v[100:101]
	v_pk_mul_f32 v[100:101], v[80:81], s[12:13] op_sel_hi:[1,0]
	v_mov_b32_e32 v99, v111
	v_pk_fma_f32 v[112:113], v[80:81], s[12:13], v[100:101] op_sel_hi:[1,0,1] neg_lo:[0,0,1] neg_hi:[0,0,1]
	v_mov_b32_e32 v84, v100
	v_pk_fma_f32 v[80:81], v[80:81], s[14:15], v[112:113] op_sel_hi:[1,0,1]
	v_mov_b32_e32 v119, v101
	v_mov_b32_e32 v92, v80
	v_pk_add_f32 v[84:85], v[84:85], v[92:93]
	v_pk_add_f32 v[92:93], v[86:87], v[82:83]
	v_mov_b32_e32 v83, v91
	v_mov_b32_e32 v87, v93
	v_pk_add_f32 v[112:113], v[100:101], v[80:81]
	v_pk_add_f32 v[82:83], v[86:87], v[82:83]
	v_pk_add_f32 v[86:87], v[90:91], v[92:93]
	v_mov_b32_e32 v123, v113
	v_pk_add_f32 v[114:115], v[112:113], v[86:87]
	v_mov_b32_e32 v120, v86
	v_mov_b32_e32 v121, v115
	v_pk_add_f32 v[120:121], v[120:121], v[122:123] neg_lo:[0,1] neg_hi:[0,1]
	v_mov_b32_e32 v116, v114
	v_mov_b32_e32 v117, v113
	v_mov_b32_e32 v118, v112
	v_mov_b32_e32 v122, v112
	v_mov_b32_e32 v123, v115
	v_mov_b32_e32 v101, v121
	v_pk_add_f32 v[116:117], v[116:117], v[118:119] neg_lo:[0,1] neg_hi:[0,1]
	v_mov_b32_e32 v118, v86
	v_mov_b32_e32 v119, v81
	v_pk_add_f32 v[100:101], v[122:123], v[100:101] neg_lo:[0,1] neg_hi:[0,1]
	v_pk_add_f32 v[118:119], v[118:119], v[116:117] neg_lo:[0,1] neg_hi:[0,1]
	v_mov_b32_e32 v122, v100
	v_mov_b32_e32 v123, v117
	v_mov_b32_e32 v124, v114
	v_mov_b32_e32 v125, v87
	v_mov_b32_e32 v117, v91
	v_pk_add_f32 v[122:123], v[80:81], v[122:123] neg_lo:[0,1] neg_hi:[0,1]
	v_pk_add_f32 v[116:117], v[124:125], v[116:117] neg_lo:[0,1] neg_hi:[0,1]
	v_mov_b32_e32 v81, v113
	v_pk_add_f32 v[84:85], v[84:85], v[116:117] neg_lo:[0,1] neg_hi:[0,1]
	v_pk_add_f32 v[80:81], v[80:81], v[100:101] neg_lo:[0,1] neg_hi:[0,1]
	v_pk_add_f32 v[82:83], v[82:83], v[120:121] neg_lo:[0,1] neg_hi:[0,1]
	v_pk_add_f32 v[86:87], v[86:87], v[90:91] neg_lo:[0,1] neg_hi:[0,1]
	v_pk_add_f32 v[90:91], v[82:83], v[80:81]
	v_mov_b32_e32 v81, v119
	v_mov_b32_e32 v83, v85
	v_pk_add_f32 v[86:87], v[92:93], v[86:87] neg_lo:[0,1] neg_hi:[0,1]
	v_pk_add_f32 v[92:93], v[118:119], v[84:85]
	v_pk_add_f32 v[82:83], v[80:81], v[82:83]
	v_mov_b32_e32 v84, v90
	v_pk_add_f32 v[82:83], v[82:83], v[122:123] neg_lo:[0,1] neg_hi:[0,1]
	v_mov_b32_e32 v85, v93
	v_pk_add_f32 v[84:85], v[84:85], v[82:83] neg_lo:[0,1] neg_hi:[0,1]
	v_pk_add_f32 v[82:83], v[86:87], v[82:83] neg_lo:[0,1] neg_hi:[0,1]
	v_pk_add_f32 v[80:81], v[80:81], v[84:85] neg_lo:[0,1] neg_hi:[0,1]
	v_lshlrev_b64 v[76:77], 6, v[76:77]
	v_pk_add_f32 v[80:81], v[82:83], v[80:81]
	v_pk_add_f32 v[82:83], v[92:93], v[90:91]
	v_lshl_add_u64 v[76:77], s[6:7], 0, v[76:77]
	v_pk_add_f32 v[84:85], v[114:115], v[82:83]
	v_lshl_add_u64 v[76:77], v[76:77], 0, v[0:1]
	v_pk_add_f32 v[86:87], v[84:85], v[114:115] neg_lo:[0,1] neg_hi:[0,1]
	s_nop 0
	v_pk_add_f32 v[82:83], v[82:83], v[86:87] neg_lo:[0,1] neg_hi:[0,1]
	s_nop 0
	v_pk_add_f32 v[80:81], v[80:81], v[82:83]
	s_nop 0
	v_pk_add_f32 v[80:81], v[84:85], v[80:81]
	v_pk_mul_f32 v[84:85], v[94:95], v[102:103]
	v_cndmask_b32_e32 v80, v160, v80, vcc
	v_cmp_neq_f32_e32 vcc, s8, v126
	v_pk_add_f32 v[86:87], v[88:89], v[84:85]
	s_nop 0
	v_cndmask_b32_e32 v81, v160, v81, vcc
	v_cmp_ngt_f32_e32 vcc, -1.0, v126
	v_pk_add_f32 v[88:89], v[86:87], v[88:89] neg_lo:[0,1] neg_hi:[0,1]
	v_mov_b32_e32 v112, v86
	v_cndmask_b32_e32 v81, v161, v81, vcc
	v_cmp_ngt_f32_e32 vcc, -1.0, v97
	v_pk_add_f32 v[84:85], v[84:85], v[88:89] neg_lo:[0,1] neg_hi:[0,1]
	s_nop 0
	v_cndmask_b32_e32 v80, v161, v80, vcc
	v_cmp_neq_f32_e32 vcc, -1.0, v97
	v_pk_add_f32 v[92:93], v[98:99], v[84:85]
	v_mov_b32_e32 v89, v85
	v_cndmask_b32_e32 v80, v162, v80, vcc
	v_cmp_neq_f32_e32 vcc, -1.0, v126
	v_mov_b32_e32 v99, v93
	v_mov_b32_e32 v85, v87
	v_cndmask_b32_e32 v81, v162, v81, vcc
	v_cmp_lt_f32_e64 vcc, |v97|, s9
	v_cndmask_b32_e64 v81, v81, v126, s[0:1]
	v_pk_add_f32 v[94:95], v[86:87], v[92:93]
	v_cndmask_b32_e32 v80, v80, v97, vcc
	v_pk_add_f32 v[80:81], v[68:69], v[80:81] neg_lo:[0,1] neg_hi:[0,1]
	v_cvt_f32_i32_e32 v69, v130
	v_cvt_f32_i32_e32 v68, v128
	v_pk_add_f32 v[84:85], v[98:99], v[84:85]
	v_mov_b32_e32 v115, v95
	v_cmp_neq_f32_e32 vcc, s8, v127
	v_pk_mul_f32 v[82:83], v[68:69], s[12:13] op_sel_hi:[1,0]
	v_cmp_lt_f32_e64 s[0:1], |v129|, s9
	v_pk_fma_f32 v[90:91], v[68:69], s[12:13], v[82:83] op_sel_hi:[1,0,1] neg_lo:[0,0,1] neg_hi:[0,0,1]
	v_mov_b32_e32 v88, v82
	v_pk_fma_f32 v[68:69], v[68:69], s[14:15], v[90:91] op_sel_hi:[1,0,1]
	v_mov_b32_e32 v103, v83
	v_pk_add_f32 v[90:91], v[82:83], v[68:69]
	v_mov_b32_e32 v110, v68
	v_pk_add_f32 v[98:99], v[90:91], v[94:95]
	v_pk_add_f32 v[88:89], v[88:89], v[110:111]
	v_mov_b32_e32 v110, v94
	v_mov_b32_e32 v111, v99
	v_mov_b32_e32 v113, v91
	v_pk_add_f32 v[110:111], v[110:111], v[112:113] neg_lo:[0,1] neg_hi:[0,1]
	v_mov_b32_e32 v100, v98
; __device__ __forceinline__ float softplusf(float x) { return fmaxf(x, 0.f) + log1pf(__expf(-fabsf(x))); }
; __device__ __forceinline__ float logsigf(float x) { return fminf(x, 0.f) - log1pf(__expf(-fabsf(x))); }
; __device__ void phaseA_tile(const Params& p, int l, int mt, int nt, char* smem) {
;     ...
;             for (int i = 0; i < 4; ++i) {
;                 const int rl = wr * 64 + i * 16 + r;
;                 const int row = m0 + rl;
; #pragma unroll
;                 for (int j = 0; j < 2; ++j) {
;                     const int c = j * 16 + g4 * 4;
;                     const float4 db = *(const float4*)(p.dt_bias + l * 32 + c);
;                     const f32x4 v = acc[i][j];
;                     *(float4*)(p.dtb + (size_t)row * 32 + c) =
;                         make_float4(softplusf(v[0] + db.x), softplusf(v[1] + db.y), softplusf(v[2] + db.z), softplusf(v[3] + db.w));
;     ...
;                     const f32x4 v = acc[i][2];
;                     float4 lf = make_float4(logsigf(v[0] + fb.x), logsigf(v[1] + fb.y), logsigf(v[2] + fb.z), logsigf(v[3] + fb.w));
;                     float* o = samp ? (p.out + O_LFS + ((size_t)l * TSM + (row - TP)) * 16 + c)
;                                     : (p.out + O_LFP + ((size_t)l * TP + row) * 16 + c);
;                     *(float4*)o = lf;
;                     *(float4*)(lf_s + rl * 16 + c) = lf;
	v_mov_b32_e32 v101, v91
	v_mov_b32_e32 v102, v90
	v_mov_b32_e32 v112, v90
	v_mov_b32_e32 v113, v99
	v_mov_b32_e32 v83, v111
	v_pk_add_f32 v[100:101], v[100:101], v[102:103] neg_lo:[0,1] neg_hi:[0,1]
	v_mov_b32_e32 v102, v94
	v_mov_b32_e32 v103, v69
	v_pk_add_f32 v[82:83], v[112:113], v[82:83] neg_lo:[0,1] neg_hi:[0,1]
	v_pk_add_f32 v[102:103], v[102:103], v[100:101] neg_lo:[0,1] neg_hi:[0,1]
	v_mov_b32_e32 v112, v82
	v_mov_b32_e32 v113, v101
	v_mov_b32_e32 v114, v98
	v_mov_b32_e32 v101, v87
	v_pk_add_f32 v[112:113], v[68:69], v[112:113] neg_lo:[0,1] neg_hi:[0,1]
	v_pk_add_f32 v[100:101], v[114:115], v[100:101] neg_lo:[0,1] neg_hi:[0,1]
	v_mov_b32_e32 v69, v91
	v_pk_add_f32 v[88:89], v[88:89], v[100:101] neg_lo:[0,1] neg_hi:[0,1]
	v_pk_add_f32 v[68:69], v[68:69], v[82:83] neg_lo:[0,1] neg_hi:[0,1]
	v_pk_add_f32 v[82:83], v[84:85], v[110:111] neg_lo:[0,1] neg_hi:[0,1]
	v_pk_add_f32 v[90:91], v[102:103], v[88:89]
	v_pk_add_f32 v[84:85], v[82:83], v[68:69]
	v_mov_b32_e32 v69, v103
	v_mov_b32_e32 v83, v89
	v_pk_add_f32 v[82:83], v[68:69], v[82:83]
	v_pk_add_f32 v[86:87], v[94:95], v[86:87] neg_lo:[0,1] neg_hi:[0,1]
	v_pk_add_f32 v[82:83], v[82:83], v[112:113] neg_lo:[0,1] neg_hi:[0,1]
	v_mov_b32_e32 v88, v84
	v_mov_b32_e32 v89, v91
	v_pk_add_f32 v[86:87], v[92:93], v[86:87] neg_lo:[0,1] neg_hi:[0,1]
	v_pk_add_f32 v[88:89], v[88:89], v[82:83] neg_lo:[0,1] neg_hi:[0,1]
	v_pk_add_f32 v[82:83], v[86:87], v[82:83] neg_lo:[0,1] neg_hi:[0,1]
	v_pk_add_f32 v[68:69], v[68:69], v[88:89] neg_lo:[0,1] neg_hi:[0,1]
	s_nop 0
	v_pk_add_f32 v[68:69], v[82:83], v[68:69]
	v_pk_add_f32 v[82:83], v[90:91], v[84:85]
	s_nop 0
	v_pk_add_f32 v[84:85], v[98:99], v[82:83]
	s_nop 0
	v_pk_add_f32 v[86:87], v[84:85], v[98:99] neg_lo:[0,1] neg_hi:[0,1]
	s_nop 0
	v_pk_add_f32 v[82:83], v[82:83], v[86:87] neg_lo:[0,1] neg_hi:[0,1]
	s_nop 0
	v_pk_add_f32 v[68:69], v[68:69], v[82:83]
	s_nop 0
	v_pk_add_f32 v[68:69], v[84:85], v[68:69]
	s_nop 0
	v_cndmask_b32_e32 v68, v160, v68, vcc
	v_cmp_neq_f32_e32 vcc, s8, v129
	s_nop 1
	v_cndmask_b32_e32 v69, v160, v69, vcc
	v_cmp_ngt_f32_e32 vcc, -1.0, v129
	s_nop 1
	v_cndmask_b32_e32 v69, v161, v69, vcc
	v_cmp_ngt_f32_e32 vcc, -1.0, v127
	s_nop 1
	v_cndmask_b32_e32 v68, v161, v68, vcc
	v_cmp_neq_f32_e32 vcc, -1.0, v127
	s_nop 1
	v_cndmask_b32_e32 v68, v162, v68, vcc
	v_cmp_neq_f32_e32 vcc, -1.0, v129
	s_nop 1
	v_cndmask_b32_e32 v69, v162, v69, vcc
	v_cmp_lt_f32_e64 vcc, |v127|, s9
	v_cndmask_b32_e64 v69, v69, v129, s[0:1]
	s_nop 0
	v_cndmask_b32_e32 v68, v68, v127, vcc
	v_pk_add_f32 v[82:83], v[78:79], v[68:69] neg_lo:[0,1] neg_hi:[0,1]
	global_store_dwordx4 v[76:77], v[80:83], off
	v_lshl_or_b32 v68, v71, 6, v0
	ds_write_b128 v68, v[80:83]
	global_load_dwordx4 v[78:81], v0, s[74:75]
	v_or_b32_e32 v82, 16, v71
	v_add_u32_e32 v68, s54, v82
	v_ashrrev_i32_e32 v69, 31, v68
	v_lshlrev_b64 v[76:77], 7, v[68:69]
	v_lshl_add_u64 v[76:77], s[10:11], 0, v[76:77]
	v_lshl_add_u64 v[76:77], v[76:77], 0, v[0:1]
	s_waitcnt vmcnt(0)
	v_add_f32_e32 v83, v46, v78
	v_max_f32_e32 v78, 0, v83
	v_mul_f32_e64 v83, |v83|, s2
	v_exp_f32_e32 v83, v83
	s_nop 0
	v_add_f32_e32 v86, 1.0, v83
	v_add_f32_e32 v84, -1.0, v86
	v_sub_f32_e32 v85, v84, v86
	v_add_f32_e32 v85, 1.0, v85
	v_sub_f32_e32 v84, v83, v84
	v_add_f32_e32 v87, v84, v85
	v_frexp_mant_f32_e32 v84, v86
	v_cmp_gt_f32_e32 vcc, s26, v84
	v_cvt_f64_f32_e32 v[84:85], v86
	v_frexp_exp_i32_f64_e32 v84, v[84:85]
	v_subbrev_co_u32_e32 v97, vcc, 0, v84, vcc
	v_sub_u32_e32 v85, 0, v97
	v_ldexp_f32 v84, v86, v85
	v_ldexp_f32 v86, v87, v85
	v_add_f32_e32 v85, v47, v79
	v_max_f32_e32 v79, 0, v85
	v_mul_f32_e64 v85, |v85|, s2
	v_exp_f32_e32 v130, v85
	s_nop 0
	v_add_f32_e32 v85, 1.0, v130
	v_add_f32_e32 v87, -1.0, v85
	v_sub_f32_e32 v88, v87, v85
	v_add_f32_e32 v88, 1.0, v88
	v_sub_f32_e32 v87, v130, v87
	v_add_f32_e32 v87, v87, v88
	v_frexp_mant_f32_e32 v88, v85
	v_cmp_gt_f32_e32 vcc, s26, v88
	v_cvt_f64_f32_e32 v[88:89], v85
	v_frexp_exp_i32_f64_e32 v88, v[88:89]
	v_subbrev_co_u32_e32 v122, vcc, 0, v88, vcc
	v_sub_u32_e32 v88, 0, v122
	v_ldexp_f32 v85, v85, v88
	v_ldexp_f32 v87, v87, v88
	v_pk_add_f32 v[88:89], v[84:85], 1.0 op_sel_hi:[1,0]
	v_pk_add_f32 v[98:99], v[84:85], -1.0 op_sel_hi:[1,0]
	v_pk_add_f32 v[90:91], v[88:89], -1.0 op_sel_hi:[1,0]
	v_pk_add_f32 v[100:101], v[98:99], 1.0 op_sel_hi:[1,0]
	v_pk_add_f32 v[90:91], v[84:85], v[90:91] neg_lo:[0,1] neg_hi:[0,1]
	v_pk_add_f32 v[84:85], v[84:85], v[100:101] neg_lo:[0,1] neg_hi:[0,1]
	v_pk_add_f32 v[90:91], v[86:87], v[90:91]
	v_pk_add_f32 v[84:85], v[86:87], v[84:85]
	v_pk_add_f32 v[92:93], v[88:89], v[90:91]
	v_pk_add_f32 v[86:87], v[98:99], v[84:85]
	v_rcp_f32_e32 v94, v92
	v_rcp_f32_e32 v95, v93
	v_pk_add_f32 v[88:89], v[92:93], v[88:89] neg_lo:[0,1] neg_hi:[0,1]
	v_pk_add_f32 v[98:99], v[86:87], v[98:99] neg_lo:[0,1] neg_hi:[0,1]
	v_pk_add_f32 v[88:89], v[90:91], v[88:89] neg_lo:[0,1] neg_hi:[0,1]
	v_pk_mul_f32 v[90:91], v[86:87], v[94:95]
	v_pk_add_f32 v[84:85], v[84:85], v[98:99] neg_lo:[0,1] neg_hi:[0,1]
	v_pk_mul_f32 v[98:99], v[92:93], v[90:91]
	v_cmp_lt_f32_e64 s[0:1], |v130|, s9
	v_pk_fma_f32 v[100:101], v[90:91], v[92:93], v[98:99] neg_lo:[0,0,1] neg_hi:[0,0,1]
	s_nop 0
	v_pk_fma_f32 v[100:101], v[90:91], v[88:89], v[100:101]
	s_nop 0
	v_pk_add_f32 v[102:103], v[98:99], v[100:101]
	s_nop 0
	v_pk_add_f32 v[110:111], v[86:87], v[102:103] neg_lo:[0,1] neg_hi:[0,1]
	v_pk_add_f32 v[98:99], v[102:103], v[98:99] neg_lo:[0,1] neg_hi:[0,1]
	v_pk_add_f32 v[86:87], v[86:87], v[110:111] neg_lo:[0,1] neg_hi:[0,1]
	s_nop 0
	v_pk_add_f32 v[86:87], v[86:87], v[102:103] neg_lo:[0,1] neg_hi:[0,1]
	s_nop 0
	v_pk_add_f32 v[84:85], v[84:85], v[86:87]
; __device__ __forceinline__ float softplusf(float x) { return fmaxf(x, 0.f) + log1pf(__expf(-fabsf(x))); }
; __device__ void phaseA_tile(const Params& p, int l, int mt, int nt, char* smem) {
;     ...
;                 for (int j = 0; j < 2; ++j) {
;                     const int c = j * 16 + g4 * 4;
;                     const float4 db = *(const float4*)(p.dt_bias + l * 32 + c);
;                     const f32x4 v = acc[i][j];
;                     *(float4*)(p.dtb + (size_t)row * 32 + c) =
;                         make_float4(softplusf(v[0] + db.x), softplusf(v[1] + db.y), softplusf(v[2] + db.z), softplusf(v[3] + db.w));
	v_pk_add_f32 v[86:87], v[98:99], v[100:101] neg_lo:[0,1] neg_hi:[0,1]
	s_nop 0
	v_pk_add_f32 v[84:85], v[86:87], v[84:85]
	s_nop 0
	v_pk_add_f32 v[86:87], v[110:111], v[84:85]
	s_nop 0
	v_pk_mul_f32 v[98:99], v[94:95], v[86:87]
	s_nop 0
	v_pk_mul_f32 v[100:101], v[92:93], v[98:99]
	s_nop 0
	v_pk_fma_f32 v[92:93], v[98:99], v[92:93], v[100:101] neg_lo:[0,0,1] neg_hi:[0,0,1]
	s_nop 0
	v_pk_fma_f32 v[88:89], v[98:99], v[88:89], v[92:93]
	v_pk_add_f32 v[92:93], v[110:111], v[86:87] neg_lo:[0,1] neg_hi:[0,1]
	s_nop 0
	v_pk_add_f32 v[84:85], v[84:85], v[92:93]
	v_pk_add_f32 v[92:93], v[100:101], v[88:89]
	s_nop 0
	v_pk_add_f32 v[102:103], v[86:87], v[92:93] neg_lo:[0,1] neg_hi:[0,1]
	v_pk_add_f32 v[100:101], v[92:93], v[100:101] neg_lo:[0,1] neg_hi:[0,1]
	v_pk_add_f32 v[86:87], v[86:87], v[102:103] neg_lo:[0,1] neg_hi:[0,1]
	s_nop 0
	v_pk_add_f32 v[86:87], v[86:87], v[92:93] neg_lo:[0,1] neg_hi:[0,1]
	s_nop 0
	v_pk_add_f32 v[84:85], v[84:85], v[86:87]
	v_pk_add_f32 v[86:87], v[100:101], v[88:89] neg_lo:[0,1] neg_hi:[0,1]
	s_nop 0
	v_pk_add_f32 v[84:85], v[86:87], v[84:85]
	v_pk_add_f32 v[86:87], v[90:91], v[98:99]
	v_pk_add_f32 v[84:85], v[102:103], v[84:85]
	v_pk_add_f32 v[88:89], v[86:87], v[90:91] neg_lo:[0,1] neg_hi:[0,1]
	v_pk_mul_f32 v[84:85], v[94:95], v[84:85]
	v_pk_add_f32 v[88:89], v[98:99], v[88:89] neg_lo:[0,1] neg_hi:[0,1]
	s_nop 0
	v_pk_add_f32 v[84:85], v[88:89], v[84:85]
	s_nop 0
	v_pk_add_f32 v[88:89], v[86:87], v[84:85]
	s_nop 0
	v_pk_add_f32 v[86:87], v[88:89], v[86:87] neg_lo:[0,1] neg_hi:[0,1]
	v_pk_mul_f32 v[90:91], v[88:89], v[88:89]
	v_pk_add_f32 v[84:85], v[84:85], v[86:87] neg_lo:[0,1] neg_hi:[0,1]
	v_pk_fma_f32 v[92:93], v[90:91], s[28:29], v[66:67] op_sel_hi:[1,0,0]
	v_ldexp_f32 v95, v85, 1
	v_add_f32_e32 v85, v48, v80
	v_max_f32_e32 v80, 0, v85
	v_mul_f32_e64 v85, |v85|, s2
	v_exp_f32_e32 v131, v85
	v_ldexp_f32 v86, v88, 1
	v_pk_fma_f32 v[92:93], v[90:91], v[92:93], s[30:31] op_sel_hi:[1,1,0]
	v_ldexp_f32 v87, v89, 1
	v_add_f32_e32 v85, 1.0, v131
	v_pk_mul_f32 v[88:89], v[88:89], v[90:91]
	v_add_f32_e32 v90, -1.0, v85
	v_sub_f32_e32 v91, v90, v85
	v_add_f32_e32 v91, 1.0, v91
	v_sub_f32_e32 v90, v131, v90
	v_add_f32_e32 v94, v90, v91
	v_frexp_mant_f32_e32 v90, v85
	v_cmp_gt_f32_e32 vcc, s26, v90
	v_cvt_f64_f32_e32 v[90:91], v85
	v_frexp_exp_i32_f64_e32 v90, v[90:91]
	v_subbrev_co_u32_e32 v132, vcc, 0, v90, vcc
	v_sub_u32_e32 v91, 0, v132
	v_ldexp_f32 v90, v85, v91
	v_add_f32_e32 v85, v49, v81
	v_max_f32_e32 v81, 0, v85
	v_mul_f32_e64 v85, |v85|, s2
	v_exp_f32_e32 v133, v85
	v_ldexp_f32 v98, v94, v91
	v_pk_mul_f32 v[88:89], v[88:89], v[92:93]
	v_ldexp_f32 v84, v84, 1
	v_add_f32_e32 v85, 1.0, v133
	v_add_f32_e32 v91, -1.0, v85
	v_sub_f32_e32 v94, v91, v85
	v_add_f32_e32 v94, 1.0, v94
	v_sub_f32_e32 v91, v133, v91
	v_add_f32_e32 v94, v91, v94
	v_frexp_mant_f32_e32 v91, v85
	v_cvt_f64_f32_e32 v[100:101], v85
	v_cmp_gt_f32_e32 vcc, s26, v91
	v_frexp_exp_i32_f64_e32 v91, v[100:101]
	v_pk_add_f32 v[92:93], v[86:87], v[88:89]
	v_subbrev_co_u32_e32 v134, vcc, 0, v91, vcc
	v_sub_u32_e32 v99, 0, v134
	v_ldexp_f32 v91, v85, v99
	v_pk_add_f32 v[100:101], v[90:91], 1.0 op_sel_hi:[1,0]
	v_ldexp_f32 v99, v94, v99
	v_pk_add_f32 v[102:103], v[100:101], -1.0 op_sel_hi:[1,0]
	v_pk_add_f32 v[114:115], v[90:91], -1.0 op_sel_hi:[1,0]
	v_pk_add_f32 v[102:103], v[90:91], v[102:103] neg_lo:[0,1] neg_hi:[0,1]
	v_pk_add_f32 v[116:117], v[114:115], 1.0 op_sel_hi:[1,0]
	v_pk_add_f32 v[102:103], v[98:99], v[102:103]
	v_pk_add_f32 v[90:91], v[90:91], v[116:117] neg_lo:[0,1] neg_hi:[0,1]
	v_pk_add_f32 v[110:111], v[100:101], v[102:103]
	v_pk_add_f32 v[90:91], v[98:99], v[90:91]
	v_rcp_f32_e32 v112, v110
	v_rcp_f32_e32 v113, v111
	v_pk_add_f32 v[98:99], v[114:115], v[90:91]
	v_pk_add_f32 v[100:101], v[110:111], v[100:101] neg_lo:[0,1] neg_hi:[0,1]
	v_pk_add_f32 v[114:115], v[98:99], v[114:115] neg_lo:[0,1] neg_hi:[0,1]
	v_pk_add_f32 v[100:101], v[102:103], v[100:101] neg_lo:[0,1] neg_hi:[0,1]
	v_pk_mul_f32 v[102:103], v[98:99], v[112:113]
	v_pk_add_f32 v[90:91], v[90:91], v[114:115] neg_lo:[0,1] neg_hi:[0,1]
	v_pk_mul_f32 v[114:115], v[110:111], v[102:103]
	v_pk_add_f32 v[86:87], v[92:93], v[86:87] neg_lo:[0,1] neg_hi:[0,1]
	v_pk_fma_f32 v[116:117], v[102:103], v[110:111], v[114:115] neg_lo:[0,0,1] neg_hi:[0,0,1]
	v_pk_add_f32 v[86:87], v[88:89], v[86:87] neg_lo:[0,1] neg_hi:[0,1]
	v_pk_fma_f32 v[116:117], v[102:103], v[100:101], v[116:117]
	v_mov_b32_e32 v89, v87
	v_pk_add_f32 v[118:119], v[114:115], v[116:117]
	v_mov_b32_e32 v85, v95
	v_pk_add_f32 v[120:121], v[98:99], v[118:119] neg_lo:[0,1] neg_hi:[0,1]
	v_pk_add_f32 v[114:115], v[118:119], v[114:115] neg_lo:[0,1] neg_hi:[0,1]
	v_pk_add_f32 v[98:99], v[98:99], v[120:121] neg_lo:[0,1] neg_hi:[0,1]
	v_mov_b32_e32 v126, v92
	v_pk_add_f32 v[98:99], v[98:99], v[118:119] neg_lo:[0,1] neg_hi:[0,1]
	v_cmp_neq_f32_e32 vcc, s8, v83
	v_pk_add_f32 v[90:91], v[90:91], v[98:99]
	v_pk_add_f32 v[98:99], v[114:115], v[116:117] neg_lo:[0,1] neg_hi:[0,1]
	s_nop 0
	v_pk_add_f32 v[90:91], v[98:99], v[90:91]
	s_nop 0
	v_pk_add_f32 v[98:99], v[120:121], v[90:91]
	s_nop 0
	v_pk_mul_f32 v[114:115], v[112:113], v[98:99]
	s_nop 0
	v_pk_mul_f32 v[116:117], v[110:111], v[114:115]
	s_nop 0
	v_pk_fma_f32 v[110:111], v[114:115], v[110:111], v[116:117] neg_lo:[0,0,1] neg_hi:[0,0,1]
	s_nop 0
	v_pk_fma_f32 v[100:101], v[114:115], v[100:101], v[110:111]
	v_pk_add_f32 v[110:111], v[120:121], v[98:99] neg_lo:[0,1] neg_hi:[0,1]
	s_nop 0
	v_pk_add_f32 v[90:91], v[90:91], v[110:111]
	v_pk_add_f32 v[110:111], v[116:117], v[100:101]
	s_nop 0
	v_pk_add_f32 v[118:119], v[98:99], v[110:111] neg_lo:[0,1] neg_hi:[0,1]
; __device__ __forceinline__ float softplusf(float x) { return fmaxf(x, 0.f) + log1pf(__expf(-fabsf(x))); }
; __device__ void phaseA_tile(const Params& p, int l, int mt, int nt, char* smem) {
;     ...
;                 for (int j = 0; j < 2; ++j) {
;                     const int c = j * 16 + g4 * 4;
;                     const float4 db = *(const float4*)(p.dt_bias + l * 32 + c);
;                     const f32x4 v = acc[i][j];
;                     *(float4*)(p.dtb + (size_t)row * 32 + c) =
;                         make_float4(softplusf(v[0] + db.x), softplusf(v[1] + db.y), softplusf(v[2] + db.z), softplusf(v[3] + db.w));
	v_pk_add_f32 v[116:117], v[110:111], v[116:117] neg_lo:[0,1] neg_hi:[0,1]
	v_pk_add_f32 v[98:99], v[98:99], v[118:119] neg_lo:[0,1] neg_hi:[0,1]
	s_nop 0
	v_pk_add_f32 v[98:99], v[98:99], v[110:111] neg_lo:[0,1] neg_hi:[0,1]
	s_nop 0
	v_pk_add_f32 v[90:91], v[90:91], v[98:99]
	v_pk_add_f32 v[98:99], v[116:117], v[100:101] neg_lo:[0,1] neg_hi:[0,1]
	s_nop 0
	v_pk_add_f32 v[90:91], v[98:99], v[90:91]
	v_pk_add_f32 v[98:99], v[102:103], v[114:115]
	v_pk_add_f32 v[90:91], v[118:119], v[90:91]
	v_pk_add_f32 v[100:101], v[98:99], v[102:103] neg_lo:[0,1] neg_hi:[0,1]
	v_pk_mul_f32 v[90:91], v[112:113], v[90:91]
	v_pk_add_f32 v[100:101], v[114:115], v[100:101] neg_lo:[0,1] neg_hi:[0,1]
	s_nop 0
	v_pk_add_f32 v[90:91], v[100:101], v[90:91]
	s_nop 0
	v_pk_add_f32 v[100:101], v[98:99], v[90:91]
	s_nop 0
	v_pk_mul_f32 v[102:103], v[100:101], v[100:101]
	v_pk_add_f32 v[98:99], v[100:101], v[98:99] neg_lo:[0,1] neg_hi:[0,1]
	v_pk_fma_f32 v[110:111], v[102:103], s[28:29], v[66:67] op_sel_hi:[1,0,0]
	v_pk_add_f32 v[90:91], v[90:91], v[98:99] neg_lo:[0,1] neg_hi:[0,1]
	v_ldexp_f32 v98, v100, 1
	v_pk_fma_f32 v[110:111], v[102:103], v[110:111], s[30:31] op_sel_hi:[1,1,0]
	v_ldexp_f32 v99, v101, 1
	v_pk_mul_f32 v[100:101], v[100:101], v[102:103]
	v_cvt_f32_i32_e32 v103, v122
	v_cvt_f32_i32_e32 v102, v97
	v_ldexp_f32 v113, v91, 1
	v_ldexp_f32 v90, v90, 1
	v_mov_b32_e32 v91, v113
	v_pk_mul_f32 v[114:115], v[102:103], s[12:13] op_sel_hi:[1,0]
	s_nop 0
	v_pk_fma_f32 v[116:117], v[102:103], s[12:13], v[114:115] op_sel_hi:[1,0,1] neg_lo:[0,0,1] neg_hi:[0,0,1]
	v_mov_b32_e32 v88, v114
	v_pk_fma_f32 v[102:103], v[102:103], s[14:15], v[116:117] op_sel_hi:[1,0,1]
	v_mov_b32_e32 v123, v115
	v_mov_b32_e32 v94, v102
	v_pk_add_f32 v[88:89], v[88:89], v[94:95]
	v_pk_add_f32 v[94:95], v[84:85], v[86:87]
	v_mov_b32_e32 v87, v93
	v_mov_b32_e32 v85, v95
	v_pk_add_f32 v[116:117], v[114:115], v[102:103]
	v_pk_add_f32 v[84:85], v[84:85], v[86:87]
	v_pk_add_f32 v[86:87], v[92:93], v[94:95]
	v_mov_b32_e32 v127, v117
	v_pk_add_f32 v[118:119], v[116:117], v[86:87]
	v_mov_b32_e32 v124, v86
	v_mov_b32_e32 v125, v119
	v_pk_add_f32 v[124:125], v[124:125], v[126:127] neg_lo:[0,1] neg_hi:[0,1]
	v_mov_b32_e32 v120, v118
	v_mov_b32_e32 v121, v117
	v_mov_b32_e32 v122, v116
	v_mov_b32_e32 v126, v116
	v_mov_b32_e32 v127, v119
	v_mov_b32_e32 v115, v125
	v_pk_add_f32 v[120:121], v[120:121], v[122:123] neg_lo:[0,1] neg_hi:[0,1]
	v_mov_b32_e32 v122, v86
	v_mov_b32_e32 v123, v103
	v_pk_add_f32 v[114:115], v[126:127], v[114:115] neg_lo:[0,1] neg_hi:[0,1]
	v_pk_add_f32 v[122:123], v[122:123], v[120:121] neg_lo:[0,1] neg_hi:[0,1]
	v_mov_b32_e32 v126, v114
	v_mov_b32_e32 v127, v121
	v_mov_b32_e32 v128, v118
	v_mov_b32_e32 v129, v87
	v_mov_b32_e32 v121, v93
	v_pk_add_f32 v[126:127], v[102:103], v[126:127] neg_lo:[0,1] neg_hi:[0,1]
	v_pk_add_f32 v[120:121], v[128:129], v[120:121] neg_lo:[0,1] neg_hi:[0,1]
	v_mov_b32_e32 v103, v117
	v_pk_add_f32 v[86:87], v[86:87], v[92:93] neg_lo:[0,1] neg_hi:[0,1]
	v_pk_add_f32 v[88:89], v[88:89], v[120:121] neg_lo:[0,1] neg_hi:[0,1]
	v_pk_add_f32 v[92:93], v[102:103], v[114:115] neg_lo:[0,1] neg_hi:[0,1]
	v_pk_add_f32 v[84:85], v[84:85], v[124:125] neg_lo:[0,1] neg_hi:[0,1]
	v_pk_add_f32 v[86:87], v[94:95], v[86:87] neg_lo:[0,1] neg_hi:[0,1]
	v_pk_add_f32 v[94:95], v[84:85], v[92:93]
	v_mov_b32_e32 v93, v123
	v_mov_b32_e32 v85, v89
	v_pk_add_f32 v[102:103], v[122:123], v[88:89]
	v_pk_add_f32 v[84:85], v[92:93], v[84:85]
	v_mov_b32_e32 v88, v94
	v_pk_add_f32 v[84:85], v[84:85], v[126:127] neg_lo:[0,1] neg_hi:[0,1]
	v_mov_b32_e32 v89, v103
	v_pk_add_f32 v[88:89], v[88:89], v[84:85] neg_lo:[0,1] neg_hi:[0,1]
	v_pk_add_f32 v[84:85], v[86:87], v[84:85] neg_lo:[0,1] neg_hi:[0,1]
	v_pk_add_f32 v[88:89], v[92:93], v[88:89] neg_lo:[0,1] neg_hi:[0,1]
	v_pk_add_f32 v[86:87], v[102:103], v[94:95]
	v_pk_add_f32 v[84:85], v[84:85], v[88:89]
	v_pk_add_f32 v[88:89], v[118:119], v[86:87]
	s_nop 0
	v_pk_add_f32 v[92:93], v[88:89], v[118:119] neg_lo:[0,1] neg_hi:[0,1]
	s_nop 0
	v_pk_add_f32 v[86:87], v[86:87], v[92:93] neg_lo:[0,1] neg_hi:[0,1]
	s_nop 0
	v_pk_add_f32 v[84:85], v[84:85], v[86:87]
	s_nop 0
	v_pk_add_f32 v[84:85], v[88:89], v[84:85]
	v_pk_mul_f32 v[88:89], v[100:101], v[110:111]
	v_cndmask_b32_e32 v84, v160, v84, vcc
	v_cmp_neq_f32_e32 vcc, s8, v130
	v_pk_add_f32 v[92:93], v[98:99], v[88:89]
	s_nop 0
	v_cndmask_b32_e32 v85, v160, v85, vcc
	v_cmp_ngt_f32_e32 vcc, -1.0, v130
	v_pk_add_f32 v[98:99], v[92:93], v[98:99] neg_lo:[0,1] neg_hi:[0,1]
	v_mov_b32_e32 v116, v92
	v_cndmask_b32_e32 v85, v161, v85, vcc
	v_cmp_ngt_f32_e32 vcc, -1.0, v83
	v_pk_add_f32 v[88:89], v[88:89], v[98:99] neg_lo:[0,1] neg_hi:[0,1]
	s_nop 0
	v_cndmask_b32_e32 v84, v161, v84, vcc
	v_cmp_neq_f32_e32 vcc, -1.0, v83
	v_pk_add_f32 v[100:101], v[90:91], v[88:89]
	v_mov_b32_e32 v99, v89
	v_cndmask_b32_e32 v84, v162, v84, vcc
	v_cmp_neq_f32_e32 vcc, -1.0, v130
	v_mov_b32_e32 v91, v101
	v_mov_b32_e32 v89, v93
	v_cndmask_b32_e32 v85, v162, v85, vcc
	v_cmp_lt_f32_e64 vcc, |v83|, s9
	v_cndmask_b32_e64 v85, v85, v130, s[0:1]
	v_pk_add_f32 v[88:89], v[90:91], v[88:89]
	v_cndmask_b32_e32 v84, v84, v83, vcc
	v_pk_add_f32 v[78:79], v[78:79], v[84:85]
	v_cvt_f32_i32_e32 v85, v134
	v_cvt_f32_i32_e32 v84, v132
	v_pk_add_f32 v[90:91], v[92:93], v[100:101]
	v_cmp_neq_f32_e32 vcc, s8, v131
	v_mov_b32_e32 v114, v90
	v_pk_mul_f32 v[86:87], v[84:85], s[12:13] op_sel_hi:[1,0]
	v_mov_b32_e32 v119, v91
	v_pk_fma_f32 v[94:95], v[84:85], s[12:13], v[86:87] op_sel_hi:[1,0,1] neg_lo:[0,0,1] neg_hi:[0,0,1]
	v_mov_b32_e32 v98, v86
	v_pk_fma_f32 v[84:85], v[84:85], s[14:15], v[94:95] op_sel_hi:[1,0,1]
	v_cmp_lt_f32_e64 s[0:1], |v133|, s9
; __device__ __forceinline__ float softplusf(float x) { return fmaxf(x, 0.f) + log1pf(__expf(-fabsf(x))); }
; __device__ void phaseA_tile(const Params& p, int l, int mt, int nt, char* smem) {
;     ...
;                 for (int j = 0; j < 2; ++j) {
;                     const int c = j * 16 + g4 * 4;
;                     const float4 db = *(const float4*)(p.dt_bias + l * 32 + c);
;                     const f32x4 v = acc[i][j];
;                     *(float4*)(p.dtb + (size_t)row * 32 + c) =
;                         make_float4(softplusf(v[0] + db.x), softplusf(v[1] + db.y), softplusf(v[2] + db.z), softplusf(v[3] + db.w));
;                 }
	v_pk_add_f32 v[94:95], v[86:87], v[84:85]
	v_mov_b32_e32 v112, v84
	v_pk_add_f32 v[102:103], v[94:95], v[90:91]
	v_mov_b32_e32 v117, v95
	v_mov_b32_e32 v115, v103
	v_pk_add_f32 v[114:115], v[114:115], v[116:117] neg_lo:[0,1] neg_hi:[0,1]
	v_pk_add_f32 v[98:99], v[98:99], v[112:113]
	v_mov_b32_e32 v110, v102
	v_mov_b32_e32 v111, v95
	v_mov_b32_e32 v112, v94
	v_mov_b32_e32 v113, v87
	v_mov_b32_e32 v116, v94
	v_mov_b32_e32 v117, v103
	v_mov_b32_e32 v87, v115
	v_pk_add_f32 v[110:111], v[110:111], v[112:113] neg_lo:[0,1] neg_hi:[0,1]
	v_mov_b32_e32 v112, v90
	v_mov_b32_e32 v113, v85
	v_pk_add_f32 v[86:87], v[116:117], v[86:87] neg_lo:[0,1] neg_hi:[0,1]
	v_pk_add_f32 v[112:113], v[112:113], v[110:111] neg_lo:[0,1] neg_hi:[0,1]
	v_mov_b32_e32 v116, v86
	v_mov_b32_e32 v117, v111
	v_mov_b32_e32 v118, v102
	v_mov_b32_e32 v111, v93
	v_pk_add_f32 v[116:117], v[84:85], v[116:117] neg_lo:[0,1] neg_hi:[0,1]
	v_pk_add_f32 v[110:111], v[118:119], v[110:111] neg_lo:[0,1] neg_hi:[0,1]
	v_mov_b32_e32 v85, v95
	v_pk_add_f32 v[90:91], v[90:91], v[92:93] neg_lo:[0,1] neg_hi:[0,1]
	v_pk_add_f32 v[92:93], v[98:99], v[110:111] neg_lo:[0,1] neg_hi:[0,1]
	v_pk_add_f32 v[84:85], v[84:85], v[86:87] neg_lo:[0,1] neg_hi:[0,1]
	v_pk_add_f32 v[86:87], v[88:89], v[114:115] neg_lo:[0,1] neg_hi:[0,1]
	v_pk_add_f32 v[94:95], v[112:113], v[92:93]
	v_pk_add_f32 v[88:89], v[86:87], v[84:85]
	v_mov_b32_e32 v85, v113
	v_mov_b32_e32 v87, v93
	v_pk_add_f32 v[86:87], v[84:85], v[86:87]
	v_mov_b32_e32 v92, v88
	v_pk_add_f32 v[86:87], v[86:87], v[116:117] neg_lo:[0,1] neg_hi:[0,1]
	v_mov_b32_e32 v93, v95
	v_pk_add_f32 v[90:91], v[100:101], v[90:91] neg_lo:[0,1] neg_hi:[0,1]
	v_pk_add_f32 v[92:93], v[92:93], v[86:87] neg_lo:[0,1] neg_hi:[0,1]
	v_pk_add_f32 v[86:87], v[90:91], v[86:87] neg_lo:[0,1] neg_hi:[0,1]
	v_pk_add_f32 v[84:85], v[84:85], v[92:93] neg_lo:[0,1] neg_hi:[0,1]
	s_nop 0
	v_pk_add_f32 v[84:85], v[86:87], v[84:85]
	v_pk_add_f32 v[86:87], v[94:95], v[88:89]
	s_nop 0
	v_pk_add_f32 v[88:89], v[102:103], v[86:87]
	s_nop 0
	v_pk_add_f32 v[90:91], v[88:89], v[102:103] neg_lo:[0,1] neg_hi:[0,1]
	s_nop 0
	v_pk_add_f32 v[86:87], v[86:87], v[90:91] neg_lo:[0,1] neg_hi:[0,1]
	s_nop 0
	v_pk_add_f32 v[84:85], v[84:85], v[86:87]
	s_nop 0
	v_pk_add_f32 v[84:85], v[88:89], v[84:85]
	s_nop 0
	v_cndmask_b32_e32 v83, v160, v84, vcc
	v_cmp_neq_f32_e32 vcc, s8, v133
	s_nop 1
	v_cndmask_b32_e32 v84, v160, v85, vcc
	v_cmp_ngt_f32_e32 vcc, -1.0, v133
	s_nop 1
	v_cndmask_b32_e32 v84, v161, v84, vcc
	v_cmp_ngt_f32_e32 vcc, -1.0, v131
	s_nop 1
	v_cndmask_b32_e32 v83, v161, v83, vcc
	v_cmp_neq_f32_e32 vcc, -1.0, v131
	s_nop 1
	v_cndmask_b32_e32 v83, v162, v83, vcc
	v_cmp_neq_f32_e32 vcc, -1.0, v133
	s_nop 1
	v_cndmask_b32_e32 v84, v162, v84, vcc
	v_cmp_lt_f32_e64 vcc, |v131|, s9
	v_cndmask_b32_e64 v85, v84, v133, s[0:1]
	s_nop 0
	v_cndmask_b32_e32 v84, v83, v131, vcc
	v_pk_add_f32 v[80:81], v[80:81], v[84:85]
	global_store_dwordx4 v[76:77], v[78:81], off
	global_load_dwordx4 v[78:81], v0, s[74:75] offset:64
	s_waitcnt vmcnt(0)
	v_add_f32_e32 v83, v42, v78
	v_max_f32_e32 v78, 0, v83
	v_mul_f32_e64 v83, |v83|, s2
	v_exp_f32_e32 v83, v83
	s_nop 0
	v_add_f32_e32 v86, 1.0, v83
	v_add_f32_e32 v84, -1.0, v86
	v_sub_f32_e32 v85, v84, v86
	v_add_f32_e32 v85, 1.0, v85
	v_sub_f32_e32 v84, v83, v84
	v_add_f32_e32 v87, v84, v85
	v_frexp_mant_f32_e32 v84, v86
	v_cmp_gt_f32_e32 vcc, s26, v84
	v_cvt_f64_f32_e32 v[84:85], v86
	v_frexp_exp_i32_f64_e32 v84, v[84:85]
	v_subbrev_co_u32_e32 v97, vcc, 0, v84, vcc
	v_sub_u32_e32 v85, 0, v97
	v_ldexp_f32 v84, v86, v85
	v_ldexp_f32 v86, v87, v85
	v_add_f32_e32 v85, v43, v79
	v_max_f32_e32 v79, 0, v85
	v_mul_f32_e64 v85, |v85|, s2
	v_exp_f32_e32 v130, v85
	s_nop 0
	v_add_f32_e32 v85, 1.0, v130
	v_add_f32_e32 v87, -1.0, v85
	v_sub_f32_e32 v88, v87, v85
	v_add_f32_e32 v88, 1.0, v88
	v_sub_f32_e32 v87, v130, v87
	v_add_f32_e32 v87, v87, v88
	v_frexp_mant_f32_e32 v88, v85
	v_cmp_gt_f32_e32 vcc, s26, v88
	v_cvt_f64_f32_e32 v[88:89], v85
	v_frexp_exp_i32_f64_e32 v88, v[88:89]
	v_subbrev_co_u32_e32 v122, vcc, 0, v88, vcc
	v_sub_u32_e32 v88, 0, v122
	v_ldexp_f32 v85, v85, v88
	v_ldexp_f32 v87, v87, v88
	v_pk_add_f32 v[88:89], v[84:85], 1.0 op_sel_hi:[1,0]
	v_pk_add_f32 v[98:99], v[84:85], -1.0 op_sel_hi:[1,0]
	v_pk_add_f32 v[90:91], v[88:89], -1.0 op_sel_hi:[1,0]
	v_pk_add_f32 v[100:101], v[98:99], 1.0 op_sel_hi:[1,0]
	v_pk_add_f32 v[90:91], v[84:85], v[90:91] neg_lo:[0,1] neg_hi:[0,1]
	v_pk_add_f32 v[84:85], v[84:85], v[100:101] neg_lo:[0,1] neg_hi:[0,1]
	v_pk_add_f32 v[90:91], v[86:87], v[90:91]
	v_pk_add_f32 v[84:85], v[86:87], v[84:85]
	v_pk_add_f32 v[92:93], v[88:89], v[90:91]
	v_pk_add_f32 v[86:87], v[98:99], v[84:85]
	v_rcp_f32_e32 v94, v92
	v_rcp_f32_e32 v95, v93
	v_pk_add_f32 v[88:89], v[92:93], v[88:89] neg_lo:[0,1] neg_hi:[0,1]
	v_pk_add_f32 v[98:99], v[86:87], v[98:99] neg_lo:[0,1] neg_hi:[0,1]
	v_pk_add_f32 v[88:89], v[90:91], v[88:89] neg_lo:[0,1] neg_hi:[0,1]
	v_pk_mul_f32 v[90:91], v[86:87], v[94:95]
	v_pk_add_f32 v[84:85], v[84:85], v[98:99] neg_lo:[0,1] neg_hi:[0,1]
	v_pk_mul_f32 v[98:99], v[92:93], v[90:91]
	v_cmp_lt_f32_e64 s[0:1], |v130|, s9
	v_pk_fma_f32 v[100:101], v[90:91], v[92:93], v[98:99] neg_lo:[0,0,1] neg_hi:[0,0,1]
	s_nop 0
	v_pk_fma_f32 v[100:101], v[90:91], v[88:89], v[100:101]
	s_nop 0
	v_pk_add_f32 v[102:103], v[98:99], v[100:101]
	s_nop 0
	v_pk_add_f32 v[110:111], v[86:87], v[102:103] neg_lo:[0,1] neg_hi:[0,1]
	v_pk_add_f32 v[98:99], v[102:103], v[98:99] neg_lo:[0,1] neg_hi:[0,1]
	v_pk_add_f32 v[86:87], v[86:87], v[110:111] neg_lo:[0,1] neg_hi:[0,1]
	s_nop 0
	v_pk_add_f32 v[86:87], v[86:87], v[102:103] neg_lo:[0,1] neg_hi:[0,1]
	s_nop 0
; __device__ __forceinline__ float softplusf(float x) { return fmaxf(x, 0.f) + log1pf(__expf(-fabsf(x))); }
; __device__ void phaseA_tile(const Params& p, int l, int mt, int nt, char* smem) {
;     ...
;                 for (int j = 0; j < 2; ++j) {
;                     const int c = j * 16 + g4 * 4;
;                     const float4 db = *(const float4*)(p.dt_bias + l * 32 + c);
;                     const f32x4 v = acc[i][j];
;                     *(float4*)(p.dtb + (size_t)row * 32 + c) =
;                         make_float4(softplusf(v[0] + db.x), softplusf(v[1] + db.y), softplusf(v[2] + db.z), softplusf(v[3] + db.w));
;                 }
	v_pk_add_f32 v[84:85], v[84:85], v[86:87]
	v_pk_add_f32 v[86:87], v[98:99], v[100:101] neg_lo:[0,1] neg_hi:[0,1]
	s_nop 0
	v_pk_add_f32 v[84:85], v[86:87], v[84:85]
	s_nop 0
	v_pk_add_f32 v[86:87], v[110:111], v[84:85]
	s_nop 0
	v_pk_mul_f32 v[98:99], v[94:95], v[86:87]
	s_nop 0
	v_pk_mul_f32 v[100:101], v[92:93], v[98:99]
	s_nop 0
	v_pk_fma_f32 v[92:93], v[98:99], v[92:93], v[100:101] neg_lo:[0,0,1] neg_hi:[0,0,1]
	s_nop 0
	v_pk_fma_f32 v[88:89], v[98:99], v[88:89], v[92:93]
	v_pk_add_f32 v[92:93], v[110:111], v[86:87] neg_lo:[0,1] neg_hi:[0,1]
	s_nop 0
	v_pk_add_f32 v[84:85], v[84:85], v[92:93]
	v_pk_add_f32 v[92:93], v[100:101], v[88:89]
	s_nop 0
	v_pk_add_f32 v[102:103], v[86:87], v[92:93] neg_lo:[0,1] neg_hi:[0,1]
	v_pk_add_f32 v[100:101], v[92:93], v[100:101] neg_lo:[0,1] neg_hi:[0,1]
	v_pk_add_f32 v[86:87], v[86:87], v[102:103] neg_lo:[0,1] neg_hi:[0,1]
	s_nop 0
	v_pk_add_f32 v[86:87], v[86:87], v[92:93] neg_lo:[0,1] neg_hi:[0,1]
	s_nop 0
	v_pk_add_f32 v[84:85], v[84:85], v[86:87]
	v_pk_add_f32 v[86:87], v[100:101], v[88:89] neg_lo:[0,1] neg_hi:[0,1]
	s_nop 0
	v_pk_add_f32 v[84:85], v[86:87], v[84:85]
	v_pk_add_f32 v[86:87], v[90:91], v[98:99]
	v_pk_add_f32 v[84:85], v[102:103], v[84:85]
	v_pk_add_f32 v[88:89], v[86:87], v[90:91] neg_lo:[0,1] neg_hi:[0,1]
	v_pk_mul_f32 v[84:85], v[94:95], v[84:85]
	v_pk_add_f32 v[88:89], v[98:99], v[88:89] neg_lo:[0,1] neg_hi:[0,1]
	s_nop 0
	v_pk_add_f32 v[84:85], v[88:89], v[84:85]
	s_nop 0
	v_pk_add_f32 v[88:89], v[86:87], v[84:85]
	s_nop 0
	v_pk_add_f32 v[86:87], v[88:89], v[86:87] neg_lo:[0,1] neg_hi:[0,1]
	v_pk_mul_f32 v[90:91], v[88:89], v[88:89]
	v_pk_add_f32 v[84:85], v[84:85], v[86:87] neg_lo:[0,1] neg_hi:[0,1]
	v_pk_fma_f32 v[92:93], v[90:91], s[28:29], v[66:67] op_sel_hi:[1,0,0]
	v_ldexp_f32 v95, v85, 1
	v_add_f32_e32 v85, v44, v80
	v_max_f32_e32 v80, 0, v85
	v_mul_f32_e64 v85, |v85|, s2
	v_exp_f32_e32 v131, v85
	v_ldexp_f32 v86, v88, 1
	v_pk_fma_f32 v[92:93], v[90:91], v[92:93], s[30:31] op_sel_hi:[1,1,0]
	v_ldexp_f32 v87, v89, 1
	v_add_f32_e32 v85, 1.0, v131
	v_pk_mul_f32 v[88:89], v[88:89], v[90:91]
	v_add_f32_e32 v90, -1.0, v85
	v_sub_f32_e32 v91, v90, v85
	v_add_f32_e32 v91, 1.0, v91
	v_sub_f32_e32 v90, v131, v90
	v_add_f32_e32 v94, v90, v91
	v_frexp_mant_f32_e32 v90, v85
	v_cmp_gt_f32_e32 vcc, s26, v90
	v_cvt_f64_f32_e32 v[90:91], v85
	v_frexp_exp_i32_f64_e32 v90, v[90:91]
	v_subbrev_co_u32_e32 v132, vcc, 0, v90, vcc
	v_sub_u32_e32 v91, 0, v132
	v_ldexp_f32 v90, v85, v91
	v_add_f32_e32 v85, v45, v81
	v_max_f32_e32 v81, 0, v85
	v_mul_f32_e64 v85, |v85|, s2
	v_exp_f32_e32 v133, v85
	v_ldexp_f32 v98, v94, v91
	v_pk_mul_f32 v[88:89], v[88:89], v[92:93]
	v_ldexp_f32 v84, v84, 1
	v_add_f32_e32 v85, 1.0, v133
	v_add_f32_e32 v91, -1.0, v85
	v_sub_f32_e32 v94, v91, v85
	v_add_f32_e32 v94, 1.0, v94
	v_sub_f32_e32 v91, v133, v91
	v_add_f32_e32 v94, v91, v94
	v_frexp_mant_f32_e32 v91, v85
	v_cvt_f64_f32_e32 v[100:101], v85
	v_cmp_gt_f32_e32 vcc, s26, v91
	v_frexp_exp_i32_f64_e32 v91, v[100:101]
	v_pk_add_f32 v[92:93], v[86:87], v[88:89]
	v_subbrev_co_u32_e32 v134, vcc, 0, v91, vcc
	v_sub_u32_e32 v99, 0, v134
	v_ldexp_f32 v91, v85, v99
	v_pk_add_f32 v[100:101], v[90:91], 1.0 op_sel_hi:[1,0]
	v_ldexp_f32 v99, v94, v99
	v_pk_add_f32 v[102:103], v[100:101], -1.0 op_sel_hi:[1,0]
	v_pk_add_f32 v[114:115], v[90:91], -1.0 op_sel_hi:[1,0]
	v_pk_add_f32 v[102:103], v[90:91], v[102:103] neg_lo:[0,1] neg_hi:[0,1]
	v_pk_add_f32 v[116:117], v[114:115], 1.0 op_sel_hi:[1,0]
	v_pk_add_f32 v[102:103], v[98:99], v[102:103]
	v_pk_add_f32 v[90:91], v[90:91], v[116:117] neg_lo:[0,1] neg_hi:[0,1]
	v_pk_add_f32 v[110:111], v[100:101], v[102:103]
	v_pk_add_f32 v[90:91], v[98:99], v[90:91]
	v_rcp_f32_e32 v112, v110
	v_rcp_f32_e32 v113, v111
	v_pk_add_f32 v[98:99], v[114:115], v[90:91]
	v_pk_add_f32 v[100:101], v[110:111], v[100:101] neg_lo:[0,1] neg_hi:[0,1]
	v_pk_add_f32 v[114:115], v[98:99], v[114:115] neg_lo:[0,1] neg_hi:[0,1]
	v_pk_add_f32 v[100:101], v[102:103], v[100:101] neg_lo:[0,1] neg_hi:[0,1]
	v_pk_mul_f32 v[102:103], v[98:99], v[112:113]
	v_pk_add_f32 v[90:91], v[90:91], v[114:115] neg_lo:[0,1] neg_hi:[0,1]
	v_pk_mul_f32 v[114:115], v[110:111], v[102:103]
	v_pk_add_f32 v[86:87], v[92:93], v[86:87] neg_lo:[0,1] neg_hi:[0,1]
	v_pk_fma_f32 v[116:117], v[102:103], v[110:111], v[114:115] neg_lo:[0,0,1] neg_hi:[0,0,1]
	v_pk_add_f32 v[86:87], v[88:89], v[86:87] neg_lo:[0,1] neg_hi:[0,1]
	v_pk_fma_f32 v[116:117], v[102:103], v[100:101], v[116:117]
	v_mov_b32_e32 v89, v87
	v_pk_add_f32 v[118:119], v[114:115], v[116:117]
	v_mov_b32_e32 v85, v95
	v_pk_add_f32 v[120:121], v[98:99], v[118:119] neg_lo:[0,1] neg_hi:[0,1]
	v_pk_add_f32 v[114:115], v[118:119], v[114:115] neg_lo:[0,1] neg_hi:[0,1]
	v_pk_add_f32 v[98:99], v[98:99], v[120:121] neg_lo:[0,1] neg_hi:[0,1]
	v_mov_b32_e32 v126, v92
	v_pk_add_f32 v[98:99], v[98:99], v[118:119] neg_lo:[0,1] neg_hi:[0,1]
	v_cmp_neq_f32_e32 vcc, s8, v83
	v_pk_add_f32 v[90:91], v[90:91], v[98:99]
	v_pk_add_f32 v[98:99], v[114:115], v[116:117] neg_lo:[0,1] neg_hi:[0,1]
	s_nop 0
	v_pk_add_f32 v[90:91], v[98:99], v[90:91]
	s_nop 0
	v_pk_add_f32 v[98:99], v[120:121], v[90:91]
	s_nop 0
	v_pk_mul_f32 v[114:115], v[112:113], v[98:99]
	s_nop 0
	v_pk_mul_f32 v[116:117], v[110:111], v[114:115]
	s_nop 0
	v_pk_fma_f32 v[110:111], v[114:115], v[110:111], v[116:117] neg_lo:[0,0,1] neg_hi:[0,0,1]
	s_nop 0
	v_pk_fma_f32 v[100:101], v[114:115], v[100:101], v[110:111]
	v_pk_add_f32 v[110:111], v[120:121], v[98:99] neg_lo:[0,1] neg_hi:[0,1]
	s_nop 0
	v_pk_add_f32 v[90:91], v[90:91], v[110:111]
	v_pk_add_f32 v[110:111], v[116:117], v[100:101]
	s_nop 0
	v_pk_add_f32 v[118:119], v[98:99], v[110:111] neg_lo:[0,1] neg_hi:[0,1]
; __device__ __forceinline__ float softplusf(float x) { return fmaxf(x, 0.f) + log1pf(__expf(-fabsf(x))); }
; __device__ void phaseA_tile(const Params& p, int l, int mt, int nt, char* smem) {
;     ...
;                 for (int j = 0; j < 2; ++j) {
;                     const int c = j * 16 + g4 * 4;
;                     const float4 db = *(const float4*)(p.dt_bias + l * 32 + c);
;                     const f32x4 v = acc[i][j];
;                     *(float4*)(p.dtb + (size_t)row * 32 + c) =
;                         make_float4(softplusf(v[0] + db.x), softplusf(v[1] + db.y), softplusf(v[2] + db.z), softplusf(v[3] + db.w));
;                 }
	v_pk_add_f32 v[116:117], v[110:111], v[116:117] neg_lo:[0,1] neg_hi:[0,1]
	v_pk_add_f32 v[98:99], v[98:99], v[118:119] neg_lo:[0,1] neg_hi:[0,1]
	s_nop 0
	v_pk_add_f32 v[98:99], v[98:99], v[110:111] neg_lo:[0,1] neg_hi:[0,1]
	s_nop 0
	v_pk_add_f32 v[90:91], v[90:91], v[98:99]
	v_pk_add_f32 v[98:99], v[116:117], v[100:101] neg_lo:[0,1] neg_hi:[0,1]
	s_nop 0
	v_pk_add_f32 v[90:91], v[98:99], v[90:91]
	v_pk_add_f32 v[98:99], v[102:103], v[114:115]
	v_pk_add_f32 v[90:91], v[118:119], v[90:91]
	v_pk_add_f32 v[100:101], v[98:99], v[102:103] neg_lo:[0,1] neg_hi:[0,1]
	v_pk_mul_f32 v[90:91], v[112:113], v[90:91]
	v_pk_add_f32 v[100:101], v[114:115], v[100:101] neg_lo:[0,1] neg_hi:[0,1]
	s_nop 0
	v_pk_add_f32 v[90:91], v[100:101], v[90:91]
	s_nop 0
	v_pk_add_f32 v[100:101], v[98:99], v[90:91]
	s_nop 0
	v_pk_mul_f32 v[102:103], v[100:101], v[100:101]
	v_pk_add_f32 v[98:99], v[100:101], v[98:99] neg_lo:[0,1] neg_hi:[0,1]
	v_pk_fma_f32 v[110:111], v[102:103], s[28:29], v[66:67] op_sel_hi:[1,0,0]
	v_pk_add_f32 v[90:91], v[90:91], v[98:99] neg_lo:[0,1] neg_hi:[0,1]
	v_ldexp_f32 v98, v100, 1
	v_pk_fma_f32 v[110:111], v[102:103], v[110:111], s[30:31] op_sel_hi:[1,1,0]
	v_ldexp_f32 v99, v101, 1
	v_pk_mul_f32 v[100:101], v[100:101], v[102:103]
	v_cvt_f32_i32_e32 v103, v122
	v_cvt_f32_i32_e32 v102, v97
	v_ldexp_f32 v113, v91, 1
	v_ldexp_f32 v90, v90, 1
	v_mov_b32_e32 v91, v113
	v_pk_mul_f32 v[114:115], v[102:103], s[12:13] op_sel_hi:[1,0]
	s_nop 0
	v_pk_fma_f32 v[116:117], v[102:103], s[12:13], v[114:115] op_sel_hi:[1,0,1] neg_lo:[0,0,1] neg_hi:[0,0,1]
	v_mov_b32_e32 v88, v114
	v_pk_fma_f32 v[102:103], v[102:103], s[14:15], v[116:117] op_sel_hi:[1,0,1]
	v_mov_b32_e32 v123, v115
	v_mov_b32_e32 v94, v102
	v_pk_add_f32 v[88:89], v[88:89], v[94:95]
	v_pk_add_f32 v[94:95], v[84:85], v[86:87]
	v_mov_b32_e32 v87, v93
	v_mov_b32_e32 v85, v95
	v_pk_add_f32 v[116:117], v[114:115], v[102:103]
	v_pk_add_f32 v[84:85], v[84:85], v[86:87]
	v_pk_add_f32 v[86:87], v[92:93], v[94:95]
	v_mov_b32_e32 v127, v117
	v_pk_add_f32 v[118:119], v[116:117], v[86:87]
	v_mov_b32_e32 v124, v86
	v_mov_b32_e32 v125, v119
	v_pk_add_f32 v[124:125], v[124:125], v[126:127] neg_lo:[0,1] neg_hi:[0,1]
	v_mov_b32_e32 v120, v118
	v_mov_b32_e32 v121, v117
	v_mov_b32_e32 v122, v116
	v_mov_b32_e32 v126, v116
	v_mov_b32_e32 v127, v119
	v_mov_b32_e32 v115, v125
	v_pk_add_f32 v[120:121], v[120:121], v[122:123] neg_lo:[0,1] neg_hi:[0,1]
	v_mov_b32_e32 v122, v86
	v_mov_b32_e32 v123, v103
	v_pk_add_f32 v[114:115], v[126:127], v[114:115] neg_lo:[0,1] neg_hi:[0,1]
	v_pk_add_f32 v[122:123], v[122:123], v[120:121] neg_lo:[0,1] neg_hi:[0,1]
	v_mov_b32_e32 v126, v114
	v_mov_b32_e32 v127, v121
	v_mov_b32_e32 v128, v118
	v_mov_b32_e32 v129, v87
	v_mov_b32_e32 v121, v93
	v_pk_add_f32 v[126:127], v[102:103], v[126:127] neg_lo:[0,1] neg_hi:[0,1]
	v_pk_add_f32 v[120:121], v[128:129], v[120:121] neg_lo:[0,1] neg_hi:[0,1]
	v_mov_b32_e32 v103, v117
	v_pk_add_f32 v[86:87], v[86:87], v[92:93] neg_lo:[0,1] neg_hi:[0,1]
	v_pk_add_f32 v[88:89], v[88:89], v[120:121] neg_lo:[0,1] neg_hi:[0,1]
	v_pk_add_f32 v[92:93], v[102:103], v[114:115] neg_lo:[0,1] neg_hi:[0,1]
	v_pk_add_f32 v[84:85], v[84:85], v[124:125] neg_lo:[0,1] neg_hi:[0,1]
	v_pk_add_f32 v[86:87], v[94:95], v[86:87] neg_lo:[0,1] neg_hi:[0,1]
	v_pk_add_f32 v[94:95], v[84:85], v[92:93]
	v_mov_b32_e32 v93, v123
	v_mov_b32_e32 v85, v89
	v_pk_add_f32 v[102:103], v[122:123], v[88:89]
	v_pk_add_f32 v[84:85], v[92:93], v[84:85]
	v_mov_b32_e32 v88, v94
	v_pk_add_f32 v[84:85], v[84:85], v[126:127] neg_lo:[0,1] neg_hi:[0,1]
	v_mov_b32_e32 v89, v103
	v_pk_add_f32 v[88:89], v[88:89], v[84:85] neg_lo:[0,1] neg_hi:[0,1]
	v_pk_add_f32 v[84:85], v[86:87], v[84:85] neg_lo:[0,1] neg_hi:[0,1]
	v_pk_add_f32 v[88:89], v[92:93], v[88:89] neg_lo:[0,1] neg_hi:[0,1]
	v_pk_add_f32 v[86:87], v[102:103], v[94:95]
	v_pk_add_f32 v[84:85], v[84:85], v[88:89]
	v_pk_add_f32 v[88:89], v[118:119], v[86:87]
	s_nop 0
	v_pk_add_f32 v[92:93], v[88:89], v[118:119] neg_lo:[0,1] neg_hi:[0,1]
	s_nop 0
	v_pk_add_f32 v[86:87], v[86:87], v[92:93] neg_lo:[0,1] neg_hi:[0,1]
	s_nop 0
	v_pk_add_f32 v[84:85], v[84:85], v[86:87]
	s_nop 0
	v_pk_add_f32 v[84:85], v[88:89], v[84:85]
	v_pk_mul_f32 v[88:89], v[100:101], v[110:111]
	v_cndmask_b32_e32 v84, v160, v84, vcc
	v_cmp_neq_f32_e32 vcc, s8, v130
	v_pk_add_f32 v[92:93], v[98:99], v[88:89]
	s_nop 0
	v_cndmask_b32_e32 v85, v160, v85, vcc
	v_cmp_ngt_f32_e32 vcc, -1.0, v130
	v_pk_add_f32 v[98:99], v[92:93], v[98:99] neg_lo:[0,1] neg_hi:[0,1]
	v_mov_b32_e32 v116, v92
	v_cndmask_b32_e32 v85, v161, v85, vcc
	v_cmp_ngt_f32_e32 vcc, -1.0, v83
	v_pk_add_f32 v[88:89], v[88:89], v[98:99] neg_lo:[0,1] neg_hi:[0,1]
	s_nop 0
	v_cndmask_b32_e32 v84, v161, v84, vcc
	v_cmp_neq_f32_e32 vcc, -1.0, v83
	v_pk_add_f32 v[100:101], v[90:91], v[88:89]
	v_mov_b32_e32 v99, v89
	v_cndmask_b32_e32 v84, v162, v84, vcc
	v_cmp_neq_f32_e32 vcc, -1.0, v130
	v_mov_b32_e32 v91, v101
	v_mov_b32_e32 v89, v93
	v_cndmask_b32_e32 v85, v162, v85, vcc
	v_cmp_lt_f32_e64 vcc, |v83|, s9
	v_cndmask_b32_e64 v85, v85, v130, s[0:1]
	v_pk_add_f32 v[88:89], v[90:91], v[88:89]
	v_cndmask_b32_e32 v84, v84, v83, vcc
	v_pk_add_f32 v[78:79], v[78:79], v[84:85]
	v_cvt_f32_i32_e32 v85, v134
	v_cvt_f32_i32_e32 v84, v132
	v_pk_add_f32 v[90:91], v[92:93], v[100:101]
	v_cmp_neq_f32_e32 vcc, s8, v131
	v_mov_b32_e32 v114, v90
	v_pk_mul_f32 v[86:87], v[84:85], s[12:13] op_sel_hi:[1,0]
	v_mov_b32_e32 v119, v91
	v_pk_fma_f32 v[94:95], v[84:85], s[12:13], v[86:87] op_sel_hi:[1,0,1] neg_lo:[0,0,1] neg_hi:[0,0,1]
	v_mov_b32_e32 v98, v86
	v_pk_fma_f32 v[84:85], v[84:85], s[14:15], v[94:95] op_sel_hi:[1,0,1]
	v_cmp_lt_f32_e64 s[0:1], |v133|, s9
; __device__ __forceinline__ float softplusf(float x) { return fmaxf(x, 0.f) + log1pf(__expf(-fabsf(x))); }
; __device__ __forceinline__ float logsigf(float x) { return fminf(x, 0.f) - log1pf(__expf(-fabsf(x))); }
; __device__ void phaseA_tile(const Params& p, int l, int mt, int nt, char* smem) {
;     ...
;                 for (int j = 0; j < 2; ++j) {
;                     const int c = j * 16 + g4 * 4;
;                     const float4 db = *(const float4*)(p.dt_bias + l * 32 + c);
;                     const f32x4 v = acc[i][j];
;                     *(float4*)(p.dtb + (size_t)row * 32 + c) =
;                         make_float4(softplusf(v[0] + db.x), softplusf(v[1] + db.y), softplusf(v[2] + db.z), softplusf(v[3] + db.w));
;                 }
;                 {
;                     const int c = g4 * 4;
;                     const float4 fb = *(const float4*)(p.b_f + l * 16 + c);
;                     const f32x4 v = acc[i][2];
;                     float4 lf = make_float4(logsigf(v[0] + fb.x), logsigf(v[1] + fb.y), logsigf(v[2] + fb.z), logsigf(v[3] + fb.w));
;                     float* o = samp ? (p.out + O_LFS + ((size_t)l * TSM + (row - TP)) * 16 + c)
;                                     : (p.out + O_LFP + ((size_t)l * TP + row) * 16 + c);
;                     *(float4*)o = lf;
;                     *(float4*)(lf_s + rl * 16 + c) = lf;
	v_pk_add_f32 v[94:95], v[86:87], v[84:85]
	v_mov_b32_e32 v112, v84
	v_pk_add_f32 v[102:103], v[94:95], v[90:91]
	v_mov_b32_e32 v117, v95
	v_mov_b32_e32 v115, v103
	v_pk_add_f32 v[114:115], v[114:115], v[116:117] neg_lo:[0,1] neg_hi:[0,1]
	v_pk_add_f32 v[98:99], v[98:99], v[112:113]
	v_mov_b32_e32 v110, v102
	v_mov_b32_e32 v111, v95
	v_mov_b32_e32 v112, v94
	v_mov_b32_e32 v113, v87
	v_mov_b32_e32 v116, v94
	v_mov_b32_e32 v117, v103
	v_mov_b32_e32 v87, v115
	v_pk_add_f32 v[110:111], v[110:111], v[112:113] neg_lo:[0,1] neg_hi:[0,1]
	v_mov_b32_e32 v112, v90
	v_mov_b32_e32 v113, v85
	v_pk_add_f32 v[86:87], v[116:117], v[86:87] neg_lo:[0,1] neg_hi:[0,1]
	v_pk_add_f32 v[112:113], v[112:113], v[110:111] neg_lo:[0,1] neg_hi:[0,1]
	v_mov_b32_e32 v116, v86
	v_mov_b32_e32 v117, v111
	v_mov_b32_e32 v118, v102
	v_mov_b32_e32 v111, v93
	v_pk_add_f32 v[116:117], v[84:85], v[116:117] neg_lo:[0,1] neg_hi:[0,1]
	v_pk_add_f32 v[110:111], v[118:119], v[110:111] neg_lo:[0,1] neg_hi:[0,1]
	v_mov_b32_e32 v85, v95
	v_pk_add_f32 v[90:91], v[90:91], v[92:93] neg_lo:[0,1] neg_hi:[0,1]
	v_pk_add_f32 v[92:93], v[98:99], v[110:111] neg_lo:[0,1] neg_hi:[0,1]
	v_pk_add_f32 v[84:85], v[84:85], v[86:87] neg_lo:[0,1] neg_hi:[0,1]
	v_pk_add_f32 v[86:87], v[88:89], v[114:115] neg_lo:[0,1] neg_hi:[0,1]
	v_pk_add_f32 v[94:95], v[112:113], v[92:93]
	v_pk_add_f32 v[88:89], v[86:87], v[84:85]
	v_mov_b32_e32 v85, v113
	v_mov_b32_e32 v87, v93
	v_pk_add_f32 v[86:87], v[84:85], v[86:87]
	v_mov_b32_e32 v92, v88
	v_pk_add_f32 v[86:87], v[86:87], v[116:117] neg_lo:[0,1] neg_hi:[0,1]
	v_mov_b32_e32 v93, v95
	v_pk_add_f32 v[90:91], v[100:101], v[90:91] neg_lo:[0,1] neg_hi:[0,1]
	v_pk_add_f32 v[92:93], v[92:93], v[86:87] neg_lo:[0,1] neg_hi:[0,1]
	v_pk_add_f32 v[86:87], v[90:91], v[86:87] neg_lo:[0,1] neg_hi:[0,1]
	v_pk_add_f32 v[84:85], v[84:85], v[92:93] neg_lo:[0,1] neg_hi:[0,1]
	s_nop 0
	v_pk_add_f32 v[84:85], v[86:87], v[84:85]
	v_pk_add_f32 v[86:87], v[94:95], v[88:89]
	s_nop 0
	v_pk_add_f32 v[88:89], v[102:103], v[86:87]
	s_nop 0
	v_pk_add_f32 v[90:91], v[88:89], v[102:103] neg_lo:[0,1] neg_hi:[0,1]
	s_nop 0
	v_pk_add_f32 v[86:87], v[86:87], v[90:91] neg_lo:[0,1] neg_hi:[0,1]
	s_nop 0
	v_pk_add_f32 v[84:85], v[84:85], v[86:87]
	s_nop 0
	v_pk_add_f32 v[84:85], v[88:89], v[84:85]
	s_nop 0
	v_cndmask_b32_e32 v83, v160, v84, vcc
	v_cmp_neq_f32_e32 vcc, s8, v133
	s_nop 1
	v_cndmask_b32_e32 v84, v160, v85, vcc
	v_cmp_ngt_f32_e32 vcc, -1.0, v133
	s_nop 1
	v_cndmask_b32_e32 v84, v161, v84, vcc
	v_cmp_ngt_f32_e32 vcc, -1.0, v131
	s_nop 1
	v_cndmask_b32_e32 v83, v161, v83, vcc
	v_cmp_neq_f32_e32 vcc, -1.0, v131
	s_nop 1
	v_cndmask_b32_e32 v83, v162, v83, vcc
	v_cmp_neq_f32_e32 vcc, -1.0, v133
	s_nop 1
	v_cndmask_b32_e32 v84, v162, v84, vcc
	v_cmp_lt_f32_e64 vcc, |v131|, s9
	v_cndmask_b32_e64 v85, v84, v133, s[0:1]
	s_nop 0
	v_cndmask_b32_e32 v84, v83, v131, vcc
	v_pk_add_f32 v[80:81], v[80:81], v[84:85]
	global_store_dwordx4 v[76:77], v[78:81], off offset:64
	global_load_dwordx4 v[76:79], v0, s[78:79]
	s_waitcnt vmcnt(0)
	v_add_f32_e32 v80, v38, v76
	v_min_f32_e32 v76, 0, v80
	v_mul_f32_e64 v80, |v80|, s2
	v_exp_f32_e32 v83, v80
	s_nop 0
	v_add_f32_e32 v84, 1.0, v83
	v_add_f32_e32 v80, -1.0, v84
	v_sub_f32_e32 v81, v80, v84
	v_add_f32_e32 v81, 1.0, v81
	v_sub_f32_e32 v80, v83, v80
	v_add_f32_e32 v85, v80, v81
	v_frexp_mant_f32_e32 v80, v84
	v_cmp_gt_f32_e32 vcc, s26, v80
	v_cvt_f64_f32_e32 v[80:81], v84
	v_frexp_exp_i32_f64_e32 v80, v[80:81]
	v_subbrev_co_u32_e32 v97, vcc, 0, v80, vcc
	v_sub_u32_e32 v81, 0, v97
	v_ldexp_f32 v80, v84, v81
	v_ldexp_f32 v84, v85, v81
	v_add_f32_e32 v81, v39, v77
	v_min_f32_e32 v77, 0, v81
	v_mul_f32_e64 v81, |v81|, s2
	v_exp_f32_e32 v128, v81
	s_nop 0
	v_add_f32_e32 v81, 1.0, v128
	v_add_f32_e32 v85, -1.0, v81
	v_sub_f32_e32 v86, v85, v81
	v_add_f32_e32 v86, 1.0, v86
	v_sub_f32_e32 v85, v128, v85
	v_add_f32_e32 v85, v85, v86
	v_frexp_mant_f32_e32 v86, v81
	v_cmp_gt_f32_e32 vcc, s26, v86
	v_cvt_f64_f32_e32 v[86:87], v81
	v_frexp_exp_i32_f64_e32 v86, v[86:87]
	v_subbrev_co_u32_e32 v120, vcc, 0, v86, vcc
	v_sub_u32_e32 v86, 0, v120
	v_ldexp_f32 v81, v81, v86
	v_ldexp_f32 v85, v85, v86
	v_pk_add_f32 v[86:87], v[80:81], 1.0 op_sel_hi:[1,0]
	v_pk_add_f32 v[94:95], v[80:81], -1.0 op_sel_hi:[1,0]
	v_pk_add_f32 v[88:89], v[86:87], -1.0 op_sel_hi:[1,0]
	v_pk_add_f32 v[98:99], v[94:95], 1.0 op_sel_hi:[1,0]
	v_pk_add_f32 v[88:89], v[80:81], v[88:89] neg_lo:[0,1] neg_hi:[0,1]
	v_pk_add_f32 v[80:81], v[80:81], v[98:99] neg_lo:[0,1] neg_hi:[0,1]
	v_pk_add_f32 v[88:89], v[84:85], v[88:89]
	v_pk_add_f32 v[80:81], v[84:85], v[80:81]
	v_pk_add_f32 v[90:91], v[86:87], v[88:89]
	v_pk_add_f32 v[84:85], v[94:95], v[80:81]
	v_rcp_f32_e32 v92, v90
	v_rcp_f32_e32 v93, v91
	v_pk_add_f32 v[86:87], v[90:91], v[86:87] neg_lo:[0,1] neg_hi:[0,1]
	v_pk_add_f32 v[94:95], v[84:85], v[94:95] neg_lo:[0,1] neg_hi:[0,1]
	v_pk_add_f32 v[86:87], v[88:89], v[86:87] neg_lo:[0,1] neg_hi:[0,1]
	v_pk_mul_f32 v[88:89], v[84:85], v[92:93]
	v_pk_add_f32 v[80:81], v[80:81], v[94:95] neg_lo:[0,1] neg_hi:[0,1]
	v_pk_mul_f32 v[94:95], v[90:91], v[88:89]
	v_cmp_lt_f32_e64 s[0:1], |v128|, s9
	v_pk_fma_f32 v[98:99], v[88:89], v[90:91], v[94:95] neg_lo:[0,0,1] neg_hi:[0,0,1]
	s_nop 0
	v_pk_fma_f32 v[98:99], v[88:89], v[86:87], v[98:99]
	s_nop 0
	v_pk_add_f32 v[100:101], v[94:95], v[98:99]
	s_nop 0
	v_pk_add_f32 v[102:103], v[84:85], v[100:101] neg_lo:[0,1] neg_hi:[0,1]
	v_pk_add_f32 v[94:95], v[100:101], v[94:95] neg_lo:[0,1] neg_hi:[0,1]
	v_pk_add_f32 v[84:85], v[84:85], v[102:103] neg_lo:[0,1] neg_hi:[0,1]
	s_nop 0
	v_pk_add_f32 v[84:85], v[84:85], v[100:101] neg_lo:[0,1] neg_hi:[0,1]
	s_nop 0
; __device__ __forceinline__ float logsigf(float x) { return fminf(x, 0.f) - log1pf(__expf(-fabsf(x))); }
; __device__ void phaseA_tile(const Params& p, int l, int mt, int nt, char* smem) {
;     ...
;                 {
;                     const int c = g4 * 4;
;                     const float4 fb = *(const float4*)(p.b_f + l * 16 + c);
;                     const f32x4 v = acc[i][2];
;                     float4 lf = make_float4(logsigf(v[0] + fb.x), logsigf(v[1] + fb.y), logsigf(v[2] + fb.z), logsigf(v[3] + fb.w));
;                     float* o = samp ? (p.out + O_LFS + ((size_t)l * TSM + (row - TP)) * 16 + c)
;                                     : (p.out + O_LFP + ((size_t)l * TP + row) * 16 + c);
;                     *(float4*)o = lf;
;                     *(float4*)(lf_s + rl * 16 + c) = lf;
	v_pk_add_f32 v[80:81], v[80:81], v[84:85]
	v_pk_add_f32 v[84:85], v[94:95], v[98:99] neg_lo:[0,1] neg_hi:[0,1]
	s_nop 0
	v_pk_add_f32 v[80:81], v[84:85], v[80:81]
	s_nop 0
	v_pk_add_f32 v[84:85], v[102:103], v[80:81]
	s_nop 0
	v_pk_mul_f32 v[94:95], v[92:93], v[84:85]
	s_nop 0
	v_pk_mul_f32 v[98:99], v[90:91], v[94:95]
	s_nop 0
	v_pk_fma_f32 v[90:91], v[94:95], v[90:91], v[98:99] neg_lo:[0,0,1] neg_hi:[0,0,1]
	s_nop 0
	v_pk_fma_f32 v[86:87], v[94:95], v[86:87], v[90:91]
	v_pk_add_f32 v[90:91], v[102:103], v[84:85] neg_lo:[0,1] neg_hi:[0,1]
	s_nop 0
	v_pk_add_f32 v[80:81], v[80:81], v[90:91]
	v_pk_add_f32 v[90:91], v[98:99], v[86:87]
	s_nop 0
	v_pk_add_f32 v[100:101], v[84:85], v[90:91] neg_lo:[0,1] neg_hi:[0,1]
	v_pk_add_f32 v[98:99], v[90:91], v[98:99] neg_lo:[0,1] neg_hi:[0,1]
	v_pk_add_f32 v[84:85], v[84:85], v[100:101] neg_lo:[0,1] neg_hi:[0,1]
	s_nop 0
	v_pk_add_f32 v[84:85], v[84:85], v[90:91] neg_lo:[0,1] neg_hi:[0,1]
	s_nop 0
	v_pk_add_f32 v[80:81], v[80:81], v[84:85]
	v_pk_add_f32 v[84:85], v[98:99], v[86:87] neg_lo:[0,1] neg_hi:[0,1]
	s_nop 0
	v_pk_add_f32 v[80:81], v[84:85], v[80:81]
	v_pk_add_f32 v[84:85], v[88:89], v[94:95]
	v_pk_add_f32 v[80:81], v[100:101], v[80:81]
	v_pk_add_f32 v[86:87], v[84:85], v[88:89] neg_lo:[0,1] neg_hi:[0,1]
	v_pk_mul_f32 v[80:81], v[92:93], v[80:81]
	v_pk_add_f32 v[86:87], v[94:95], v[86:87] neg_lo:[0,1] neg_hi:[0,1]
	s_nop 0
	v_pk_add_f32 v[80:81], v[86:87], v[80:81]
	s_nop 0
	v_pk_add_f32 v[86:87], v[84:85], v[80:81]
	s_nop 0
	v_pk_add_f32 v[84:85], v[86:87], v[84:85] neg_lo:[0,1] neg_hi:[0,1]
	v_pk_mul_f32 v[88:89], v[86:87], v[86:87]
	v_pk_add_f32 v[80:81], v[80:81], v[84:85] neg_lo:[0,1] neg_hi:[0,1]
	v_pk_fma_f32 v[90:91], v[88:89], s[28:29], v[66:67] op_sel_hi:[1,0,0]
	v_ldexp_f32 v93, v81, 1
	v_add_f32_e32 v81, v40, v78
	v_min_f32_e32 v78, 0, v81
	v_mul_f32_e64 v81, |v81|, s2
	v_exp_f32_e32 v129, v81
	v_ldexp_f32 v84, v86, 1
	v_pk_fma_f32 v[90:91], v[88:89], v[90:91], s[30:31] op_sel_hi:[1,1,0]
	v_ldexp_f32 v85, v87, 1
	v_add_f32_e32 v81, 1.0, v129
	v_pk_mul_f32 v[86:87], v[86:87], v[88:89]
	v_add_f32_e32 v88, -1.0, v81
	v_sub_f32_e32 v89, v88, v81
	v_add_f32_e32 v89, 1.0, v89
	v_sub_f32_e32 v88, v129, v88
	v_add_f32_e32 v92, v88, v89
	v_frexp_mant_f32_e32 v88, v81
	v_cmp_gt_f32_e32 vcc, s26, v88
	v_cvt_f64_f32_e32 v[88:89], v81
	v_frexp_exp_i32_f64_e32 v88, v[88:89]
	v_subbrev_co_u32_e32 v130, vcc, 0, v88, vcc
	v_sub_u32_e32 v89, 0, v130
	v_ldexp_f32 v88, v81, v89
	v_add_f32_e32 v81, v41, v79
	v_min_f32_e32 v79, 0, v81
	v_mul_f32_e64 v81, |v81|, s2
	v_exp_f32_e32 v131, v81
	v_ldexp_f32 v94, v92, v89
	v_pk_mul_f32 v[86:87], v[86:87], v[90:91]
	v_ldexp_f32 v80, v80, 1
	v_add_f32_e32 v81, 1.0, v131
	v_add_f32_e32 v89, -1.0, v81
	v_sub_f32_e32 v92, v89, v81
	v_add_f32_e32 v92, 1.0, v92
	v_sub_f32_e32 v89, v131, v89
	v_add_f32_e32 v92, v89, v92
	v_frexp_mant_f32_e32 v89, v81
	v_cvt_f64_f32_e32 v[98:99], v81
	v_cmp_gt_f32_e32 vcc, s26, v89
	v_frexp_exp_i32_f64_e32 v89, v[98:99]
	v_pk_add_f32 v[90:91], v[84:85], v[86:87]
	v_subbrev_co_u32_e32 v132, vcc, 0, v89, vcc
	v_sub_u32_e32 v95, 0, v132
	v_ldexp_f32 v89, v81, v95
	v_pk_add_f32 v[98:99], v[88:89], 1.0 op_sel_hi:[1,0]
	v_ldexp_f32 v95, v92, v95
	v_pk_add_f32 v[100:101], v[98:99], -1.0 op_sel_hi:[1,0]
	v_pk_add_f32 v[112:113], v[88:89], -1.0 op_sel_hi:[1,0]
	v_pk_add_f32 v[100:101], v[88:89], v[100:101] neg_lo:[0,1] neg_hi:[0,1]
	v_pk_add_f32 v[114:115], v[112:113], 1.0 op_sel_hi:[1,0]
	v_pk_add_f32 v[100:101], v[94:95], v[100:101]
	v_pk_add_f32 v[88:89], v[88:89], v[114:115] neg_lo:[0,1] neg_hi:[0,1]
	v_pk_add_f32 v[102:103], v[98:99], v[100:101]
	v_pk_add_f32 v[88:89], v[94:95], v[88:89]
	v_rcp_f32_e32 v110, v102
	v_rcp_f32_e32 v111, v103
	v_pk_add_f32 v[94:95], v[112:113], v[88:89]
	v_pk_add_f32 v[98:99], v[102:103], v[98:99] neg_lo:[0,1] neg_hi:[0,1]
	v_pk_add_f32 v[112:113], v[94:95], v[112:113] neg_lo:[0,1] neg_hi:[0,1]
	v_pk_add_f32 v[98:99], v[100:101], v[98:99] neg_lo:[0,1] neg_hi:[0,1]
	v_pk_mul_f32 v[100:101], v[94:95], v[110:111]
	v_pk_add_f32 v[88:89], v[88:89], v[112:113] neg_lo:[0,1] neg_hi:[0,1]
	v_pk_mul_f32 v[112:113], v[102:103], v[100:101]
	v_pk_add_f32 v[84:85], v[90:91], v[84:85] neg_lo:[0,1] neg_hi:[0,1]
	v_pk_fma_f32 v[114:115], v[100:101], v[102:103], v[112:113] neg_lo:[0,0,1] neg_hi:[0,0,1]
	v_add_u32_e32 v81, 0xffff8000, v68
	v_pk_fma_f32 v[114:115], v[100:101], v[98:99], v[114:115]
	v_pk_add_f32 v[84:85], v[86:87], v[84:85] neg_lo:[0,1] neg_hi:[0,1]
	v_pk_add_f32 v[116:117], v[112:113], v[114:115]
	v_cndmask_b32_e64 v68, v68, v81, s[60:61]
	v_pk_add_f32 v[118:119], v[94:95], v[116:117] neg_lo:[0,1] neg_hi:[0,1]
	v_pk_add_f32 v[112:113], v[116:117], v[112:113] neg_lo:[0,1] neg_hi:[0,1]
	v_pk_add_f32 v[94:95], v[94:95], v[118:119] neg_lo:[0,1] neg_hi:[0,1]
	v_mov_b32_e32 v87, v85
	v_pk_add_f32 v[94:95], v[94:95], v[116:117] neg_lo:[0,1] neg_hi:[0,1]
	v_mov_b32_e32 v124, v90
	v_pk_add_f32 v[88:89], v[88:89], v[94:95]
	v_pk_add_f32 v[94:95], v[112:113], v[114:115] neg_lo:[0,1] neg_hi:[0,1]
	v_cmp_neq_f32_e32 vcc, s8, v83
	v_pk_add_f32 v[88:89], v[94:95], v[88:89]
	s_nop 0
	v_pk_add_f32 v[94:95], v[118:119], v[88:89]
	s_nop 0
	v_pk_mul_f32 v[112:113], v[110:111], v[94:95]
	s_nop 0
	v_pk_mul_f32 v[114:115], v[102:103], v[112:113]
	s_nop 0
	v_pk_fma_f32 v[102:103], v[112:113], v[102:103], v[114:115] neg_lo:[0,0,1] neg_hi:[0,0,1]
	s_nop 0
	v_pk_fma_f32 v[98:99], v[112:113], v[98:99], v[102:103]
	v_pk_add_f32 v[102:103], v[118:119], v[94:95] neg_lo:[0,1] neg_hi:[0,1]
	s_nop 0
	v_pk_add_f32 v[88:89], v[88:89], v[102:103]
	v_pk_add_f32 v[102:103], v[114:115], v[98:99]
	s_nop 0
	v_pk_add_f32 v[116:117], v[94:95], v[102:103] neg_lo:[0,1] neg_hi:[0,1]
; __device__ __forceinline__ float logsigf(float x) { return fminf(x, 0.f) - log1pf(__expf(-fabsf(x))); }
; __device__ void phaseA_tile(const Params& p, int l, int mt, int nt, char* smem) {
;     ...
;                 {
;                     const int c = g4 * 4;
;                     const float4 fb = *(const float4*)(p.b_f + l * 16 + c);
;                     const f32x4 v = acc[i][2];
;                     float4 lf = make_float4(logsigf(v[0] + fb.x), logsigf(v[1] + fb.y), logsigf(v[2] + fb.z), logsigf(v[3] + fb.w));
;                     float* o = samp ? (p.out + O_LFS + ((size_t)l * TSM + (row - TP)) * 16 + c)
;                                     : (p.out + O_LFP + ((size_t)l * TP + row) * 16 + c);
;                     *(float4*)o = lf;
;                     *(float4*)(lf_s + rl * 16 + c) = lf;
	v_pk_add_f32 v[114:115], v[102:103], v[114:115] neg_lo:[0,1] neg_hi:[0,1]
	v_pk_add_f32 v[94:95], v[94:95], v[116:117] neg_lo:[0,1] neg_hi:[0,1]
	s_nop 0
	v_pk_add_f32 v[94:95], v[94:95], v[102:103] neg_lo:[0,1] neg_hi:[0,1]
	s_nop 0
	v_pk_add_f32 v[88:89], v[88:89], v[94:95]
	v_pk_add_f32 v[94:95], v[114:115], v[98:99] neg_lo:[0,1] neg_hi:[0,1]
	s_nop 0
	v_pk_add_f32 v[88:89], v[94:95], v[88:89]
	v_pk_add_f32 v[94:95], v[100:101], v[112:113]
	v_pk_add_f32 v[88:89], v[116:117], v[88:89]
	v_pk_add_f32 v[98:99], v[94:95], v[100:101] neg_lo:[0,1] neg_hi:[0,1]
	v_pk_mul_f32 v[88:89], v[110:111], v[88:89]
	v_pk_add_f32 v[98:99], v[112:113], v[98:99] neg_lo:[0,1] neg_hi:[0,1]
	s_nop 0
	v_pk_add_f32 v[88:89], v[98:99], v[88:89]
	s_nop 0
	v_pk_add_f32 v[98:99], v[94:95], v[88:89]
	s_nop 0
	v_pk_mul_f32 v[100:101], v[98:99], v[98:99]
	v_pk_add_f32 v[94:95], v[98:99], v[94:95] neg_lo:[0,1] neg_hi:[0,1]
	v_pk_fma_f32 v[102:103], v[100:101], s[28:29], v[66:67] op_sel_hi:[1,0,0]
	v_pk_add_f32 v[88:89], v[88:89], v[94:95] neg_lo:[0,1] neg_hi:[0,1]
	v_ldexp_f32 v94, v98, 1
	v_pk_fma_f32 v[102:103], v[100:101], v[102:103], s[30:31] op_sel_hi:[1,1,0]
	v_ldexp_f32 v95, v99, 1
	v_pk_mul_f32 v[98:99], v[98:99], v[100:101]
	v_cvt_f32_i32_e32 v101, v120
	v_cvt_f32_i32_e32 v100, v97
	v_ldexp_f32 v111, v89, 1
	v_ashrrev_i32_e32 v89, 31, v81
	v_mov_b32_e32 v81, v93
	v_pk_mul_f32 v[112:113], v[100:101], s[12:13] op_sel_hi:[1,0]
	v_ldexp_f32 v88, v88, 1
	v_pk_fma_f32 v[114:115], v[100:101], s[12:13], v[112:113] op_sel_hi:[1,0,1] neg_lo:[0,0,1] neg_hi:[0,0,1]
	v_mov_b32_e32 v86, v112
	v_pk_fma_f32 v[100:101], v[100:101], s[14:15], v[114:115] op_sel_hi:[1,0,1]
	v_mov_b32_e32 v121, v113
	v_mov_b32_e32 v92, v100
	v_pk_add_f32 v[86:87], v[86:87], v[92:93]
	v_pk_add_f32 v[92:93], v[80:81], v[84:85]
	v_mov_b32_e32 v85, v91
	v_mov_b32_e32 v81, v93
	v_pk_add_f32 v[114:115], v[112:113], v[100:101]
	v_pk_add_f32 v[80:81], v[80:81], v[84:85]
	v_pk_add_f32 v[84:85], v[90:91], v[92:93]
	v_mov_b32_e32 v125, v115
	v_pk_add_f32 v[116:117], v[114:115], v[84:85]
	v_mov_b32_e32 v122, v84
	v_mov_b32_e32 v123, v117
	v_pk_add_f32 v[122:123], v[122:123], v[124:125] neg_lo:[0,1] neg_hi:[0,1]
	v_mov_b32_e32 v118, v116
	v_mov_b32_e32 v119, v115
	v_mov_b32_e32 v120, v114
	v_mov_b32_e32 v124, v114
	v_mov_b32_e32 v125, v117
	v_mov_b32_e32 v113, v123
	v_pk_add_f32 v[118:119], v[118:119], v[120:121] neg_lo:[0,1] neg_hi:[0,1]
	v_mov_b32_e32 v120, v84
	v_mov_b32_e32 v121, v101
	v_pk_add_f32 v[112:113], v[124:125], v[112:113] neg_lo:[0,1] neg_hi:[0,1]
	v_pk_add_f32 v[120:121], v[120:121], v[118:119] neg_lo:[0,1] neg_hi:[0,1]
	v_mov_b32_e32 v124, v112
	v_mov_b32_e32 v125, v119
	v_mov_b32_e32 v126, v116
	v_mov_b32_e32 v127, v85
	v_mov_b32_e32 v119, v91
	v_pk_add_f32 v[124:125], v[100:101], v[124:125] neg_lo:[0,1] neg_hi:[0,1]
	v_pk_add_f32 v[118:119], v[126:127], v[118:119] neg_lo:[0,1] neg_hi:[0,1]
	v_mov_b32_e32 v101, v115
	v_pk_add_f32 v[84:85], v[84:85], v[90:91] neg_lo:[0,1] neg_hi:[0,1]
	v_pk_add_f32 v[86:87], v[86:87], v[118:119] neg_lo:[0,1] neg_hi:[0,1]
	v_pk_add_f32 v[90:91], v[100:101], v[112:113] neg_lo:[0,1] neg_hi:[0,1]
	v_pk_add_f32 v[80:81], v[80:81], v[122:123] neg_lo:[0,1] neg_hi:[0,1]
	v_pk_add_f32 v[84:85], v[92:93], v[84:85] neg_lo:[0,1] neg_hi:[0,1]
	v_pk_add_f32 v[92:93], v[80:81], v[90:91]
	v_mov_b32_e32 v91, v121
	v_mov_b32_e32 v81, v87
	v_pk_add_f32 v[100:101], v[120:121], v[86:87]
	v_pk_add_f32 v[80:81], v[90:91], v[80:81]
	v_mov_b32_e32 v86, v92
	v_pk_add_f32 v[80:81], v[80:81], v[124:125] neg_lo:[0,1] neg_hi:[0,1]
	v_mov_b32_e32 v87, v101
	v_pk_add_f32 v[86:87], v[86:87], v[80:81] neg_lo:[0,1] neg_hi:[0,1]
	v_pk_add_f32 v[80:81], v[84:85], v[80:81] neg_lo:[0,1] neg_hi:[0,1]
	v_pk_add_f32 v[86:87], v[90:91], v[86:87] neg_lo:[0,1] neg_hi:[0,1]
	v_pk_add_f32 v[84:85], v[100:101], v[92:93]
	v_pk_add_f32 v[80:81], v[80:81], v[86:87]
	v_pk_add_f32 v[86:87], v[116:117], v[84:85]
	v_cndmask_b32_e64 v69, v69, v89, s[60:61]
	v_pk_add_f32 v[90:91], v[86:87], v[116:117] neg_lo:[0,1] neg_hi:[0,1]
	v_mov_b32_e32 v89, v111
	v_pk_add_f32 v[84:85], v[84:85], v[90:91] neg_lo:[0,1] neg_hi:[0,1]
	v_lshlrev_b64 v[68:69], 6, v[68:69]
	v_pk_add_f32 v[80:81], v[80:81], v[84:85]
	v_lshl_add_u64 v[68:69], s[6:7], 0, v[68:69]
	v_pk_add_f32 v[80:81], v[86:87], v[80:81]
	v_pk_mul_f32 v[86:87], v[98:99], v[102:103]
	v_cndmask_b32_e32 v80, v160, v80, vcc
	v_cmp_neq_f32_e32 vcc, s8, v128
	v_pk_add_f32 v[90:91], v[94:95], v[86:87]
	v_lshl_add_u64 v[68:69], v[68:69], 0, v[0:1]
	v_cndmask_b32_e32 v81, v160, v81, vcc
	v_cmp_ngt_f32_e32 vcc, -1.0, v128
	v_pk_add_f32 v[94:95], v[90:91], v[94:95] neg_lo:[0,1] neg_hi:[0,1]
	v_mov_b32_e32 v114, v90
	v_cndmask_b32_e32 v81, v161, v81, vcc
	v_cmp_ngt_f32_e32 vcc, -1.0, v83
	v_pk_add_f32 v[86:87], v[86:87], v[94:95] neg_lo:[0,1] neg_hi:[0,1]
	s_nop 0
	v_cndmask_b32_e32 v80, v161, v80, vcc
	v_cmp_neq_f32_e32 vcc, -1.0, v83
	v_pk_add_f32 v[98:99], v[88:89], v[86:87]
	v_mov_b32_e32 v95, v87
	v_cndmask_b32_e32 v80, v162, v80, vcc
	v_cmp_neq_f32_e32 vcc, -1.0, v128
	v_mov_b32_e32 v89, v99
	v_mov_b32_e32 v87, v91
	v_cndmask_b32_e32 v81, v162, v81, vcc
	v_cmp_lt_f32_e64 vcc, |v83|, s9
	v_cndmask_b32_e64 v81, v81, v128, s[0:1]
	v_pk_add_f32 v[86:87], v[88:89], v[86:87]
	v_cndmask_b32_e32 v80, v80, v83, vcc
	v_pk_add_f32 v[76:77], v[76:77], v[80:81] neg_lo:[0,1] neg_hi:[0,1]
	v_cvt_f32_i32_e32 v81, v132
	v_cvt_f32_i32_e32 v80, v130
	v_pk_add_f32 v[88:89], v[90:91], v[98:99]
	v_cmp_neq_f32_e32 vcc, s8, v129
	v_mov_b32_e32 v112, v88
	v_pk_mul_f32 v[84:85], v[80:81], s[12:13] op_sel_hi:[1,0]
	v_mov_b32_e32 v117, v89
	v_pk_fma_f32 v[92:93], v[80:81], s[12:13], v[84:85] op_sel_hi:[1,0,1] neg_lo:[0,0,1] neg_hi:[0,0,1]
; __device__ __forceinline__ float softplusf(float x) { return fmaxf(x, 0.f) + log1pf(__expf(-fabsf(x))); }
; __device__ __forceinline__ float logsigf(float x) { return fminf(x, 0.f) - log1pf(__expf(-fabsf(x))); }
; __device__ void phaseA_tile(const Params& p, int l, int mt, int nt, char* smem) {
;     ...
;                 for (int j = 0; j < 2; ++j) {
;                     const int c = j * 16 + g4 * 4;
;                     const float4 db = *(const float4*)(p.dt_bias + l * 32 + c);
;                     const f32x4 v = acc[i][j];
;                     *(float4*)(p.dtb + (size_t)row * 32 + c) =
;                         make_float4(softplusf(v[0] + db.x), softplusf(v[1] + db.y), softplusf(v[2] + db.z), softplusf(v[3] + db.w));
;                 }
;                 {
;                     const int c = g4 * 4;
;                     const float4 fb = *(const float4*)(p.b_f + l * 16 + c);
;                     const f32x4 v = acc[i][2];
;                     float4 lf = make_float4(logsigf(v[0] + fb.x), logsigf(v[1] + fb.y), logsigf(v[2] + fb.z), logsigf(v[3] + fb.w));
;                     float* o = samp ? (p.out + O_LFS + ((size_t)l * TSM + (row - TP)) * 16 + c)
;                                     : (p.out + O_LFP + ((size_t)l * TP + row) * 16 + c);
;                     *(float4*)o = lf;
;                     *(float4*)(lf_s + rl * 16 + c) = lf;
;                 }
;             }
	v_mov_b32_e32 v94, v84
	v_pk_fma_f32 v[80:81], v[80:81], s[14:15], v[92:93] op_sel_hi:[1,0,1]
	v_cmp_lt_f32_e64 s[0:1], |v131|, s9
	v_pk_add_f32 v[92:93], v[84:85], v[80:81]
	v_mov_b32_e32 v110, v80
	v_pk_add_f32 v[100:101], v[92:93], v[88:89]
	v_mov_b32_e32 v115, v93
	v_mov_b32_e32 v113, v101
	v_pk_add_f32 v[112:113], v[112:113], v[114:115] neg_lo:[0,1] neg_hi:[0,1]
	v_pk_add_f32 v[94:95], v[94:95], v[110:111]
	v_mov_b32_e32 v102, v100
	v_mov_b32_e32 v103, v93
	v_mov_b32_e32 v110, v92
	v_mov_b32_e32 v111, v85
	v_mov_b32_e32 v114, v92
	v_mov_b32_e32 v115, v101
	v_mov_b32_e32 v85, v113
	v_pk_add_f32 v[102:103], v[102:103], v[110:111] neg_lo:[0,1] neg_hi:[0,1]
	v_mov_b32_e32 v110, v88
	v_mov_b32_e32 v111, v81
	v_pk_add_f32 v[84:85], v[114:115], v[84:85] neg_lo:[0,1] neg_hi:[0,1]
	v_pk_add_f32 v[110:111], v[110:111], v[102:103] neg_lo:[0,1] neg_hi:[0,1]
	v_mov_b32_e32 v114, v84
	v_mov_b32_e32 v115, v103
	v_mov_b32_e32 v116, v100
	v_mov_b32_e32 v103, v91
	v_pk_add_f32 v[114:115], v[80:81], v[114:115] neg_lo:[0,1] neg_hi:[0,1]
	v_pk_add_f32 v[102:103], v[116:117], v[102:103] neg_lo:[0,1] neg_hi:[0,1]
	v_mov_b32_e32 v81, v93
	v_pk_add_f32 v[88:89], v[88:89], v[90:91] neg_lo:[0,1] neg_hi:[0,1]
	v_pk_add_f32 v[90:91], v[94:95], v[102:103] neg_lo:[0,1] neg_hi:[0,1]
	v_pk_add_f32 v[80:81], v[80:81], v[84:85] neg_lo:[0,1] neg_hi:[0,1]
	v_pk_add_f32 v[84:85], v[86:87], v[112:113] neg_lo:[0,1] neg_hi:[0,1]
	v_pk_add_f32 v[92:93], v[110:111], v[90:91]
	v_pk_add_f32 v[86:87], v[84:85], v[80:81]
	v_mov_b32_e32 v81, v111
	v_mov_b32_e32 v85, v91
	v_pk_add_f32 v[84:85], v[80:81], v[84:85]
	v_mov_b32_e32 v90, v86
	v_pk_add_f32 v[84:85], v[84:85], v[114:115] neg_lo:[0,1] neg_hi:[0,1]
	v_mov_b32_e32 v91, v93
	v_pk_add_f32 v[88:89], v[98:99], v[88:89] neg_lo:[0,1] neg_hi:[0,1]
	v_pk_add_f32 v[90:91], v[90:91], v[84:85] neg_lo:[0,1] neg_hi:[0,1]
	v_pk_add_f32 v[84:85], v[88:89], v[84:85] neg_lo:[0,1] neg_hi:[0,1]
	v_pk_add_f32 v[80:81], v[80:81], v[90:91] neg_lo:[0,1] neg_hi:[0,1]
	s_nop 0
	v_pk_add_f32 v[80:81], v[84:85], v[80:81]
	v_pk_add_f32 v[84:85], v[92:93], v[86:87]
	s_nop 0
	v_pk_add_f32 v[86:87], v[100:101], v[84:85]
	s_nop 0
	v_pk_add_f32 v[88:89], v[86:87], v[100:101] neg_lo:[0,1] neg_hi:[0,1]
	s_nop 0
	v_pk_add_f32 v[84:85], v[84:85], v[88:89] neg_lo:[0,1] neg_hi:[0,1]
	s_nop 0
	v_pk_add_f32 v[80:81], v[80:81], v[84:85]
	s_nop 0
	v_pk_add_f32 v[80:81], v[86:87], v[80:81]
	s_nop 0
	v_cndmask_b32_e32 v80, v160, v80, vcc
	v_cmp_neq_f32_e32 vcc, s8, v131
	s_nop 1
	v_cndmask_b32_e32 v81, v160, v81, vcc
	v_cmp_ngt_f32_e32 vcc, -1.0, v131
	s_nop 1
	v_cndmask_b32_e32 v81, v161, v81, vcc
	v_cmp_ngt_f32_e32 vcc, -1.0, v129
	s_nop 1
	v_cndmask_b32_e32 v80, v161, v80, vcc
	v_cmp_neq_f32_e32 vcc, -1.0, v129
	s_nop 1
	v_cndmask_b32_e32 v80, v162, v80, vcc
	v_cmp_neq_f32_e32 vcc, -1.0, v131
	s_nop 1
	v_cndmask_b32_e32 v81, v162, v81, vcc
	v_cmp_lt_f32_e64 vcc, |v129|, s9
	v_cndmask_b32_e64 v81, v81, v131, s[0:1]
	s_nop 0
	v_cndmask_b32_e32 v80, v80, v129, vcc
	v_pk_add_f32 v[78:79], v[78:79], v[80:81] neg_lo:[0,1] neg_hi:[0,1]
	global_store_dwordx4 v[68:69], v[76:79], off
	v_lshl_or_b32 v68, v82, 6, v0
	ds_write_b128 v68, v[76:79]
	global_load_dwordx4 v[78:81], v0, s[74:75]
	v_or_b32_e32 v82, 32, v71
	v_add_u32_e32 v68, s54, v82
	v_ashrrev_i32_e32 v69, 31, v68
	v_lshlrev_b64 v[76:77], 7, v[68:69]
	v_lshl_add_u64 v[76:77], s[10:11], 0, v[76:77]
	v_lshl_add_u64 v[76:77], v[76:77], 0, v[0:1]
	v_or_b32_e32 v71, 48, v71
	s_waitcnt vmcnt(0)
	v_add_f32_e32 v83, v30, v78
	v_max_f32_e32 v78, 0, v83
	v_mul_f32_e64 v83, |v83|, s2
	v_exp_f32_e32 v83, v83
	s_nop 0
	v_add_f32_e32 v86, 1.0, v83
	v_add_f32_e32 v84, -1.0, v86
	v_sub_f32_e32 v85, v84, v86
	v_add_f32_e32 v85, 1.0, v85
	v_sub_f32_e32 v84, v83, v84
	v_add_f32_e32 v87, v84, v85
	v_frexp_mant_f32_e32 v84, v86
	v_cmp_gt_f32_e32 vcc, s26, v84
	v_cvt_f64_f32_e32 v[84:85], v86
	v_frexp_exp_i32_f64_e32 v84, v[84:85]
	v_subbrev_co_u32_e32 v97, vcc, 0, v84, vcc
	v_sub_u32_e32 v85, 0, v97
	v_ldexp_f32 v84, v86, v85
	v_ldexp_f32 v86, v87, v85
	v_add_f32_e32 v85, v31, v79
	v_max_f32_e32 v79, 0, v85
	v_mul_f32_e64 v85, |v85|, s2
	v_exp_f32_e32 v130, v85
	s_nop 0
	v_add_f32_e32 v85, 1.0, v130
	v_add_f32_e32 v87, -1.0, v85
	v_sub_f32_e32 v88, v87, v85
	v_add_f32_e32 v88, 1.0, v88
	v_sub_f32_e32 v87, v130, v87
	v_add_f32_e32 v87, v87, v88
	v_frexp_mant_f32_e32 v88, v85
	v_cmp_gt_f32_e32 vcc, s26, v88
	v_cvt_f64_f32_e32 v[88:89], v85
	v_frexp_exp_i32_f64_e32 v88, v[88:89]
	v_subbrev_co_u32_e32 v122, vcc, 0, v88, vcc
	v_sub_u32_e32 v88, 0, v122
	v_ldexp_f32 v85, v85, v88
	v_ldexp_f32 v87, v87, v88
	v_pk_add_f32 v[88:89], v[84:85], 1.0 op_sel_hi:[1,0]
	v_pk_add_f32 v[98:99], v[84:85], -1.0 op_sel_hi:[1,0]
	v_pk_add_f32 v[90:91], v[88:89], -1.0 op_sel_hi:[1,0]
	v_pk_add_f32 v[100:101], v[98:99], 1.0 op_sel_hi:[1,0]
	v_pk_add_f32 v[90:91], v[84:85], v[90:91] neg_lo:[0,1] neg_hi:[0,1]
	v_pk_add_f32 v[84:85], v[84:85], v[100:101] neg_lo:[0,1] neg_hi:[0,1]
	v_pk_add_f32 v[90:91], v[86:87], v[90:91]
	v_pk_add_f32 v[84:85], v[86:87], v[84:85]
	v_pk_add_f32 v[92:93], v[88:89], v[90:91]
	v_pk_add_f32 v[86:87], v[98:99], v[84:85]
	v_rcp_f32_e32 v94, v92
	v_rcp_f32_e32 v95, v93
	v_pk_add_f32 v[88:89], v[92:93], v[88:89] neg_lo:[0,1] neg_hi:[0,1]
	v_pk_add_f32 v[98:99], v[86:87], v[98:99] neg_lo:[0,1] neg_hi:[0,1]
	v_pk_add_f32 v[88:89], v[90:91], v[88:89] neg_lo:[0,1] neg_hi:[0,1]
	v_pk_mul_f32 v[90:91], v[86:87], v[94:95]
	v_pk_add_f32 v[84:85], v[84:85], v[98:99] neg_lo:[0,1] neg_hi:[0,1]
	v_pk_mul_f32 v[98:99], v[92:93], v[90:91]
	v_cmp_lt_f32_e64 s[0:1], |v130|, s9
	v_pk_fma_f32 v[100:101], v[90:91], v[92:93], v[98:99] neg_lo:[0,0,1] neg_hi:[0,0,1]
; __device__ __forceinline__ float softplusf(float x) { return fmaxf(x, 0.f) + log1pf(__expf(-fabsf(x))); }
; __device__ void phaseA_tile(const Params& p, int l, int mt, int nt, char* smem) {
;     ...
;                 for (int j = 0; j < 2; ++j) {
;                     const int c = j * 16 + g4 * 4;
;                     const float4 db = *(const float4*)(p.dt_bias + l * 32 + c);
;                     const f32x4 v = acc[i][j];
;                     *(float4*)(p.dtb + (size_t)row * 32 + c) =
;                         make_float4(softplusf(v[0] + db.x), softplusf(v[1] + db.y), softplusf(v[2] + db.z), softplusf(v[3] + db.w));
;                 }
	s_nop 0
	v_pk_fma_f32 v[100:101], v[90:91], v[88:89], v[100:101]
	s_nop 0
	v_pk_add_f32 v[102:103], v[98:99], v[100:101]
	s_nop 0
	v_pk_add_f32 v[110:111], v[86:87], v[102:103] neg_lo:[0,1] neg_hi:[0,1]
	v_pk_add_f32 v[98:99], v[102:103], v[98:99] neg_lo:[0,1] neg_hi:[0,1]
	v_pk_add_f32 v[86:87], v[86:87], v[110:111] neg_lo:[0,1] neg_hi:[0,1]
	s_nop 0
	v_pk_add_f32 v[86:87], v[86:87], v[102:103] neg_lo:[0,1] neg_hi:[0,1]
	s_nop 0
	v_pk_add_f32 v[84:85], v[84:85], v[86:87]
	v_pk_add_f32 v[86:87], v[98:99], v[100:101] neg_lo:[0,1] neg_hi:[0,1]
	s_nop 0
	v_pk_add_f32 v[84:85], v[86:87], v[84:85]
	s_nop 0
	v_pk_add_f32 v[86:87], v[110:111], v[84:85]
	s_nop 0
	v_pk_mul_f32 v[98:99], v[94:95], v[86:87]
	s_nop 0
	v_pk_mul_f32 v[100:101], v[92:93], v[98:99]
	s_nop 0
	v_pk_fma_f32 v[92:93], v[98:99], v[92:93], v[100:101] neg_lo:[0,0,1] neg_hi:[0,0,1]
	s_nop 0
	v_pk_fma_f32 v[88:89], v[98:99], v[88:89], v[92:93]
	v_pk_add_f32 v[92:93], v[110:111], v[86:87] neg_lo:[0,1] neg_hi:[0,1]
	s_nop 0
	v_pk_add_f32 v[84:85], v[84:85], v[92:93]
	v_pk_add_f32 v[92:93], v[100:101], v[88:89]
	s_nop 0
	v_pk_add_f32 v[102:103], v[86:87], v[92:93] neg_lo:[0,1] neg_hi:[0,1]
	v_pk_add_f32 v[100:101], v[92:93], v[100:101] neg_lo:[0,1] neg_hi:[0,1]
	v_pk_add_f32 v[86:87], v[86:87], v[102:103] neg_lo:[0,1] neg_hi:[0,1]
	s_nop 0
	v_pk_add_f32 v[86:87], v[86:87], v[92:93] neg_lo:[0,1] neg_hi:[0,1]
	s_nop 0
	v_pk_add_f32 v[84:85], v[84:85], v[86:87]
	v_pk_add_f32 v[86:87], v[100:101], v[88:89] neg_lo:[0,1] neg_hi:[0,1]
	s_nop 0
	v_pk_add_f32 v[84:85], v[86:87], v[84:85]
	v_pk_add_f32 v[86:87], v[90:91], v[98:99]
	v_pk_add_f32 v[84:85], v[102:103], v[84:85]
	v_pk_add_f32 v[88:89], v[86:87], v[90:91] neg_lo:[0,1] neg_hi:[0,1]
	v_pk_mul_f32 v[84:85], v[94:95], v[84:85]
	v_pk_add_f32 v[88:89], v[98:99], v[88:89] neg_lo:[0,1] neg_hi:[0,1]
	s_nop 0
	v_pk_add_f32 v[84:85], v[88:89], v[84:85]
	s_nop 0
	v_pk_add_f32 v[88:89], v[86:87], v[84:85]
	s_nop 0
	v_pk_add_f32 v[86:87], v[88:89], v[86:87] neg_lo:[0,1] neg_hi:[0,1]
	v_pk_mul_f32 v[90:91], v[88:89], v[88:89]
	v_pk_add_f32 v[84:85], v[84:85], v[86:87] neg_lo:[0,1] neg_hi:[0,1]
	v_pk_fma_f32 v[92:93], v[90:91], s[28:29], v[66:67] op_sel_hi:[1,0,0]
	v_ldexp_f32 v95, v85, 1
	v_add_f32_e32 v85, v32, v80
	v_max_f32_e32 v80, 0, v85
	v_mul_f32_e64 v85, |v85|, s2
	v_exp_f32_e32 v131, v85
	v_ldexp_f32 v86, v88, 1
	v_pk_fma_f32 v[92:93], v[90:91], v[92:93], s[30:31] op_sel_hi:[1,1,0]
	v_ldexp_f32 v87, v89, 1
	v_add_f32_e32 v85, 1.0, v131
	v_pk_mul_f32 v[88:89], v[88:89], v[90:91]
	v_add_f32_e32 v90, -1.0, v85
	v_sub_f32_e32 v91, v90, v85
	v_add_f32_e32 v91, 1.0, v91
	v_sub_f32_e32 v90, v131, v90
	v_add_f32_e32 v94, v90, v91
	v_frexp_mant_f32_e32 v90, v85
	v_cmp_gt_f32_e32 vcc, s26, v90
	v_cvt_f64_f32_e32 v[90:91], v85
	v_frexp_exp_i32_f64_e32 v90, v[90:91]
	v_subbrev_co_u32_e32 v132, vcc, 0, v90, vcc
	v_sub_u32_e32 v91, 0, v132
	v_ldexp_f32 v90, v85, v91
	v_add_f32_e32 v85, v33, v81
	v_max_f32_e32 v81, 0, v85
	v_mul_f32_e64 v85, |v85|, s2
	v_exp_f32_e32 v133, v85
	v_ldexp_f32 v98, v94, v91
	v_pk_mul_f32 v[88:89], v[88:89], v[92:93]
	v_ldexp_f32 v84, v84, 1
	v_add_f32_e32 v85, 1.0, v133
	v_add_f32_e32 v91, -1.0, v85
	v_sub_f32_e32 v94, v91, v85
	v_add_f32_e32 v94, 1.0, v94
	v_sub_f32_e32 v91, v133, v91
	v_add_f32_e32 v94, v91, v94
	v_frexp_mant_f32_e32 v91, v85
	v_cvt_f64_f32_e32 v[100:101], v85
	v_cmp_gt_f32_e32 vcc, s26, v91
	v_frexp_exp_i32_f64_e32 v91, v[100:101]
	v_pk_add_f32 v[92:93], v[86:87], v[88:89]
	v_subbrev_co_u32_e32 v134, vcc, 0, v91, vcc
	v_sub_u32_e32 v99, 0, v134
	v_ldexp_f32 v91, v85, v99
	v_pk_add_f32 v[100:101], v[90:91], 1.0 op_sel_hi:[1,0]
	v_ldexp_f32 v99, v94, v99
	v_pk_add_f32 v[102:103], v[100:101], -1.0 op_sel_hi:[1,0]
	v_pk_add_f32 v[114:115], v[90:91], -1.0 op_sel_hi:[1,0]
	v_pk_add_f32 v[102:103], v[90:91], v[102:103] neg_lo:[0,1] neg_hi:[0,1]
	v_pk_add_f32 v[116:117], v[114:115], 1.0 op_sel_hi:[1,0]
	v_pk_add_f32 v[102:103], v[98:99], v[102:103]
	v_pk_add_f32 v[90:91], v[90:91], v[116:117] neg_lo:[0,1] neg_hi:[0,1]
	v_pk_add_f32 v[110:111], v[100:101], v[102:103]
	v_pk_add_f32 v[90:91], v[98:99], v[90:91]
	v_rcp_f32_e32 v112, v110
	v_rcp_f32_e32 v113, v111
	v_pk_add_f32 v[98:99], v[114:115], v[90:91]
	v_pk_add_f32 v[100:101], v[110:111], v[100:101] neg_lo:[0,1] neg_hi:[0,1]
	v_pk_add_f32 v[114:115], v[98:99], v[114:115] neg_lo:[0,1] neg_hi:[0,1]
	v_pk_add_f32 v[100:101], v[102:103], v[100:101] neg_lo:[0,1] neg_hi:[0,1]
	v_pk_mul_f32 v[102:103], v[98:99], v[112:113]
	v_pk_add_f32 v[90:91], v[90:91], v[114:115] neg_lo:[0,1] neg_hi:[0,1]
	v_pk_mul_f32 v[114:115], v[110:111], v[102:103]
	v_pk_add_f32 v[86:87], v[92:93], v[86:87] neg_lo:[0,1] neg_hi:[0,1]
	v_pk_fma_f32 v[116:117], v[102:103], v[110:111], v[114:115] neg_lo:[0,0,1] neg_hi:[0,0,1]
	v_pk_add_f32 v[86:87], v[88:89], v[86:87] neg_lo:[0,1] neg_hi:[0,1]
	v_pk_fma_f32 v[116:117], v[102:103], v[100:101], v[116:117]
	v_mov_b32_e32 v89, v87
	v_pk_add_f32 v[118:119], v[114:115], v[116:117]
	v_mov_b32_e32 v85, v95
	v_pk_add_f32 v[120:121], v[98:99], v[118:119] neg_lo:[0,1] neg_hi:[0,1]
	v_pk_add_f32 v[114:115], v[118:119], v[114:115] neg_lo:[0,1] neg_hi:[0,1]
	v_pk_add_f32 v[98:99], v[98:99], v[120:121] neg_lo:[0,1] neg_hi:[0,1]
	v_mov_b32_e32 v126, v92
	v_pk_add_f32 v[98:99], v[98:99], v[118:119] neg_lo:[0,1] neg_hi:[0,1]
	v_cmp_neq_f32_e32 vcc, s8, v83
	v_pk_add_f32 v[90:91], v[90:91], v[98:99]
	v_pk_add_f32 v[98:99], v[114:115], v[116:117] neg_lo:[0,1] neg_hi:[0,1]
	s_nop 0
	v_pk_add_f32 v[90:91], v[98:99], v[90:91]
	s_nop 0
	v_pk_add_f32 v[98:99], v[120:121], v[90:91]
	s_nop 0
	v_pk_mul_f32 v[114:115], v[112:113], v[98:99]
	s_nop 0
; __device__ __forceinline__ float softplusf(float x) { return fmaxf(x, 0.f) + log1pf(__expf(-fabsf(x))); }
; __device__ void phaseA_tile(const Params& p, int l, int mt, int nt, char* smem) {
;     ...
;                 for (int j = 0; j < 2; ++j) {
;                     const int c = j * 16 + g4 * 4;
;                     const float4 db = *(const float4*)(p.dt_bias + l * 32 + c);
;                     const f32x4 v = acc[i][j];
;                     *(float4*)(p.dtb + (size_t)row * 32 + c) =
;                         make_float4(softplusf(v[0] + db.x), softplusf(v[1] + db.y), softplusf(v[2] + db.z), softplusf(v[3] + db.w));
;                 }
	v_pk_mul_f32 v[116:117], v[110:111], v[114:115]
	s_nop 0
	v_pk_fma_f32 v[110:111], v[114:115], v[110:111], v[116:117] neg_lo:[0,0,1] neg_hi:[0,0,1]
	s_nop 0
	v_pk_fma_f32 v[100:101], v[114:115], v[100:101], v[110:111]
	v_pk_add_f32 v[110:111], v[120:121], v[98:99] neg_lo:[0,1] neg_hi:[0,1]
	s_nop 0
	v_pk_add_f32 v[90:91], v[90:91], v[110:111]
	v_pk_add_f32 v[110:111], v[116:117], v[100:101]
	s_nop 0
	v_pk_add_f32 v[118:119], v[98:99], v[110:111] neg_lo:[0,1] neg_hi:[0,1]
	v_pk_add_f32 v[116:117], v[110:111], v[116:117] neg_lo:[0,1] neg_hi:[0,1]
	v_pk_add_f32 v[98:99], v[98:99], v[118:119] neg_lo:[0,1] neg_hi:[0,1]
	s_nop 0
	v_pk_add_f32 v[98:99], v[98:99], v[110:111] neg_lo:[0,1] neg_hi:[0,1]
	s_nop 0
	v_pk_add_f32 v[90:91], v[90:91], v[98:99]
	v_pk_add_f32 v[98:99], v[116:117], v[100:101] neg_lo:[0,1] neg_hi:[0,1]
	s_nop 0
	v_pk_add_f32 v[90:91], v[98:99], v[90:91]
	v_pk_add_f32 v[98:99], v[102:103], v[114:115]
	v_pk_add_f32 v[90:91], v[118:119], v[90:91]
	v_pk_add_f32 v[100:101], v[98:99], v[102:103] neg_lo:[0,1] neg_hi:[0,1]
	v_pk_mul_f32 v[90:91], v[112:113], v[90:91]
	v_pk_add_f32 v[100:101], v[114:115], v[100:101] neg_lo:[0,1] neg_hi:[0,1]
	s_nop 0
	v_pk_add_f32 v[90:91], v[100:101], v[90:91]
	s_nop 0
	v_pk_add_f32 v[100:101], v[98:99], v[90:91]
	s_nop 0
	v_pk_mul_f32 v[102:103], v[100:101], v[100:101]
	v_pk_add_f32 v[98:99], v[100:101], v[98:99] neg_lo:[0,1] neg_hi:[0,1]
	v_pk_fma_f32 v[110:111], v[102:103], s[28:29], v[66:67] op_sel_hi:[1,0,0]
	v_pk_add_f32 v[90:91], v[90:91], v[98:99] neg_lo:[0,1] neg_hi:[0,1]
	v_ldexp_f32 v98, v100, 1
	v_pk_fma_f32 v[110:111], v[102:103], v[110:111], s[30:31] op_sel_hi:[1,1,0]
	v_ldexp_f32 v99, v101, 1
	v_pk_mul_f32 v[100:101], v[100:101], v[102:103]
	v_cvt_f32_i32_e32 v103, v122
	v_cvt_f32_i32_e32 v102, v97
	v_ldexp_f32 v113, v91, 1
	v_ldexp_f32 v90, v90, 1
	v_mov_b32_e32 v91, v113
	v_pk_mul_f32 v[114:115], v[102:103], s[12:13] op_sel_hi:[1,0]
	s_nop 0
	v_pk_fma_f32 v[116:117], v[102:103], s[12:13], v[114:115] op_sel_hi:[1,0,1] neg_lo:[0,0,1] neg_hi:[0,0,1]
	v_mov_b32_e32 v88, v114
	v_pk_fma_f32 v[102:103], v[102:103], s[14:15], v[116:117] op_sel_hi:[1,0,1]
	v_mov_b32_e32 v123, v115
	v_mov_b32_e32 v94, v102
	v_pk_add_f32 v[88:89], v[88:89], v[94:95]
	v_pk_add_f32 v[94:95], v[84:85], v[86:87]
	v_mov_b32_e32 v87, v93
	v_mov_b32_e32 v85, v95
	v_pk_add_f32 v[116:117], v[114:115], v[102:103]
	v_pk_add_f32 v[84:85], v[84:85], v[86:87]
	v_pk_add_f32 v[86:87], v[92:93], v[94:95]
	v_mov_b32_e32 v127, v117
	v_pk_add_f32 v[118:119], v[116:117], v[86:87]
	v_mov_b32_e32 v124, v86
	v_mov_b32_e32 v125, v119
	v_pk_add_f32 v[124:125], v[124:125], v[126:127] neg_lo:[0,1] neg_hi:[0,1]
	v_mov_b32_e32 v120, v118
	v_mov_b32_e32 v121, v117
	v_mov_b32_e32 v122, v116
	v_mov_b32_e32 v126, v116
	v_mov_b32_e32 v127, v119
	v_mov_b32_e32 v115, v125
	v_pk_add_f32 v[120:121], v[120:121], v[122:123] neg_lo:[0,1] neg_hi:[0,1]
	v_mov_b32_e32 v122, v86
	v_mov_b32_e32 v123, v103
	v_pk_add_f32 v[114:115], v[126:127], v[114:115] neg_lo:[0,1] neg_hi:[0,1]
	v_pk_add_f32 v[122:123], v[122:123], v[120:121] neg_lo:[0,1] neg_hi:[0,1]
	v_mov_b32_e32 v126, v114
	v_mov_b32_e32 v127, v121
	v_mov_b32_e32 v128, v118
	v_mov_b32_e32 v129, v87
	v_mov_b32_e32 v121, v93
	v_pk_add_f32 v[126:127], v[102:103], v[126:127] neg_lo:[0,1] neg_hi:[0,1]
	v_pk_add_f32 v[120:121], v[128:129], v[120:121] neg_lo:[0,1] neg_hi:[0,1]
	v_mov_b32_e32 v103, v117
	v_pk_add_f32 v[86:87], v[86:87], v[92:93] neg_lo:[0,1] neg_hi:[0,1]
	v_pk_add_f32 v[88:89], v[88:89], v[120:121] neg_lo:[0,1] neg_hi:[0,1]
	v_pk_add_f32 v[92:93], v[102:103], v[114:115] neg_lo:[0,1] neg_hi:[0,1]
	v_pk_add_f32 v[84:85], v[84:85], v[124:125] neg_lo:[0,1] neg_hi:[0,1]
	v_pk_add_f32 v[86:87], v[94:95], v[86:87] neg_lo:[0,1] neg_hi:[0,1]
	v_pk_add_f32 v[94:95], v[84:85], v[92:93]
	v_mov_b32_e32 v93, v123
	v_mov_b32_e32 v85, v89
	v_pk_add_f32 v[102:103], v[122:123], v[88:89]
	v_pk_add_f32 v[84:85], v[92:93], v[84:85]
	v_mov_b32_e32 v88, v94
	v_pk_add_f32 v[84:85], v[84:85], v[126:127] neg_lo:[0,1] neg_hi:[0,1]
	v_mov_b32_e32 v89, v103
	v_pk_add_f32 v[88:89], v[88:89], v[84:85] neg_lo:[0,1] neg_hi:[0,1]
	v_pk_add_f32 v[84:85], v[86:87], v[84:85] neg_lo:[0,1] neg_hi:[0,1]
	v_pk_add_f32 v[88:89], v[92:93], v[88:89] neg_lo:[0,1] neg_hi:[0,1]
	v_pk_add_f32 v[86:87], v[102:103], v[94:95]
	v_pk_add_f32 v[84:85], v[84:85], v[88:89]
	v_pk_add_f32 v[88:89], v[118:119], v[86:87]
	s_nop 0
	v_pk_add_f32 v[92:93], v[88:89], v[118:119] neg_lo:[0,1] neg_hi:[0,1]
	s_nop 0
	v_pk_add_f32 v[86:87], v[86:87], v[92:93] neg_lo:[0,1] neg_hi:[0,1]
	s_nop 0
	v_pk_add_f32 v[84:85], v[84:85], v[86:87]
	s_nop 0
	v_pk_add_f32 v[84:85], v[88:89], v[84:85]
	v_pk_mul_f32 v[88:89], v[100:101], v[110:111]
	v_cndmask_b32_e32 v84, v160, v84, vcc
	v_cmp_neq_f32_e32 vcc, s8, v130
	v_pk_add_f32 v[92:93], v[98:99], v[88:89]
	s_nop 0
	v_cndmask_b32_e32 v85, v160, v85, vcc
	v_cmp_ngt_f32_e32 vcc, -1.0, v130
	v_pk_add_f32 v[98:99], v[92:93], v[98:99] neg_lo:[0,1] neg_hi:[0,1]
	v_mov_b32_e32 v116, v92
	v_cndmask_b32_e32 v85, v161, v85, vcc
	v_cmp_ngt_f32_e32 vcc, -1.0, v83
	v_pk_add_f32 v[88:89], v[88:89], v[98:99] neg_lo:[0,1] neg_hi:[0,1]
	s_nop 0
	v_cndmask_b32_e32 v84, v161, v84, vcc
	v_cmp_neq_f32_e32 vcc, -1.0, v83
	v_pk_add_f32 v[100:101], v[90:91], v[88:89]
	v_mov_b32_e32 v99, v89
	v_cndmask_b32_e32 v84, v162, v84, vcc
	v_cmp_neq_f32_e32 vcc, -1.0, v130
	v_mov_b32_e32 v91, v101
	v_mov_b32_e32 v89, v93
	v_cndmask_b32_e32 v85, v162, v85, vcc
	v_cmp_lt_f32_e64 vcc, |v83|, s9
	v_cndmask_b32_e64 v85, v85, v130, s[0:1]
	v_pk_add_f32 v[88:89], v[90:91], v[88:89]
	v_cndmask_b32_e32 v84, v84, v83, vcc
	v_pk_add_f32 v[78:79], v[78:79], v[84:85]
; __device__ __forceinline__ float softplusf(float x) { return fmaxf(x, 0.f) + log1pf(__expf(-fabsf(x))); }
; __device__ void phaseA_tile(const Params& p, int l, int mt, int nt, char* smem) {
;     ...
;                 for (int j = 0; j < 2; ++j) {
;                     const int c = j * 16 + g4 * 4;
;                     const float4 db = *(const float4*)(p.dt_bias + l * 32 + c);
;                     const f32x4 v = acc[i][j];
;                     *(float4*)(p.dtb + (size_t)row * 32 + c) =
;                         make_float4(softplusf(v[0] + db.x), softplusf(v[1] + db.y), softplusf(v[2] + db.z), softplusf(v[3] + db.w));
;                 }
	v_cvt_f32_i32_e32 v85, v134
	v_cvt_f32_i32_e32 v84, v132
	v_pk_add_f32 v[90:91], v[92:93], v[100:101]
	v_cmp_neq_f32_e32 vcc, s8, v131
	v_mov_b32_e32 v114, v90
	v_pk_mul_f32 v[86:87], v[84:85], s[12:13] op_sel_hi:[1,0]
	v_mov_b32_e32 v119, v91
	v_pk_fma_f32 v[94:95], v[84:85], s[12:13], v[86:87] op_sel_hi:[1,0,1] neg_lo:[0,0,1] neg_hi:[0,0,1]
	v_mov_b32_e32 v98, v86
	v_pk_fma_f32 v[84:85], v[84:85], s[14:15], v[94:95] op_sel_hi:[1,0,1]
	v_cmp_lt_f32_e64 s[0:1], |v133|, s9
	v_pk_add_f32 v[94:95], v[86:87], v[84:85]
	v_mov_b32_e32 v112, v84
	v_pk_add_f32 v[102:103], v[94:95], v[90:91]
	v_mov_b32_e32 v117, v95
	v_mov_b32_e32 v115, v103
	v_pk_add_f32 v[114:115], v[114:115], v[116:117] neg_lo:[0,1] neg_hi:[0,1]
	v_pk_add_f32 v[98:99], v[98:99], v[112:113]
	v_mov_b32_e32 v110, v102
	v_mov_b32_e32 v111, v95
	v_mov_b32_e32 v112, v94
	v_mov_b32_e32 v113, v87
	v_mov_b32_e32 v116, v94
	v_mov_b32_e32 v117, v103
	v_mov_b32_e32 v87, v115
	v_pk_add_f32 v[110:111], v[110:111], v[112:113] neg_lo:[0,1] neg_hi:[0,1]
	v_mov_b32_e32 v112, v90
	v_mov_b32_e32 v113, v85
	v_pk_add_f32 v[86:87], v[116:117], v[86:87] neg_lo:[0,1] neg_hi:[0,1]
	v_pk_add_f32 v[112:113], v[112:113], v[110:111] neg_lo:[0,1] neg_hi:[0,1]
	v_mov_b32_e32 v116, v86
	v_mov_b32_e32 v117, v111
	v_mov_b32_e32 v118, v102
	v_mov_b32_e32 v111, v93
	v_pk_add_f32 v[116:117], v[84:85], v[116:117] neg_lo:[0,1] neg_hi:[0,1]
	v_pk_add_f32 v[110:111], v[118:119], v[110:111] neg_lo:[0,1] neg_hi:[0,1]
	v_mov_b32_e32 v85, v95
	v_pk_add_f32 v[90:91], v[90:91], v[92:93] neg_lo:[0,1] neg_hi:[0,1]
	v_pk_add_f32 v[92:93], v[98:99], v[110:111] neg_lo:[0,1] neg_hi:[0,1]
	v_pk_add_f32 v[84:85], v[84:85], v[86:87] neg_lo:[0,1] neg_hi:[0,1]
	v_pk_add_f32 v[86:87], v[88:89], v[114:115] neg_lo:[0,1] neg_hi:[0,1]
	v_pk_add_f32 v[94:95], v[112:113], v[92:93]
	v_pk_add_f32 v[88:89], v[86:87], v[84:85]
	v_mov_b32_e32 v85, v113
	v_mov_b32_e32 v87, v93
	v_pk_add_f32 v[86:87], v[84:85], v[86:87]
	v_mov_b32_e32 v92, v88
	v_pk_add_f32 v[86:87], v[86:87], v[116:117] neg_lo:[0,1] neg_hi:[0,1]
	v_mov_b32_e32 v93, v95
	v_pk_add_f32 v[90:91], v[100:101], v[90:91] neg_lo:[0,1] neg_hi:[0,1]
	v_pk_add_f32 v[92:93], v[92:93], v[86:87] neg_lo:[0,1] neg_hi:[0,1]
	v_pk_add_f32 v[86:87], v[90:91], v[86:87] neg_lo:[0,1] neg_hi:[0,1]
	v_pk_add_f32 v[84:85], v[84:85], v[92:93] neg_lo:[0,1] neg_hi:[0,1]
	s_nop 0
	v_pk_add_f32 v[84:85], v[86:87], v[84:85]
	v_pk_add_f32 v[86:87], v[94:95], v[88:89]
	s_nop 0
	v_pk_add_f32 v[88:89], v[102:103], v[86:87]
	s_nop 0
	v_pk_add_f32 v[90:91], v[88:89], v[102:103] neg_lo:[0,1] neg_hi:[0,1]
	s_nop 0
	v_pk_add_f32 v[86:87], v[86:87], v[90:91] neg_lo:[0,1] neg_hi:[0,1]
	s_nop 0
	v_pk_add_f32 v[84:85], v[84:85], v[86:87]
	s_nop 0
	v_pk_add_f32 v[84:85], v[88:89], v[84:85]
	s_nop 0
	v_cndmask_b32_e32 v83, v160, v84, vcc
	v_cmp_neq_f32_e32 vcc, s8, v133
	s_nop 1
	v_cndmask_b32_e32 v84, v160, v85, vcc
	v_cmp_ngt_f32_e32 vcc, -1.0, v133
	s_nop 1
	v_cndmask_b32_e32 v84, v161, v84, vcc
	v_cmp_ngt_f32_e32 vcc, -1.0, v131
	s_nop 1
	v_cndmask_b32_e32 v83, v161, v83, vcc
	v_cmp_neq_f32_e32 vcc, -1.0, v131
	s_nop 1
	v_cndmask_b32_e32 v83, v162, v83, vcc
	v_cmp_neq_f32_e32 vcc, -1.0, v133
	s_nop 1
	v_cndmask_b32_e32 v84, v162, v84, vcc
	v_cmp_lt_f32_e64 vcc, |v131|, s9
	v_cndmask_b32_e64 v85, v84, v133, s[0:1]
	s_nop 0
	v_cndmask_b32_e32 v84, v83, v131, vcc
	v_pk_add_f32 v[80:81], v[80:81], v[84:85]
	global_store_dwordx4 v[76:77], v[78:81], off
	global_load_dwordx4 v[78:81], v0, s[74:75] offset:64
	s_waitcnt vmcnt(0)
	v_add_f32_e32 v83, v26, v78
	v_max_f32_e32 v78, 0, v83
	v_mul_f32_e64 v83, |v83|, s2
	v_exp_f32_e32 v83, v83
	s_nop 0
	v_add_f32_e32 v86, 1.0, v83
	v_add_f32_e32 v84, -1.0, v86
	v_sub_f32_e32 v85, v84, v86
	v_add_f32_e32 v85, 1.0, v85
	v_sub_f32_e32 v84, v83, v84
	v_add_f32_e32 v87, v84, v85
	v_frexp_mant_f32_e32 v84, v86
	v_cmp_gt_f32_e32 vcc, s26, v84
	v_cvt_f64_f32_e32 v[84:85], v86
	v_frexp_exp_i32_f64_e32 v84, v[84:85]
	v_subbrev_co_u32_e32 v97, vcc, 0, v84, vcc
	v_sub_u32_e32 v85, 0, v97
	v_ldexp_f32 v84, v86, v85
	v_ldexp_f32 v86, v87, v85
	v_add_f32_e32 v85, v27, v79
	v_max_f32_e32 v79, 0, v85
	v_mul_f32_e64 v85, |v85|, s2
	v_exp_f32_e32 v130, v85
	s_nop 0
	v_add_f32_e32 v85, 1.0, v130
	v_add_f32_e32 v87, -1.0, v85
	v_sub_f32_e32 v88, v87, v85
	v_add_f32_e32 v88, 1.0, v88
	v_sub_f32_e32 v87, v130, v87
	v_add_f32_e32 v87, v87, v88
	v_frexp_mant_f32_e32 v88, v85
	v_cmp_gt_f32_e32 vcc, s26, v88
	v_cvt_f64_f32_e32 v[88:89], v85
	v_frexp_exp_i32_f64_e32 v88, v[88:89]
	v_subbrev_co_u32_e32 v122, vcc, 0, v88, vcc
	v_sub_u32_e32 v88, 0, v122
	v_ldexp_f32 v85, v85, v88
	v_ldexp_f32 v87, v87, v88
	v_pk_add_f32 v[88:89], v[84:85], 1.0 op_sel_hi:[1,0]
	v_pk_add_f32 v[98:99], v[84:85], -1.0 op_sel_hi:[1,0]
	v_pk_add_f32 v[90:91], v[88:89], -1.0 op_sel_hi:[1,0]
	v_pk_add_f32 v[100:101], v[98:99], 1.0 op_sel_hi:[1,0]
	v_pk_add_f32 v[90:91], v[84:85], v[90:91] neg_lo:[0,1] neg_hi:[0,1]
	v_pk_add_f32 v[84:85], v[84:85], v[100:101] neg_lo:[0,1] neg_hi:[0,1]
	v_pk_add_f32 v[90:91], v[86:87], v[90:91]
	v_pk_add_f32 v[84:85], v[86:87], v[84:85]
	v_pk_add_f32 v[92:93], v[88:89], v[90:91]
	v_pk_add_f32 v[86:87], v[98:99], v[84:85]
	v_rcp_f32_e32 v94, v92
	v_rcp_f32_e32 v95, v93
	v_pk_add_f32 v[88:89], v[92:93], v[88:89] neg_lo:[0,1] neg_hi:[0,1]
	v_pk_add_f32 v[98:99], v[86:87], v[98:99] neg_lo:[0,1] neg_hi:[0,1]
	v_pk_add_f32 v[88:89], v[90:91], v[88:89] neg_lo:[0,1] neg_hi:[0,1]
	v_pk_mul_f32 v[90:91], v[86:87], v[94:95]
	v_pk_add_f32 v[84:85], v[84:85], v[98:99] neg_lo:[0,1] neg_hi:[0,1]
	v_pk_mul_f32 v[98:99], v[92:93], v[90:91]
	v_cmp_lt_f32_e64 s[0:1], |v130|, s9
	v_pk_fma_f32 v[100:101], v[90:91], v[92:93], v[98:99] neg_lo:[0,0,1] neg_hi:[0,0,1]
; __device__ __forceinline__ float softplusf(float x) { return fmaxf(x, 0.f) + log1pf(__expf(-fabsf(x))); }
; __device__ void phaseA_tile(const Params& p, int l, int mt, int nt, char* smem) {
;     ...
;                 for (int j = 0; j < 2; ++j) {
;                     const int c = j * 16 + g4 * 4;
;                     const float4 db = *(const float4*)(p.dt_bias + l * 32 + c);
;                     const f32x4 v = acc[i][j];
;                     *(float4*)(p.dtb + (size_t)row * 32 + c) =
;                         make_float4(softplusf(v[0] + db.x), softplusf(v[1] + db.y), softplusf(v[2] + db.z), softplusf(v[3] + db.w));
;                 }
	s_nop 0
	v_pk_fma_f32 v[100:101], v[90:91], v[88:89], v[100:101]
	s_nop 0
	v_pk_add_f32 v[102:103], v[98:99], v[100:101]
	s_nop 0
	v_pk_add_f32 v[110:111], v[86:87], v[102:103] neg_lo:[0,1] neg_hi:[0,1]
	v_pk_add_f32 v[98:99], v[102:103], v[98:99] neg_lo:[0,1] neg_hi:[0,1]
	v_pk_add_f32 v[86:87], v[86:87], v[110:111] neg_lo:[0,1] neg_hi:[0,1]
	s_nop 0
	v_pk_add_f32 v[86:87], v[86:87], v[102:103] neg_lo:[0,1] neg_hi:[0,1]
	s_nop 0
	v_pk_add_f32 v[84:85], v[84:85], v[86:87]
	v_pk_add_f32 v[86:87], v[98:99], v[100:101] neg_lo:[0,1] neg_hi:[0,1]
	s_nop 0
	v_pk_add_f32 v[84:85], v[86:87], v[84:85]
	s_nop 0
	v_pk_add_f32 v[86:87], v[110:111], v[84:85]
	s_nop 0
	v_pk_mul_f32 v[98:99], v[94:95], v[86:87]
	s_nop 0
	v_pk_mul_f32 v[100:101], v[92:93], v[98:99]
	s_nop 0
	v_pk_fma_f32 v[92:93], v[98:99], v[92:93], v[100:101] neg_lo:[0,0,1] neg_hi:[0,0,1]
	s_nop 0
	v_pk_fma_f32 v[88:89], v[98:99], v[88:89], v[92:93]
	v_pk_add_f32 v[92:93], v[110:111], v[86:87] neg_lo:[0,1] neg_hi:[0,1]
	s_nop 0
	v_pk_add_f32 v[84:85], v[84:85], v[92:93]
	v_pk_add_f32 v[92:93], v[100:101], v[88:89]
	s_nop 0
	v_pk_add_f32 v[102:103], v[86:87], v[92:93] neg_lo:[0,1] neg_hi:[0,1]
	v_pk_add_f32 v[100:101], v[92:93], v[100:101] neg_lo:[0,1] neg_hi:[0,1]
	v_pk_add_f32 v[86:87], v[86:87], v[102:103] neg_lo:[0,1] neg_hi:[0,1]
	s_nop 0
	v_pk_add_f32 v[86:87], v[86:87], v[92:93] neg_lo:[0,1] neg_hi:[0,1]
	s_nop 0
	v_pk_add_f32 v[84:85], v[84:85], v[86:87]
	v_pk_add_f32 v[86:87], v[100:101], v[88:89] neg_lo:[0,1] neg_hi:[0,1]
	s_nop 0
	v_pk_add_f32 v[84:85], v[86:87], v[84:85]
	v_pk_add_f32 v[86:87], v[90:91], v[98:99]
	v_pk_add_f32 v[84:85], v[102:103], v[84:85]
	v_pk_add_f32 v[88:89], v[86:87], v[90:91] neg_lo:[0,1] neg_hi:[0,1]
	v_pk_mul_f32 v[84:85], v[94:95], v[84:85]
	v_pk_add_f32 v[88:89], v[98:99], v[88:89] neg_lo:[0,1] neg_hi:[0,1]
	s_nop 0
	v_pk_add_f32 v[84:85], v[88:89], v[84:85]
	s_nop 0
	v_pk_add_f32 v[88:89], v[86:87], v[84:85]
	s_nop 0
	v_pk_add_f32 v[86:87], v[88:89], v[86:87] neg_lo:[0,1] neg_hi:[0,1]
	v_pk_mul_f32 v[90:91], v[88:89], v[88:89]
	v_pk_add_f32 v[84:85], v[84:85], v[86:87] neg_lo:[0,1] neg_hi:[0,1]
	v_pk_fma_f32 v[92:93], v[90:91], s[28:29], v[66:67] op_sel_hi:[1,0,0]
	v_ldexp_f32 v95, v85, 1
	v_add_f32_e32 v85, v28, v80
	v_max_f32_e32 v80, 0, v85
	v_mul_f32_e64 v85, |v85|, s2
	v_exp_f32_e32 v131, v85
	v_ldexp_f32 v86, v88, 1
	v_pk_fma_f32 v[92:93], v[90:91], v[92:93], s[30:31] op_sel_hi:[1,1,0]
	v_ldexp_f32 v87, v89, 1
	v_add_f32_e32 v85, 1.0, v131
	v_pk_mul_f32 v[88:89], v[88:89], v[90:91]
	v_add_f32_e32 v90, -1.0, v85
	v_sub_f32_e32 v91, v90, v85
	v_add_f32_e32 v91, 1.0, v91
	v_sub_f32_e32 v90, v131, v90
	v_add_f32_e32 v94, v90, v91
	v_frexp_mant_f32_e32 v90, v85
	v_cmp_gt_f32_e32 vcc, s26, v90
	v_cvt_f64_f32_e32 v[90:91], v85
	v_frexp_exp_i32_f64_e32 v90, v[90:91]
	v_subbrev_co_u32_e32 v132, vcc, 0, v90, vcc
	v_sub_u32_e32 v91, 0, v132
	v_ldexp_f32 v90, v85, v91
	v_add_f32_e32 v85, v29, v81
	v_max_f32_e32 v81, 0, v85
	v_mul_f32_e64 v85, |v85|, s2
	v_exp_f32_e32 v133, v85
	v_ldexp_f32 v98, v94, v91
	v_pk_mul_f32 v[88:89], v[88:89], v[92:93]
	v_ldexp_f32 v84, v84, 1
	v_add_f32_e32 v85, 1.0, v133
	v_add_f32_e32 v91, -1.0, v85
	v_sub_f32_e32 v94, v91, v85
	v_add_f32_e32 v94, 1.0, v94
	v_sub_f32_e32 v91, v133, v91
	v_add_f32_e32 v94, v91, v94
	v_frexp_mant_f32_e32 v91, v85
	v_cvt_f64_f32_e32 v[100:101], v85
	v_cmp_gt_f32_e32 vcc, s26, v91
	v_frexp_exp_i32_f64_e32 v91, v[100:101]
	v_pk_add_f32 v[92:93], v[86:87], v[88:89]
	v_subbrev_co_u32_e32 v134, vcc, 0, v91, vcc
	v_sub_u32_e32 v99, 0, v134
	v_ldexp_f32 v91, v85, v99
	v_pk_add_f32 v[100:101], v[90:91], 1.0 op_sel_hi:[1,0]
	v_ldexp_f32 v99, v94, v99
	v_pk_add_f32 v[102:103], v[100:101], -1.0 op_sel_hi:[1,0]
	v_pk_add_f32 v[114:115], v[90:91], -1.0 op_sel_hi:[1,0]
	v_pk_add_f32 v[102:103], v[90:91], v[102:103] neg_lo:[0,1] neg_hi:[0,1]
	v_pk_add_f32 v[116:117], v[114:115], 1.0 op_sel_hi:[1,0]
	v_pk_add_f32 v[102:103], v[98:99], v[102:103]
	v_pk_add_f32 v[90:91], v[90:91], v[116:117] neg_lo:[0,1] neg_hi:[0,1]
	v_pk_add_f32 v[110:111], v[100:101], v[102:103]
	v_pk_add_f32 v[90:91], v[98:99], v[90:91]
	v_rcp_f32_e32 v112, v110
	v_rcp_f32_e32 v113, v111
	v_pk_add_f32 v[98:99], v[114:115], v[90:91]
	v_pk_add_f32 v[100:101], v[110:111], v[100:101] neg_lo:[0,1] neg_hi:[0,1]
	v_pk_add_f32 v[114:115], v[98:99], v[114:115] neg_lo:[0,1] neg_hi:[0,1]
	v_pk_add_f32 v[100:101], v[102:103], v[100:101] neg_lo:[0,1] neg_hi:[0,1]
	v_pk_mul_f32 v[102:103], v[98:99], v[112:113]
	v_pk_add_f32 v[90:91], v[90:91], v[114:115] neg_lo:[0,1] neg_hi:[0,1]
	v_pk_mul_f32 v[114:115], v[110:111], v[102:103]
	v_pk_add_f32 v[86:87], v[92:93], v[86:87] neg_lo:[0,1] neg_hi:[0,1]
	v_pk_fma_f32 v[116:117], v[102:103], v[110:111], v[114:115] neg_lo:[0,0,1] neg_hi:[0,0,1]
	v_pk_add_f32 v[86:87], v[88:89], v[86:87] neg_lo:[0,1] neg_hi:[0,1]
	v_pk_fma_f32 v[116:117], v[102:103], v[100:101], v[116:117]
	v_mov_b32_e32 v89, v87
	v_pk_add_f32 v[118:119], v[114:115], v[116:117]
	v_mov_b32_e32 v85, v95
	v_pk_add_f32 v[120:121], v[98:99], v[118:119] neg_lo:[0,1] neg_hi:[0,1]
	v_pk_add_f32 v[114:115], v[118:119], v[114:115] neg_lo:[0,1] neg_hi:[0,1]
	v_pk_add_f32 v[98:99], v[98:99], v[120:121] neg_lo:[0,1] neg_hi:[0,1]
	v_mov_b32_e32 v126, v92
	v_pk_add_f32 v[98:99], v[98:99], v[118:119] neg_lo:[0,1] neg_hi:[0,1]
	v_cmp_neq_f32_e32 vcc, s8, v83
	v_pk_add_f32 v[90:91], v[90:91], v[98:99]
	v_pk_add_f32 v[98:99], v[114:115], v[116:117] neg_lo:[0,1] neg_hi:[0,1]
	s_nop 0
	v_pk_add_f32 v[90:91], v[98:99], v[90:91]
	s_nop 0
	v_pk_add_f32 v[98:99], v[120:121], v[90:91]
	s_nop 0
	v_pk_mul_f32 v[114:115], v[112:113], v[98:99]
	s_nop 0
; __device__ __forceinline__ float softplusf(float x) { return fmaxf(x, 0.f) + log1pf(__expf(-fabsf(x))); }
; __device__ void phaseA_tile(const Params& p, int l, int mt, int nt, char* smem) {
;     ...
;                 for (int j = 0; j < 2; ++j) {
;                     const int c = j * 16 + g4 * 4;
;                     const float4 db = *(const float4*)(p.dt_bias + l * 32 + c);
;                     const f32x4 v = acc[i][j];
;                     *(float4*)(p.dtb + (size_t)row * 32 + c) =
;                         make_float4(softplusf(v[0] + db.x), softplusf(v[1] + db.y), softplusf(v[2] + db.z), softplusf(v[3] + db.w));
;                 }
	v_pk_mul_f32 v[116:117], v[110:111], v[114:115]
	s_nop 0
	v_pk_fma_f32 v[110:111], v[114:115], v[110:111], v[116:117] neg_lo:[0,0,1] neg_hi:[0,0,1]
	s_nop 0
	v_pk_fma_f32 v[100:101], v[114:115], v[100:101], v[110:111]
	v_pk_add_f32 v[110:111], v[120:121], v[98:99] neg_lo:[0,1] neg_hi:[0,1]
	s_nop 0
	v_pk_add_f32 v[90:91], v[90:91], v[110:111]
	v_pk_add_f32 v[110:111], v[116:117], v[100:101]
	s_nop 0
	v_pk_add_f32 v[118:119], v[98:99], v[110:111] neg_lo:[0,1] neg_hi:[0,1]
	v_pk_add_f32 v[116:117], v[110:111], v[116:117] neg_lo:[0,1] neg_hi:[0,1]
	v_pk_add_f32 v[98:99], v[98:99], v[118:119] neg_lo:[0,1] neg_hi:[0,1]
	s_nop 0
	v_pk_add_f32 v[98:99], v[98:99], v[110:111] neg_lo:[0,1] neg_hi:[0,1]
	s_nop 0
	v_pk_add_f32 v[90:91], v[90:91], v[98:99]
	v_pk_add_f32 v[98:99], v[116:117], v[100:101] neg_lo:[0,1] neg_hi:[0,1]
	s_nop 0
	v_pk_add_f32 v[90:91], v[98:99], v[90:91]
	v_pk_add_f32 v[98:99], v[102:103], v[114:115]
	v_pk_add_f32 v[90:91], v[118:119], v[90:91]
	v_pk_add_f32 v[100:101], v[98:99], v[102:103] neg_lo:[0,1] neg_hi:[0,1]
	v_pk_mul_f32 v[90:91], v[112:113], v[90:91]
	v_pk_add_f32 v[100:101], v[114:115], v[100:101] neg_lo:[0,1] neg_hi:[0,1]
	s_nop 0
	v_pk_add_f32 v[90:91], v[100:101], v[90:91]
	s_nop 0
	v_pk_add_f32 v[100:101], v[98:99], v[90:91]
	s_nop 0
	v_pk_mul_f32 v[102:103], v[100:101], v[100:101]
	v_pk_add_f32 v[98:99], v[100:101], v[98:99] neg_lo:[0,1] neg_hi:[0,1]
	v_pk_fma_f32 v[110:111], v[102:103], s[28:29], v[66:67] op_sel_hi:[1,0,0]
	v_pk_add_f32 v[90:91], v[90:91], v[98:99] neg_lo:[0,1] neg_hi:[0,1]
	v_ldexp_f32 v98, v100, 1
	v_pk_fma_f32 v[110:111], v[102:103], v[110:111], s[30:31] op_sel_hi:[1,1,0]
	v_ldexp_f32 v99, v101, 1
	v_pk_mul_f32 v[100:101], v[100:101], v[102:103]
	v_cvt_f32_i32_e32 v103, v122
	v_cvt_f32_i32_e32 v102, v97
	v_ldexp_f32 v113, v91, 1
	v_ldexp_f32 v90, v90, 1
	v_mov_b32_e32 v91, v113
	v_pk_mul_f32 v[114:115], v[102:103], s[12:13] op_sel_hi:[1,0]
	s_nop 0
	v_pk_fma_f32 v[116:117], v[102:103], s[12:13], v[114:115] op_sel_hi:[1,0,1] neg_lo:[0,0,1] neg_hi:[0,0,1]
	v_mov_b32_e32 v88, v114
	v_pk_fma_f32 v[102:103], v[102:103], s[14:15], v[116:117] op_sel_hi:[1,0,1]
	v_mov_b32_e32 v123, v115
	v_mov_b32_e32 v94, v102
	v_pk_add_f32 v[88:89], v[88:89], v[94:95]
	v_pk_add_f32 v[94:95], v[84:85], v[86:87]
	v_mov_b32_e32 v87, v93
	v_mov_b32_e32 v85, v95
	v_pk_add_f32 v[116:117], v[114:115], v[102:103]
	v_pk_add_f32 v[84:85], v[84:85], v[86:87]
	v_pk_add_f32 v[86:87], v[92:93], v[94:95]
	v_mov_b32_e32 v127, v117
	v_pk_add_f32 v[118:119], v[116:117], v[86:87]
	v_mov_b32_e32 v124, v86
	v_mov_b32_e32 v125, v119
	v_pk_add_f32 v[124:125], v[124:125], v[126:127] neg_lo:[0,1] neg_hi:[0,1]
	v_mov_b32_e32 v120, v118
	v_mov_b32_e32 v121, v117
	v_mov_b32_e32 v122, v116
	v_mov_b32_e32 v126, v116
	v_mov_b32_e32 v127, v119
	v_mov_b32_e32 v115, v125
	v_pk_add_f32 v[120:121], v[120:121], v[122:123] neg_lo:[0,1] neg_hi:[0,1]
	v_mov_b32_e32 v122, v86
	v_mov_b32_e32 v123, v103
	v_pk_add_f32 v[114:115], v[126:127], v[114:115] neg_lo:[0,1] neg_hi:[0,1]
	v_pk_add_f32 v[122:123], v[122:123], v[120:121] neg_lo:[0,1] neg_hi:[0,1]
	v_mov_b32_e32 v126, v114
	v_mov_b32_e32 v127, v121
	v_mov_b32_e32 v128, v118
	v_mov_b32_e32 v129, v87
	v_mov_b32_e32 v121, v93
	v_pk_add_f32 v[126:127], v[102:103], v[126:127] neg_lo:[0,1] neg_hi:[0,1]
	v_pk_add_f32 v[120:121], v[128:129], v[120:121] neg_lo:[0,1] neg_hi:[0,1]
	v_mov_b32_e32 v103, v117
	v_pk_add_f32 v[86:87], v[86:87], v[92:93] neg_lo:[0,1] neg_hi:[0,1]
	v_pk_add_f32 v[88:89], v[88:89], v[120:121] neg_lo:[0,1] neg_hi:[0,1]
	v_pk_add_f32 v[92:93], v[102:103], v[114:115] neg_lo:[0,1] neg_hi:[0,1]
	v_pk_add_f32 v[84:85], v[84:85], v[124:125] neg_lo:[0,1] neg_hi:[0,1]
	v_pk_add_f32 v[86:87], v[94:95], v[86:87] neg_lo:[0,1] neg_hi:[0,1]
	v_pk_add_f32 v[94:95], v[84:85], v[92:93]
	v_mov_b32_e32 v93, v123
	v_mov_b32_e32 v85, v89
	v_pk_add_f32 v[102:103], v[122:123], v[88:89]
	v_pk_add_f32 v[84:85], v[92:93], v[84:85]
	v_mov_b32_e32 v88, v94
	v_pk_add_f32 v[84:85], v[84:85], v[126:127] neg_lo:[0,1] neg_hi:[0,1]
	v_mov_b32_e32 v89, v103
	v_pk_add_f32 v[88:89], v[88:89], v[84:85] neg_lo:[0,1] neg_hi:[0,1]
	v_pk_add_f32 v[84:85], v[86:87], v[84:85] neg_lo:[0,1] neg_hi:[0,1]
	v_pk_add_f32 v[88:89], v[92:93], v[88:89] neg_lo:[0,1] neg_hi:[0,1]
	v_pk_add_f32 v[86:87], v[102:103], v[94:95]
	v_pk_add_f32 v[84:85], v[84:85], v[88:89]
	v_pk_add_f32 v[88:89], v[118:119], v[86:87]
	s_nop 0
	v_pk_add_f32 v[92:93], v[88:89], v[118:119] neg_lo:[0,1] neg_hi:[0,1]
	s_nop 0
	v_pk_add_f32 v[86:87], v[86:87], v[92:93] neg_lo:[0,1] neg_hi:[0,1]
	s_nop 0
	v_pk_add_f32 v[84:85], v[84:85], v[86:87]
	s_nop 0
	v_pk_add_f32 v[84:85], v[88:89], v[84:85]
	v_pk_mul_f32 v[88:89], v[100:101], v[110:111]
	v_cndmask_b32_e32 v84, v160, v84, vcc
	v_cmp_neq_f32_e32 vcc, s8, v130
	v_pk_add_f32 v[92:93], v[98:99], v[88:89]
	s_nop 0
	v_cndmask_b32_e32 v85, v160, v85, vcc
	v_cmp_ngt_f32_e32 vcc, -1.0, v130
	v_pk_add_f32 v[98:99], v[92:93], v[98:99] neg_lo:[0,1] neg_hi:[0,1]
	v_mov_b32_e32 v116, v92
	v_cndmask_b32_e32 v85, v161, v85, vcc
	v_cmp_ngt_f32_e32 vcc, -1.0, v83
	v_pk_add_f32 v[88:89], v[88:89], v[98:99] neg_lo:[0,1] neg_hi:[0,1]
	s_nop 0
	v_cndmask_b32_e32 v84, v161, v84, vcc
	v_cmp_neq_f32_e32 vcc, -1.0, v83
	v_pk_add_f32 v[100:101], v[90:91], v[88:89]
	v_mov_b32_e32 v99, v89
	v_cndmask_b32_e32 v84, v162, v84, vcc
	v_cmp_neq_f32_e32 vcc, -1.0, v130
	v_mov_b32_e32 v91, v101
	v_mov_b32_e32 v89, v93
	v_cndmask_b32_e32 v85, v162, v85, vcc
	v_cmp_lt_f32_e64 vcc, |v83|, s9
	v_cndmask_b32_e64 v85, v85, v130, s[0:1]
	v_pk_add_f32 v[88:89], v[90:91], v[88:89]
	v_cndmask_b32_e32 v84, v84, v83, vcc
	v_pk_add_f32 v[78:79], v[78:79], v[84:85]
; __device__ __forceinline__ float softplusf(float x) { return fmaxf(x, 0.f) + log1pf(__expf(-fabsf(x))); }
; __device__ __forceinline__ float logsigf(float x) { return fminf(x, 0.f) - log1pf(__expf(-fabsf(x))); }
; __device__ void phaseA_tile(const Params& p, int l, int mt, int nt, char* smem) {
;     ...
;                 for (int j = 0; j < 2; ++j) {
;                     const int c = j * 16 + g4 * 4;
;                     const float4 db = *(const float4*)(p.dt_bias + l * 32 + c);
;                     const f32x4 v = acc[i][j];
;                     *(float4*)(p.dtb + (size_t)row * 32 + c) =
;                         make_float4(softplusf(v[0] + db.x), softplusf(v[1] + db.y), softplusf(v[2] + db.z), softplusf(v[3] + db.w));
;                 }
;                 {
;                     const int c = g4 * 4;
;                     const float4 fb = *(const float4*)(p.b_f + l * 16 + c);
;                     const f32x4 v = acc[i][2];
;                     float4 lf = make_float4(logsigf(v[0] + fb.x), logsigf(v[1] + fb.y), logsigf(v[2] + fb.z), logsigf(v[3] + fb.w));
;                     float* o = samp ? (p.out + O_LFS + ((size_t)l * TSM + (row - TP)) * 16 + c)
;                                     : (p.out + O_LFP + ((size_t)l * TP + row) * 16 + c);
;                     *(float4*)o = lf;
;                     *(float4*)(lf_s + rl * 16 + c) = lf;
	v_cvt_f32_i32_e32 v85, v134
	v_cvt_f32_i32_e32 v84, v132
	v_pk_add_f32 v[90:91], v[92:93], v[100:101]
	v_cmp_neq_f32_e32 vcc, s8, v131
	v_mov_b32_e32 v114, v90
	v_pk_mul_f32 v[86:87], v[84:85], s[12:13] op_sel_hi:[1,0]
	v_mov_b32_e32 v119, v91
	v_pk_fma_f32 v[94:95], v[84:85], s[12:13], v[86:87] op_sel_hi:[1,0,1] neg_lo:[0,0,1] neg_hi:[0,0,1]
	v_mov_b32_e32 v98, v86
	v_pk_fma_f32 v[84:85], v[84:85], s[14:15], v[94:95] op_sel_hi:[1,0,1]
	v_cmp_lt_f32_e64 s[0:1], |v133|, s9
	v_pk_add_f32 v[94:95], v[86:87], v[84:85]
	v_mov_b32_e32 v112, v84
	v_pk_add_f32 v[102:103], v[94:95], v[90:91]
	v_mov_b32_e32 v117, v95
	v_mov_b32_e32 v115, v103
	v_pk_add_f32 v[114:115], v[114:115], v[116:117] neg_lo:[0,1] neg_hi:[0,1]
	v_pk_add_f32 v[98:99], v[98:99], v[112:113]
	v_mov_b32_e32 v110, v102
	v_mov_b32_e32 v111, v95
	v_mov_b32_e32 v112, v94
	v_mov_b32_e32 v113, v87
	v_mov_b32_e32 v116, v94
	v_mov_b32_e32 v117, v103
	v_mov_b32_e32 v87, v115
	v_pk_add_f32 v[110:111], v[110:111], v[112:113] neg_lo:[0,1] neg_hi:[0,1]
	v_mov_b32_e32 v112, v90
	v_mov_b32_e32 v113, v85
	v_pk_add_f32 v[86:87], v[116:117], v[86:87] neg_lo:[0,1] neg_hi:[0,1]
	v_pk_add_f32 v[112:113], v[112:113], v[110:111] neg_lo:[0,1] neg_hi:[0,1]
	v_mov_b32_e32 v116, v86
	v_mov_b32_e32 v117, v111
	v_mov_b32_e32 v118, v102
	v_mov_b32_e32 v111, v93
	v_pk_add_f32 v[116:117], v[84:85], v[116:117] neg_lo:[0,1] neg_hi:[0,1]
	v_pk_add_f32 v[110:111], v[118:119], v[110:111] neg_lo:[0,1] neg_hi:[0,1]
	v_mov_b32_e32 v85, v95
	v_pk_add_f32 v[90:91], v[90:91], v[92:93] neg_lo:[0,1] neg_hi:[0,1]
	v_pk_add_f32 v[92:93], v[98:99], v[110:111] neg_lo:[0,1] neg_hi:[0,1]
	v_pk_add_f32 v[84:85], v[84:85], v[86:87] neg_lo:[0,1] neg_hi:[0,1]
	v_pk_add_f32 v[86:87], v[88:89], v[114:115] neg_lo:[0,1] neg_hi:[0,1]
	v_pk_add_f32 v[94:95], v[112:113], v[92:93]
	v_pk_add_f32 v[88:89], v[86:87], v[84:85]
	v_mov_b32_e32 v85, v113
	v_mov_b32_e32 v87, v93
	v_pk_add_f32 v[86:87], v[84:85], v[86:87]
	v_mov_b32_e32 v92, v88
	v_pk_add_f32 v[86:87], v[86:87], v[116:117] neg_lo:[0,1] neg_hi:[0,1]
	v_mov_b32_e32 v93, v95
	v_pk_add_f32 v[90:91], v[100:101], v[90:91] neg_lo:[0,1] neg_hi:[0,1]
	v_pk_add_f32 v[92:93], v[92:93], v[86:87] neg_lo:[0,1] neg_hi:[0,1]
	v_pk_add_f32 v[86:87], v[90:91], v[86:87] neg_lo:[0,1] neg_hi:[0,1]
	v_pk_add_f32 v[84:85], v[84:85], v[92:93] neg_lo:[0,1] neg_hi:[0,1]
	s_nop 0
	v_pk_add_f32 v[84:85], v[86:87], v[84:85]
	v_pk_add_f32 v[86:87], v[94:95], v[88:89]
	s_nop 0
	v_pk_add_f32 v[88:89], v[102:103], v[86:87]
	s_nop 0
	v_pk_add_f32 v[90:91], v[88:89], v[102:103] neg_lo:[0,1] neg_hi:[0,1]
	s_nop 0
	v_pk_add_f32 v[86:87], v[86:87], v[90:91] neg_lo:[0,1] neg_hi:[0,1]
	s_nop 0
	v_pk_add_f32 v[84:85], v[84:85], v[86:87]
	s_nop 0
	v_pk_add_f32 v[84:85], v[88:89], v[84:85]
	s_nop 0
	v_cndmask_b32_e32 v83, v160, v84, vcc
	v_cmp_neq_f32_e32 vcc, s8, v133
	s_nop 1
	v_cndmask_b32_e32 v84, v160, v85, vcc
	v_cmp_ngt_f32_e32 vcc, -1.0, v133
	s_nop 1
	v_cndmask_b32_e32 v84, v161, v84, vcc
	v_cmp_ngt_f32_e32 vcc, -1.0, v131
	s_nop 1
	v_cndmask_b32_e32 v83, v161, v83, vcc
	v_cmp_neq_f32_e32 vcc, -1.0, v131
	s_nop 1
	v_cndmask_b32_e32 v83, v162, v83, vcc
	v_cmp_neq_f32_e32 vcc, -1.0, v133
	s_nop 1
	v_cndmask_b32_e32 v84, v162, v84, vcc
	v_cmp_lt_f32_e64 vcc, |v131|, s9
	v_cndmask_b32_e64 v85, v84, v133, s[0:1]
	s_nop 0
	v_cndmask_b32_e32 v84, v83, v131, vcc
	v_pk_add_f32 v[80:81], v[80:81], v[84:85]
	global_store_dwordx4 v[76:77], v[78:81], off offset:64
	global_load_dwordx4 v[76:79], v0, s[78:79]
	s_waitcnt vmcnt(0)
	v_add_f32_e32 v80, v22, v76
	v_min_f32_e32 v76, 0, v80
	v_mul_f32_e64 v80, |v80|, s2
	v_exp_f32_e32 v83, v80
	s_nop 0
	v_add_f32_e32 v84, 1.0, v83
	v_add_f32_e32 v80, -1.0, v84
	v_sub_f32_e32 v81, v80, v84
	v_add_f32_e32 v81, 1.0, v81
	v_sub_f32_e32 v80, v83, v80
	v_add_f32_e32 v85, v80, v81
	v_frexp_mant_f32_e32 v80, v84
	v_cmp_gt_f32_e32 vcc, s26, v80
	v_cvt_f64_f32_e32 v[80:81], v84
	v_frexp_exp_i32_f64_e32 v80, v[80:81]
	v_subbrev_co_u32_e32 v97, vcc, 0, v80, vcc
	v_sub_u32_e32 v81, 0, v97
	v_ldexp_f32 v80, v84, v81
	v_ldexp_f32 v84, v85, v81
	v_add_f32_e32 v81, v23, v77
	v_min_f32_e32 v77, 0, v81
	v_mul_f32_e64 v81, |v81|, s2
	v_exp_f32_e32 v128, v81
	s_nop 0
	v_add_f32_e32 v81, 1.0, v128
	v_add_f32_e32 v85, -1.0, v81
	v_sub_f32_e32 v86, v85, v81
	v_add_f32_e32 v86, 1.0, v86
	v_sub_f32_e32 v85, v128, v85
	v_add_f32_e32 v85, v85, v86
	v_frexp_mant_f32_e32 v86, v81
	v_cmp_gt_f32_e32 vcc, s26, v86
	v_cvt_f64_f32_e32 v[86:87], v81
	v_frexp_exp_i32_f64_e32 v86, v[86:87]
	v_subbrev_co_u32_e32 v120, vcc, 0, v86, vcc
	v_sub_u32_e32 v86, 0, v120
	v_ldexp_f32 v81, v81, v86
	v_ldexp_f32 v85, v85, v86
	v_pk_add_f32 v[86:87], v[80:81], 1.0 op_sel_hi:[1,0]
	v_pk_add_f32 v[94:95], v[80:81], -1.0 op_sel_hi:[1,0]
	v_pk_add_f32 v[88:89], v[86:87], -1.0 op_sel_hi:[1,0]
	v_pk_add_f32 v[98:99], v[94:95], 1.0 op_sel_hi:[1,0]
	v_pk_add_f32 v[88:89], v[80:81], v[88:89] neg_lo:[0,1] neg_hi:[0,1]
	v_pk_add_f32 v[80:81], v[80:81], v[98:99] neg_lo:[0,1] neg_hi:[0,1]
	v_pk_add_f32 v[88:89], v[84:85], v[88:89]
	v_pk_add_f32 v[80:81], v[84:85], v[80:81]
	v_pk_add_f32 v[90:91], v[86:87], v[88:89]
	v_pk_add_f32 v[84:85], v[94:95], v[80:81]
	v_rcp_f32_e32 v92, v90
	v_rcp_f32_e32 v93, v91
	v_pk_add_f32 v[86:87], v[90:91], v[86:87] neg_lo:[0,1] neg_hi:[0,1]
	v_pk_add_f32 v[94:95], v[84:85], v[94:95] neg_lo:[0,1] neg_hi:[0,1]
	v_pk_add_f32 v[86:87], v[88:89], v[86:87] neg_lo:[0,1] neg_hi:[0,1]
	v_pk_mul_f32 v[88:89], v[84:85], v[92:93]
	v_pk_add_f32 v[80:81], v[80:81], v[94:95] neg_lo:[0,1] neg_hi:[0,1]
	v_pk_mul_f32 v[94:95], v[90:91], v[88:89]
	v_cmp_lt_f32_e64 s[0:1], |v128|, s9
	v_pk_fma_f32 v[98:99], v[88:89], v[90:91], v[94:95] neg_lo:[0,0,1] neg_hi:[0,0,1]
; __device__ __forceinline__ float logsigf(float x) { return fminf(x, 0.f) - log1pf(__expf(-fabsf(x))); }
; __device__ void phaseA_tile(const Params& p, int l, int mt, int nt, char* smem) {
;     ...
;                 {
;                     const int c = g4 * 4;
;                     const float4 fb = *(const float4*)(p.b_f + l * 16 + c);
;                     const f32x4 v = acc[i][2];
;                     float4 lf = make_float4(logsigf(v[0] + fb.x), logsigf(v[1] + fb.y), logsigf(v[2] + fb.z), logsigf(v[3] + fb.w));
;                     float* o = samp ? (p.out + O_LFS + ((size_t)l * TSM + (row - TP)) * 16 + c)
;                                     : (p.out + O_LFP + ((size_t)l * TP + row) * 16 + c);
;                     *(float4*)o = lf;
;                     *(float4*)(lf_s + rl * 16 + c) = lf;
	s_nop 0
	v_pk_fma_f32 v[98:99], v[88:89], v[86:87], v[98:99]
	s_nop 0
	v_pk_add_f32 v[100:101], v[94:95], v[98:99]
	s_nop 0
	v_pk_add_f32 v[102:103], v[84:85], v[100:101] neg_lo:[0,1] neg_hi:[0,1]
	v_pk_add_f32 v[94:95], v[100:101], v[94:95] neg_lo:[0,1] neg_hi:[0,1]
	v_pk_add_f32 v[84:85], v[84:85], v[102:103] neg_lo:[0,1] neg_hi:[0,1]
	s_nop 0
	v_pk_add_f32 v[84:85], v[84:85], v[100:101] neg_lo:[0,1] neg_hi:[0,1]
	s_nop 0
	v_pk_add_f32 v[80:81], v[80:81], v[84:85]
	v_pk_add_f32 v[84:85], v[94:95], v[98:99] neg_lo:[0,1] neg_hi:[0,1]
	s_nop 0
	v_pk_add_f32 v[80:81], v[84:85], v[80:81]
	s_nop 0
	v_pk_add_f32 v[84:85], v[102:103], v[80:81]
	s_nop 0
	v_pk_mul_f32 v[94:95], v[92:93], v[84:85]
	s_nop 0
	v_pk_mul_f32 v[98:99], v[90:91], v[94:95]
	s_nop 0
	v_pk_fma_f32 v[90:91], v[94:95], v[90:91], v[98:99] neg_lo:[0,0,1] neg_hi:[0,0,1]
	s_nop 0
	v_pk_fma_f32 v[86:87], v[94:95], v[86:87], v[90:91]
	v_pk_add_f32 v[90:91], v[102:103], v[84:85] neg_lo:[0,1] neg_hi:[0,1]
	s_nop 0
	v_pk_add_f32 v[80:81], v[80:81], v[90:91]
	v_pk_add_f32 v[90:91], v[98:99], v[86:87]
	s_nop 0
	v_pk_add_f32 v[100:101], v[84:85], v[90:91] neg_lo:[0,1] neg_hi:[0,1]
	v_pk_add_f32 v[98:99], v[90:91], v[98:99] neg_lo:[0,1] neg_hi:[0,1]
	v_pk_add_f32 v[84:85], v[84:85], v[100:101] neg_lo:[0,1] neg_hi:[0,1]
	s_nop 0
	v_pk_add_f32 v[84:85], v[84:85], v[90:91] neg_lo:[0,1] neg_hi:[0,1]
	s_nop 0
	v_pk_add_f32 v[80:81], v[80:81], v[84:85]
	v_pk_add_f32 v[84:85], v[98:99], v[86:87] neg_lo:[0,1] neg_hi:[0,1]
	s_nop 0
	v_pk_add_f32 v[80:81], v[84:85], v[80:81]
	v_pk_add_f32 v[84:85], v[88:89], v[94:95]
	v_pk_add_f32 v[80:81], v[100:101], v[80:81]
	v_pk_add_f32 v[86:87], v[84:85], v[88:89] neg_lo:[0,1] neg_hi:[0,1]
	v_pk_mul_f32 v[80:81], v[92:93], v[80:81]
	v_pk_add_f32 v[86:87], v[94:95], v[86:87] neg_lo:[0,1] neg_hi:[0,1]
	s_nop 0
	v_pk_add_f32 v[80:81], v[86:87], v[80:81]
	s_nop 0
	v_pk_add_f32 v[86:87], v[84:85], v[80:81]
	s_nop 0
	v_pk_add_f32 v[84:85], v[86:87], v[84:85] neg_lo:[0,1] neg_hi:[0,1]
	v_pk_mul_f32 v[88:89], v[86:87], v[86:87]
	v_pk_add_f32 v[80:81], v[80:81], v[84:85] neg_lo:[0,1] neg_hi:[0,1]
	v_pk_fma_f32 v[90:91], v[88:89], s[28:29], v[66:67] op_sel_hi:[1,0,0]
	v_ldexp_f32 v93, v81, 1
	v_add_f32_e32 v81, v24, v78
	v_min_f32_e32 v78, 0, v81
	v_mul_f32_e64 v81, |v81|, s2
	v_exp_f32_e32 v129, v81
	v_ldexp_f32 v84, v86, 1
	v_pk_fma_f32 v[90:91], v[88:89], v[90:91], s[30:31] op_sel_hi:[1,1,0]
	v_ldexp_f32 v85, v87, 1
	v_add_f32_e32 v81, 1.0, v129
	v_pk_mul_f32 v[86:87], v[86:87], v[88:89]
	v_add_f32_e32 v88, -1.0, v81
	v_sub_f32_e32 v89, v88, v81
	v_add_f32_e32 v89, 1.0, v89
	v_sub_f32_e32 v88, v129, v88
	v_add_f32_e32 v92, v88, v89
	v_frexp_mant_f32_e32 v88, v81
	v_cmp_gt_f32_e32 vcc, s26, v88
	v_cvt_f64_f32_e32 v[88:89], v81
	v_frexp_exp_i32_f64_e32 v88, v[88:89]
	v_subbrev_co_u32_e32 v130, vcc, 0, v88, vcc
	v_sub_u32_e32 v89, 0, v130
	v_ldexp_f32 v88, v81, v89
	v_add_f32_e32 v81, v25, v79
	v_min_f32_e32 v79, 0, v81
	v_mul_f32_e64 v81, |v81|, s2
	v_exp_f32_e32 v131, v81
	v_ldexp_f32 v94, v92, v89
	v_pk_mul_f32 v[86:87], v[86:87], v[90:91]
	v_ldexp_f32 v80, v80, 1
	v_add_f32_e32 v81, 1.0, v131
	v_add_f32_e32 v89, -1.0, v81
	v_sub_f32_e32 v92, v89, v81
	v_add_f32_e32 v92, 1.0, v92
	v_sub_f32_e32 v89, v131, v89
	v_add_f32_e32 v92, v89, v92
	v_frexp_mant_f32_e32 v89, v81
	v_cvt_f64_f32_e32 v[98:99], v81
	v_cmp_gt_f32_e32 vcc, s26, v89
	v_frexp_exp_i32_f64_e32 v89, v[98:99]
	v_pk_add_f32 v[90:91], v[84:85], v[86:87]
	v_subbrev_co_u32_e32 v132, vcc, 0, v89, vcc
	v_sub_u32_e32 v95, 0, v132
	v_ldexp_f32 v89, v81, v95
	v_pk_add_f32 v[98:99], v[88:89], 1.0 op_sel_hi:[1,0]
	v_ldexp_f32 v95, v92, v95
	v_pk_add_f32 v[100:101], v[98:99], -1.0 op_sel_hi:[1,0]
	v_pk_add_f32 v[112:113], v[88:89], -1.0 op_sel_hi:[1,0]
	v_pk_add_f32 v[100:101], v[88:89], v[100:101] neg_lo:[0,1] neg_hi:[0,1]
	v_pk_add_f32 v[114:115], v[112:113], 1.0 op_sel_hi:[1,0]
	v_pk_add_f32 v[100:101], v[94:95], v[100:101]
	v_pk_add_f32 v[88:89], v[88:89], v[114:115] neg_lo:[0,1] neg_hi:[0,1]
	v_pk_add_f32 v[102:103], v[98:99], v[100:101]
	v_pk_add_f32 v[88:89], v[94:95], v[88:89]
	v_rcp_f32_e32 v110, v102
	v_rcp_f32_e32 v111, v103
	v_pk_add_f32 v[94:95], v[112:113], v[88:89]
	v_pk_add_f32 v[98:99], v[102:103], v[98:99] neg_lo:[0,1] neg_hi:[0,1]
	v_pk_add_f32 v[112:113], v[94:95], v[112:113] neg_lo:[0,1] neg_hi:[0,1]
	v_pk_add_f32 v[98:99], v[100:101], v[98:99] neg_lo:[0,1] neg_hi:[0,1]
	v_pk_mul_f32 v[100:101], v[94:95], v[110:111]
	v_pk_add_f32 v[88:89], v[88:89], v[112:113] neg_lo:[0,1] neg_hi:[0,1]
	v_pk_mul_f32 v[112:113], v[102:103], v[100:101]
	v_pk_add_f32 v[84:85], v[90:91], v[84:85] neg_lo:[0,1] neg_hi:[0,1]
	v_pk_fma_f32 v[114:115], v[100:101], v[102:103], v[112:113] neg_lo:[0,0,1] neg_hi:[0,0,1]
	v_add_u32_e32 v81, 0xffff8000, v68
	v_pk_fma_f32 v[114:115], v[100:101], v[98:99], v[114:115]
	v_pk_add_f32 v[84:85], v[86:87], v[84:85] neg_lo:[0,1] neg_hi:[0,1]
	v_pk_add_f32 v[116:117], v[112:113], v[114:115]
	v_cndmask_b32_e64 v68, v68, v81, s[60:61]
	v_pk_add_f32 v[118:119], v[94:95], v[116:117] neg_lo:[0,1] neg_hi:[0,1]
	v_pk_add_f32 v[112:113], v[116:117], v[112:113] neg_lo:[0,1] neg_hi:[0,1]
	v_pk_add_f32 v[94:95], v[94:95], v[118:119] neg_lo:[0,1] neg_hi:[0,1]
	v_mov_b32_e32 v87, v85
	v_pk_add_f32 v[94:95], v[94:95], v[116:117] neg_lo:[0,1] neg_hi:[0,1]
	v_mov_b32_e32 v124, v90
	v_pk_add_f32 v[88:89], v[88:89], v[94:95]
	v_pk_add_f32 v[94:95], v[112:113], v[114:115] neg_lo:[0,1] neg_hi:[0,1]
	v_cmp_neq_f32_e32 vcc, s8, v83
	v_pk_add_f32 v[88:89], v[94:95], v[88:89]
	s_nop 0
	v_pk_add_f32 v[94:95], v[118:119], v[88:89]
	s_nop 0
	v_pk_mul_f32 v[112:113], v[110:111], v[94:95]
	s_nop 0
; __device__ __forceinline__ float logsigf(float x) { return fminf(x, 0.f) - log1pf(__expf(-fabsf(x))); }
; __device__ void phaseA_tile(const Params& p, int l, int mt, int nt, char* smem) {
;     ...
;                 {
;                     const int c = g4 * 4;
;                     const float4 fb = *(const float4*)(p.b_f + l * 16 + c);
;                     const f32x4 v = acc[i][2];
;                     float4 lf = make_float4(logsigf(v[0] + fb.x), logsigf(v[1] + fb.y), logsigf(v[2] + fb.z), logsigf(v[3] + fb.w));
;                     float* o = samp ? (p.out + O_LFS + ((size_t)l * TSM + (row - TP)) * 16 + c)
;                                     : (p.out + O_LFP + ((size_t)l * TP + row) * 16 + c);
;                     *(float4*)o = lf;
;                     *(float4*)(lf_s + rl * 16 + c) = lf;
	v_pk_mul_f32 v[114:115], v[102:103], v[112:113]
	s_nop 0
	v_pk_fma_f32 v[102:103], v[112:113], v[102:103], v[114:115] neg_lo:[0,0,1] neg_hi:[0,0,1]
	s_nop 0
	v_pk_fma_f32 v[98:99], v[112:113], v[98:99], v[102:103]
	v_pk_add_f32 v[102:103], v[118:119], v[94:95] neg_lo:[0,1] neg_hi:[0,1]
	s_nop 0
	v_pk_add_f32 v[88:89], v[88:89], v[102:103]
	v_pk_add_f32 v[102:103], v[114:115], v[98:99]
	s_nop 0
	v_pk_add_f32 v[116:117], v[94:95], v[102:103] neg_lo:[0,1] neg_hi:[0,1]
	v_pk_add_f32 v[114:115], v[102:103], v[114:115] neg_lo:[0,1] neg_hi:[0,1]
	v_pk_add_f32 v[94:95], v[94:95], v[116:117] neg_lo:[0,1] neg_hi:[0,1]
	s_nop 0
	v_pk_add_f32 v[94:95], v[94:95], v[102:103] neg_lo:[0,1] neg_hi:[0,1]
	s_nop 0
	v_pk_add_f32 v[88:89], v[88:89], v[94:95]
	v_pk_add_f32 v[94:95], v[114:115], v[98:99] neg_lo:[0,1] neg_hi:[0,1]
	s_nop 0
	v_pk_add_f32 v[88:89], v[94:95], v[88:89]
	v_pk_add_f32 v[94:95], v[100:101], v[112:113]
	v_pk_add_f32 v[88:89], v[116:117], v[88:89]
	v_pk_add_f32 v[98:99], v[94:95], v[100:101] neg_lo:[0,1] neg_hi:[0,1]
	v_pk_mul_f32 v[88:89], v[110:111], v[88:89]
	v_pk_add_f32 v[98:99], v[112:113], v[98:99] neg_lo:[0,1] neg_hi:[0,1]
	s_nop 0
	v_pk_add_f32 v[88:89], v[98:99], v[88:89]
	s_nop 0
	v_pk_add_f32 v[98:99], v[94:95], v[88:89]
	s_nop 0
	v_pk_mul_f32 v[100:101], v[98:99], v[98:99]
	v_pk_add_f32 v[94:95], v[98:99], v[94:95] neg_lo:[0,1] neg_hi:[0,1]
	v_pk_fma_f32 v[102:103], v[100:101], s[28:29], v[66:67] op_sel_hi:[1,0,0]
	v_pk_add_f32 v[88:89], v[88:89], v[94:95] neg_lo:[0,1] neg_hi:[0,1]
	v_ldexp_f32 v94, v98, 1
	v_pk_fma_f32 v[102:103], v[100:101], v[102:103], s[30:31] op_sel_hi:[1,1,0]
	v_ldexp_f32 v95, v99, 1
	v_pk_mul_f32 v[98:99], v[98:99], v[100:101]
	v_cvt_f32_i32_e32 v101, v120
	v_cvt_f32_i32_e32 v100, v97
	v_ldexp_f32 v111, v89, 1
	v_ashrrev_i32_e32 v89, 31, v81
	v_mov_b32_e32 v81, v93
	v_pk_mul_f32 v[112:113], v[100:101], s[12:13] op_sel_hi:[1,0]
	v_ldexp_f32 v88, v88, 1
	v_pk_fma_f32 v[114:115], v[100:101], s[12:13], v[112:113] op_sel_hi:[1,0,1] neg_lo:[0,0,1] neg_hi:[0,0,1]
	v_mov_b32_e32 v86, v112
	v_pk_fma_f32 v[100:101], v[100:101], s[14:15], v[114:115] op_sel_hi:[1,0,1]
	v_mov_b32_e32 v121, v113
	v_mov_b32_e32 v92, v100
	v_pk_add_f32 v[86:87], v[86:87], v[92:93]
	v_pk_add_f32 v[92:93], v[80:81], v[84:85]
	v_mov_b32_e32 v85, v91
	v_mov_b32_e32 v81, v93
	v_pk_add_f32 v[114:115], v[112:113], v[100:101]
	v_pk_add_f32 v[80:81], v[80:81], v[84:85]
	v_pk_add_f32 v[84:85], v[90:91], v[92:93]
	v_mov_b32_e32 v125, v115
	v_pk_add_f32 v[116:117], v[114:115], v[84:85]
	v_mov_b32_e32 v122, v84
	v_mov_b32_e32 v123, v117
	v_pk_add_f32 v[122:123], v[122:123], v[124:125] neg_lo:[0,1] neg_hi:[0,1]
	v_mov_b32_e32 v118, v116
	v_mov_b32_e32 v119, v115
	v_mov_b32_e32 v120, v114
	v_mov_b32_e32 v124, v114
	v_mov_b32_e32 v125, v117
	v_mov_b32_e32 v113, v123
	v_pk_add_f32 v[118:119], v[118:119], v[120:121] neg_lo:[0,1] neg_hi:[0,1]
	v_mov_b32_e32 v120, v84
	v_mov_b32_e32 v121, v101
	v_pk_add_f32 v[112:113], v[124:125], v[112:113] neg_lo:[0,1] neg_hi:[0,1]
	v_pk_add_f32 v[120:121], v[120:121], v[118:119] neg_lo:[0,1] neg_hi:[0,1]
	v_mov_b32_e32 v124, v112
	v_mov_b32_e32 v125, v119
	v_mov_b32_e32 v126, v116
	v_mov_b32_e32 v127, v85
	v_mov_b32_e32 v119, v91
	v_pk_add_f32 v[124:125], v[100:101], v[124:125] neg_lo:[0,1] neg_hi:[0,1]
	v_pk_add_f32 v[118:119], v[126:127], v[118:119] neg_lo:[0,1] neg_hi:[0,1]
	v_mov_b32_e32 v101, v115
	v_pk_add_f32 v[84:85], v[84:85], v[90:91] neg_lo:[0,1] neg_hi:[0,1]
	v_pk_add_f32 v[86:87], v[86:87], v[118:119] neg_lo:[0,1] neg_hi:[0,1]
	v_pk_add_f32 v[90:91], v[100:101], v[112:113] neg_lo:[0,1] neg_hi:[0,1]
	v_pk_add_f32 v[80:81], v[80:81], v[122:123] neg_lo:[0,1] neg_hi:[0,1]
	v_pk_add_f32 v[84:85], v[92:93], v[84:85] neg_lo:[0,1] neg_hi:[0,1]
	v_pk_add_f32 v[92:93], v[80:81], v[90:91]
	v_mov_b32_e32 v91, v121
	v_mov_b32_e32 v81, v87
	v_pk_add_f32 v[100:101], v[120:121], v[86:87]
	v_pk_add_f32 v[80:81], v[90:91], v[80:81]
	v_mov_b32_e32 v86, v92
	v_pk_add_f32 v[80:81], v[80:81], v[124:125] neg_lo:[0,1] neg_hi:[0,1]
	v_mov_b32_e32 v87, v101
	v_pk_add_f32 v[86:87], v[86:87], v[80:81] neg_lo:[0,1] neg_hi:[0,1]
	v_pk_add_f32 v[80:81], v[84:85], v[80:81] neg_lo:[0,1] neg_hi:[0,1]
	v_pk_add_f32 v[86:87], v[90:91], v[86:87] neg_lo:[0,1] neg_hi:[0,1]
	v_pk_add_f32 v[84:85], v[100:101], v[92:93]
	v_pk_add_f32 v[80:81], v[80:81], v[86:87]
	v_pk_add_f32 v[86:87], v[116:117], v[84:85]
	v_cndmask_b32_e64 v69, v69, v89, s[60:61]
	v_pk_add_f32 v[90:91], v[86:87], v[116:117] neg_lo:[0,1] neg_hi:[0,1]
	v_mov_b32_e32 v89, v111
	v_pk_add_f32 v[84:85], v[84:85], v[90:91] neg_lo:[0,1] neg_hi:[0,1]
	v_lshlrev_b64 v[68:69], 6, v[68:69]
	v_pk_add_f32 v[80:81], v[80:81], v[84:85]
	v_lshl_add_u64 v[68:69], s[6:7], 0, v[68:69]
	v_pk_add_f32 v[80:81], v[86:87], v[80:81]
	v_pk_mul_f32 v[86:87], v[98:99], v[102:103]
	v_cndmask_b32_e32 v80, v160, v80, vcc
	v_cmp_neq_f32_e32 vcc, s8, v128
	v_pk_add_f32 v[90:91], v[94:95], v[86:87]
	v_lshl_add_u64 v[68:69], v[68:69], 0, v[0:1]
	v_cndmask_b32_e32 v81, v160, v81, vcc
	v_cmp_ngt_f32_e32 vcc, -1.0, v128
	v_pk_add_f32 v[94:95], v[90:91], v[94:95] neg_lo:[0,1] neg_hi:[0,1]
	v_mov_b32_e32 v114, v90
	v_cndmask_b32_e32 v81, v161, v81, vcc
	v_cmp_ngt_f32_e32 vcc, -1.0, v83
	v_pk_add_f32 v[86:87], v[86:87], v[94:95] neg_lo:[0,1] neg_hi:[0,1]
	s_nop 0
	v_cndmask_b32_e32 v80, v161, v80, vcc
	v_cmp_neq_f32_e32 vcc, -1.0, v83
	v_pk_add_f32 v[98:99], v[88:89], v[86:87]
	v_mov_b32_e32 v95, v87
	v_cndmask_b32_e32 v80, v162, v80, vcc
	v_cmp_neq_f32_e32 vcc, -1.0, v128
	v_mov_b32_e32 v89, v99
	v_mov_b32_e32 v87, v91
	v_cndmask_b32_e32 v81, v162, v81, vcc
	v_cmp_lt_f32_e64 vcc, |v83|, s9
	v_cndmask_b32_e64 v81, v81, v128, s[0:1]
; __device__ __forceinline__ float softplusf(float x) { return fmaxf(x, 0.f) + log1pf(__expf(-fabsf(x))); }
; __device__ __forceinline__ float logsigf(float x) { return fminf(x, 0.f) - log1pf(__expf(-fabsf(x))); }
; __device__ void phaseA_tile(const Params& p, int l, int mt, int nt, char* smem) {
;     ...
;                 for (int j = 0; j < 2; ++j) {
;                     const int c = j * 16 + g4 * 4;
;                     const float4 db = *(const float4*)(p.dt_bias + l * 32 + c);
;                     const f32x4 v = acc[i][j];
;                     *(float4*)(p.dtb + (size_t)row * 32 + c) =
;                         make_float4(softplusf(v[0] + db.x), softplusf(v[1] + db.y), softplusf(v[2] + db.z), softplusf(v[3] + db.w));
;                 }
;                 {
;                     const int c = g4 * 4;
;                     const float4 fb = *(const float4*)(p.b_f + l * 16 + c);
;                     const f32x4 v = acc[i][2];
;                     float4 lf = make_float4(logsigf(v[0] + fb.x), logsigf(v[1] + fb.y), logsigf(v[2] + fb.z), logsigf(v[3] + fb.w));
;                     float* o = samp ? (p.out + O_LFS + ((size_t)l * TSM + (row - TP)) * 16 + c)
;                                     : (p.out + O_LFP + ((size_t)l * TP + row) * 16 + c);
;                     *(float4*)o = lf;
;                     *(float4*)(lf_s + rl * 16 + c) = lf;
;                 }
;             }
	v_pk_add_f32 v[86:87], v[88:89], v[86:87]
	v_cndmask_b32_e32 v80, v80, v83, vcc
	v_pk_add_f32 v[76:77], v[76:77], v[80:81] neg_lo:[0,1] neg_hi:[0,1]
	v_cvt_f32_i32_e32 v81, v132
	v_cvt_f32_i32_e32 v80, v130
	v_pk_add_f32 v[88:89], v[90:91], v[98:99]
	v_cmp_neq_f32_e32 vcc, s8, v129
	v_mov_b32_e32 v112, v88
	v_pk_mul_f32 v[84:85], v[80:81], s[12:13] op_sel_hi:[1,0]
	v_mov_b32_e32 v117, v89
	v_pk_fma_f32 v[92:93], v[80:81], s[12:13], v[84:85] op_sel_hi:[1,0,1] neg_lo:[0,0,1] neg_hi:[0,0,1]
	v_mov_b32_e32 v94, v84
	v_pk_fma_f32 v[80:81], v[80:81], s[14:15], v[92:93] op_sel_hi:[1,0,1]
	v_cmp_lt_f32_e64 s[0:1], |v131|, s9
	v_pk_add_f32 v[92:93], v[84:85], v[80:81]
	v_mov_b32_e32 v110, v80
	v_pk_add_f32 v[100:101], v[92:93], v[88:89]
	v_mov_b32_e32 v115, v93
	v_mov_b32_e32 v113, v101
	v_pk_add_f32 v[112:113], v[112:113], v[114:115] neg_lo:[0,1] neg_hi:[0,1]
	v_pk_add_f32 v[94:95], v[94:95], v[110:111]
	v_mov_b32_e32 v102, v100
	v_mov_b32_e32 v103, v93
	v_mov_b32_e32 v110, v92
	v_mov_b32_e32 v111, v85
	v_mov_b32_e32 v114, v92
	v_mov_b32_e32 v115, v101
	v_mov_b32_e32 v85, v113
	v_pk_add_f32 v[102:103], v[102:103], v[110:111] neg_lo:[0,1] neg_hi:[0,1]
	v_mov_b32_e32 v110, v88
	v_mov_b32_e32 v111, v81
	v_pk_add_f32 v[84:85], v[114:115], v[84:85] neg_lo:[0,1] neg_hi:[0,1]
	v_pk_add_f32 v[110:111], v[110:111], v[102:103] neg_lo:[0,1] neg_hi:[0,1]
	v_mov_b32_e32 v114, v84
	v_mov_b32_e32 v115, v103
	v_mov_b32_e32 v116, v100
	v_mov_b32_e32 v103, v91
	v_pk_add_f32 v[114:115], v[80:81], v[114:115] neg_lo:[0,1] neg_hi:[0,1]
	v_pk_add_f32 v[102:103], v[116:117], v[102:103] neg_lo:[0,1] neg_hi:[0,1]
	v_mov_b32_e32 v81, v93
	v_pk_add_f32 v[88:89], v[88:89], v[90:91] neg_lo:[0,1] neg_hi:[0,1]
	v_pk_add_f32 v[90:91], v[94:95], v[102:103] neg_lo:[0,1] neg_hi:[0,1]
	v_pk_add_f32 v[80:81], v[80:81], v[84:85] neg_lo:[0,1] neg_hi:[0,1]
	v_pk_add_f32 v[84:85], v[86:87], v[112:113] neg_lo:[0,1] neg_hi:[0,1]
	v_pk_add_f32 v[92:93], v[110:111], v[90:91]
	v_pk_add_f32 v[86:87], v[84:85], v[80:81]
	v_mov_b32_e32 v81, v111
	v_mov_b32_e32 v85, v91
	v_pk_add_f32 v[84:85], v[80:81], v[84:85]
	v_mov_b32_e32 v90, v86
	v_pk_add_f32 v[84:85], v[84:85], v[114:115] neg_lo:[0,1] neg_hi:[0,1]
	v_mov_b32_e32 v91, v93
	v_pk_add_f32 v[88:89], v[98:99], v[88:89] neg_lo:[0,1] neg_hi:[0,1]
	v_pk_add_f32 v[90:91], v[90:91], v[84:85] neg_lo:[0,1] neg_hi:[0,1]
	v_pk_add_f32 v[84:85], v[88:89], v[84:85] neg_lo:[0,1] neg_hi:[0,1]
	v_pk_add_f32 v[80:81], v[80:81], v[90:91] neg_lo:[0,1] neg_hi:[0,1]
	s_nop 0
	v_pk_add_f32 v[80:81], v[84:85], v[80:81]
	v_pk_add_f32 v[84:85], v[92:93], v[86:87]
	s_nop 0
	v_pk_add_f32 v[86:87], v[100:101], v[84:85]
	s_nop 0
	v_pk_add_f32 v[88:89], v[86:87], v[100:101] neg_lo:[0,1] neg_hi:[0,1]
	s_nop 0
	v_pk_add_f32 v[84:85], v[84:85], v[88:89] neg_lo:[0,1] neg_hi:[0,1]
	s_nop 0
	v_pk_add_f32 v[80:81], v[80:81], v[84:85]
	s_nop 0
	v_pk_add_f32 v[80:81], v[86:87], v[80:81]
	s_nop 0
	v_cndmask_b32_e32 v80, v160, v80, vcc
	v_cmp_neq_f32_e32 vcc, s8, v131
	s_nop 1
	v_cndmask_b32_e32 v81, v160, v81, vcc
	v_cmp_ngt_f32_e32 vcc, -1.0, v131
	s_nop 1
	v_cndmask_b32_e32 v81, v161, v81, vcc
	v_cmp_ngt_f32_e32 vcc, -1.0, v129
	s_nop 1
	v_cndmask_b32_e32 v80, v161, v80, vcc
	v_cmp_neq_f32_e32 vcc, -1.0, v129
	s_nop 1
	v_cndmask_b32_e32 v80, v162, v80, vcc
	v_cmp_neq_f32_e32 vcc, -1.0, v131
	s_nop 1
	v_cndmask_b32_e32 v81, v162, v81, vcc
	v_cmp_lt_f32_e64 vcc, |v129|, s9
	v_cndmask_b32_e64 v81, v81, v131, s[0:1]
	s_nop 0
	v_cndmask_b32_e32 v80, v80, v129, vcc
	v_pk_add_f32 v[78:79], v[78:79], v[80:81] neg_lo:[0,1] neg_hi:[0,1]
	global_store_dwordx4 v[68:69], v[76:79], off
	v_lshl_or_b32 v68, v82, 6, v0
	ds_write_b128 v68, v[76:79]
	global_load_dwordx4 v[78:81], v0, s[74:75]
	v_add_u32_e32 v68, s54, v71
	v_ashrrev_i32_e32 v69, 31, v68
	v_lshlrev_b64 v[76:77], 7, v[68:69]
	v_lshl_add_u64 v[76:77], s[10:11], 0, v[76:77]
	v_lshl_add_u64 v[76:77], v[76:77], 0, v[0:1]
	s_waitcnt vmcnt(0)
	v_add_f32_e32 v82, v14, v78
	v_max_f32_e32 v78, 0, v82
	v_mul_f32_e64 v82, |v82|, s2
	v_exp_f32_e32 v97, v82
	s_nop 0
	v_add_f32_e32 v84, 1.0, v97
	v_add_f32_e32 v82, -1.0, v84
	v_sub_f32_e32 v83, v82, v84
	v_add_f32_e32 v83, 1.0, v83
	v_sub_f32_e32 v82, v97, v82
	v_add_f32_e32 v85, v82, v83
	v_frexp_mant_f32_e32 v82, v84
	v_cmp_gt_f32_e32 vcc, s26, v82
	v_cvt_f64_f32_e32 v[82:83], v84
	v_frexp_exp_i32_f64_e32 v82, v[82:83]
	v_subbrev_co_u32_e32 v120, vcc, 0, v82, vcc
	v_sub_u32_e32 v83, 0, v120
	v_ldexp_f32 v82, v84, v83
	v_ldexp_f32 v84, v85, v83
	v_add_f32_e32 v83, v15, v79
	v_max_f32_e32 v79, 0, v83
	v_mul_f32_e64 v83, |v83|, s2
	v_exp_f32_e32 v128, v83
	s_nop 0
	v_add_f32_e32 v83, 1.0, v128
	v_add_f32_e32 v85, -1.0, v83
	v_sub_f32_e32 v86, v85, v83
	v_add_f32_e32 v86, 1.0, v86
	v_sub_f32_e32 v85, v128, v85
	v_add_f32_e32 v85, v85, v86
	v_frexp_mant_f32_e32 v86, v83
	v_cmp_gt_f32_e32 vcc, s26, v86
	v_cvt_f64_f32_e32 v[86:87], v83
	v_frexp_exp_i32_f64_e32 v86, v[86:87]
	v_subbrev_co_u32_e32 v121, vcc, 0, v86, vcc
	v_sub_u32_e32 v86, 0, v121
	v_ldexp_f32 v83, v83, v86
	v_ldexp_f32 v85, v85, v86
	v_pk_add_f32 v[86:87], v[82:83], 1.0 op_sel_hi:[1,0]
	v_pk_add_f32 v[94:95], v[82:83], -1.0 op_sel_hi:[1,0]
	v_pk_add_f32 v[88:89], v[86:87], -1.0 op_sel_hi:[1,0]
	v_pk_add_f32 v[98:99], v[94:95], 1.0 op_sel_hi:[1,0]
	v_pk_add_f32 v[88:89], v[82:83], v[88:89] neg_lo:[0,1] neg_hi:[0,1]
	v_pk_add_f32 v[82:83], v[82:83], v[98:99] neg_lo:[0,1] neg_hi:[0,1]
	v_pk_add_f32 v[88:89], v[84:85], v[88:89]
	v_pk_add_f32 v[82:83], v[84:85], v[82:83]
	v_pk_add_f32 v[90:91], v[86:87], v[88:89]
	v_pk_add_f32 v[84:85], v[94:95], v[82:83]
	v_rcp_f32_e32 v92, v90
	v_rcp_f32_e32 v93, v91
	v_pk_add_f32 v[86:87], v[90:91], v[86:87] neg_lo:[0,1] neg_hi:[0,1]
; __device__ __forceinline__ float softplusf(float x) { return fmaxf(x, 0.f) + log1pf(__expf(-fabsf(x))); }
; __device__ void phaseA_tile(const Params& p, int l, int mt, int nt, char* smem) {
;     ...
;                 for (int j = 0; j < 2; ++j) {
;                     const int c = j * 16 + g4 * 4;
;                     const float4 db = *(const float4*)(p.dt_bias + l * 32 + c);
;                     const f32x4 v = acc[i][j];
;                     *(float4*)(p.dtb + (size_t)row * 32 + c) =
;                         make_float4(softplusf(v[0] + db.x), softplusf(v[1] + db.y), softplusf(v[2] + db.z), softplusf(v[3] + db.w));
;                 }
	v_pk_add_f32 v[94:95], v[84:85], v[94:95] neg_lo:[0,1] neg_hi:[0,1]
	v_pk_add_f32 v[86:87], v[88:89], v[86:87] neg_lo:[0,1] neg_hi:[0,1]
	v_pk_mul_f32 v[88:89], v[84:85], v[92:93]
	v_pk_add_f32 v[82:83], v[82:83], v[94:95] neg_lo:[0,1] neg_hi:[0,1]
	v_pk_mul_f32 v[94:95], v[90:91], v[88:89]
	v_cmp_lt_f32_e64 s[0:1], |v128|, s9
	v_pk_fma_f32 v[98:99], v[88:89], v[90:91], v[94:95] neg_lo:[0,0,1] neg_hi:[0,0,1]
	s_nop 0
	v_pk_fma_f32 v[98:99], v[88:89], v[86:87], v[98:99]
	s_nop 0
	v_pk_add_f32 v[100:101], v[94:95], v[98:99]
	s_nop 0
	v_pk_add_f32 v[102:103], v[84:85], v[100:101] neg_lo:[0,1] neg_hi:[0,1]
	v_pk_add_f32 v[94:95], v[100:101], v[94:95] neg_lo:[0,1] neg_hi:[0,1]
	v_pk_add_f32 v[84:85], v[84:85], v[102:103] neg_lo:[0,1] neg_hi:[0,1]
	s_nop 0
	v_pk_add_f32 v[84:85], v[84:85], v[100:101] neg_lo:[0,1] neg_hi:[0,1]
	s_nop 0
	v_pk_add_f32 v[82:83], v[82:83], v[84:85]
	v_pk_add_f32 v[84:85], v[94:95], v[98:99] neg_lo:[0,1] neg_hi:[0,1]
	s_nop 0
	v_pk_add_f32 v[82:83], v[84:85], v[82:83]
	s_nop 0
	v_pk_add_f32 v[84:85], v[102:103], v[82:83]
	s_nop 0
	v_pk_mul_f32 v[94:95], v[92:93], v[84:85]
	s_nop 0
	v_pk_mul_f32 v[98:99], v[90:91], v[94:95]
	s_nop 0
	v_pk_fma_f32 v[90:91], v[94:95], v[90:91], v[98:99] neg_lo:[0,0,1] neg_hi:[0,0,1]
	s_nop 0
	v_pk_fma_f32 v[86:87], v[94:95], v[86:87], v[90:91]
	v_pk_add_f32 v[90:91], v[102:103], v[84:85] neg_lo:[0,1] neg_hi:[0,1]
	s_nop 0
	v_pk_add_f32 v[82:83], v[82:83], v[90:91]
	v_pk_add_f32 v[90:91], v[98:99], v[86:87]
	s_nop 0
	v_pk_add_f32 v[100:101], v[84:85], v[90:91] neg_lo:[0,1] neg_hi:[0,1]
	v_pk_add_f32 v[98:99], v[90:91], v[98:99] neg_lo:[0,1] neg_hi:[0,1]
	v_pk_add_f32 v[84:85], v[84:85], v[100:101] neg_lo:[0,1] neg_hi:[0,1]
	s_nop 0
	v_pk_add_f32 v[84:85], v[84:85], v[90:91] neg_lo:[0,1] neg_hi:[0,1]
	s_nop 0
	v_pk_add_f32 v[82:83], v[82:83], v[84:85]
	v_pk_add_f32 v[84:85], v[98:99], v[86:87] neg_lo:[0,1] neg_hi:[0,1]
	s_nop 0
	v_pk_add_f32 v[82:83], v[84:85], v[82:83]
	v_pk_add_f32 v[84:85], v[88:89], v[94:95]
	v_pk_add_f32 v[82:83], v[100:101], v[82:83]
	v_pk_add_f32 v[86:87], v[84:85], v[88:89] neg_lo:[0,1] neg_hi:[0,1]
	v_pk_mul_f32 v[82:83], v[92:93], v[82:83]
	v_pk_add_f32 v[86:87], v[94:95], v[86:87] neg_lo:[0,1] neg_hi:[0,1]
	s_nop 0
	v_pk_add_f32 v[82:83], v[86:87], v[82:83]
	s_nop 0
	v_pk_add_f32 v[86:87], v[84:85], v[82:83]
	s_nop 0
	v_pk_add_f32 v[84:85], v[86:87], v[84:85] neg_lo:[0,1] neg_hi:[0,1]
	v_pk_mul_f32 v[88:89], v[86:87], v[86:87]
	v_pk_add_f32 v[82:83], v[82:83], v[84:85] neg_lo:[0,1] neg_hi:[0,1]
	v_pk_fma_f32 v[90:91], v[88:89], s[28:29], v[66:67] op_sel_hi:[1,0,0]
	v_ldexp_f32 v93, v83, 1
	v_add_f32_e32 v83, v16, v80
	v_max_f32_e32 v80, 0, v83
	v_mul_f32_e64 v83, |v83|, s2
	v_exp_f32_e32 v129, v83
	v_ldexp_f32 v84, v86, 1
	v_pk_fma_f32 v[90:91], v[88:89], v[90:91], s[30:31] op_sel_hi:[1,1,0]
	v_ldexp_f32 v85, v87, 1
	v_add_f32_e32 v83, 1.0, v129
	v_pk_mul_f32 v[86:87], v[86:87], v[88:89]
	v_add_f32_e32 v88, -1.0, v83
	v_sub_f32_e32 v89, v88, v83
	v_add_f32_e32 v89, 1.0, v89
	v_sub_f32_e32 v88, v129, v88
	v_add_f32_e32 v92, v88, v89
	v_frexp_mant_f32_e32 v88, v83
	v_cmp_gt_f32_e32 vcc, s26, v88
	v_cvt_f64_f32_e32 v[88:89], v83
	v_frexp_exp_i32_f64_e32 v88, v[88:89]
	v_subbrev_co_u32_e32 v130, vcc, 0, v88, vcc
	v_sub_u32_e32 v89, 0, v130
	v_ldexp_f32 v88, v83, v89
	v_add_f32_e32 v83, v17, v81
	v_max_f32_e32 v81, 0, v83
	v_mul_f32_e64 v83, |v83|, s2
	v_exp_f32_e32 v131, v83
	v_ldexp_f32 v94, v92, v89
	v_pk_mul_f32 v[86:87], v[86:87], v[90:91]
	v_ldexp_f32 v82, v82, 1
	v_add_f32_e32 v83, 1.0, v131
	v_add_f32_e32 v89, -1.0, v83
	v_sub_f32_e32 v92, v89, v83
	v_add_f32_e32 v92, 1.0, v92
	v_sub_f32_e32 v89, v131, v89
	v_add_f32_e32 v92, v89, v92
	v_frexp_mant_f32_e32 v89, v83
	v_cvt_f64_f32_e32 v[98:99], v83
	v_cmp_gt_f32_e32 vcc, s26, v89
	v_frexp_exp_i32_f64_e32 v89, v[98:99]
	v_pk_add_f32 v[90:91], v[84:85], v[86:87]
	v_subbrev_co_u32_e32 v132, vcc, 0, v89, vcc
	v_sub_u32_e32 v95, 0, v132
	v_ldexp_f32 v89, v83, v95
	v_pk_add_f32 v[98:99], v[88:89], 1.0 op_sel_hi:[1,0]
	v_ldexp_f32 v95, v92, v95
	v_pk_add_f32 v[100:101], v[98:99], -1.0 op_sel_hi:[1,0]
	v_pk_add_f32 v[112:113], v[88:89], -1.0 op_sel_hi:[1,0]
	v_pk_add_f32 v[100:101], v[88:89], v[100:101] neg_lo:[0,1] neg_hi:[0,1]
	v_pk_add_f32 v[114:115], v[112:113], 1.0 op_sel_hi:[1,0]
	v_pk_add_f32 v[100:101], v[94:95], v[100:101]
	v_pk_add_f32 v[88:89], v[88:89], v[114:115] neg_lo:[0,1] neg_hi:[0,1]
	v_pk_add_f32 v[102:103], v[98:99], v[100:101]
	v_pk_add_f32 v[88:89], v[94:95], v[88:89]
	v_rcp_f32_e32 v110, v102
	v_rcp_f32_e32 v111, v103
	v_pk_add_f32 v[94:95], v[112:113], v[88:89]
	v_pk_add_f32 v[98:99], v[102:103], v[98:99] neg_lo:[0,1] neg_hi:[0,1]
	v_pk_add_f32 v[112:113], v[94:95], v[112:113] neg_lo:[0,1] neg_hi:[0,1]
	v_pk_add_f32 v[98:99], v[100:101], v[98:99] neg_lo:[0,1] neg_hi:[0,1]
	v_pk_mul_f32 v[100:101], v[94:95], v[110:111]
	v_pk_add_f32 v[88:89], v[88:89], v[112:113] neg_lo:[0,1] neg_hi:[0,1]
	v_pk_mul_f32 v[112:113], v[102:103], v[100:101]
	v_pk_add_f32 v[84:85], v[90:91], v[84:85] neg_lo:[0,1] neg_hi:[0,1]
	v_pk_fma_f32 v[114:115], v[100:101], v[102:103], v[112:113] neg_lo:[0,0,1] neg_hi:[0,0,1]
	v_pk_add_f32 v[84:85], v[86:87], v[84:85] neg_lo:[0,1] neg_hi:[0,1]
	v_pk_fma_f32 v[114:115], v[100:101], v[98:99], v[114:115]
	v_mov_b32_e32 v87, v85
	v_pk_add_f32 v[116:117], v[112:113], v[114:115]
	v_mov_b32_e32 v83, v93
	v_pk_add_f32 v[118:119], v[94:95], v[116:117] neg_lo:[0,1] neg_hi:[0,1]
	v_pk_add_f32 v[112:113], v[116:117], v[112:113] neg_lo:[0,1] neg_hi:[0,1]
	v_pk_add_f32 v[94:95], v[94:95], v[118:119] neg_lo:[0,1] neg_hi:[0,1]
	v_mov_b32_e32 v124, v90
	v_pk_add_f32 v[94:95], v[94:95], v[116:117] neg_lo:[0,1] neg_hi:[0,1]
; __device__ __forceinline__ float softplusf(float x) { return fmaxf(x, 0.f) + log1pf(__expf(-fabsf(x))); }
; __device__ void phaseA_tile(const Params& p, int l, int mt, int nt, char* smem) {
;     ...
;                 for (int j = 0; j < 2; ++j) {
;                     const int c = j * 16 + g4 * 4;
;                     const float4 db = *(const float4*)(p.dt_bias + l * 32 + c);
;                     const f32x4 v = acc[i][j];
;                     *(float4*)(p.dtb + (size_t)row * 32 + c) =
;                         make_float4(softplusf(v[0] + db.x), softplusf(v[1] + db.y), softplusf(v[2] + db.z), softplusf(v[3] + db.w));
;                 }
	v_cmp_neq_f32_e32 vcc, s8, v97
	v_pk_add_f32 v[88:89], v[88:89], v[94:95]
	v_pk_add_f32 v[94:95], v[112:113], v[114:115] neg_lo:[0,1] neg_hi:[0,1]
	s_nop 0
	v_pk_add_f32 v[88:89], v[94:95], v[88:89]
	s_nop 0
	v_pk_add_f32 v[94:95], v[118:119], v[88:89]
	s_nop 0
	v_pk_mul_f32 v[112:113], v[110:111], v[94:95]
	s_nop 0
	v_pk_mul_f32 v[114:115], v[102:103], v[112:113]
	s_nop 0
	v_pk_fma_f32 v[102:103], v[112:113], v[102:103], v[114:115] neg_lo:[0,0,1] neg_hi:[0,0,1]
	s_nop 0
	v_pk_fma_f32 v[98:99], v[112:113], v[98:99], v[102:103]
	v_pk_add_f32 v[102:103], v[118:119], v[94:95] neg_lo:[0,1] neg_hi:[0,1]
	s_nop 0
	v_pk_add_f32 v[88:89], v[88:89], v[102:103]
	v_pk_add_f32 v[102:103], v[114:115], v[98:99]
	s_nop 0
	v_pk_add_f32 v[116:117], v[94:95], v[102:103] neg_lo:[0,1] neg_hi:[0,1]
	v_pk_add_f32 v[114:115], v[102:103], v[114:115] neg_lo:[0,1] neg_hi:[0,1]
	v_pk_add_f32 v[94:95], v[94:95], v[116:117] neg_lo:[0,1] neg_hi:[0,1]
	s_nop 0
	v_pk_add_f32 v[94:95], v[94:95], v[102:103] neg_lo:[0,1] neg_hi:[0,1]
	s_nop 0
	v_pk_add_f32 v[88:89], v[88:89], v[94:95]
	v_pk_add_f32 v[94:95], v[114:115], v[98:99] neg_lo:[0,1] neg_hi:[0,1]
	s_nop 0
	v_pk_add_f32 v[88:89], v[94:95], v[88:89]
	v_pk_add_f32 v[94:95], v[100:101], v[112:113]
	v_pk_add_f32 v[88:89], v[116:117], v[88:89]
	v_pk_add_f32 v[98:99], v[94:95], v[100:101] neg_lo:[0,1] neg_hi:[0,1]
	v_pk_mul_f32 v[88:89], v[110:111], v[88:89]
	v_pk_add_f32 v[98:99], v[112:113], v[98:99] neg_lo:[0,1] neg_hi:[0,1]
	s_nop 0
	v_pk_add_f32 v[88:89], v[98:99], v[88:89]
	s_nop 0
	v_pk_add_f32 v[98:99], v[94:95], v[88:89]
	s_nop 0
	v_pk_mul_f32 v[100:101], v[98:99], v[98:99]
	v_pk_add_f32 v[94:95], v[98:99], v[94:95] neg_lo:[0,1] neg_hi:[0,1]
	v_pk_fma_f32 v[102:103], v[100:101], s[28:29], v[66:67] op_sel_hi:[1,0,0]
	v_pk_add_f32 v[88:89], v[88:89], v[94:95] neg_lo:[0,1] neg_hi:[0,1]
	v_ldexp_f32 v94, v98, 1
	v_pk_fma_f32 v[102:103], v[100:101], v[102:103], s[30:31] op_sel_hi:[1,1,0]
	v_ldexp_f32 v95, v99, 1
	v_pk_mul_f32 v[98:99], v[98:99], v[100:101]
	v_cvt_f32_i32_e32 v101, v121
	v_cvt_f32_i32_e32 v100, v120
	v_ldexp_f32 v111, v89, 1
	v_ldexp_f32 v88, v88, 1
	v_mov_b32_e32 v89, v111
	v_pk_mul_f32 v[112:113], v[100:101], s[12:13] op_sel_hi:[1,0]
	s_nop 0
	v_pk_fma_f32 v[114:115], v[100:101], s[12:13], v[112:113] op_sel_hi:[1,0,1] neg_lo:[0,0,1] neg_hi:[0,0,1]
	v_mov_b32_e32 v86, v112
	v_pk_fma_f32 v[100:101], v[100:101], s[14:15], v[114:115] op_sel_hi:[1,0,1]
	v_mov_b32_e32 v121, v113
	v_mov_b32_e32 v92, v100
	v_pk_add_f32 v[86:87], v[86:87], v[92:93]
	v_pk_add_f32 v[92:93], v[82:83], v[84:85]
	v_mov_b32_e32 v85, v91
	v_mov_b32_e32 v83, v93
	v_pk_add_f32 v[114:115], v[112:113], v[100:101]
	v_pk_add_f32 v[82:83], v[82:83], v[84:85]
	v_pk_add_f32 v[84:85], v[90:91], v[92:93]
	v_mov_b32_e32 v125, v115
	v_pk_add_f32 v[116:117], v[114:115], v[84:85]
	v_mov_b32_e32 v122, v84
	v_mov_b32_e32 v123, v117
	v_pk_add_f32 v[122:123], v[122:123], v[124:125] neg_lo:[0,1] neg_hi:[0,1]
	v_mov_b32_e32 v118, v116
	v_mov_b32_e32 v119, v115
	v_mov_b32_e32 v120, v114
	v_mov_b32_e32 v124, v114
	v_mov_b32_e32 v125, v117
	v_mov_b32_e32 v113, v123
	v_pk_add_f32 v[118:119], v[118:119], v[120:121] neg_lo:[0,1] neg_hi:[0,1]
	v_mov_b32_e32 v120, v84
	v_mov_b32_e32 v121, v101
	v_pk_add_f32 v[112:113], v[124:125], v[112:113] neg_lo:[0,1] neg_hi:[0,1]
	v_pk_add_f32 v[120:121], v[120:121], v[118:119] neg_lo:[0,1] neg_hi:[0,1]
	v_mov_b32_e32 v124, v112
	v_mov_b32_e32 v125, v119
	v_mov_b32_e32 v126, v116
	v_mov_b32_e32 v127, v85
	v_mov_b32_e32 v119, v91
	v_pk_add_f32 v[124:125], v[100:101], v[124:125] neg_lo:[0,1] neg_hi:[0,1]
	v_pk_add_f32 v[118:119], v[126:127], v[118:119] neg_lo:[0,1] neg_hi:[0,1]
	v_mov_b32_e32 v101, v115
	v_pk_add_f32 v[84:85], v[84:85], v[90:91] neg_lo:[0,1] neg_hi:[0,1]
	v_pk_add_f32 v[86:87], v[86:87], v[118:119] neg_lo:[0,1] neg_hi:[0,1]
	v_pk_add_f32 v[90:91], v[100:101], v[112:113] neg_lo:[0,1] neg_hi:[0,1]
	v_pk_add_f32 v[82:83], v[82:83], v[122:123] neg_lo:[0,1] neg_hi:[0,1]
	v_pk_add_f32 v[84:85], v[92:93], v[84:85] neg_lo:[0,1] neg_hi:[0,1]
	v_pk_add_f32 v[92:93], v[82:83], v[90:91]
	v_mov_b32_e32 v91, v121
	v_mov_b32_e32 v83, v87
	v_pk_add_f32 v[100:101], v[120:121], v[86:87]
	v_pk_add_f32 v[82:83], v[90:91], v[82:83]
	v_mov_b32_e32 v86, v92
	v_pk_add_f32 v[82:83], v[82:83], v[124:125] neg_lo:[0,1] neg_hi:[0,1]
	v_mov_b32_e32 v87, v101
	v_pk_add_f32 v[86:87], v[86:87], v[82:83] neg_lo:[0,1] neg_hi:[0,1]
	v_pk_add_f32 v[82:83], v[84:85], v[82:83] neg_lo:[0,1] neg_hi:[0,1]
	v_pk_add_f32 v[86:87], v[90:91], v[86:87] neg_lo:[0,1] neg_hi:[0,1]
	v_pk_add_f32 v[84:85], v[100:101], v[92:93]
	v_pk_add_f32 v[82:83], v[82:83], v[86:87]
	v_pk_add_f32 v[86:87], v[116:117], v[84:85]
	s_nop 0
	v_pk_add_f32 v[90:91], v[86:87], v[116:117] neg_lo:[0,1] neg_hi:[0,1]
	s_nop 0
	v_pk_add_f32 v[84:85], v[84:85], v[90:91] neg_lo:[0,1] neg_hi:[0,1]
	s_nop 0
	v_pk_add_f32 v[82:83], v[82:83], v[84:85]
	s_nop 0
	v_pk_add_f32 v[82:83], v[86:87], v[82:83]
	v_pk_mul_f32 v[86:87], v[98:99], v[102:103]
	v_cndmask_b32_e32 v82, v160, v82, vcc
	v_cmp_neq_f32_e32 vcc, s8, v128
	v_pk_add_f32 v[90:91], v[94:95], v[86:87]
	s_nop 0
	v_cndmask_b32_e32 v83, v160, v83, vcc
	v_cmp_ngt_f32_e32 vcc, -1.0, v128
	v_pk_add_f32 v[94:95], v[90:91], v[94:95] neg_lo:[0,1] neg_hi:[0,1]
	v_mov_b32_e32 v114, v90
	v_cndmask_b32_e32 v83, v161, v83, vcc
	v_cmp_ngt_f32_e32 vcc, -1.0, v97
	v_pk_add_f32 v[86:87], v[86:87], v[94:95] neg_lo:[0,1] neg_hi:[0,1]
	s_nop 0
	v_cndmask_b32_e32 v82, v161, v82, vcc
	v_cmp_neq_f32_e32 vcc, -1.0, v97
	v_pk_add_f32 v[98:99], v[88:89], v[86:87]
	v_mov_b32_e32 v95, v87
	v_cndmask_b32_e32 v82, v162, v82, vcc
	v_cmp_neq_f32_e32 vcc, -1.0, v128
; __device__ __forceinline__ float softplusf(float x) { return fmaxf(x, 0.f) + log1pf(__expf(-fabsf(x))); }
; __device__ void phaseA_tile(const Params& p, int l, int mt, int nt, char* smem) {
;     ...
;                 for (int j = 0; j < 2; ++j) {
;                     const int c = j * 16 + g4 * 4;
;                     const float4 db = *(const float4*)(p.dt_bias + l * 32 + c);
;                     const f32x4 v = acc[i][j];
;                     *(float4*)(p.dtb + (size_t)row * 32 + c) =
;                         make_float4(softplusf(v[0] + db.x), softplusf(v[1] + db.y), softplusf(v[2] + db.z), softplusf(v[3] + db.w));
;                 }
	v_mov_b32_e32 v89, v99
	v_mov_b32_e32 v87, v91
	v_cndmask_b32_e32 v83, v162, v83, vcc
	v_cmp_lt_f32_e64 vcc, |v97|, s9
	v_cndmask_b32_e64 v83, v83, v128, s[0:1]
	v_pk_add_f32 v[86:87], v[88:89], v[86:87]
	v_cndmask_b32_e32 v82, v82, v97, vcc
	v_pk_add_f32 v[78:79], v[78:79], v[82:83]
	v_cvt_f32_i32_e32 v83, v132
	v_cvt_f32_i32_e32 v82, v130
	v_pk_add_f32 v[88:89], v[90:91], v[98:99]
	v_cmp_neq_f32_e32 vcc, s8, v129
	v_mov_b32_e32 v112, v88
	v_pk_mul_f32 v[84:85], v[82:83], s[12:13] op_sel_hi:[1,0]
	v_mov_b32_e32 v117, v89
	v_pk_fma_f32 v[92:93], v[82:83], s[12:13], v[84:85] op_sel_hi:[1,0,1] neg_lo:[0,0,1] neg_hi:[0,0,1]
	v_mov_b32_e32 v94, v84
	v_pk_fma_f32 v[82:83], v[82:83], s[14:15], v[92:93] op_sel_hi:[1,0,1]
	v_cmp_lt_f32_e64 s[0:1], |v131|, s9
	v_pk_add_f32 v[92:93], v[84:85], v[82:83]
	v_mov_b32_e32 v110, v82
	v_pk_add_f32 v[100:101], v[92:93], v[88:89]
	v_mov_b32_e32 v115, v93
	v_mov_b32_e32 v113, v101
	v_pk_add_f32 v[112:113], v[112:113], v[114:115] neg_lo:[0,1] neg_hi:[0,1]
	v_pk_add_f32 v[94:95], v[94:95], v[110:111]
	v_mov_b32_e32 v102, v100
	v_mov_b32_e32 v103, v93
	v_mov_b32_e32 v110, v92
	v_mov_b32_e32 v111, v85
	v_mov_b32_e32 v114, v92
	v_mov_b32_e32 v115, v101
	v_mov_b32_e32 v85, v113
	v_pk_add_f32 v[102:103], v[102:103], v[110:111] neg_lo:[0,1] neg_hi:[0,1]
	v_mov_b32_e32 v110, v88
	v_mov_b32_e32 v111, v83
	v_pk_add_f32 v[84:85], v[114:115], v[84:85] neg_lo:[0,1] neg_hi:[0,1]
	v_pk_add_f32 v[110:111], v[110:111], v[102:103] neg_lo:[0,1] neg_hi:[0,1]
	v_mov_b32_e32 v114, v84
	v_mov_b32_e32 v115, v103
	v_mov_b32_e32 v116, v100
	v_mov_b32_e32 v103, v91
	v_pk_add_f32 v[114:115], v[82:83], v[114:115] neg_lo:[0,1] neg_hi:[0,1]
	v_pk_add_f32 v[102:103], v[116:117], v[102:103] neg_lo:[0,1] neg_hi:[0,1]
	v_mov_b32_e32 v83, v93
	v_pk_add_f32 v[88:89], v[88:89], v[90:91] neg_lo:[0,1] neg_hi:[0,1]
	v_pk_add_f32 v[90:91], v[94:95], v[102:103] neg_lo:[0,1] neg_hi:[0,1]
	v_pk_add_f32 v[82:83], v[82:83], v[84:85] neg_lo:[0,1] neg_hi:[0,1]
	v_pk_add_f32 v[84:85], v[86:87], v[112:113] neg_lo:[0,1] neg_hi:[0,1]
	v_pk_add_f32 v[92:93], v[110:111], v[90:91]
	v_pk_add_f32 v[86:87], v[84:85], v[82:83]
	v_mov_b32_e32 v83, v111
	v_mov_b32_e32 v85, v91
	v_pk_add_f32 v[84:85], v[82:83], v[84:85]
	v_mov_b32_e32 v90, v86
	v_pk_add_f32 v[84:85], v[84:85], v[114:115] neg_lo:[0,1] neg_hi:[0,1]
	v_mov_b32_e32 v91, v93
	v_pk_add_f32 v[88:89], v[98:99], v[88:89] neg_lo:[0,1] neg_hi:[0,1]
	v_pk_add_f32 v[90:91], v[90:91], v[84:85] neg_lo:[0,1] neg_hi:[0,1]
	v_pk_add_f32 v[84:85], v[88:89], v[84:85] neg_lo:[0,1] neg_hi:[0,1]
	v_pk_add_f32 v[82:83], v[82:83], v[90:91] neg_lo:[0,1] neg_hi:[0,1]
	s_nop 0
	v_pk_add_f32 v[82:83], v[84:85], v[82:83]
	v_pk_add_f32 v[84:85], v[92:93], v[86:87]
	s_nop 0
	v_pk_add_f32 v[86:87], v[100:101], v[84:85]
	s_nop 0
	v_pk_add_f32 v[88:89], v[86:87], v[100:101] neg_lo:[0,1] neg_hi:[0,1]
	s_nop 0
	v_pk_add_f32 v[84:85], v[84:85], v[88:89] neg_lo:[0,1] neg_hi:[0,1]
	s_nop 0
	v_pk_add_f32 v[82:83], v[82:83], v[84:85]
	s_nop 0
	v_pk_add_f32 v[82:83], v[86:87], v[82:83]
	s_nop 0
	v_cndmask_b32_e32 v82, v160, v82, vcc
	v_cmp_neq_f32_e32 vcc, s8, v131
	s_nop 1
	v_cndmask_b32_e32 v83, v160, v83, vcc
	v_cmp_ngt_f32_e32 vcc, -1.0, v131
	s_nop 1
	v_cndmask_b32_e32 v83, v161, v83, vcc
	v_cmp_ngt_f32_e32 vcc, -1.0, v129
	s_nop 1
	v_cndmask_b32_e32 v82, v161, v82, vcc
	v_cmp_neq_f32_e32 vcc, -1.0, v129
	s_nop 1
	v_cndmask_b32_e32 v82, v162, v82, vcc
	v_cmp_neq_f32_e32 vcc, -1.0, v131
	s_nop 1
	v_cndmask_b32_e32 v83, v162, v83, vcc
	v_cmp_lt_f32_e64 vcc, |v129|, s9
	v_cndmask_b32_e64 v83, v83, v131, s[0:1]
	s_nop 0
	v_cndmask_b32_e32 v82, v82, v129, vcc
	v_pk_add_f32 v[80:81], v[80:81], v[82:83]
	global_store_dwordx4 v[76:77], v[78:81], off
	global_load_dwordx4 v[78:81], v0, s[74:75] offset:64
	s_waitcnt vmcnt(0)
	v_add_f32_e32 v82, v10, v78
	v_max_f32_e32 v78, 0, v82
	v_mul_f32_e64 v82, |v82|, s2
	v_exp_f32_e32 v97, v82
	s_nop 0
	v_add_f32_e32 v84, 1.0, v97
	v_add_f32_e32 v82, -1.0, v84
	v_sub_f32_e32 v83, v82, v84
	v_add_f32_e32 v83, 1.0, v83
	v_sub_f32_e32 v82, v97, v82
	v_add_f32_e32 v85, v82, v83
	v_frexp_mant_f32_e32 v82, v84
	v_cmp_gt_f32_e32 vcc, s26, v82
	v_cvt_f64_f32_e32 v[82:83], v84
	v_frexp_exp_i32_f64_e32 v82, v[82:83]
	v_subbrev_co_u32_e32 v120, vcc, 0, v82, vcc
	v_sub_u32_e32 v83, 0, v120
	v_ldexp_f32 v82, v84, v83
	v_ldexp_f32 v84, v85, v83
	v_add_f32_e32 v83, v11, v79
	v_max_f32_e32 v79, 0, v83
	v_mul_f32_e64 v83, |v83|, s2
	v_exp_f32_e32 v128, v83
	s_nop 0
	v_add_f32_e32 v83, 1.0, v128
	v_add_f32_e32 v85, -1.0, v83
	v_sub_f32_e32 v86, v85, v83
	v_add_f32_e32 v86, 1.0, v86
	v_sub_f32_e32 v85, v128, v85
	v_add_f32_e32 v85, v85, v86
	v_frexp_mant_f32_e32 v86, v83
	v_cmp_gt_f32_e32 vcc, s26, v86
	v_cvt_f64_f32_e32 v[86:87], v83
	v_frexp_exp_i32_f64_e32 v86, v[86:87]
	v_subbrev_co_u32_e32 v121, vcc, 0, v86, vcc
	v_sub_u32_e32 v86, 0, v121
	v_ldexp_f32 v83, v83, v86
	v_ldexp_f32 v85, v85, v86
	v_pk_add_f32 v[86:87], v[82:83], 1.0 op_sel_hi:[1,0]
	v_pk_add_f32 v[94:95], v[82:83], -1.0 op_sel_hi:[1,0]
	v_pk_add_f32 v[88:89], v[86:87], -1.0 op_sel_hi:[1,0]
	v_pk_add_f32 v[98:99], v[94:95], 1.0 op_sel_hi:[1,0]
	v_pk_add_f32 v[88:89], v[82:83], v[88:89] neg_lo:[0,1] neg_hi:[0,1]
	v_pk_add_f32 v[82:83], v[82:83], v[98:99] neg_lo:[0,1] neg_hi:[0,1]
	v_pk_add_f32 v[88:89], v[84:85], v[88:89]
	v_pk_add_f32 v[82:83], v[84:85], v[82:83]
	v_pk_add_f32 v[90:91], v[86:87], v[88:89]
	v_pk_add_f32 v[84:85], v[94:95], v[82:83]
	v_rcp_f32_e32 v92, v90
	v_rcp_f32_e32 v93, v91
	v_pk_add_f32 v[86:87], v[90:91], v[86:87] neg_lo:[0,1] neg_hi:[0,1]
	v_pk_add_f32 v[94:95], v[84:85], v[94:95] neg_lo:[0,1] neg_hi:[0,1]
; __device__ __forceinline__ float softplusf(float x) { return fmaxf(x, 0.f) + log1pf(__expf(-fabsf(x))); }
; __device__ void phaseA_tile(const Params& p, int l, int mt, int nt, char* smem) {
;     ...
;                 for (int j = 0; j < 2; ++j) {
;                     const int c = j * 16 + g4 * 4;
;                     const float4 db = *(const float4*)(p.dt_bias + l * 32 + c);
;                     const f32x4 v = acc[i][j];
;                     *(float4*)(p.dtb + (size_t)row * 32 + c) =
;                         make_float4(softplusf(v[0] + db.x), softplusf(v[1] + db.y), softplusf(v[2] + db.z), softplusf(v[3] + db.w));
;                 }
	v_pk_add_f32 v[86:87], v[88:89], v[86:87] neg_lo:[0,1] neg_hi:[0,1]
	v_pk_mul_f32 v[88:89], v[84:85], v[92:93]
	v_pk_add_f32 v[82:83], v[82:83], v[94:95] neg_lo:[0,1] neg_hi:[0,1]
	v_pk_mul_f32 v[94:95], v[90:91], v[88:89]
	v_cmp_lt_f32_e64 s[0:1], |v128|, s9
	v_pk_fma_f32 v[98:99], v[88:89], v[90:91], v[94:95] neg_lo:[0,0,1] neg_hi:[0,0,1]
	s_nop 0
	v_pk_fma_f32 v[98:99], v[88:89], v[86:87], v[98:99]
	s_nop 0
	v_pk_add_f32 v[100:101], v[94:95], v[98:99]
	s_nop 0
	v_pk_add_f32 v[102:103], v[84:85], v[100:101] neg_lo:[0,1] neg_hi:[0,1]
	v_pk_add_f32 v[94:95], v[100:101], v[94:95] neg_lo:[0,1] neg_hi:[0,1]
	v_pk_add_f32 v[84:85], v[84:85], v[102:103] neg_lo:[0,1] neg_hi:[0,1]
	s_nop 0
	v_pk_add_f32 v[84:85], v[84:85], v[100:101] neg_lo:[0,1] neg_hi:[0,1]
	s_nop 0
	v_pk_add_f32 v[82:83], v[82:83], v[84:85]
	v_pk_add_f32 v[84:85], v[94:95], v[98:99] neg_lo:[0,1] neg_hi:[0,1]
	s_nop 0
	v_pk_add_f32 v[82:83], v[84:85], v[82:83]
	s_nop 0
	v_pk_add_f32 v[84:85], v[102:103], v[82:83]
	s_nop 0
	v_pk_mul_f32 v[94:95], v[92:93], v[84:85]
	s_nop 0
	v_pk_mul_f32 v[98:99], v[90:91], v[94:95]
	s_nop 0
	v_pk_fma_f32 v[90:91], v[94:95], v[90:91], v[98:99] neg_lo:[0,0,1] neg_hi:[0,0,1]
	s_nop 0
	v_pk_fma_f32 v[86:87], v[94:95], v[86:87], v[90:91]
	v_pk_add_f32 v[90:91], v[102:103], v[84:85] neg_lo:[0,1] neg_hi:[0,1]
	s_nop 0
	v_pk_add_f32 v[82:83], v[82:83], v[90:91]
	v_pk_add_f32 v[90:91], v[98:99], v[86:87]
	s_nop 0
	v_pk_add_f32 v[100:101], v[84:85], v[90:91] neg_lo:[0,1] neg_hi:[0,1]
	v_pk_add_f32 v[98:99], v[90:91], v[98:99] neg_lo:[0,1] neg_hi:[0,1]
	v_pk_add_f32 v[84:85], v[84:85], v[100:101] neg_lo:[0,1] neg_hi:[0,1]
	s_nop 0
	v_pk_add_f32 v[84:85], v[84:85], v[90:91] neg_lo:[0,1] neg_hi:[0,1]
	s_nop 0
	v_pk_add_f32 v[82:83], v[82:83], v[84:85]
	v_pk_add_f32 v[84:85], v[98:99], v[86:87] neg_lo:[0,1] neg_hi:[0,1]
	s_nop 0
	v_pk_add_f32 v[82:83], v[84:85], v[82:83]
	v_pk_add_f32 v[84:85], v[88:89], v[94:95]
	v_pk_add_f32 v[82:83], v[100:101], v[82:83]
	v_pk_add_f32 v[86:87], v[84:85], v[88:89] neg_lo:[0,1] neg_hi:[0,1]
	v_pk_mul_f32 v[82:83], v[92:93], v[82:83]
	v_pk_add_f32 v[86:87], v[94:95], v[86:87] neg_lo:[0,1] neg_hi:[0,1]
	s_nop 0
	v_pk_add_f32 v[82:83], v[86:87], v[82:83]
	s_nop 0
	v_pk_add_f32 v[86:87], v[84:85], v[82:83]
	s_nop 0
	v_pk_add_f32 v[84:85], v[86:87], v[84:85] neg_lo:[0,1] neg_hi:[0,1]
	v_pk_mul_f32 v[88:89], v[86:87], v[86:87]
	v_pk_add_f32 v[82:83], v[82:83], v[84:85] neg_lo:[0,1] neg_hi:[0,1]
	v_pk_fma_f32 v[90:91], v[88:89], s[28:29], v[66:67] op_sel_hi:[1,0,0]
	v_ldexp_f32 v93, v83, 1
	v_add_f32_e32 v83, v12, v80
	v_max_f32_e32 v80, 0, v83
	v_mul_f32_e64 v83, |v83|, s2
	v_exp_f32_e32 v129, v83
	v_ldexp_f32 v84, v86, 1
	v_pk_fma_f32 v[90:91], v[88:89], v[90:91], s[30:31] op_sel_hi:[1,1,0]
	v_ldexp_f32 v85, v87, 1
	v_add_f32_e32 v83, 1.0, v129
	v_pk_mul_f32 v[86:87], v[86:87], v[88:89]
	v_add_f32_e32 v88, -1.0, v83
	v_sub_f32_e32 v89, v88, v83
	v_add_f32_e32 v89, 1.0, v89
	v_sub_f32_e32 v88, v129, v88
	v_add_f32_e32 v92, v88, v89
	v_frexp_mant_f32_e32 v88, v83
	v_cmp_gt_f32_e32 vcc, s26, v88
	v_cvt_f64_f32_e32 v[88:89], v83
	v_frexp_exp_i32_f64_e32 v88, v[88:89]
	v_subbrev_co_u32_e32 v130, vcc, 0, v88, vcc
	v_sub_u32_e32 v89, 0, v130
	v_ldexp_f32 v88, v83, v89
	v_add_f32_e32 v83, v13, v81
	v_max_f32_e32 v81, 0, v83
	v_mul_f32_e64 v83, |v83|, s2
	v_exp_f32_e32 v131, v83
	v_ldexp_f32 v94, v92, v89
	v_pk_mul_f32 v[86:87], v[86:87], v[90:91]
	v_ldexp_f32 v82, v82, 1
	v_add_f32_e32 v83, 1.0, v131
	v_add_f32_e32 v89, -1.0, v83
	v_sub_f32_e32 v92, v89, v83
	v_add_f32_e32 v92, 1.0, v92
	v_sub_f32_e32 v89, v131, v89
	v_add_f32_e32 v92, v89, v92
	v_frexp_mant_f32_e32 v89, v83
	v_cvt_f64_f32_e32 v[98:99], v83
	v_cmp_gt_f32_e32 vcc, s26, v89
	v_frexp_exp_i32_f64_e32 v89, v[98:99]
	v_pk_add_f32 v[90:91], v[84:85], v[86:87]
	v_subbrev_co_u32_e32 v132, vcc, 0, v89, vcc
	v_sub_u32_e32 v95, 0, v132
	v_ldexp_f32 v89, v83, v95
	v_pk_add_f32 v[98:99], v[88:89], 1.0 op_sel_hi:[1,0]
	v_ldexp_f32 v95, v92, v95
	v_pk_add_f32 v[100:101], v[98:99], -1.0 op_sel_hi:[1,0]
	v_pk_add_f32 v[112:113], v[88:89], -1.0 op_sel_hi:[1,0]
	v_pk_add_f32 v[100:101], v[88:89], v[100:101] neg_lo:[0,1] neg_hi:[0,1]
	v_pk_add_f32 v[114:115], v[112:113], 1.0 op_sel_hi:[1,0]
	v_pk_add_f32 v[100:101], v[94:95], v[100:101]
	v_pk_add_f32 v[88:89], v[88:89], v[114:115] neg_lo:[0,1] neg_hi:[0,1]
	v_pk_add_f32 v[102:103], v[98:99], v[100:101]
	v_pk_add_f32 v[88:89], v[94:95], v[88:89]
	v_rcp_f32_e32 v110, v102
	v_rcp_f32_e32 v111, v103
	v_pk_add_f32 v[94:95], v[112:113], v[88:89]
	v_pk_add_f32 v[98:99], v[102:103], v[98:99] neg_lo:[0,1] neg_hi:[0,1]
	v_pk_add_f32 v[112:113], v[94:95], v[112:113] neg_lo:[0,1] neg_hi:[0,1]
	v_pk_add_f32 v[98:99], v[100:101], v[98:99] neg_lo:[0,1] neg_hi:[0,1]
	v_pk_mul_f32 v[100:101], v[94:95], v[110:111]
	v_pk_add_f32 v[88:89], v[88:89], v[112:113] neg_lo:[0,1] neg_hi:[0,1]
	v_pk_mul_f32 v[112:113], v[102:103], v[100:101]
	v_pk_add_f32 v[84:85], v[90:91], v[84:85] neg_lo:[0,1] neg_hi:[0,1]
	v_pk_fma_f32 v[114:115], v[100:101], v[102:103], v[112:113] neg_lo:[0,0,1] neg_hi:[0,0,1]
	v_pk_add_f32 v[84:85], v[86:87], v[84:85] neg_lo:[0,1] neg_hi:[0,1]
	v_pk_fma_f32 v[114:115], v[100:101], v[98:99], v[114:115]
	v_mov_b32_e32 v87, v85
	v_pk_add_f32 v[116:117], v[112:113], v[114:115]
	v_mov_b32_e32 v83, v93
	v_pk_add_f32 v[118:119], v[94:95], v[116:117] neg_lo:[0,1] neg_hi:[0,1]
	v_pk_add_f32 v[112:113], v[116:117], v[112:113] neg_lo:[0,1] neg_hi:[0,1]
	v_pk_add_f32 v[94:95], v[94:95], v[118:119] neg_lo:[0,1] neg_hi:[0,1]
	v_mov_b32_e32 v124, v90
	v_pk_add_f32 v[94:95], v[94:95], v[116:117] neg_lo:[0,1] neg_hi:[0,1]
	v_cmp_neq_f32_e32 vcc, s8, v97
; __device__ __forceinline__ float softplusf(float x) { return fmaxf(x, 0.f) + log1pf(__expf(-fabsf(x))); }
; __device__ void phaseA_tile(const Params& p, int l, int mt, int nt, char* smem) {
;     ...
;                 for (int j = 0; j < 2; ++j) {
;                     const int c = j * 16 + g4 * 4;
;                     const float4 db = *(const float4*)(p.dt_bias + l * 32 + c);
;                     const f32x4 v = acc[i][j];
;                     *(float4*)(p.dtb + (size_t)row * 32 + c) =
;                         make_float4(softplusf(v[0] + db.x), softplusf(v[1] + db.y), softplusf(v[2] + db.z), softplusf(v[3] + db.w));
;                 }
	v_pk_add_f32 v[88:89], v[88:89], v[94:95]
	v_pk_add_f32 v[94:95], v[112:113], v[114:115] neg_lo:[0,1] neg_hi:[0,1]
	s_nop 0
	v_pk_add_f32 v[88:89], v[94:95], v[88:89]
	s_nop 0
	v_pk_add_f32 v[94:95], v[118:119], v[88:89]
	s_nop 0
	v_pk_mul_f32 v[112:113], v[110:111], v[94:95]
	s_nop 0
	v_pk_mul_f32 v[114:115], v[102:103], v[112:113]
	s_nop 0
	v_pk_fma_f32 v[102:103], v[112:113], v[102:103], v[114:115] neg_lo:[0,0,1] neg_hi:[0,0,1]
	s_nop 0
	v_pk_fma_f32 v[98:99], v[112:113], v[98:99], v[102:103]
	v_pk_add_f32 v[102:103], v[118:119], v[94:95] neg_lo:[0,1] neg_hi:[0,1]
	s_nop 0
	v_pk_add_f32 v[88:89], v[88:89], v[102:103]
	v_pk_add_f32 v[102:103], v[114:115], v[98:99]
	s_nop 0
	v_pk_add_f32 v[116:117], v[94:95], v[102:103] neg_lo:[0,1] neg_hi:[0,1]
	v_pk_add_f32 v[114:115], v[102:103], v[114:115] neg_lo:[0,1] neg_hi:[0,1]
	v_pk_add_f32 v[94:95], v[94:95], v[116:117] neg_lo:[0,1] neg_hi:[0,1]
	s_nop 0
	v_pk_add_f32 v[94:95], v[94:95], v[102:103] neg_lo:[0,1] neg_hi:[0,1]
	s_nop 0
	v_pk_add_f32 v[88:89], v[88:89], v[94:95]
	v_pk_add_f32 v[94:95], v[114:115], v[98:99] neg_lo:[0,1] neg_hi:[0,1]
	s_nop 0
	v_pk_add_f32 v[88:89], v[94:95], v[88:89]
	v_pk_add_f32 v[94:95], v[100:101], v[112:113]
	v_pk_add_f32 v[88:89], v[116:117], v[88:89]
	v_pk_add_f32 v[98:99], v[94:95], v[100:101] neg_lo:[0,1] neg_hi:[0,1]
	v_pk_mul_f32 v[88:89], v[110:111], v[88:89]
	v_pk_add_f32 v[98:99], v[112:113], v[98:99] neg_lo:[0,1] neg_hi:[0,1]
	s_nop 0
	v_pk_add_f32 v[88:89], v[98:99], v[88:89]
	s_nop 0
	v_pk_add_f32 v[98:99], v[94:95], v[88:89]
	s_nop 0
	v_pk_mul_f32 v[100:101], v[98:99], v[98:99]
	v_pk_add_f32 v[94:95], v[98:99], v[94:95] neg_lo:[0,1] neg_hi:[0,1]
	v_pk_fma_f32 v[102:103], v[100:101], s[28:29], v[66:67] op_sel_hi:[1,0,0]
	v_pk_add_f32 v[88:89], v[88:89], v[94:95] neg_lo:[0,1] neg_hi:[0,1]
	v_ldexp_f32 v94, v98, 1
	v_pk_fma_f32 v[102:103], v[100:101], v[102:103], s[30:31] op_sel_hi:[1,1,0]
	v_ldexp_f32 v95, v99, 1
	v_pk_mul_f32 v[98:99], v[98:99], v[100:101]
	v_cvt_f32_i32_e32 v101, v121
	v_cvt_f32_i32_e32 v100, v120
	v_ldexp_f32 v111, v89, 1
	v_ldexp_f32 v88, v88, 1
	v_mov_b32_e32 v89, v111
	v_pk_mul_f32 v[112:113], v[100:101], s[12:13] op_sel_hi:[1,0]
	s_nop 0
	v_pk_fma_f32 v[114:115], v[100:101], s[12:13], v[112:113] op_sel_hi:[1,0,1] neg_lo:[0,0,1] neg_hi:[0,0,1]
	v_mov_b32_e32 v86, v112
	v_pk_fma_f32 v[100:101], v[100:101], s[14:15], v[114:115] op_sel_hi:[1,0,1]
	v_mov_b32_e32 v121, v113
	v_mov_b32_e32 v92, v100
	v_pk_add_f32 v[86:87], v[86:87], v[92:93]
	v_pk_add_f32 v[92:93], v[82:83], v[84:85]
	v_mov_b32_e32 v85, v91
	v_mov_b32_e32 v83, v93
	v_pk_add_f32 v[114:115], v[112:113], v[100:101]
	v_pk_add_f32 v[82:83], v[82:83], v[84:85]
	v_pk_add_f32 v[84:85], v[90:91], v[92:93]
	v_mov_b32_e32 v125, v115
	v_pk_add_f32 v[116:117], v[114:115], v[84:85]
	v_mov_b32_e32 v122, v84
	v_mov_b32_e32 v123, v117
	v_pk_add_f32 v[122:123], v[122:123], v[124:125] neg_lo:[0,1] neg_hi:[0,1]
	v_mov_b32_e32 v118, v116
	v_mov_b32_e32 v119, v115
	v_mov_b32_e32 v120, v114
	v_mov_b32_e32 v124, v114
	v_mov_b32_e32 v125, v117
	v_mov_b32_e32 v113, v123
	v_pk_add_f32 v[118:119], v[118:119], v[120:121] neg_lo:[0,1] neg_hi:[0,1]
	v_mov_b32_e32 v120, v84
	v_mov_b32_e32 v121, v101
	v_pk_add_f32 v[112:113], v[124:125], v[112:113] neg_lo:[0,1] neg_hi:[0,1]
	v_pk_add_f32 v[120:121], v[120:121], v[118:119] neg_lo:[0,1] neg_hi:[0,1]
	v_mov_b32_e32 v124, v112
	v_mov_b32_e32 v125, v119
	v_mov_b32_e32 v126, v116
	v_mov_b32_e32 v127, v85
	v_mov_b32_e32 v119, v91
	v_pk_add_f32 v[124:125], v[100:101], v[124:125] neg_lo:[0,1] neg_hi:[0,1]
	v_pk_add_f32 v[118:119], v[126:127], v[118:119] neg_lo:[0,1] neg_hi:[0,1]
	v_mov_b32_e32 v101, v115
	v_pk_add_f32 v[84:85], v[84:85], v[90:91] neg_lo:[0,1] neg_hi:[0,1]
	v_pk_add_f32 v[86:87], v[86:87], v[118:119] neg_lo:[0,1] neg_hi:[0,1]
	v_pk_add_f32 v[90:91], v[100:101], v[112:113] neg_lo:[0,1] neg_hi:[0,1]
	v_pk_add_f32 v[82:83], v[82:83], v[122:123] neg_lo:[0,1] neg_hi:[0,1]
	v_pk_add_f32 v[84:85], v[92:93], v[84:85] neg_lo:[0,1] neg_hi:[0,1]
	v_pk_add_f32 v[92:93], v[82:83], v[90:91]
	v_mov_b32_e32 v91, v121
	v_mov_b32_e32 v83, v87
	v_pk_add_f32 v[100:101], v[120:121], v[86:87]
	v_pk_add_f32 v[82:83], v[90:91], v[82:83]
	v_mov_b32_e32 v86, v92
	v_pk_add_f32 v[82:83], v[82:83], v[124:125] neg_lo:[0,1] neg_hi:[0,1]
	v_mov_b32_e32 v87, v101
	v_pk_add_f32 v[86:87], v[86:87], v[82:83] neg_lo:[0,1] neg_hi:[0,1]
	v_pk_add_f32 v[82:83], v[84:85], v[82:83] neg_lo:[0,1] neg_hi:[0,1]
	v_pk_add_f32 v[86:87], v[90:91], v[86:87] neg_lo:[0,1] neg_hi:[0,1]
	v_pk_add_f32 v[84:85], v[100:101], v[92:93]
	v_pk_add_f32 v[82:83], v[82:83], v[86:87]
	v_pk_add_f32 v[86:87], v[116:117], v[84:85]
	s_nop 0
	v_pk_add_f32 v[90:91], v[86:87], v[116:117] neg_lo:[0,1] neg_hi:[0,1]
	s_nop 0
	v_pk_add_f32 v[84:85], v[84:85], v[90:91] neg_lo:[0,1] neg_hi:[0,1]
	s_nop 0
	v_pk_add_f32 v[82:83], v[82:83], v[84:85]
	s_nop 0
	v_pk_add_f32 v[82:83], v[86:87], v[82:83]
	v_pk_mul_f32 v[86:87], v[98:99], v[102:103]
	v_cndmask_b32_e32 v82, v160, v82, vcc
	v_cmp_neq_f32_e32 vcc, s8, v128
	v_pk_add_f32 v[90:91], v[94:95], v[86:87]
	s_nop 0
	v_cndmask_b32_e32 v83, v160, v83, vcc
	v_cmp_ngt_f32_e32 vcc, -1.0, v128
	v_pk_add_f32 v[94:95], v[90:91], v[94:95] neg_lo:[0,1] neg_hi:[0,1]
	v_mov_b32_e32 v114, v90
	v_cndmask_b32_e32 v83, v161, v83, vcc
	v_cmp_ngt_f32_e32 vcc, -1.0, v97
	v_pk_add_f32 v[86:87], v[86:87], v[94:95] neg_lo:[0,1] neg_hi:[0,1]
	s_nop 0
	v_cndmask_b32_e32 v82, v161, v82, vcc
	v_cmp_neq_f32_e32 vcc, -1.0, v97
	v_pk_add_f32 v[98:99], v[88:89], v[86:87]
	v_mov_b32_e32 v95, v87
	v_cndmask_b32_e32 v82, v162, v82, vcc
	v_cmp_neq_f32_e32 vcc, -1.0, v128
	v_mov_b32_e32 v89, v99
; __device__ __forceinline__ float softplusf(float x) { return fmaxf(x, 0.f) + log1pf(__expf(-fabsf(x))); }
; __device__ __forceinline__ float logsigf(float x) { return fminf(x, 0.f) - log1pf(__expf(-fabsf(x))); }
; __device__ void phaseA_tile(const Params& p, int l, int mt, int nt, char* smem) {
;     ...
;                 for (int j = 0; j < 2; ++j) {
;                     const int c = j * 16 + g4 * 4;
;                     const float4 db = *(const float4*)(p.dt_bias + l * 32 + c);
;                     const f32x4 v = acc[i][j];
;                     *(float4*)(p.dtb + (size_t)row * 32 + c) =
;                         make_float4(softplusf(v[0] + db.x), softplusf(v[1] + db.y), softplusf(v[2] + db.z), softplusf(v[3] + db.w));
;                 }
;                 {
;                     const int c = g4 * 4;
;                     const float4 fb = *(const float4*)(p.b_f + l * 16 + c);
;                     const f32x4 v = acc[i][2];
;                     float4 lf = make_float4(logsigf(v[0] + fb.x), logsigf(v[1] + fb.y), logsigf(v[2] + fb.z), logsigf(v[3] + fb.w));
	v_mov_b32_e32 v87, v91
	v_cndmask_b32_e32 v83, v162, v83, vcc
	v_cmp_lt_f32_e64 vcc, |v97|, s9
	v_cndmask_b32_e64 v83, v83, v128, s[0:1]
	v_pk_add_f32 v[86:87], v[88:89], v[86:87]
	v_cndmask_b32_e32 v82, v82, v97, vcc
	v_pk_add_f32 v[78:79], v[78:79], v[82:83]
	v_cvt_f32_i32_e32 v83, v132
	v_cvt_f32_i32_e32 v82, v130
	v_pk_add_f32 v[88:89], v[90:91], v[98:99]
	v_cmp_neq_f32_e32 vcc, s8, v129
	v_mov_b32_e32 v112, v88
	v_pk_mul_f32 v[84:85], v[82:83], s[12:13] op_sel_hi:[1,0]
	v_mov_b32_e32 v117, v89
	v_pk_fma_f32 v[92:93], v[82:83], s[12:13], v[84:85] op_sel_hi:[1,0,1] neg_lo:[0,0,1] neg_hi:[0,0,1]
	v_mov_b32_e32 v94, v84
	v_pk_fma_f32 v[82:83], v[82:83], s[14:15], v[92:93] op_sel_hi:[1,0,1]
	v_cmp_lt_f32_e64 s[0:1], |v131|, s9
	v_pk_add_f32 v[92:93], v[84:85], v[82:83]
	v_mov_b32_e32 v110, v82
	v_pk_add_f32 v[100:101], v[92:93], v[88:89]
	v_mov_b32_e32 v115, v93
	v_mov_b32_e32 v113, v101
	v_pk_add_f32 v[112:113], v[112:113], v[114:115] neg_lo:[0,1] neg_hi:[0,1]
	v_pk_add_f32 v[94:95], v[94:95], v[110:111]
	v_mov_b32_e32 v102, v100
	v_mov_b32_e32 v103, v93
	v_mov_b32_e32 v110, v92
	v_mov_b32_e32 v111, v85
	v_mov_b32_e32 v114, v92
	v_mov_b32_e32 v115, v101
	v_mov_b32_e32 v85, v113
	v_pk_add_f32 v[102:103], v[102:103], v[110:111] neg_lo:[0,1] neg_hi:[0,1]
	v_mov_b32_e32 v110, v88
	v_mov_b32_e32 v111, v83
	v_pk_add_f32 v[84:85], v[114:115], v[84:85] neg_lo:[0,1] neg_hi:[0,1]
	v_pk_add_f32 v[110:111], v[110:111], v[102:103] neg_lo:[0,1] neg_hi:[0,1]
	v_mov_b32_e32 v114, v84
	v_mov_b32_e32 v115, v103
	v_mov_b32_e32 v116, v100
	v_mov_b32_e32 v103, v91
	v_pk_add_f32 v[114:115], v[82:83], v[114:115] neg_lo:[0,1] neg_hi:[0,1]
	v_pk_add_f32 v[102:103], v[116:117], v[102:103] neg_lo:[0,1] neg_hi:[0,1]
	v_mov_b32_e32 v83, v93
	v_pk_add_f32 v[88:89], v[88:89], v[90:91] neg_lo:[0,1] neg_hi:[0,1]
	v_pk_add_f32 v[90:91], v[94:95], v[102:103] neg_lo:[0,1] neg_hi:[0,1]
	v_pk_add_f32 v[82:83], v[82:83], v[84:85] neg_lo:[0,1] neg_hi:[0,1]
	v_pk_add_f32 v[84:85], v[86:87], v[112:113] neg_lo:[0,1] neg_hi:[0,1]
	v_pk_add_f32 v[92:93], v[110:111], v[90:91]
	v_pk_add_f32 v[86:87], v[84:85], v[82:83]
	v_mov_b32_e32 v83, v111
	v_mov_b32_e32 v85, v91
	v_pk_add_f32 v[84:85], v[82:83], v[84:85]
	v_mov_b32_e32 v90, v86
	v_pk_add_f32 v[84:85], v[84:85], v[114:115] neg_lo:[0,1] neg_hi:[0,1]
	v_mov_b32_e32 v91, v93
	v_pk_add_f32 v[88:89], v[98:99], v[88:89] neg_lo:[0,1] neg_hi:[0,1]
	v_pk_add_f32 v[90:91], v[90:91], v[84:85] neg_lo:[0,1] neg_hi:[0,1]
	v_pk_add_f32 v[84:85], v[88:89], v[84:85] neg_lo:[0,1] neg_hi:[0,1]
	v_pk_add_f32 v[82:83], v[82:83], v[90:91] neg_lo:[0,1] neg_hi:[0,1]
	s_nop 0
	v_pk_add_f32 v[82:83], v[84:85], v[82:83]
	v_pk_add_f32 v[84:85], v[92:93], v[86:87]
	s_nop 0
	v_pk_add_f32 v[86:87], v[100:101], v[84:85]
	s_nop 0
	v_pk_add_f32 v[88:89], v[86:87], v[100:101] neg_lo:[0,1] neg_hi:[0,1]
	s_nop 0
	v_pk_add_f32 v[84:85], v[84:85], v[88:89] neg_lo:[0,1] neg_hi:[0,1]
	s_nop 0
	v_pk_add_f32 v[82:83], v[82:83], v[84:85]
	s_nop 0
	v_pk_add_f32 v[82:83], v[86:87], v[82:83]
	s_nop 0
	v_cndmask_b32_e32 v82, v160, v82, vcc
	v_cmp_neq_f32_e32 vcc, s8, v131
	s_nop 1
	v_cndmask_b32_e32 v83, v160, v83, vcc
	v_cmp_ngt_f32_e32 vcc, -1.0, v131
	s_nop 1
	v_cndmask_b32_e32 v83, v161, v83, vcc
	v_cmp_ngt_f32_e32 vcc, -1.0, v129
	s_nop 1
	v_cndmask_b32_e32 v82, v161, v82, vcc
	v_cmp_neq_f32_e32 vcc, -1.0, v129
	s_nop 1
	v_cndmask_b32_e32 v82, v162, v82, vcc
	v_cmp_neq_f32_e32 vcc, -1.0, v131
	s_nop 1
	v_cndmask_b32_e32 v83, v162, v83, vcc
	v_cmp_lt_f32_e64 vcc, |v129|, s9
	v_cndmask_b32_e64 v83, v83, v131, s[0:1]
	s_nop 0
	v_cndmask_b32_e32 v82, v82, v129, vcc
	v_pk_add_f32 v[80:81], v[80:81], v[82:83]
	global_store_dwordx4 v[76:77], v[78:81], off offset:64
	global_load_dwordx4 v[76:79], v0, s[78:79]
	s_waitcnt vmcnt(0)
	v_add_f32_e32 v80, v6, v76
	v_min_f32_e32 v76, 0, v80
	v_mul_f32_e64 v80, |v80|, s2
	v_exp_f32_e32 v97, v80
	s_nop 0
	v_add_f32_e32 v82, 1.0, v97
	v_add_f32_e32 v80, -1.0, v82
	v_sub_f32_e32 v81, v80, v82
	v_add_f32_e32 v81, 1.0, v81
	v_sub_f32_e32 v80, v97, v80
	v_add_f32_e32 v83, v80, v81
	v_frexp_mant_f32_e32 v80, v82
	v_cmp_gt_f32_e32 vcc, s26, v80
	v_cvt_f64_f32_e32 v[80:81], v82
	v_frexp_exp_i32_f64_e32 v80, v[80:81]
	v_subbrev_co_u32_e32 v118, vcc, 0, v80, vcc
	v_sub_u32_e32 v81, 0, v118
	v_ldexp_f32 v80, v82, v81
	v_ldexp_f32 v82, v83, v81
	v_add_f32_e32 v81, v7, v77
	v_min_f32_e32 v77, 0, v81
	v_mul_f32_e64 v81, |v81|, s2
	v_exp_f32_e32 v124, v81
	s_nop 0
	v_add_f32_e32 v81, 1.0, v124
	v_add_f32_e32 v83, -1.0, v81
	v_sub_f32_e32 v84, v83, v81
	v_add_f32_e32 v84, 1.0, v84
	v_sub_f32_e32 v83, v124, v83
	v_add_f32_e32 v83, v83, v84
	v_frexp_mant_f32_e32 v84, v81
	v_cmp_gt_f32_e32 vcc, s26, v84
	v_cvt_f64_f32_e32 v[84:85], v81
	v_frexp_exp_i32_f64_e32 v84, v[84:85]
	v_subbrev_co_u32_e32 v119, vcc, 0, v84, vcc
	v_sub_u32_e32 v84, 0, v119
	v_ldexp_f32 v81, v81, v84
	v_ldexp_f32 v83, v83, v84
	v_pk_add_f32 v[84:85], v[80:81], 1.0 op_sel_hi:[1,0]
	v_pk_add_f32 v[92:93], v[80:81], -1.0 op_sel_hi:[1,0]
	v_pk_add_f32 v[86:87], v[84:85], -1.0 op_sel_hi:[1,0]
	v_pk_add_f32 v[94:95], v[92:93], 1.0 op_sel_hi:[1,0]
	v_pk_add_f32 v[86:87], v[80:81], v[86:87] neg_lo:[0,1] neg_hi:[0,1]
	v_pk_add_f32 v[80:81], v[80:81], v[94:95] neg_lo:[0,1] neg_hi:[0,1]
	v_pk_add_f32 v[86:87], v[82:83], v[86:87]
	v_pk_add_f32 v[80:81], v[82:83], v[80:81]
	v_pk_add_f32 v[88:89], v[84:85], v[86:87]
	v_pk_add_f32 v[82:83], v[92:93], v[80:81]
	v_rcp_f32_e32 v90, v88
	v_rcp_f32_e32 v91, v89
	v_pk_add_f32 v[84:85], v[88:89], v[84:85] neg_lo:[0,1] neg_hi:[0,1]
	v_pk_add_f32 v[92:93], v[82:83], v[92:93] neg_lo:[0,1] neg_hi:[0,1]
	v_pk_add_f32 v[84:85], v[86:87], v[84:85] neg_lo:[0,1] neg_hi:[0,1]
; __device__ __forceinline__ float softplusf(float x) { return fmaxf(x, 0.f) + log1pf(__expf(-fabsf(x))); }
; __device__ __forceinline__ float logsigf(float x) { return fminf(x, 0.f) - log1pf(__expf(-fabsf(x))); }
; __device__ void phaseA_tile(const Params& p, int l, int mt, int nt, char* smem) {
;     ...
;                     const float4 fb = *(const float4*)(p.b_f + l * 16 + c);
;                     const f32x4 v = acc[i][2];
;                     float4 lf = make_float4(logsigf(v[0] + fb.x), logsigf(v[1] + fb.y), logsigf(v[2] + fb.z), logsigf(v[3] + fb.w));
	v_pk_mul_f32 v[86:87], v[82:83], v[90:91]
	v_pk_add_f32 v[80:81], v[80:81], v[92:93] neg_lo:[0,1] neg_hi:[0,1]
	v_pk_mul_f32 v[92:93], v[88:89], v[86:87]
	v_cmp_lt_f32_e64 s[0:1], |v124|, s9
	v_pk_fma_f32 v[94:95], v[86:87], v[88:89], v[92:93] neg_lo:[0,0,1] neg_hi:[0,0,1]
	s_nop 0
	v_pk_fma_f32 v[94:95], v[86:87], v[84:85], v[94:95]
	s_nop 0
	v_pk_add_f32 v[98:99], v[92:93], v[94:95]
	s_nop 0
	v_pk_add_f32 v[100:101], v[82:83], v[98:99] neg_lo:[0,1] neg_hi:[0,1]
	v_pk_add_f32 v[92:93], v[98:99], v[92:93] neg_lo:[0,1] neg_hi:[0,1]
	v_pk_add_f32 v[82:83], v[82:83], v[100:101] neg_lo:[0,1] neg_hi:[0,1]
	s_nop 0
	v_pk_add_f32 v[82:83], v[82:83], v[98:99] neg_lo:[0,1] neg_hi:[0,1]
	s_nop 0
	v_pk_add_f32 v[80:81], v[80:81], v[82:83]
	v_pk_add_f32 v[82:83], v[92:93], v[94:95] neg_lo:[0,1] neg_hi:[0,1]
	s_nop 0
	v_pk_add_f32 v[80:81], v[82:83], v[80:81]
	s_nop 0
	v_pk_add_f32 v[82:83], v[100:101], v[80:81]
	s_nop 0
	v_pk_mul_f32 v[92:93], v[90:91], v[82:83]
	s_nop 0
	v_pk_mul_f32 v[94:95], v[88:89], v[92:93]
	s_nop 0
	v_pk_fma_f32 v[88:89], v[92:93], v[88:89], v[94:95] neg_lo:[0,0,1] neg_hi:[0,0,1]
	s_nop 0
	v_pk_fma_f32 v[84:85], v[92:93], v[84:85], v[88:89]
	v_pk_add_f32 v[88:89], v[100:101], v[82:83] neg_lo:[0,1] neg_hi:[0,1]
	s_nop 0
	v_pk_add_f32 v[80:81], v[80:81], v[88:89]
	v_pk_add_f32 v[88:89], v[94:95], v[84:85]
	s_nop 0
	v_pk_add_f32 v[98:99], v[82:83], v[88:89] neg_lo:[0,1] neg_hi:[0,1]
	v_pk_add_f32 v[94:95], v[88:89], v[94:95] neg_lo:[0,1] neg_hi:[0,1]
	v_pk_add_f32 v[82:83], v[82:83], v[98:99] neg_lo:[0,1] neg_hi:[0,1]
	s_nop 0
	v_pk_add_f32 v[82:83], v[82:83], v[88:89] neg_lo:[0,1] neg_hi:[0,1]
	s_nop 0
	v_pk_add_f32 v[80:81], v[80:81], v[82:83]
	v_pk_add_f32 v[82:83], v[94:95], v[84:85] neg_lo:[0,1] neg_hi:[0,1]
	s_nop 0
	v_pk_add_f32 v[80:81], v[82:83], v[80:81]
	v_pk_add_f32 v[82:83], v[86:87], v[92:93]
	v_pk_add_f32 v[80:81], v[98:99], v[80:81]
	v_pk_add_f32 v[84:85], v[82:83], v[86:87] neg_lo:[0,1] neg_hi:[0,1]
	v_pk_mul_f32 v[80:81], v[90:91], v[80:81]
	v_pk_add_f32 v[84:85], v[92:93], v[84:85] neg_lo:[0,1] neg_hi:[0,1]
	s_nop 0
	v_pk_add_f32 v[80:81], v[84:85], v[80:81]
	s_nop 0
	v_pk_add_f32 v[84:85], v[82:83], v[80:81]
	s_nop 0
	v_pk_add_f32 v[82:83], v[84:85], v[82:83] neg_lo:[0,1] neg_hi:[0,1]
	v_pk_mul_f32 v[86:87], v[84:85], v[84:85]
	v_pk_add_f32 v[80:81], v[80:81], v[82:83] neg_lo:[0,1] neg_hi:[0,1]
	v_pk_fma_f32 v[88:89], v[86:87], s[28:29], v[66:67] op_sel_hi:[1,0,0]
	v_ldexp_f32 v91, v81, 1
	v_add_f32_e32 v81, v8, v78
	v_min_f32_e32 v78, 0, v81
	v_mul_f32_e64 v81, |v81|, s2
	v_exp_f32_e32 v125, v81
	v_ldexp_f32 v82, v84, 1
	v_pk_fma_f32 v[88:89], v[86:87], v[88:89], s[30:31] op_sel_hi:[1,1,0]
	v_ldexp_f32 v83, v85, 1
	v_add_f32_e32 v81, 1.0, v125
	v_pk_mul_f32 v[84:85], v[84:85], v[86:87]
	v_add_f32_e32 v86, -1.0, v81
	v_sub_f32_e32 v87, v86, v81
	v_add_f32_e32 v87, 1.0, v87
	v_sub_f32_e32 v86, v125, v86
	v_add_f32_e32 v90, v86, v87
	v_frexp_mant_f32_e32 v86, v81
	v_cmp_gt_f32_e32 vcc, s26, v86
	v_cvt_f64_f32_e32 v[86:87], v81
	v_frexp_exp_i32_f64_e32 v86, v[86:87]
	v_subbrev_co_u32_e32 v126, vcc, 0, v86, vcc
	v_sub_u32_e32 v87, 0, v126
	v_ldexp_f32 v86, v81, v87
	v_add_f32_e32 v81, v9, v79
	v_min_f32_e32 v79, 0, v81
	v_mul_f32_e64 v81, |v81|, s2
	v_exp_f32_e32 v127, v81
	v_ldexp_f32 v92, v90, v87
	v_pk_mul_f32 v[84:85], v[84:85], v[88:89]
	v_ldexp_f32 v80, v80, 1
	v_add_f32_e32 v81, 1.0, v127
	v_add_f32_e32 v87, -1.0, v81
	v_sub_f32_e32 v90, v87, v81
	v_add_f32_e32 v90, 1.0, v90
	v_sub_f32_e32 v87, v127, v87
	v_add_f32_e32 v90, v87, v90
	v_frexp_mant_f32_e32 v87, v81
	v_cvt_f64_f32_e32 v[94:95], v81
	v_cmp_gt_f32_e32 vcc, s26, v87
	v_frexp_exp_i32_f64_e32 v87, v[94:95]
	v_pk_add_f32 v[88:89], v[82:83], v[84:85]
	v_subbrev_co_u32_e32 v128, vcc, 0, v87, vcc
	v_sub_u32_e32 v93, 0, v128
	v_ldexp_f32 v87, v81, v93
	v_pk_add_f32 v[94:95], v[86:87], 1.0 op_sel_hi:[1,0]
	v_ldexp_f32 v93, v90, v93
	v_pk_add_f32 v[98:99], v[94:95], -1.0 op_sel_hi:[1,0]
	v_pk_add_f32 v[110:111], v[86:87], -1.0 op_sel_hi:[1,0]
	v_pk_add_f32 v[98:99], v[86:87], v[98:99] neg_lo:[0,1] neg_hi:[0,1]
	v_pk_add_f32 v[112:113], v[110:111], 1.0 op_sel_hi:[1,0]
	v_pk_add_f32 v[98:99], v[92:93], v[98:99]
	v_pk_add_f32 v[86:87], v[86:87], v[112:113] neg_lo:[0,1] neg_hi:[0,1]
	v_pk_add_f32 v[100:101], v[94:95], v[98:99]
	v_pk_add_f32 v[86:87], v[92:93], v[86:87]
	v_rcp_f32_e32 v102, v100
	v_rcp_f32_e32 v103, v101
	v_pk_add_f32 v[92:93], v[110:111], v[86:87]
	v_pk_add_f32 v[94:95], v[100:101], v[94:95] neg_lo:[0,1] neg_hi:[0,1]
	v_pk_add_f32 v[110:111], v[92:93], v[110:111] neg_lo:[0,1] neg_hi:[0,1]
	v_pk_add_f32 v[94:95], v[98:99], v[94:95] neg_lo:[0,1] neg_hi:[0,1]
	v_pk_mul_f32 v[98:99], v[92:93], v[102:103]
	v_pk_add_f32 v[86:87], v[86:87], v[110:111] neg_lo:[0,1] neg_hi:[0,1]
	v_pk_mul_f32 v[110:111], v[100:101], v[98:99]
	v_pk_add_f32 v[82:83], v[88:89], v[82:83] neg_lo:[0,1] neg_hi:[0,1]
	v_pk_fma_f32 v[112:113], v[98:99], v[100:101], v[110:111] neg_lo:[0,0,1] neg_hi:[0,0,1]
	v_pk_add_f32 v[82:83], v[84:85], v[82:83] neg_lo:[0,1] neg_hi:[0,1]
	v_pk_fma_f32 v[112:113], v[98:99], v[94:95], v[112:113]
	v_mov_b32_e32 v85, v83
	v_pk_add_f32 v[114:115], v[110:111], v[112:113]
	v_mov_b32_e32 v81, v91
	v_pk_add_f32 v[116:117], v[92:93], v[114:115] neg_lo:[0,1] neg_hi:[0,1]
	v_pk_add_f32 v[110:111], v[114:115], v[110:111] neg_lo:[0,1] neg_hi:[0,1]
	v_pk_add_f32 v[92:93], v[92:93], v[116:117] neg_lo:[0,1] neg_hi:[0,1]
	v_mov_b32_e32 v120, v88
	v_pk_add_f32 v[92:93], v[92:93], v[114:115] neg_lo:[0,1] neg_hi:[0,1]
	v_cmp_neq_f32_e32 vcc, s8, v97
	v_pk_add_f32 v[86:87], v[86:87], v[92:93]
	v_pk_add_f32 v[92:93], v[110:111], v[112:113] neg_lo:[0,1] neg_hi:[0,1]
; __device__ __forceinline__ float logsigf(float x) { return fminf(x, 0.f) - log1pf(__expf(-fabsf(x))); }
; __device__ void phaseA_tile(const Params& p, int l, int mt, int nt, char* smem) {
;     ...
;                     const float4 fb = *(const float4*)(p.b_f + l * 16 + c);
;                     const f32x4 v = acc[i][2];
;                     float4 lf = make_float4(logsigf(v[0] + fb.x), logsigf(v[1] + fb.y), logsigf(v[2] + fb.z), logsigf(v[3] + fb.w));
;                     float* o = samp ? (p.out + O_LFS + ((size_t)l * TSM + (row - TP)) * 16 + c)
;                                     : (p.out + O_LFP + ((size_t)l * TP + row) * 16 + c);
	s_nop 0
	v_pk_add_f32 v[86:87], v[92:93], v[86:87]
	s_nop 0
	v_pk_add_f32 v[92:93], v[116:117], v[86:87]
	s_nop 0
	v_pk_mul_f32 v[110:111], v[102:103], v[92:93]
	s_nop 0
	v_pk_mul_f32 v[112:113], v[100:101], v[110:111]
	s_nop 0
	v_pk_fma_f32 v[100:101], v[110:111], v[100:101], v[112:113] neg_lo:[0,0,1] neg_hi:[0,0,1]
	s_nop 0
	v_pk_fma_f32 v[94:95], v[110:111], v[94:95], v[100:101]
	v_pk_add_f32 v[100:101], v[116:117], v[92:93] neg_lo:[0,1] neg_hi:[0,1]
	s_nop 0
	v_pk_add_f32 v[86:87], v[86:87], v[100:101]
	v_pk_add_f32 v[100:101], v[112:113], v[94:95]
	s_nop 0
	v_pk_add_f32 v[114:115], v[92:93], v[100:101] neg_lo:[0,1] neg_hi:[0,1]
	v_pk_add_f32 v[112:113], v[100:101], v[112:113] neg_lo:[0,1] neg_hi:[0,1]
	v_pk_add_f32 v[92:93], v[92:93], v[114:115] neg_lo:[0,1] neg_hi:[0,1]
	s_nop 0
	v_pk_add_f32 v[92:93], v[92:93], v[100:101] neg_lo:[0,1] neg_hi:[0,1]
	s_nop 0
	v_pk_add_f32 v[86:87], v[86:87], v[92:93]
	v_pk_add_f32 v[92:93], v[112:113], v[94:95] neg_lo:[0,1] neg_hi:[0,1]
	s_nop 0
	v_pk_add_f32 v[86:87], v[92:93], v[86:87]
	v_pk_add_f32 v[92:93], v[98:99], v[110:111]
	v_pk_add_f32 v[86:87], v[114:115], v[86:87]
	v_pk_add_f32 v[94:95], v[92:93], v[98:99] neg_lo:[0,1] neg_hi:[0,1]
	v_pk_mul_f32 v[86:87], v[102:103], v[86:87]
	v_pk_add_f32 v[94:95], v[110:111], v[94:95] neg_lo:[0,1] neg_hi:[0,1]
	s_nop 0
	v_pk_add_f32 v[86:87], v[94:95], v[86:87]
	s_nop 0
	v_pk_add_f32 v[94:95], v[92:93], v[86:87]
	s_nop 0
	v_pk_mul_f32 v[98:99], v[94:95], v[94:95]
	v_pk_add_f32 v[92:93], v[94:95], v[92:93] neg_lo:[0,1] neg_hi:[0,1]
	v_pk_fma_f32 v[66:67], v[98:99], s[28:29], v[66:67] op_sel_hi:[1,0,0]
	v_pk_add_f32 v[86:87], v[86:87], v[92:93] neg_lo:[0,1] neg_hi:[0,1]
	v_pk_fma_f32 v[100:101], v[98:99], v[66:67], s[30:31] op_sel_hi:[1,1,0]
	v_add_u32_e32 v66, 0xffff8000, v68
	v_ashrrev_i32_e32 v67, 31, v66
	v_cndmask_b32_e64 v67, v69, v67, s[60:61]
	v_cndmask_b32_e64 v66, v68, v66, s[60:61]
	v_cvt_f32_i32_e32 v69, v119
	v_cvt_f32_i32_e32 v68, v118
	v_ldexp_f32 v92, v94, 1
	v_ldexp_f32 v93, v95, 1
	v_pk_mul_f32 v[94:95], v[94:95], v[98:99]
	v_pk_mul_f32 v[98:99], v[68:69], s[12:13] op_sel_hi:[1,0]
	v_ldexp_f32 v103, v87, 1
	v_pk_fma_f32 v[110:111], v[68:69], s[12:13], v[98:99] op_sel_hi:[1,0,1] neg_lo:[0,0,1] neg_hi:[0,0,1]
	v_mov_b32_e32 v84, v98
	v_pk_fma_f32 v[68:69], v[68:69], s[14:15], v[110:111] op_sel_hi:[1,0,1]
	v_mov_b32_e32 v117, v99
	v_mov_b32_e32 v90, v68
	v_pk_add_f32 v[84:85], v[84:85], v[90:91]
	v_pk_add_f32 v[90:91], v[80:81], v[82:83]
	v_mov_b32_e32 v83, v89
	v_mov_b32_e32 v81, v91
	v_pk_add_f32 v[110:111], v[98:99], v[68:69]
	v_pk_add_f32 v[80:81], v[80:81], v[82:83]
	v_pk_add_f32 v[82:83], v[88:89], v[90:91]
	v_mov_b32_e32 v121, v111
	v_pk_add_f32 v[112:113], v[110:111], v[82:83]
	v_mov_b32_e32 v118, v82
	v_mov_b32_e32 v119, v113
	v_pk_add_f32 v[118:119], v[118:119], v[120:121] neg_lo:[0,1] neg_hi:[0,1]
	v_mov_b32_e32 v114, v112
	v_mov_b32_e32 v115, v111
	v_mov_b32_e32 v116, v110
	v_mov_b32_e32 v120, v110
	v_mov_b32_e32 v121, v113
	v_mov_b32_e32 v99, v119
	v_pk_add_f32 v[114:115], v[114:115], v[116:117] neg_lo:[0,1] neg_hi:[0,1]
	v_mov_b32_e32 v116, v82
	v_mov_b32_e32 v117, v69
	v_pk_add_f32 v[98:99], v[120:121], v[98:99] neg_lo:[0,1] neg_hi:[0,1]
	v_pk_add_f32 v[116:117], v[116:117], v[114:115] neg_lo:[0,1] neg_hi:[0,1]
	v_mov_b32_e32 v120, v98
	v_mov_b32_e32 v121, v115
	v_mov_b32_e32 v122, v112
	v_mov_b32_e32 v123, v83
	v_mov_b32_e32 v115, v89
	v_pk_add_f32 v[120:121], v[68:69], v[120:121] neg_lo:[0,1] neg_hi:[0,1]
	v_pk_add_f32 v[114:115], v[122:123], v[114:115] neg_lo:[0,1] neg_hi:[0,1]
	v_mov_b32_e32 v69, v111
	v_pk_add_f32 v[84:85], v[84:85], v[114:115] neg_lo:[0,1] neg_hi:[0,1]
	v_pk_add_f32 v[68:69], v[68:69], v[98:99] neg_lo:[0,1] neg_hi:[0,1]
	v_pk_add_f32 v[80:81], v[80:81], v[118:119] neg_lo:[0,1] neg_hi:[0,1]
	v_pk_add_f32 v[82:83], v[82:83], v[88:89] neg_lo:[0,1] neg_hi:[0,1]
	v_pk_add_f32 v[88:89], v[80:81], v[68:69]
	v_mov_b32_e32 v69, v117
	v_mov_b32_e32 v81, v85
	v_pk_add_f32 v[82:83], v[90:91], v[82:83] neg_lo:[0,1] neg_hi:[0,1]
	v_pk_add_f32 v[90:91], v[116:117], v[84:85]
	v_pk_add_f32 v[80:81], v[68:69], v[80:81]
	v_mov_b32_e32 v84, v88
	v_pk_add_f32 v[80:81], v[80:81], v[120:121] neg_lo:[0,1] neg_hi:[0,1]
	v_mov_b32_e32 v85, v91
	v_pk_add_f32 v[84:85], v[84:85], v[80:81] neg_lo:[0,1] neg_hi:[0,1]
	v_pk_add_f32 v[80:81], v[82:83], v[80:81] neg_lo:[0,1] neg_hi:[0,1]
	v_pk_add_f32 v[68:69], v[68:69], v[84:85] neg_lo:[0,1] neg_hi:[0,1]
	v_ldexp_f32 v86, v86, 1
	v_pk_add_f32 v[68:69], v[80:81], v[68:69]
	v_pk_add_f32 v[80:81], v[90:91], v[88:89]
	v_mov_b32_e32 v87, v103
	v_pk_add_f32 v[82:83], v[112:113], v[80:81]
	v_lshlrev_b64 v[66:67], 6, v[66:67]
	v_pk_add_f32 v[84:85], v[82:83], v[112:113] neg_lo:[0,1] neg_hi:[0,1]
; __device__ __forceinline__ float logsigf(float x) { return fminf(x, 0.f) - log1pf(__expf(-fabsf(x))); }
; __device__ void phaseA_tile(const Params& p, int l, int mt, int nt, char* smem) {
;     ...
;                     const float4 fb = *(const float4*)(p.b_f + l * 16 + c);
;                     const f32x4 v = acc[i][2];
;                     float4 lf = make_float4(logsigf(v[0] + fb.x), logsigf(v[1] + fb.y), logsigf(v[2] + fb.z), logsigf(v[3] + fb.w));
;                     float* o = samp ? (p.out + O_LFS + ((size_t)l * TSM + (row - TP)) * 16 + c)
;                                     : (p.out + O_LFP + ((size_t)l * TP + row) * 16 + c);
;                     *(float4*)o = lf;
;                     *(float4*)(lf_s + rl * 16 + c) = lf;
	v_lshl_add_u64 v[66:67], s[6:7], 0, v[66:67]
	v_pk_add_f32 v[80:81], v[80:81], v[84:85] neg_lo:[0,1] neg_hi:[0,1]
	v_lshl_add_u64 v[66:67], v[66:67], 0, v[0:1]
	v_pk_add_f32 v[68:69], v[68:69], v[80:81]
	v_lshl_or_b32 v0, v71, 6, v0
	v_pk_add_f32 v[68:69], v[82:83], v[68:69]
	v_pk_mul_f32 v[82:83], v[94:95], v[100:101]
	v_cndmask_b32_e32 v68, v160, v68, vcc
	v_cmp_neq_f32_e32 vcc, s8, v124
	v_pk_add_f32 v[84:85], v[92:93], v[82:83]
	s_nop 0
	v_cndmask_b32_e32 v69, v160, v69, vcc
	v_cmp_ngt_f32_e32 vcc, -1.0, v124
	v_pk_add_f32 v[90:91], v[84:85], v[92:93] neg_lo:[0,1] neg_hi:[0,1]
	v_mov_b32_e32 v110, v84
	v_cndmask_b32_e32 v69, v161, v69, vcc
	v_cmp_ngt_f32_e32 vcc, -1.0, v97
	v_pk_add_f32 v[82:83], v[82:83], v[90:91] neg_lo:[0,1] neg_hi:[0,1]
	s_nop 0
	v_cndmask_b32_e32 v68, v161, v68, vcc
	v_cmp_neq_f32_e32 vcc, -1.0, v97
	v_pk_add_f32 v[92:93], v[86:87], v[82:83]
	v_mov_b32_e32 v91, v83
	v_cndmask_b32_e32 v68, v162, v68, vcc
	v_cmp_neq_f32_e32 vcc, -1.0, v124
	v_mov_b32_e32 v87, v93
	v_mov_b32_e32 v83, v85
	v_cndmask_b32_e32 v69, v162, v69, vcc
	v_cmp_lt_f32_e64 vcc, |v97|, s9
	v_cndmask_b32_e64 v69, v69, v124, s[0:1]
	v_pk_add_f32 v[82:83], v[86:87], v[82:83]
	v_cndmask_b32_e32 v68, v68, v97, vcc
	v_pk_add_f32 v[76:77], v[76:77], v[68:69] neg_lo:[0,1] neg_hi:[0,1]
	v_cvt_f32_i32_e32 v69, v128
	v_cvt_f32_i32_e32 v68, v126
	v_pk_add_f32 v[86:87], v[84:85], v[92:93]
	v_cmp_neq_f32_e32 vcc, s8, v125
	v_mov_b32_e32 v113, v87
	v_pk_mul_f32 v[80:81], v[68:69], s[12:13] op_sel_hi:[1,0]
	v_cmp_lt_f32_e64 s[0:1], |v127|, s9
	v_pk_fma_f32 v[88:89], v[68:69], s[12:13], v[80:81] op_sel_hi:[1,0,1] neg_lo:[0,0,1] neg_hi:[0,0,1]
	v_mov_b32_e32 v90, v80
	v_pk_fma_f32 v[68:69], v[68:69], s[14:15], v[88:89] op_sel_hi:[1,0,1]
	v_mov_b32_e32 v101, v81
	v_pk_add_f32 v[88:89], v[80:81], v[68:69]
	v_mov_b32_e32 v102, v68
	v_pk_add_f32 v[94:95], v[88:89], v[86:87]
	v_pk_add_f32 v[90:91], v[90:91], v[102:103]
	v_mov_b32_e32 v102, v86
	v_mov_b32_e32 v103, v95
	v_mov_b32_e32 v111, v89
	v_pk_add_f32 v[102:103], v[102:103], v[110:111] neg_lo:[0,1] neg_hi:[0,1]
	v_mov_b32_e32 v98, v94
	v_mov_b32_e32 v99, v89
	v_mov_b32_e32 v100, v88
	v_mov_b32_e32 v110, v88
	v_mov_b32_e32 v111, v95
	v_mov_b32_e32 v81, v103
	v_pk_add_f32 v[98:99], v[98:99], v[100:101] neg_lo:[0,1] neg_hi:[0,1]
	v_mov_b32_e32 v100, v86
	v_mov_b32_e32 v101, v69
	v_pk_add_f32 v[80:81], v[110:111], v[80:81] neg_lo:[0,1] neg_hi:[0,1]
	v_pk_add_f32 v[100:101], v[100:101], v[98:99] neg_lo:[0,1] neg_hi:[0,1]
	v_mov_b32_e32 v110, v80
	v_mov_b32_e32 v111, v99
	v_mov_b32_e32 v112, v94
	v_mov_b32_e32 v99, v85
	v_pk_add_f32 v[110:111], v[68:69], v[110:111] neg_lo:[0,1] neg_hi:[0,1]
	v_pk_add_f32 v[98:99], v[112:113], v[98:99] neg_lo:[0,1] neg_hi:[0,1]
	v_mov_b32_e32 v69, v89
	v_pk_add_f32 v[84:85], v[86:87], v[84:85] neg_lo:[0,1] neg_hi:[0,1]
	v_pk_add_f32 v[86:87], v[90:91], v[98:99] neg_lo:[0,1] neg_hi:[0,1]
	v_pk_add_f32 v[68:69], v[68:69], v[80:81] neg_lo:[0,1] neg_hi:[0,1]
	v_pk_add_f32 v[80:81], v[82:83], v[102:103] neg_lo:[0,1] neg_hi:[0,1]
	v_pk_add_f32 v[88:89], v[100:101], v[86:87]
	v_pk_add_f32 v[82:83], v[80:81], v[68:69]
	v_mov_b32_e32 v69, v101
	v_mov_b32_e32 v81, v87
	v_pk_add_f32 v[80:81], v[68:69], v[80:81]
	v_mov_b32_e32 v86, v82
	v_pk_add_f32 v[80:81], v[80:81], v[110:111] neg_lo:[0,1] neg_hi:[0,1]
	v_mov_b32_e32 v87, v89
	v_pk_add_f32 v[84:85], v[92:93], v[84:85] neg_lo:[0,1] neg_hi:[0,1]
	v_pk_add_f32 v[86:87], v[86:87], v[80:81] neg_lo:[0,1] neg_hi:[0,1]
	v_pk_add_f32 v[80:81], v[84:85], v[80:81] neg_lo:[0,1] neg_hi:[0,1]
	v_pk_add_f32 v[68:69], v[68:69], v[86:87] neg_lo:[0,1] neg_hi:[0,1]
	s_nop 0
	v_pk_add_f32 v[68:69], v[80:81], v[68:69]
	v_pk_add_f32 v[80:81], v[88:89], v[82:83]
	s_nop 0
	v_pk_add_f32 v[82:83], v[94:95], v[80:81]
	s_nop 0
	v_pk_add_f32 v[84:85], v[82:83], v[94:95] neg_lo:[0,1] neg_hi:[0,1]
	s_nop 0
	v_pk_add_f32 v[80:81], v[80:81], v[84:85] neg_lo:[0,1] neg_hi:[0,1]
	s_nop 0
	v_pk_add_f32 v[68:69], v[68:69], v[80:81]
	s_nop 0
	v_pk_add_f32 v[68:69], v[82:83], v[68:69]
	s_nop 0
	v_cndmask_b32_e32 v68, v160, v68, vcc
	v_cmp_neq_f32_e32 vcc, s8, v127
	s_nop 1
	v_cndmask_b32_e32 v69, v160, v69, vcc
	v_cmp_ngt_f32_e32 vcc, -1.0, v127
	s_nop 1
	v_cndmask_b32_e32 v69, v161, v69, vcc
	v_cmp_ngt_f32_e32 vcc, -1.0, v125
	s_nop 1
	v_cndmask_b32_e32 v68, v161, v68, vcc
	v_cmp_neq_f32_e32 vcc, -1.0, v125
	s_nop 1
	v_cndmask_b32_e32 v68, v162, v68, vcc
	v_cmp_neq_f32_e32 vcc, -1.0, v127
	s_nop 1
	v_cndmask_b32_e32 v69, v162, v69, vcc
	v_cmp_lt_f32_e64 vcc, |v125|, s9
	v_cndmask_b32_e64 v69, v69, v127, s[0:1]
	s_nop 0
	v_cndmask_b32_e32 v68, v68, v125, vcc
	v_pk_add_f32 v[78:79], v[78:79], v[68:69] neg_lo:[0,1] neg_hi:[0,1]
	global_store_dwordx4 v[66:67], v[76:79], off
	ds_write_b128 v0, v[76:79]
